# address-hoist extended to all 28 K-loops (partial in 12 loops where SGPR reuse blocks the s_add/addc pair); bit-identical
# baseline (speedup 1.0000x reference)
; #define PG8_STAGE(bufoff, gbase, voff) do { _Pragma("unroll") for (int _i = 0; _i < 2; ++_i) \
;         __builtin_amdgcn_global_load_lds((const unsigned*)((const char*)(gbase) + (voff)[_i]), (PG8_LAS unsigned*)(lds + (bufoff) + ldsw + _i * 8192), 16, 0, 0); } while (0)
; #define PG8_LDA(dst, b, h) do { _Pragma("unroll") for (int m = 0; m < 4; ++m) _Pragma("unroll") for (int k = 0; k < 2; ++k) dst[m][k] = *(const PG8_LAS bf16x8*)(lds + PG8_SA(b, h) + aoff + m * 2048 + k * 1024); } while (0)
; #define PG8_LDB(dst, b, h) do { _Pragma("unroll") for (int n = 0; n < 2; ++n) _Pragma("unroll") for (int k = 0; k < 2; ++k) dst[n][k] = *(const PG8_LAS bf16x8*)(lds + PG8_SB(b, h) + boff + n * 2048 + k * 1024); } while (0)
; #define PG8_MMA(ai, bj, At, Bt) do { __builtin_amdgcn_s_setprio(1); _Pragma("unroll") for (int m = 0; m < 4; ++m) _Pragma("unroll") for (int n = 0; n < 2; ++n) _Pragma("unroll") for (int k = 0; k < 2; ++k) \
;         acc[ai][bj][m][n] = __builtin_amdgcn_mfma_f32_16x16x32_bf16(Bt[n][k], At[m][k], acc[ai][bj][m][n], 0, 0, 0); __builtin_amdgcn_s_setprio(0); } while (0)
; #define PG8_WAIT_V(n) asm volatile("s_waitcnt vmcnt(" #n ")" ::: "memory")
; #define PG8_WAIT_L(n) asm volatile("s_waitcnt lgkmcnt(" #n ")" ::: "memory")
; #define PG8_BAR __builtin_amdgcn_s_barrier()
; #define PG8_SCHED __builtin_amdgcn_sched_barrier(0)
; template <class Epi, class Sched, bool ALIGN_EPI = false, bool SP2 = false>
; __device__ __forceinline__ void gemm_phase(PG8_LAS unsigned char* lds, const Gemm g, const Sched& S, const Epi& E, const int wave_s) {
;     ...
;             const bool last = (t == nt - 2);
;             const char* a1 = cA + (size_t)(t + 1) * kstep;
;             const char* a2 = last ? nA : cA + (size_t)(t + 2) * kstep; const char* b2 = last ? nB : cB + (size_t)(t + 2) * kstep;
;             const char* a3 = a2 + kstep; const char* b3 = b2 + kstep;
;             if (last && has_next) S.a_ready(nxt);
;             if constexpr (SP2) {
;             PG8_LDB(B0, 0, 0); PG8_LDB(B1, 0, 1); PG8_SCHED; PG8_LDA(At, 0, 0); PG8_STAGE(PG8_SA(1, 1), a1 + hstep, voffA);
;             PG8_WAIT_V(8); PG8_WAIT_L(0); PG8_BAR; PG8_MMA(0, 0, At, B0); PG8_MMA(0, 1, At, B1); PG8_BAR; PG8_SCHED;
;             PG8_LDA(At, 0, 1); PG8_STAGE(PG8_SB(0, 0), b2, voffB); PG8_STAGE(PG8_SB(0, 1), b2 + hstep, voffB); PG8_STAGE(PG8_SA(0, 0), a2, voffA);
.LBB0_348:
	ds_read_b128 v[128:131], v203
	ds_read_b128 v[132:135], v203 offset:1024
	ds_read_b128 v[136:139], v203 offset:2048
	ds_read_b128 v[140:143], v203 offset:3072
	ds_read_b128 v[144:147], v205
	ds_read_b128 v[148:151], v205 offset:1024
	ds_read_b128 v[152:155], v205 offset:2048
	ds_read_b128 v[156:159], v205 offset:3072
	s_add_u32 s34, s8, 0xfffc0080
	s_addc_u32 s35, s9, -1
	s_cmp_eq_u32 s69, 12
	s_cselect_b32 s37, s7, s35
	s_cselect_b32 s36, s10, s34
	s_cselect_b32 s35, s25, s68
	s_cselect_b32 s34, s27, s67
	v_lshl_add_u64 v[218:219], s[8:9], 0, v[186:187]
	s_add_i32 m0, s44, 0xc000
	ds_read_b128 v[160:163], v207
	ds_read_b128 v[164:167], v207 offset:1024
	ds_read_b128 v[168:171], v207 offset:2048
	ds_read_b128 v[172:175], v207 offset:3072
	ds_read_b128 v[192:195], v207 offset:4096
	ds_read_b128 v[196:199], v207 offset:5120
	ds_read_b128 v[208:211], v207 offset:6144
	ds_read_b128 v[214:217], v207 offset:7168
	global_load_lds_dwordx4 v[218:219], off
	v_lshl_add_u64 v[218:219], s[8:9], 0, v[184:185]
	s_add_i32 m0, s44, 0xe000
	s_nop 0
	global_load_lds_dwordx4 v[218:219], off
	v_lshl_add_u64 v[230:231], s[34:35], 0, v[180:181]
	v_lshl_add_u64 v[232:233], s[34:35], 0, v[176:177]
	v_lshl_add_u64 v[234:235], s[36:37], 0, v[178:179]
	s_waitcnt vmcnt(8)
	s_waitcnt lgkmcnt(0)
	s_barrier
	s_setprio 1
	s_waitcnt lgkmcnt(0)
	v_mfma_f32_16x16x32_bf16 v[124:127], v[128:131], v[160:163], v[124:127]
	v_mfma_f32_16x16x32_bf16 v[120:123], v[136:139], v[160:163], v[120:123]
	v_mfma_f32_16x16x32_bf16 v[116:119], v[128:131], v[168:171], v[116:119]
	v_mfma_f32_16x16x32_bf16 v[108:111], v[136:139], v[168:171], v[108:111]
	v_mfma_f32_16x16x32_bf16 v[100:103], v[128:131], v[192:195], v[100:103]
	v_mfma_f32_16x16x32_bf16 v[92:95], v[136:139], v[192:195], v[92:95]
	v_mfma_f32_16x16x32_bf16 v[84:87], v[128:131], v[208:211], v[84:87]
	v_mfma_f32_16x16x32_bf16 v[76:79], v[136:139], v[208:211], v[76:79]
	v_mfma_f32_16x16x32_bf16 v[124:127], v[132:135], v[164:167], v[124:127]
	v_mfma_f32_16x16x32_bf16 v[120:123], v[140:143], v[164:167], v[120:123]
	v_mfma_f32_16x16x32_bf16 v[116:119], v[132:135], v[172:175], v[116:119]
	v_mfma_f32_16x16x32_bf16 v[108:111], v[140:143], v[172:175], v[108:111]
	v_mfma_f32_16x16x32_bf16 v[100:103], v[132:135], v[196:199], v[100:103]
	v_mfma_f32_16x16x32_bf16 v[92:95], v[140:143], v[196:199], v[92:95]
	v_mfma_f32_16x16x32_bf16 v[84:87], v[132:135], v[214:217], v[84:87]
	v_mfma_f32_16x16x32_bf16 v[76:79], v[140:143], v[214:217], v[76:79]
	s_setprio 0
	s_setprio 1
	v_mfma_f32_16x16x32_bf16 v[112:115], v[144:147], v[160:163], v[112:115]
	v_mfma_f32_16x16x32_bf16 v[104:107], v[152:155], v[160:163], v[104:107]
	v_mfma_f32_16x16x32_bf16 v[96:99], v[144:147], v[168:171], v[96:99]
	v_mfma_f32_16x16x32_bf16 v[88:91], v[152:155], v[168:171], v[88:91]
	v_mfma_f32_16x16x32_bf16 v[80:83], v[144:147], v[192:195], v[80:83]
	v_mfma_f32_16x16x32_bf16 v[72:75], v[152:155], v[192:195], v[72:75]
	v_mfma_f32_16x16x32_bf16 v[68:71], v[144:147], v[208:211], v[68:71]
	v_mfma_f32_16x16x32_bf16 v[64:67], v[152:155], v[208:211], v[64:67]
	v_mfma_f32_16x16x32_bf16 v[112:115], v[148:151], v[164:167], v[112:115]
	v_mfma_f32_16x16x32_bf16 v[104:107], v[156:159], v[164:167], v[104:107]
	v_mfma_f32_16x16x32_bf16 v[96:99], v[148:151], v[172:175], v[96:99]
	v_mfma_f32_16x16x32_bf16 v[88:91], v[156:159], v[172:175], v[88:91]
	v_mfma_f32_16x16x32_bf16 v[80:83], v[148:151], v[196:199], v[80:83]
	v_mfma_f32_16x16x32_bf16 v[72:75], v[156:159], v[196:199], v[72:75]
	v_mfma_f32_16x16x32_bf16 v[68:71], v[148:151], v[214:217], v[68:71]
	v_mfma_f32_16x16x32_bf16 v[64:67], v[156:159], v[214:217], v[64:67]
	s_setprio 0
	s_barrier
	s_add_i32 s70, s62, s33
	s_mov_b32 m0, s70
	ds_read_b128 v[160:163], v207 offset:16384
	ds_read_b128 v[164:167], v207 offset:17408
	ds_read_b128 v[168:171], v207 offset:18432
	ds_read_b128 v[172:175], v207 offset:19456
	ds_read_b128 v[192:195], v207 offset:20480
	ds_read_b128 v[196:199], v207 offset:21504
	ds_read_b128 v[208:211], v207 offset:22528
	ds_read_b128 v[214:217], v207 offset:23552
	global_load_lds_dwordx4 v[230:231], off
	s_add_i32 m0, s70, 0x2000
	s_add_u32 s70, s34, 0x40000
	s_addc_u32 s71, s35, 0
	s_add_i32 s72, s63, s33
	global_load_lds_dwordx4 v[232:233], off
	v_lshl_add_u64 v[222:223], s[70:71], 0, v[180:181]
	s_mov_b32 m0, s72
	s_nop 0
	global_load_lds_dwordx4 v[222:223], off
	v_lshl_add_u64 v[222:223], s[70:71], 0, v[176:177]
	s_add_i32 m0, s72, 0x2000
	s_nop 0
	global_load_lds_dwordx4 v[222:223], off
	v_lshl_add_u64 v[222:223], s[36:37], 0, v[182:183]
	s_mov_b32 m0, s44
	s_nop 0
	global_load_lds_dwordx4 v[222:223], off
	s_mov_b32 m0, s45
	s_nop 0
	global_load_lds_dwordx4 v[234:235], off
	s_waitcnt vmcnt(8)
	s_waitcnt lgkmcnt(0)
	s_barrier
; #define PG8_STAGE(bufoff, gbase, voff) do { _Pragma("unroll") for (int _i = 0; _i < 2; ++_i) \
;         __builtin_amdgcn_global_load_lds((const unsigned*)((const char*)(gbase) + (voff)[_i]), (PG8_LAS unsigned*)(lds + (bufoff) + ldsw + _i * 8192), 16, 0, 0); } while (0)
; #define PG8_LDA(dst, b, h) do { _Pragma("unroll") for (int m = 0; m < 4; ++m) _Pragma("unroll") for (int k = 0; k < 2; ++k) dst[m][k] = *(const PG8_LAS bf16x8*)(lds + PG8_SA(b, h) + aoff + m * 2048 + k * 1024); } while (0)
; #define PG8_LDB(dst, b, h) do { _Pragma("unroll") for (int n = 0; n < 2; ++n) _Pragma("unroll") for (int k = 0; k < 2; ++k) dst[n][k] = *(const PG8_LAS bf16x8*)(lds + PG8_SB(b, h) + boff + n * 2048 + k * 1024); } while (0)
; #define PG8_MMA(ai, bj, At, Bt) do { __builtin_amdgcn_s_setprio(1); _Pragma("unroll") for (int m = 0; m < 4; ++m) _Pragma("unroll") for (int n = 0; n < 2; ++n) _Pragma("unroll") for (int k = 0; k < 2; ++k) \
;         acc[ai][bj][m][n] = __builtin_amdgcn_mfma_f32_16x16x32_bf16(Bt[n][k], At[m][k], acc[ai][bj][m][n], 0, 0, 0); __builtin_amdgcn_s_setprio(0); } while (0)
; #define PG8_WAIT_V(n) asm volatile("s_waitcnt vmcnt(" #n ")" ::: "memory")
; #define PG8_WAIT_L(n) asm volatile("s_waitcnt lgkmcnt(" #n ")" ::: "memory")
; #define PG8_BAR __builtin_amdgcn_s_barrier()
; #define PG8_SCHED __builtin_amdgcn_sched_barrier(0)
; template <class Epi, class Sched, bool ALIGN_EPI = false, bool SP2 = false>
; __device__ __forceinline__ void gemm_phase(PG8_LAS unsigned char* lds, const Gemm g, const Sched& S, const Epi& E, const int wave_s) {
;     ...
;             PG8_WAIT_V(8); PG8_WAIT_L(0); PG8_BAR; PG8_MMA(1, 0, At, B0); PG8_MMA(1, 1, At, B1); PG8_BAR; PG8_SCHED;
;             PG8_LDB(B0, 1, 0); PG8_LDB(B1, 1, 1); PG8_SCHED; PG8_LDA(At, 1, 0); PG8_STAGE(PG8_SA(0, 1), a2 + hstep, voffA);
;             PG8_WAIT_V(8); PG8_WAIT_L(0); PG8_BAR; PG8_MMA(0, 0, At, B0); PG8_MMA(0, 1, At, B1); PG8_BAR; PG8_SCHED;
	s_setprio 1
	s_waitcnt lgkmcnt(0)
	v_mfma_f32_16x16x32_bf16 v[60:63], v[128:131], v[160:163], v[60:63]
	v_mfma_f32_16x16x32_bf16 v[56:59], v[136:139], v[160:163], v[56:59]
	v_mfma_f32_16x16x32_bf16 v[52:55], v[128:131], v[168:171], v[52:55]
	v_mfma_f32_16x16x32_bf16 v[44:47], v[136:139], v[168:171], v[44:47]
	v_mfma_f32_16x16x32_bf16 v[36:39], v[128:131], v[192:195], v[36:39]
	v_mfma_f32_16x16x32_bf16 v[28:31], v[136:139], v[192:195], v[28:31]
	v_mfma_f32_16x16x32_bf16 v[20:23], v[128:131], v[208:211], v[20:23]
	v_mfma_f32_16x16x32_bf16 v[12:15], v[136:139], v[208:211], v[12:15]
	v_mfma_f32_16x16x32_bf16 v[60:63], v[132:135], v[164:167], v[60:63]
	v_mfma_f32_16x16x32_bf16 v[56:59], v[140:143], v[164:167], v[56:59]
	v_mfma_f32_16x16x32_bf16 v[52:55], v[132:135], v[172:175], v[52:55]
	v_mfma_f32_16x16x32_bf16 v[44:47], v[140:143], v[172:175], v[44:47]
	v_mfma_f32_16x16x32_bf16 v[36:39], v[132:135], v[196:199], v[36:39]
	v_mfma_f32_16x16x32_bf16 v[28:31], v[140:143], v[196:199], v[28:31]
	v_mfma_f32_16x16x32_bf16 v[20:23], v[132:135], v[214:217], v[20:23]
	v_mfma_f32_16x16x32_bf16 v[12:15], v[140:143], v[214:217], v[12:15]
	s_setprio 0
	s_setprio 1
	v_mfma_f32_16x16x32_bf16 v[48:51], v[144:147], v[160:163], v[48:51]
	v_mfma_f32_16x16x32_bf16 v[40:43], v[152:155], v[160:163], v[40:43]
	v_mfma_f32_16x16x32_bf16 v[32:35], v[144:147], v[168:171], v[32:35]
	v_mfma_f32_16x16x32_bf16 v[24:27], v[152:155], v[168:171], v[24:27]
	v_mfma_f32_16x16x32_bf16 v[16:19], v[144:147], v[192:195], v[16:19]
	v_mfma_f32_16x16x32_bf16 v[8:11], v[152:155], v[192:195], v[8:11]
	v_mfma_f32_16x16x32_bf16 v[4:7], v[144:147], v[208:211], v[4:7]
	v_mfma_f32_16x16x32_bf16 v[0:3], v[152:155], v[208:211], v[0:3]
	v_mfma_f32_16x16x32_bf16 v[48:51], v[148:151], v[164:167], v[48:51]
	v_mfma_f32_16x16x32_bf16 v[40:43], v[156:159], v[164:167], v[40:43]
	v_mfma_f32_16x16x32_bf16 v[32:35], v[148:151], v[172:175], v[32:35]
	v_mfma_f32_16x16x32_bf16 v[24:27], v[156:159], v[172:175], v[24:27]
	v_mfma_f32_16x16x32_bf16 v[16:19], v[148:151], v[196:199], v[16:19]
	v_mfma_f32_16x16x32_bf16 v[8:11], v[156:159], v[196:199], v[8:11]
	v_mfma_f32_16x16x32_bf16 v[4:7], v[148:151], v[214:217], v[4:7]
	v_mfma_f32_16x16x32_bf16 v[0:3], v[156:159], v[214:217], v[0:3]
	s_setprio 0
	s_barrier
	s_add_i32 s70, 0, 0x18000
	s_add_i32 s71, 0, 0x1c000
	v_add_u32_e32 v140, s70, v201
	v_add_u32_e32 v156, s71, v201
	ds_read_b128 v[128:131], v140
	ds_read_b128 v[132:135], v140 offset:1024
	ds_read_b128 v[136:139], v140 offset:2048
	ds_read_b128 v[140:143], v140 offset:3072
	ds_read_b128 v[144:147], v156
	ds_read_b128 v[148:151], v156 offset:1024
	ds_read_b128 v[152:155], v156 offset:2048
	ds_read_b128 v[156:159], v156 offset:3072
	s_add_u32 s36, s36, 0x40000
	s_addc_u32 s37, s37, 0
	s_mov_b32 m0, s46
	v_lshl_add_u64 v[226:227], s[36:37], 0, v[182:183]
	ds_read_b128 v[160:163], v207 offset:32768
	ds_read_b128 v[164:167], v207 offset:33792
	ds_read_b128 v[168:171], v207 offset:34816
	ds_read_b128 v[172:175], v207 offset:35840
	ds_read_b128 v[192:195], v207 offset:36864
	ds_read_b128 v[196:199], v207 offset:37888
	ds_read_b128 v[208:211], v207 offset:38912
	ds_read_b128 v[214:217], v207 offset:39936
	global_load_lds_dwordx4 v[226:227], off
	v_lshl_add_u64 v[226:227], s[36:37], 0, v[178:179]
	s_mov_b32 m0, s47
	s_nop 0
	global_load_lds_dwordx4 v[226:227], off
	v_lshl_add_u64 v[236:237], v[230:231], 0, s[20:21]
	s_add_u32 s34, s34, 0x40080
	v_lshl_add_u64 v[238:239], v[232:233], 0, s[20:21]
	s_addc_u32 s35, s35, 0
	v_lshl_add_u64 v[240:241], s[34:35], 0, v[180:181]
	v_lshl_add_u64 v[242:243], s[34:35], 0, v[176:177]
	v_lshl_add_u64 v[244:245], v[222:223], 0, s[20:21]
	v_lshl_add_u64 v[246:247], v[234:235], 0, s[20:21]
	s_waitcnt vmcnt(8)
	s_waitcnt lgkmcnt(0)
	s_barrier
; #define PG8_STAGE(bufoff, gbase, voff) do { _Pragma("unroll") for (int _i = 0; _i < 2; ++_i) \
;         __builtin_amdgcn_global_load_lds((const unsigned*)((const char*)(gbase) + (voff)[_i]), (PG8_LAS unsigned*)(lds + (bufoff) + ldsw + _i * 8192), 16, 0, 0); } while (0)
; #define PG8_LDA(dst, b, h) do { _Pragma("unroll") for (int m = 0; m < 4; ++m) _Pragma("unroll") for (int k = 0; k < 2; ++k) dst[m][k] = *(const PG8_LAS bf16x8*)(lds + PG8_SA(b, h) + aoff + m * 2048 + k * 1024); } while (0)
; #define PG8_MMA(ai, bj, At, Bt) do { __builtin_amdgcn_s_setprio(1); _Pragma("unroll") for (int m = 0; m < 4; ++m) _Pragma("unroll") for (int n = 0; n < 2; ++n) _Pragma("unroll") for (int k = 0; k < 2; ++k) \
;         acc[ai][bj][m][n] = __builtin_amdgcn_mfma_f32_16x16x32_bf16(Bt[n][k], At[m][k], acc[ai][bj][m][n], 0, 0, 0); __builtin_amdgcn_s_setprio(0); } while (0)
; #define PG8_WAIT_V(n) asm volatile("s_waitcnt vmcnt(" #n ")" ::: "memory")
; #define PG8_WAIT_L(n) asm volatile("s_waitcnt lgkmcnt(" #n ")" ::: "memory")
; #define PG8_BAR __builtin_amdgcn_s_barrier()
; #define PG8_SCHED __builtin_amdgcn_sched_barrier(0)
; template <class Epi, class Sched, bool ALIGN_EPI = false, bool SP2 = false>
; __device__ __forceinline__ void gemm_phase(PG8_LAS unsigned char* lds, const Gemm g, const Sched& S, const Epi& E, const int wave_s) {
;     ...
;             PG8_WAIT_V(8); PG8_WAIT_L(0); PG8_BAR; PG8_MMA(0, 0, At, B0); PG8_MMA(0, 1, At, B1); PG8_BAR; PG8_SCHED;
;             PG8_LDA(At, 1, 1); PG8_STAGE(PG8_SB(1, 0), b3, voffB); PG8_STAGE(PG8_SB(1, 1), b3 + hstep, voffB); PG8_STAGE(PG8_SA(1, 0), a3, voffA);
;             PG8_WAIT_V(8); PG8_WAIT_L(0); PG8_BAR; PG8_MMA(1, 0, At, B0); PG8_MMA(1, 1, At, B1); PG8_BAR; PG8_SCHED;
	s_setprio 1
	s_waitcnt lgkmcnt(0)
	v_mfma_f32_16x16x32_bf16 v[124:127], v[128:131], v[160:163], v[124:127]
	v_mfma_f32_16x16x32_bf16 v[120:123], v[136:139], v[160:163], v[120:123]
	v_mfma_f32_16x16x32_bf16 v[116:119], v[128:131], v[168:171], v[116:119]
	v_mfma_f32_16x16x32_bf16 v[108:111], v[136:139], v[168:171], v[108:111]
	v_mfma_f32_16x16x32_bf16 v[100:103], v[128:131], v[192:195], v[100:103]
	v_mfma_f32_16x16x32_bf16 v[92:95], v[136:139], v[192:195], v[92:95]
	v_mfma_f32_16x16x32_bf16 v[84:87], v[128:131], v[208:211], v[84:87]
	v_mfma_f32_16x16x32_bf16 v[76:79], v[136:139], v[208:211], v[76:79]
	v_mfma_f32_16x16x32_bf16 v[124:127], v[132:135], v[164:167], v[124:127]
	v_mfma_f32_16x16x32_bf16 v[120:123], v[140:143], v[164:167], v[120:123]
	v_mfma_f32_16x16x32_bf16 v[116:119], v[132:135], v[172:175], v[116:119]
	v_mfma_f32_16x16x32_bf16 v[108:111], v[140:143], v[172:175], v[108:111]
	v_mfma_f32_16x16x32_bf16 v[100:103], v[132:135], v[196:199], v[100:103]
	v_mfma_f32_16x16x32_bf16 v[92:95], v[140:143], v[196:199], v[92:95]
	v_mfma_f32_16x16x32_bf16 v[84:87], v[132:135], v[214:217], v[84:87]
	v_mfma_f32_16x16x32_bf16 v[76:79], v[140:143], v[214:217], v[76:79]
	s_setprio 0
	s_setprio 1
	v_mfma_f32_16x16x32_bf16 v[112:115], v[144:147], v[160:163], v[112:115]
	v_mfma_f32_16x16x32_bf16 v[104:107], v[152:155], v[160:163], v[104:107]
	v_mfma_f32_16x16x32_bf16 v[96:99], v[144:147], v[168:171], v[96:99]
	v_mfma_f32_16x16x32_bf16 v[88:91], v[152:155], v[168:171], v[88:91]
	v_mfma_f32_16x16x32_bf16 v[80:83], v[144:147], v[192:195], v[80:83]
	v_mfma_f32_16x16x32_bf16 v[72:75], v[152:155], v[192:195], v[72:75]
	v_mfma_f32_16x16x32_bf16 v[68:71], v[144:147], v[208:211], v[68:71]
	v_mfma_f32_16x16x32_bf16 v[64:67], v[152:155], v[208:211], v[64:67]
	v_mfma_f32_16x16x32_bf16 v[112:115], v[148:151], v[164:167], v[112:115]
	v_mfma_f32_16x16x32_bf16 v[104:107], v[156:159], v[164:167], v[104:107]
	v_mfma_f32_16x16x32_bf16 v[96:99], v[148:151], v[172:175], v[96:99]
	v_mfma_f32_16x16x32_bf16 v[88:91], v[156:159], v[172:175], v[88:91]
	v_mfma_f32_16x16x32_bf16 v[80:83], v[148:151], v[196:199], v[80:83]
	v_mfma_f32_16x16x32_bf16 v[72:75], v[156:159], v[196:199], v[72:75]
	v_mfma_f32_16x16x32_bf16 v[68:71], v[148:151], v[214:217], v[68:71]
	v_mfma_f32_16x16x32_bf16 v[64:67], v[156:159], v[214:217], v[64:67]
	s_setprio 0
	s_barrier
	s_add_i32 s36, s70, s33
	s_mov_b32 m0, s36
	ds_read_b128 v[160:163], v207 offset:49152
	ds_read_b128 v[164:167], v207 offset:50176
	ds_read_b128 v[168:171], v207 offset:51200
	ds_read_b128 v[172:175], v207 offset:52224
	ds_read_b128 v[192:195], v207 offset:53248
	ds_read_b128 v[196:199], v207 offset:54272
	ds_read_b128 v[208:211], v207 offset:55296
	ds_read_b128 v[214:217], v207 offset:56320
	global_load_lds_dwordx4 v[236:237], off
	s_add_i32 m0, s36, 0x2000
	s_add_i32 s36, s71, s33
	global_load_lds_dwordx4 v[238:239], off
	s_mov_b32 m0, s36
	s_nop 0
	global_load_lds_dwordx4 v[240:241], off
	s_add_i32 m0, s36, 0x2000
	s_nop 0
	global_load_lds_dwordx4 v[242:243], off
	s_mov_b32 m0, s48
	s_nop 0
	global_load_lds_dwordx4 v[244:245], off
	s_mov_b32 m0, s49
	s_nop 0
	global_load_lds_dwordx4 v[246:247], off
	s_waitcnt vmcnt(8)
	s_waitcnt lgkmcnt(0)
	s_barrier
	s_setprio 1
	s_waitcnt lgkmcnt(0)
	v_mfma_f32_16x16x32_bf16 v[60:63], v[128:131], v[160:163], v[60:63]
	v_mfma_f32_16x16x32_bf16 v[56:59], v[136:139], v[160:163], v[56:59]
	v_mfma_f32_16x16x32_bf16 v[52:55], v[128:131], v[168:171], v[52:55]
	v_mfma_f32_16x16x32_bf16 v[44:47], v[136:139], v[168:171], v[44:47]
	v_mfma_f32_16x16x32_bf16 v[36:39], v[128:131], v[192:195], v[36:39]
	v_mfma_f32_16x16x32_bf16 v[28:31], v[136:139], v[192:195], v[28:31]
	v_mfma_f32_16x16x32_bf16 v[20:23], v[128:131], v[208:211], v[20:23]
	v_mfma_f32_16x16x32_bf16 v[12:15], v[136:139], v[208:211], v[12:15]
	v_mfma_f32_16x16x32_bf16 v[60:63], v[132:135], v[164:167], v[60:63]
	v_mfma_f32_16x16x32_bf16 v[56:59], v[140:143], v[164:167], v[56:59]
	v_mfma_f32_16x16x32_bf16 v[52:55], v[132:135], v[172:175], v[52:55]
	v_mfma_f32_16x16x32_bf16 v[44:47], v[140:143], v[172:175], v[44:47]
	v_mfma_f32_16x16x32_bf16 v[36:39], v[132:135], v[196:199], v[36:39]
	v_mfma_f32_16x16x32_bf16 v[28:31], v[140:143], v[196:199], v[28:31]
	v_mfma_f32_16x16x32_bf16 v[20:23], v[132:135], v[214:217], v[20:23]
	v_mfma_f32_16x16x32_bf16 v[12:15], v[140:143], v[214:217], v[12:15]
	s_setprio 0
	s_setprio 1
	v_mfma_f32_16x16x32_bf16 v[48:51], v[144:147], v[160:163], v[48:51]
	v_mfma_f32_16x16x32_bf16 v[40:43], v[152:155], v[160:163], v[40:43]
	v_mfma_f32_16x16x32_bf16 v[32:35], v[144:147], v[168:171], v[32:35]
	v_mfma_f32_16x16x32_bf16 v[24:27], v[152:155], v[168:171], v[24:27]
	v_mfma_f32_16x16x32_bf16 v[16:19], v[144:147], v[192:195], v[16:19]
	v_mfma_f32_16x16x32_bf16 v[8:11], v[152:155], v[192:195], v[8:11]
	v_mfma_f32_16x16x32_bf16 v[4:7], v[144:147], v[208:211], v[4:7]
	v_mfma_f32_16x16x32_bf16 v[0:3], v[152:155], v[208:211], v[0:3]
	v_mfma_f32_16x16x32_bf16 v[48:51], v[148:151], v[164:167], v[48:51]
	v_mfma_f32_16x16x32_bf16 v[40:43], v[156:159], v[164:167], v[40:43]
	v_mfma_f32_16x16x32_bf16 v[32:35], v[148:151], v[172:175], v[32:35]
	v_mfma_f32_16x16x32_bf16 v[24:27], v[156:159], v[172:175], v[24:27]
	v_mfma_f32_16x16x32_bf16 v[16:19], v[148:151], v[196:199], v[16:19]
	v_mfma_f32_16x16x32_bf16 v[8:11], v[156:159], v[196:199], v[8:11]
	v_mfma_f32_16x16x32_bf16 v[4:7], v[148:151], v[214:217], v[4:7]
	v_mfma_f32_16x16x32_bf16 v[0:3], v[156:159], v[214:217], v[0:3]
	s_setprio 0
	s_barrier
	s_add_i32 s69, s69, 2
	s_add_u32 s67, s67, 0x100
	s_addc_u32 s68, s68, 0
	s_add_u32 s8, s8, 0x100
	s_addc_u32 s9, s9, 0
	s_cmp_gt_u32 s69, 13
	s_cbranch_scc0 .LBB0_348
	s_and_b64 vcc, exec, s[22:23]
	s_cbranch_vccz .LBB0_351
	s_barrier

; #define PG8_STAGE(bufoff, gbase, voff) do { _Pragma("unroll") for (int _i = 0; _i < 2; ++_i) \
;         __builtin_amdgcn_global_load_lds((const unsigned*)((const char*)(gbase) + (voff)[_i]), (PG8_LAS unsigned*)(lds + (bufoff) + ldsw + _i * 8192), 16, 0, 0); } while (0)
; #define PG8_LDA(dst, b, h) do { _Pragma("unroll") for (int m = 0; m < 4; ++m) _Pragma("unroll") for (int k = 0; k < 2; ++k) dst[m][k] = *(const PG8_LAS bf16x8*)(lds + PG8_SA(b, h) + aoff + m * 2048 + k * 1024); } while (0)
; #define PG8_LDB(dst, b, h) do { _Pragma("unroll") for (int n = 0; n < 2; ++n) _Pragma("unroll") for (int k = 0; k < 2; ++k) dst[n][k] = *(const PG8_LAS bf16x8*)(lds + PG8_SB(b, h) + boff + n * 2048 + k * 1024); } while (0)
; #define PG8_MMA(ai, bj, At, Bt) do { __builtin_amdgcn_s_setprio(1); _Pragma("unroll") for (int m = 0; m < 4; ++m) _Pragma("unroll") for (int n = 0; n < 2; ++n) _Pragma("unroll") for (int k = 0; k < 2; ++k) \
;         acc[ai][bj][m][n] = __builtin_amdgcn_mfma_f32_16x16x32_bf16(Bt[n][k], At[m][k], acc[ai][bj][m][n], 0, 0, 0); __builtin_amdgcn_s_setprio(0); } while (0)
; #define PG8_WAIT_V(n) asm volatile("s_waitcnt vmcnt(" #n ")" ::: "memory")
; #define PG8_WAIT_L(n) asm volatile("s_waitcnt lgkmcnt(" #n ")" ::: "memory")
; #define PG8_BAR __builtin_amdgcn_s_barrier()
; #define PG8_SCHED __builtin_amdgcn_sched_barrier(0)
; template <class Epi, class Sched, bool ALIGN_EPI = false, bool SP2 = false>
; __device__ __forceinline__ void gemm_phase(PG8_LAS unsigned char* lds, const Gemm g, const Sched& S, const Epi& E, const int wave_s) {
;     ...
;             const bool last = (t == nt - 2);
;             const char* a1 = cA + (size_t)(t + 1) * kstep;
;             const char* a2 = last ? nA : cA + (size_t)(t + 2) * kstep; const char* b2 = last ? nB : cB + (size_t)(t + 2) * kstep;
;             const char* a3 = a2 + kstep; const char* b3 = b2 + kstep;
;             if (last && has_next) S.a_ready(nxt);
;             if constexpr (SP2) {
;             PG8_LDB(B0, 0, 0); PG8_LDB(B1, 0, 1); PG8_SCHED; PG8_LDA(At, 0, 0); PG8_STAGE(PG8_SA(1, 1), a1 + hstep, voffA);
;             PG8_WAIT_V(8); PG8_WAIT_L(0); PG8_BAR; PG8_MMA(0, 0, At, B0); PG8_MMA(0, 1, At, B1); PG8_BAR; PG8_SCHED;
;             PG8_LDA(At, 0, 1); PG8_STAGE(PG8_SB(0, 0), b2, voffB); PG8_STAGE(PG8_SB(0, 1), b2 + hstep, voffB); PG8_STAGE(PG8_SA(0, 0), a2, voffA);
.LBB0_562:
	ds_read_b128 v[124:127], v163
	ds_read_b128 v[132:135], v163 offset:1024
	ds_read_b128 v[136:139], v163 offset:2048
	ds_read_b128 v[140:143], v163 offset:3072
	ds_read_b128 v[166:169], v164
	ds_read_b128 v[170:173], v164 offset:1024
	ds_read_b128 v[174:177], v164 offset:2048
	ds_read_b128 v[178:181], v164 offset:3072
	s_add_u32 s22, s20, 0xfffc0080
	s_addc_u32 s23, s21, -1
	s_cmp_eq_u32 s57, 12
	s_cselect_b32 s25, s15, s23
	s_cselect_b32 s24, s26, s22
	s_cselect_b32 s23, s13, s56
	s_cselect_b32 s22, s27, s55
	v_lshl_add_u64 v[160:161], s[20:21], 0, v[154:155]
	s_add_i32 m0, s36, 0xc000
	ds_read_b128 v[182:185], v165
	ds_read_b128 v[186:189], v165 offset:1024
	ds_read_b128 v[190:193], v165 offset:2048
	ds_read_b128 v[194:197], v165 offset:3072
	ds_read_b128 v[198:201], v165 offset:4096
	ds_read_b128 v[202:205], v165 offset:5120
	ds_read_b128 v[206:209], v165 offset:6144
	ds_read_b128 v[210:213], v165 offset:7168
	global_load_lds_dwordx4 v[160:161], off
	v_lshl_add_u64 v[160:161], s[20:21], 0, v[152:153]
	s_add_i32 m0, s36, 0xe000
	s_nop 0
	global_load_lds_dwordx4 v[160:161], off
	v_lshl_add_u64 v[230:231], s[22:23], 0, v[148:149]
	v_lshl_add_u64 v[232:233], s[22:23], 0, v[144:145]
	v_lshl_add_u64 v[234:235], s[24:25], 0, v[146:147]
	s_waitcnt vmcnt(8)
	s_waitcnt lgkmcnt(0)
	s_barrier
	s_setprio 1
	s_waitcnt lgkmcnt(0)
	v_mfma_f32_16x16x32_bf16 v[128:131], v[124:127], v[182:185], v[128:131]
	v_mfma_f32_16x16x32_bf16 v[120:123], v[136:139], v[182:185], v[120:123]
	v_mfma_f32_16x16x32_bf16 v[112:115], v[124:127], v[190:193], v[112:115]
	v_mfma_f32_16x16x32_bf16 v[104:107], v[136:139], v[190:193], v[104:107]
	v_mfma_f32_16x16x32_bf16 v[92:95], v[124:127], v[198:201], v[92:95]
	v_mfma_f32_16x16x32_bf16 v[88:91], v[136:139], v[198:201], v[88:91]
	v_mfma_f32_16x16x32_bf16 v[76:79], v[124:127], v[206:209], v[76:79]
	v_mfma_f32_16x16x32_bf16 v[72:75], v[136:139], v[206:209], v[72:75]
	v_mfma_f32_16x16x32_bf16 v[128:131], v[132:135], v[186:189], v[128:131]
	v_mfma_f32_16x16x32_bf16 v[120:123], v[140:143], v[186:189], v[120:123]
	v_mfma_f32_16x16x32_bf16 v[112:115], v[132:135], v[194:197], v[112:115]
	v_mfma_f32_16x16x32_bf16 v[104:107], v[140:143], v[194:197], v[104:107]
	v_mfma_f32_16x16x32_bf16 v[92:95], v[132:135], v[202:205], v[92:95]
	v_mfma_f32_16x16x32_bf16 v[88:91], v[140:143], v[202:205], v[88:91]
	v_mfma_f32_16x16x32_bf16 v[76:79], v[132:135], v[210:213], v[76:79]
	v_mfma_f32_16x16x32_bf16 v[72:75], v[140:143], v[210:213], v[72:75]
	s_setprio 0
	s_setprio 1
	v_mfma_f32_16x16x32_bf16 v[116:119], v[166:169], v[182:185], v[116:119]
	v_mfma_f32_16x16x32_bf16 v[108:111], v[174:177], v[182:185], v[108:111]
	v_mfma_f32_16x16x32_bf16 v[100:103], v[166:169], v[190:193], v[100:103]
	v_mfma_f32_16x16x32_bf16 v[96:99], v[174:177], v[190:193], v[96:99]
	v_mfma_f32_16x16x32_bf16 v[84:87], v[166:169], v[198:201], v[84:87]
	v_mfma_f32_16x16x32_bf16 v[80:83], v[174:177], v[198:201], v[80:83]
	v_mfma_f32_16x16x32_bf16 v[68:71], v[166:169], v[206:209], v[68:71]
	v_mfma_f32_16x16x32_bf16 v[64:67], v[174:177], v[206:209], v[64:67]
	v_mfma_f32_16x16x32_bf16 v[116:119], v[170:173], v[186:189], v[116:119]
	v_mfma_f32_16x16x32_bf16 v[108:111], v[178:181], v[186:189], v[108:111]
	v_mfma_f32_16x16x32_bf16 v[100:103], v[170:173], v[194:197], v[100:103]
	v_mfma_f32_16x16x32_bf16 v[96:99], v[178:181], v[194:197], v[96:99]
	v_mfma_f32_16x16x32_bf16 v[84:87], v[170:173], v[202:205], v[84:87]
	v_mfma_f32_16x16x32_bf16 v[80:83], v[178:181], v[202:205], v[80:83]
	v_mfma_f32_16x16x32_bf16 v[68:71], v[170:173], v[210:213], v[68:71]
	v_mfma_f32_16x16x32_bf16 v[64:67], v[178:181], v[210:213], v[64:67]
	s_setprio 0
	s_barrier
	s_add_i32 s58, s51, s33
	s_mov_b32 m0, s58
	ds_read_b128 v[182:185], v165 offset:16384
	ds_read_b128 v[186:189], v165 offset:17408
	ds_read_b128 v[190:193], v165 offset:18432
	ds_read_b128 v[194:197], v165 offset:19456
	ds_read_b128 v[198:201], v165 offset:20480
	ds_read_b128 v[202:205], v165 offset:21504
	ds_read_b128 v[206:209], v165 offset:22528
	ds_read_b128 v[210:213], v165 offset:23552
	global_load_lds_dwordx4 v[230:231], off
	s_add_i32 m0, s58, 0x2000
	s_add_u32 s58, s22, 0x40000
	s_addc_u32 s59, s23, 0
	s_add_i32 s60, s52, s33
	global_load_lds_dwordx4 v[232:233], off
	v_lshl_add_u64 v[216:217], s[58:59], 0, v[148:149]
	s_mov_b32 m0, s60
	s_nop 0
	global_load_lds_dwordx4 v[216:217], off
	v_lshl_add_u64 v[216:217], s[58:59], 0, v[144:145]
	s_add_i32 m0, s60, 0x2000
	s_nop 0
	global_load_lds_dwordx4 v[216:217], off
	v_lshl_add_u64 v[216:217], s[24:25], 0, v[150:151]
	s_mov_b32 m0, s36
	s_nop 0
	global_load_lds_dwordx4 v[216:217], off
	s_mov_b32 m0, s37
	s_nop 0
	global_load_lds_dwordx4 v[234:235], off
	s_waitcnt vmcnt(8)
	s_waitcnt lgkmcnt(0)
	s_barrier
; #define PG8_STAGE(bufoff, gbase, voff) do { _Pragma("unroll") for (int _i = 0; _i < 2; ++_i) \
;         __builtin_amdgcn_global_load_lds((const unsigned*)((const char*)(gbase) + (voff)[_i]), (PG8_LAS unsigned*)(lds + (bufoff) + ldsw + _i * 8192), 16, 0, 0); } while (0)
; #define PG8_LDA(dst, b, h) do { _Pragma("unroll") for (int m = 0; m < 4; ++m) _Pragma("unroll") for (int k = 0; k < 2; ++k) dst[m][k] = *(const PG8_LAS bf16x8*)(lds + PG8_SA(b, h) + aoff + m * 2048 + k * 1024); } while (0)
; #define PG8_LDB(dst, b, h) do { _Pragma("unroll") for (int n = 0; n < 2; ++n) _Pragma("unroll") for (int k = 0; k < 2; ++k) dst[n][k] = *(const PG8_LAS bf16x8*)(lds + PG8_SB(b, h) + boff + n * 2048 + k * 1024); } while (0)
; #define PG8_MMA(ai, bj, At, Bt) do { __builtin_amdgcn_s_setprio(1); _Pragma("unroll") for (int m = 0; m < 4; ++m) _Pragma("unroll") for (int n = 0; n < 2; ++n) _Pragma("unroll") for (int k = 0; k < 2; ++k) \
;         acc[ai][bj][m][n] = __builtin_amdgcn_mfma_f32_16x16x32_bf16(Bt[n][k], At[m][k], acc[ai][bj][m][n], 0, 0, 0); __builtin_amdgcn_s_setprio(0); } while (0)
; #define PG8_WAIT_V(n) asm volatile("s_waitcnt vmcnt(" #n ")" ::: "memory")
; #define PG8_WAIT_L(n) asm volatile("s_waitcnt lgkmcnt(" #n ")" ::: "memory")
; #define PG8_BAR __builtin_amdgcn_s_barrier()
; #define PG8_SCHED __builtin_amdgcn_sched_barrier(0)
; template <class Epi, class Sched, bool ALIGN_EPI = false, bool SP2 = false>
; __device__ __forceinline__ void gemm_phase(PG8_LAS unsigned char* lds, const Gemm g, const Sched& S, const Epi& E, const int wave_s) {
;     ...
;             PG8_WAIT_V(8); PG8_WAIT_L(0); PG8_BAR; PG8_MMA(1, 0, At, B0); PG8_MMA(1, 1, At, B1); PG8_BAR; PG8_SCHED;
;             PG8_LDB(B0, 1, 0); PG8_LDB(B1, 1, 1); PG8_SCHED; PG8_LDA(At, 1, 0); PG8_STAGE(PG8_SA(0, 1), a2 + hstep, voffA);
;             PG8_WAIT_V(8); PG8_WAIT_L(0); PG8_BAR; PG8_MMA(0, 0, At, B0); PG8_MMA(0, 1, At, B1); PG8_BAR; PG8_SCHED;
	s_setprio 1
	s_waitcnt lgkmcnt(0)
	v_mfma_f32_16x16x32_bf16 v[60:63], v[124:127], v[182:185], v[60:63]
	v_mfma_f32_16x16x32_bf16 v[56:59], v[136:139], v[182:185], v[56:59]
	v_mfma_f32_16x16x32_bf16 v[48:51], v[124:127], v[190:193], v[48:51]
	v_mfma_f32_16x16x32_bf16 v[40:43], v[136:139], v[190:193], v[40:43]
	v_mfma_f32_16x16x32_bf16 v[28:31], v[124:127], v[198:201], v[28:31]
	v_mfma_f32_16x16x32_bf16 v[24:27], v[136:139], v[198:201], v[24:27]
	v_mfma_f32_16x16x32_bf16 v[16:19], v[124:127], v[206:209], v[16:19]
	v_mfma_f32_16x16x32_bf16 v[8:11], v[136:139], v[206:209], v[8:11]
	v_mfma_f32_16x16x32_bf16 v[60:63], v[132:135], v[186:189], v[60:63]
	v_mfma_f32_16x16x32_bf16 v[56:59], v[140:143], v[186:189], v[56:59]
	v_mfma_f32_16x16x32_bf16 v[48:51], v[132:135], v[194:197], v[48:51]
	v_mfma_f32_16x16x32_bf16 v[40:43], v[140:143], v[194:197], v[40:43]
	v_mfma_f32_16x16x32_bf16 v[28:31], v[132:135], v[202:205], v[28:31]
	v_mfma_f32_16x16x32_bf16 v[24:27], v[140:143], v[202:205], v[24:27]
	v_mfma_f32_16x16x32_bf16 v[16:19], v[132:135], v[210:213], v[16:19]
	v_mfma_f32_16x16x32_bf16 v[8:11], v[140:143], v[210:213], v[8:11]
	s_setprio 0
	s_setprio 1
	v_mfma_f32_16x16x32_bf16 v[52:55], v[166:169], v[182:185], v[52:55]
	v_mfma_f32_16x16x32_bf16 v[44:47], v[174:177], v[182:185], v[44:47]
	v_mfma_f32_16x16x32_bf16 v[36:39], v[166:169], v[190:193], v[36:39]
	v_mfma_f32_16x16x32_bf16 v[32:35], v[174:177], v[190:193], v[32:35]
	v_mfma_f32_16x16x32_bf16 v[20:23], v[166:169], v[198:201], v[20:23]
	v_mfma_f32_16x16x32_bf16 v[12:15], v[174:177], v[198:201], v[12:15]
	v_mfma_f32_16x16x32_bf16 v[4:7], v[166:169], v[206:209], v[4:7]
	v_mfma_f32_16x16x32_bf16 v[0:3], v[174:177], v[206:209], v[0:3]
	v_mfma_f32_16x16x32_bf16 v[52:55], v[170:173], v[186:189], v[52:55]
	v_mfma_f32_16x16x32_bf16 v[44:47], v[178:181], v[186:189], v[44:47]
	v_mfma_f32_16x16x32_bf16 v[36:39], v[170:173], v[194:197], v[36:39]
	v_mfma_f32_16x16x32_bf16 v[32:35], v[178:181], v[194:197], v[32:35]
	v_mfma_f32_16x16x32_bf16 v[20:23], v[170:173], v[202:205], v[20:23]
	v_mfma_f32_16x16x32_bf16 v[12:15], v[178:181], v[202:205], v[12:15]
	v_mfma_f32_16x16x32_bf16 v[4:7], v[170:173], v[210:213], v[4:7]
	v_mfma_f32_16x16x32_bf16 v[0:3], v[178:181], v[210:213], v[0:3]
	s_setprio 0
	s_barrier
	s_add_i32 s58, 0, 0x18000
	s_add_i32 s59, 0, 0x1c000
	v_add_u32_e32 v140, s58, v162
	v_add_u32_e32 v178, s59, v162
	ds_read_b128 v[124:127], v140
	ds_read_b128 v[132:135], v140 offset:1024
	ds_read_b128 v[136:139], v140 offset:2048
	ds_read_b128 v[140:143], v140 offset:3072
	ds_read_b128 v[166:169], v178
	ds_read_b128 v[170:173], v178 offset:1024
	ds_read_b128 v[174:177], v178 offset:2048
	ds_read_b128 v[178:181], v178 offset:3072
	s_add_u32 s24, s24, 0x40000
	s_addc_u32 s25, s25, 0
	s_mov_b32 m0, s38
	v_lshl_add_u64 v[220:221], s[24:25], 0, v[150:151]
	ds_read_b128 v[182:185], v165 offset:32768
	ds_read_b128 v[186:189], v165 offset:33792
	ds_read_b128 v[190:193], v165 offset:34816
	ds_read_b128 v[194:197], v165 offset:35840
	ds_read_b128 v[198:201], v165 offset:36864
	ds_read_b128 v[202:205], v165 offset:37888
	ds_read_b128 v[206:209], v165 offset:38912
	ds_read_b128 v[210:213], v165 offset:39936
	global_load_lds_dwordx4 v[220:221], off
	v_lshl_add_u64 v[220:221], s[24:25], 0, v[146:147]
	s_mov_b32 m0, s39
	s_nop 0
	global_load_lds_dwordx4 v[220:221], off
	v_lshl_add_u64 v[236:237], v[230:231], 0, s[2:3]
	s_add_u32 s22, s22, 0x40080
	v_lshl_add_u64 v[238:239], v[232:233], 0, s[2:3]
	s_addc_u32 s23, s23, 0
	v_lshl_add_u64 v[240:241], s[22:23], 0, v[148:149]
	v_lshl_add_u64 v[242:243], s[22:23], 0, v[144:145]
	v_lshl_add_u64 v[244:245], v[216:217], 0, s[2:3]
	v_lshl_add_u64 v[246:247], v[234:235], 0, s[2:3]
	s_waitcnt vmcnt(8)
	s_waitcnt lgkmcnt(0)
	s_barrier
; #define PG8_STAGE(bufoff, gbase, voff) do { _Pragma("unroll") for (int _i = 0; _i < 2; ++_i) \
;         __builtin_amdgcn_global_load_lds((const unsigned*)((const char*)(gbase) + (voff)[_i]), (PG8_LAS unsigned*)(lds + (bufoff) + ldsw + _i * 8192), 16, 0, 0); } while (0)
; #define PG8_LDA(dst, b, h) do { _Pragma("unroll") for (int m = 0; m < 4; ++m) _Pragma("unroll") for (int k = 0; k < 2; ++k) dst[m][k] = *(const PG8_LAS bf16x8*)(lds + PG8_SA(b, h) + aoff + m * 2048 + k * 1024); } while (0)
; #define PG8_MMA(ai, bj, At, Bt) do { __builtin_amdgcn_s_setprio(1); _Pragma("unroll") for (int m = 0; m < 4; ++m) _Pragma("unroll") for (int n = 0; n < 2; ++n) _Pragma("unroll") for (int k = 0; k < 2; ++k) \
;         acc[ai][bj][m][n] = __builtin_amdgcn_mfma_f32_16x16x32_bf16(Bt[n][k], At[m][k], acc[ai][bj][m][n], 0, 0, 0); __builtin_amdgcn_s_setprio(0); } while (0)
; #define PG8_WAIT_V(n) asm volatile("s_waitcnt vmcnt(" #n ")" ::: "memory")
; #define PG8_WAIT_L(n) asm volatile("s_waitcnt lgkmcnt(" #n ")" ::: "memory")
; #define PG8_BAR __builtin_amdgcn_s_barrier()
; #define PG8_SCHED __builtin_amdgcn_sched_barrier(0)
; template <class Epi, class Sched, bool ALIGN_EPI = false, bool SP2 = false>
; __device__ __forceinline__ void gemm_phase(PG8_LAS unsigned char* lds, const Gemm g, const Sched& S, const Epi& E, const int wave_s) {
;     ...
;             PG8_WAIT_V(8); PG8_WAIT_L(0); PG8_BAR; PG8_MMA(0, 0, At, B0); PG8_MMA(0, 1, At, B1); PG8_BAR; PG8_SCHED;
;             PG8_LDA(At, 1, 1); PG8_STAGE(PG8_SB(1, 0), b3, voffB); PG8_STAGE(PG8_SB(1, 1), b3 + hstep, voffB); PG8_STAGE(PG8_SA(1, 0), a3, voffA);
;             PG8_WAIT_V(8); PG8_WAIT_L(0); PG8_BAR; PG8_MMA(1, 0, At, B0); PG8_MMA(1, 1, At, B1); PG8_BAR; PG8_SCHED;
;     __device__ __forceinline__ void operator()(const af4 (&acc)[2][2][4][2], const pg8::Unit& u, int wr, int wc, int fr_, int fq_) const {
;     ...
;         const int grow = rowbase + u.pm * 256; const int bi = grow < TL ? grow / LSEQ : NB;
;         float* xb = grow < TL ? xl + (size_t)grow * DM : xc + (size_t)(grow - TL) * DM;
;         const float* stb = stats + 2 * (size_t)grow;
;         const int col0 = u.pn * 256 + wc * 32 + 8 * fq; const float* gp = gate + (size_t)bi * 6144 + col0;
	s_setprio 1
	s_waitcnt lgkmcnt(0)
	v_mfma_f32_16x16x32_bf16 v[128:131], v[124:127], v[182:185], v[128:131]
	v_mfma_f32_16x16x32_bf16 v[120:123], v[136:139], v[182:185], v[120:123]
	v_mfma_f32_16x16x32_bf16 v[112:115], v[124:127], v[190:193], v[112:115]
	v_mfma_f32_16x16x32_bf16 v[104:107], v[136:139], v[190:193], v[104:107]
	v_mfma_f32_16x16x32_bf16 v[92:95], v[124:127], v[198:201], v[92:95]
	v_mfma_f32_16x16x32_bf16 v[88:91], v[136:139], v[198:201], v[88:91]
	v_mfma_f32_16x16x32_bf16 v[76:79], v[124:127], v[206:209], v[76:79]
	v_mfma_f32_16x16x32_bf16 v[72:75], v[136:139], v[206:209], v[72:75]
	v_mfma_f32_16x16x32_bf16 v[128:131], v[132:135], v[186:189], v[128:131]
	v_mfma_f32_16x16x32_bf16 v[120:123], v[140:143], v[186:189], v[120:123]
	v_mfma_f32_16x16x32_bf16 v[112:115], v[132:135], v[194:197], v[112:115]
	v_mfma_f32_16x16x32_bf16 v[104:107], v[140:143], v[194:197], v[104:107]
	v_mfma_f32_16x16x32_bf16 v[92:95], v[132:135], v[202:205], v[92:95]
	v_mfma_f32_16x16x32_bf16 v[88:91], v[140:143], v[202:205], v[88:91]
	v_mfma_f32_16x16x32_bf16 v[76:79], v[132:135], v[210:213], v[76:79]
	v_mfma_f32_16x16x32_bf16 v[72:75], v[140:143], v[210:213], v[72:75]
	s_setprio 0
	s_setprio 1
	v_mfma_f32_16x16x32_bf16 v[116:119], v[166:169], v[182:185], v[116:119]
	v_mfma_f32_16x16x32_bf16 v[108:111], v[174:177], v[182:185], v[108:111]
	v_mfma_f32_16x16x32_bf16 v[100:103], v[166:169], v[190:193], v[100:103]
	v_mfma_f32_16x16x32_bf16 v[96:99], v[174:177], v[190:193], v[96:99]
	v_mfma_f32_16x16x32_bf16 v[84:87], v[166:169], v[198:201], v[84:87]
	v_mfma_f32_16x16x32_bf16 v[80:83], v[174:177], v[198:201], v[80:83]
	v_mfma_f32_16x16x32_bf16 v[68:71], v[166:169], v[206:209], v[68:71]
	v_mfma_f32_16x16x32_bf16 v[64:67], v[174:177], v[206:209], v[64:67]
	v_mfma_f32_16x16x32_bf16 v[116:119], v[170:173], v[186:189], v[116:119]
	v_mfma_f32_16x16x32_bf16 v[108:111], v[178:181], v[186:189], v[108:111]
	v_mfma_f32_16x16x32_bf16 v[100:103], v[170:173], v[194:197], v[100:103]
	v_mfma_f32_16x16x32_bf16 v[96:99], v[178:181], v[194:197], v[96:99]
	v_mfma_f32_16x16x32_bf16 v[84:87], v[170:173], v[202:205], v[84:87]
	v_mfma_f32_16x16x32_bf16 v[80:83], v[178:181], v[202:205], v[80:83]
	v_mfma_f32_16x16x32_bf16 v[68:71], v[170:173], v[210:213], v[68:71]
	v_mfma_f32_16x16x32_bf16 v[64:67], v[178:181], v[210:213], v[64:67]
	s_setprio 0
	s_barrier
	s_add_i32 s24, s58, s33
	s_mov_b32 m0, s24
	ds_read_b128 v[182:185], v165 offset:49152
	ds_read_b128 v[186:189], v165 offset:50176
	ds_read_b128 v[190:193], v165 offset:51200
	ds_read_b128 v[194:197], v165 offset:52224
	ds_read_b128 v[198:201], v165 offset:53248
	ds_read_b128 v[202:205], v165 offset:54272
	ds_read_b128 v[206:209], v165 offset:55296
	ds_read_b128 v[210:213], v165 offset:56320
	global_load_lds_dwordx4 v[236:237], off
	s_add_i32 m0, s24, 0x2000
	s_add_i32 s24, s59, s33
	global_load_lds_dwordx4 v[238:239], off
	s_mov_b32 m0, s24
	s_nop 0
	global_load_lds_dwordx4 v[240:241], off
	s_add_i32 m0, s24, 0x2000
	s_nop 0
	global_load_lds_dwordx4 v[242:243], off
	s_mov_b32 m0, s47
	s_nop 0
	global_load_lds_dwordx4 v[244:245], off
	s_mov_b32 m0, s48
	s_nop 0
	global_load_lds_dwordx4 v[246:247], off
	s_waitcnt vmcnt(8)
	s_waitcnt lgkmcnt(0)
	s_barrier
	s_setprio 1
	s_waitcnt lgkmcnt(0)
	v_mfma_f32_16x16x32_bf16 v[60:63], v[124:127], v[182:185], v[60:63]
	v_mfma_f32_16x16x32_bf16 v[56:59], v[136:139], v[182:185], v[56:59]
	v_mfma_f32_16x16x32_bf16 v[48:51], v[124:127], v[190:193], v[48:51]
	v_mfma_f32_16x16x32_bf16 v[40:43], v[136:139], v[190:193], v[40:43]
	v_mfma_f32_16x16x32_bf16 v[28:31], v[124:127], v[198:201], v[28:31]
	v_mfma_f32_16x16x32_bf16 v[24:27], v[136:139], v[198:201], v[24:27]
	v_mfma_f32_16x16x32_bf16 v[16:19], v[124:127], v[206:209], v[16:19]
	v_mfma_f32_16x16x32_bf16 v[8:11], v[136:139], v[206:209], v[8:11]
	v_mfma_f32_16x16x32_bf16 v[60:63], v[132:135], v[186:189], v[60:63]
	v_mfma_f32_16x16x32_bf16 v[56:59], v[140:143], v[186:189], v[56:59]
	v_mfma_f32_16x16x32_bf16 v[48:51], v[132:135], v[194:197], v[48:51]
	v_mfma_f32_16x16x32_bf16 v[40:43], v[140:143], v[194:197], v[40:43]
	v_mfma_f32_16x16x32_bf16 v[28:31], v[132:135], v[202:205], v[28:31]
	v_mfma_f32_16x16x32_bf16 v[24:27], v[140:143], v[202:205], v[24:27]
	v_mfma_f32_16x16x32_bf16 v[16:19], v[132:135], v[210:213], v[16:19]
	v_mfma_f32_16x16x32_bf16 v[8:11], v[140:143], v[210:213], v[8:11]
	s_setprio 0
	s_setprio 1
	v_mfma_f32_16x16x32_bf16 v[52:55], v[166:169], v[182:185], v[52:55]
	v_mfma_f32_16x16x32_bf16 v[44:47], v[174:177], v[182:185], v[44:47]
	v_mfma_f32_16x16x32_bf16 v[36:39], v[166:169], v[190:193], v[36:39]
	v_mfma_f32_16x16x32_bf16 v[32:35], v[174:177], v[190:193], v[32:35]
	v_mfma_f32_16x16x32_bf16 v[20:23], v[166:169], v[198:201], v[20:23]
	v_mfma_f32_16x16x32_bf16 v[12:15], v[174:177], v[198:201], v[12:15]
	v_mfma_f32_16x16x32_bf16 v[4:7], v[166:169], v[206:209], v[4:7]
	v_mfma_f32_16x16x32_bf16 v[0:3], v[174:177], v[206:209], v[0:3]
	v_mfma_f32_16x16x32_bf16 v[52:55], v[170:173], v[186:189], v[52:55]
	v_mfma_f32_16x16x32_bf16 v[44:47], v[178:181], v[186:189], v[44:47]
	v_mfma_f32_16x16x32_bf16 v[36:39], v[170:173], v[194:197], v[36:39]
	v_mfma_f32_16x16x32_bf16 v[32:35], v[178:181], v[194:197], v[32:35]
	v_mfma_f32_16x16x32_bf16 v[20:23], v[170:173], v[202:205], v[20:23]
	v_mfma_f32_16x16x32_bf16 v[12:15], v[178:181], v[202:205], v[12:15]
	v_mfma_f32_16x16x32_bf16 v[4:7], v[170:173], v[210:213], v[4:7]
	v_mfma_f32_16x16x32_bf16 v[0:3], v[178:181], v[210:213], v[0:3]
	s_setprio 0
	s_barrier
	s_add_i32 s57, s57, 2
	s_add_u32 s55, s55, 0x100
	s_addc_u32 s56, s56, 0
	s_add_u32 s20, s20, 0x100
	s_addc_u32 s21, s21, 0
	s_cmp_gt_u32 s57, 13
	s_cbranch_scc0 .LBB0_562
	s_cmpk_gt_i32 s4, 0xff
	s_cselect_b64 s[24:25], -1, 0
	s_mov_b64 s[22:23], 0x18000
	s_and_b64 vcc, exec, s[24:25]
	v_mbcnt_lo_u32_b32 v160, -1, 0
	v_mbcnt_hi_u32_b32 v160, -1, v160
	s_cbranch_vccnz .LBB0_565
	s_ashr_i32 s13, s4, 31
	s_lshr_b32 s13, s13, 28
	s_add_i32 s13, s4, s13
	s_ashr_i32 s13, s13, 4
	s_mul_hi_i32 s23, s13, 0x1800
	s_mul_i32 s22, s13, 0x1800

; #define PG8_STAGE(bufoff, gbase, voff) do { _Pragma("unroll") for (int _i = 0; _i < 2; ++_i) \
;         __builtin_amdgcn_global_load_lds((const unsigned*)((const char*)(gbase) + (voff)[_i]), (PG8_LAS unsigned*)(lds + (bufoff) + ldsw + _i * 8192), 16, 0, 0); } while (0)
; #define PG8_LDA(dst, b, h) do { _Pragma("unroll") for (int m = 0; m < 4; ++m) _Pragma("unroll") for (int k = 0; k < 2; ++k) dst[m][k] = *(const PG8_LAS bf16x8*)(lds + PG8_SA(b, h) + aoff + m * 2048 + k * 1024); } while (0)
; #define PG8_LDB(dst, b, h) do { _Pragma("unroll") for (int n = 0; n < 2; ++n) _Pragma("unroll") for (int k = 0; k < 2; ++k) dst[n][k] = *(const PG8_LAS bf16x8*)(lds + PG8_SB(b, h) + boff + n * 2048 + k * 1024); } while (0)
; #define PG8_MMA(ai, bj, At, Bt) do { __builtin_amdgcn_s_setprio(1); _Pragma("unroll") for (int m = 0; m < 4; ++m) _Pragma("unroll") for (int n = 0; n < 2; ++n) _Pragma("unroll") for (int k = 0; k < 2; ++k) \
;         acc[ai][bj][m][n] = __builtin_amdgcn_mfma_f32_16x16x32_bf16(Bt[n][k], At[m][k], acc[ai][bj][m][n], 0, 0, 0); __builtin_amdgcn_s_setprio(0); } while (0)
; #define PG8_WAIT_V(n) asm volatile("s_waitcnt vmcnt(" #n ")" ::: "memory")
; #define PG8_WAIT_L(n) asm volatile("s_waitcnt lgkmcnt(" #n ")" ::: "memory")
; #define PG8_BAR __builtin_amdgcn_s_barrier()
; #define PG8_SCHED __builtin_amdgcn_sched_barrier(0)
; template <class Epi, class Sched, bool ALIGN_EPI = false, bool SP2 = false>
; __device__ __forceinline__ void gemm_phase(PG8_LAS unsigned char* lds, const Gemm g, const Sched& S, const Epi& E, const int wave_s) {
;     ...
;             const bool last = (t == nt - 2);
;             const char* a1 = cA + (size_t)(t + 1) * kstep;
;             const char* a2 = last ? nA : cA + (size_t)(t + 2) * kstep; const char* b2 = last ? nB : cB + (size_t)(t + 2) * kstep;
;             const char* a3 = a2 + kstep; const char* b3 = b2 + kstep;
;             if (last && has_next) S.a_ready(nxt);
;             if constexpr (SP2) {
;             PG8_LDB(B0, 0, 0); PG8_LDB(B1, 0, 1); PG8_SCHED; PG8_LDA(At, 0, 0); PG8_STAGE(PG8_SA(1, 1), a1 + hstep, voffA);
;             PG8_WAIT_V(8); PG8_WAIT_L(0); PG8_BAR; PG8_MMA(0, 0, At, B0); PG8_MMA(0, 1, At, B1); PG8_BAR; PG8_SCHED;
;             PG8_LDA(At, 0, 1); PG8_STAGE(PG8_SB(0, 0), b2, voffB); PG8_STAGE(PG8_SB(0, 1), b2 + hstep, voffB); PG8_STAGE(PG8_SA(0, 0), a2, voffA);
.LBB0_810:
	ds_read_b128 v[100:103], v215
	ds_read_b128 v[108:111], v215 offset:1024
	ds_read_b128 v[112:115], v215 offset:2048
	ds_read_b128 v[116:119], v215 offset:3072
	ds_read_b128 v[144:147], v216
	ds_read_b128 v[148:151], v216 offset:1024
	ds_read_b128 v[152:155], v216 offset:2048
	ds_read_b128 v[156:159], v216 offset:3072
	s_add_u32 s12, s26, 0x100
	s_addc_u32 s13, s27, 0
	s_cmp_eq_u32 s62, 40
	s_cselect_b32 s31, s25, s13
	s_cselect_b32 s30, s24, s12
	s_cselect_b32 s29, s15, s61
	s_cselect_b32 s28, s14, s8
	v_lshl_add_u64 v[208:209], s[26:27], 0, v[170:171]
	s_add_i32 m0, s37, 0xc000
	ds_read_b128 v[176:179], v217
	ds_read_b128 v[180:183], v217 offset:1024
	ds_read_b128 v[184:187], v217 offset:2048
	ds_read_b128 v[188:191], v217 offset:3072
	ds_read_b128 v[192:195], v217 offset:4096
	ds_read_b128 v[196:199], v217 offset:5120
	ds_read_b128 v[200:203], v217 offset:6144
	ds_read_b128 v[204:207], v217 offset:7168
	global_load_lds_dwordx4 v[208:209], off
	v_lshl_add_u64 v[208:209], s[26:27], 0, v[168:169]
	s_add_i32 m0, s37, 0xe000
	s_nop 0
	global_load_lds_dwordx4 v[208:209], off
	v_lshl_add_u64 v[230:231], s[28:29], 0, v[162:163]
	v_lshl_add_u64 v[232:233], s[28:29], 0, v[166:167]
	v_lshl_add_u64 v[234:235], s[30:31], 0, v[164:165]
	s_waitcnt vmcnt(8)
	s_waitcnt lgkmcnt(0)
	s_barrier
	s_setprio 1
	s_waitcnt lgkmcnt(0)
	v_mfma_f32_16x16x32_bf16 v[140:143], v[100:103], v[176:179], v[140:143]
	v_mfma_f32_16x16x32_bf16 v[136:139], v[112:115], v[176:179], v[136:139]
	v_mfma_f32_16x16x32_bf16 v[124:127], v[100:103], v[184:187], v[124:127]
	v_mfma_f32_16x16x32_bf16 v[120:123], v[112:115], v[184:187], v[120:123]
	v_mfma_f32_16x16x32_bf16 v[92:95], v[100:103], v[192:195], v[92:95]
	v_mfma_f32_16x16x32_bf16 v[88:91], v[112:115], v[192:195], v[88:91]
	v_mfma_f32_16x16x32_bf16 v[76:79], v[100:103], v[200:203], v[76:79]
	v_mfma_f32_16x16x32_bf16 v[72:75], v[112:115], v[200:203], v[72:75]
	v_mfma_f32_16x16x32_bf16 v[140:143], v[108:111], v[180:183], v[140:143]
	v_mfma_f32_16x16x32_bf16 v[136:139], v[116:119], v[180:183], v[136:139]
	v_mfma_f32_16x16x32_bf16 v[124:127], v[108:111], v[188:191], v[124:127]
	v_mfma_f32_16x16x32_bf16 v[120:123], v[116:119], v[188:191], v[120:123]
	v_mfma_f32_16x16x32_bf16 v[92:95], v[108:111], v[196:199], v[92:95]
	v_mfma_f32_16x16x32_bf16 v[88:91], v[116:119], v[196:199], v[88:91]
	v_mfma_f32_16x16x32_bf16 v[76:79], v[108:111], v[204:207], v[76:79]
	v_mfma_f32_16x16x32_bf16 v[72:75], v[116:119], v[204:207], v[72:75]
	s_setprio 0
	s_setprio 1
	v_mfma_f32_16x16x32_bf16 v[132:135], v[144:147], v[176:179], v[132:135]
	v_mfma_f32_16x16x32_bf16 v[128:131], v[152:155], v[176:179], v[128:131]
	v_mfma_f32_16x16x32_bf16 v[104:107], v[144:147], v[184:187], v[104:107]
	v_mfma_f32_16x16x32_bf16 v[96:99], v[152:155], v[184:187], v[96:99]
	v_mfma_f32_16x16x32_bf16 v[84:87], v[144:147], v[192:195], v[84:87]
	v_mfma_f32_16x16x32_bf16 v[80:83], v[152:155], v[192:195], v[80:83]
	v_mfma_f32_16x16x32_bf16 v[68:71], v[144:147], v[200:203], v[68:71]
	v_mfma_f32_16x16x32_bf16 v[64:67], v[152:155], v[200:203], v[64:67]
	v_mfma_f32_16x16x32_bf16 v[132:135], v[148:151], v[180:183], v[132:135]
	v_mfma_f32_16x16x32_bf16 v[128:131], v[156:159], v[180:183], v[128:131]
	v_mfma_f32_16x16x32_bf16 v[104:107], v[148:151], v[188:191], v[104:107]
	v_mfma_f32_16x16x32_bf16 v[96:99], v[156:159], v[188:191], v[96:99]
	v_mfma_f32_16x16x32_bf16 v[84:87], v[148:151], v[196:199], v[84:87]
	v_mfma_f32_16x16x32_bf16 v[80:83], v[156:159], v[196:199], v[80:83]
	v_mfma_f32_16x16x32_bf16 v[68:71], v[148:151], v[204:207], v[68:71]
	v_mfma_f32_16x16x32_bf16 v[64:67], v[156:159], v[204:207], v[64:67]
	s_setprio 0
	s_barrier
	s_add_i32 s26, s54, s33
	s_mov_b32 m0, s26
	ds_read_b128 v[176:179], v217 offset:16384
	ds_read_b128 v[180:183], v217 offset:17408
	ds_read_b128 v[184:187], v217 offset:18432
	ds_read_b128 v[188:191], v217 offset:19456
	ds_read_b128 v[192:195], v217 offset:20480
	ds_read_b128 v[196:199], v217 offset:21504
	ds_read_b128 v[200:203], v217 offset:22528
	ds_read_b128 v[204:207], v217 offset:23552
	global_load_lds_dwordx4 v[230:231], off
	s_add_i32 m0, s26, 0x2000
	s_add_u32 s26, s28, 0xb0000
	s_addc_u32 s27, s29, 0
	s_add_i32 s63, s55, s33
	global_load_lds_dwordx4 v[232:233], off
	v_lshl_add_u64 v[212:213], s[26:27], 0, v[162:163]
	s_mov_b32 m0, s63
	s_nop 0
	global_load_lds_dwordx4 v[212:213], off
	v_lshl_add_u64 v[212:213], s[26:27], 0, v[166:167]
	s_add_i32 m0, s63, 0x2000
	s_nop 0
	global_load_lds_dwordx4 v[212:213], off
	v_lshl_add_u64 v[212:213], s[30:31], 0, v[160:161]
	s_mov_b32 m0, s37
	s_nop 0
	global_load_lds_dwordx4 v[212:213], off
	s_mov_b32 m0, s38
	s_nop 0
	global_load_lds_dwordx4 v[234:235], off
	s_waitcnt vmcnt(8)
	s_waitcnt lgkmcnt(0)
	s_barrier
; #define PG8_STAGE(bufoff, gbase, voff) do { _Pragma("unroll") for (int _i = 0; _i < 2; ++_i) \
;         __builtin_amdgcn_global_load_lds((const unsigned*)((const char*)(gbase) + (voff)[_i]), (PG8_LAS unsigned*)(lds + (bufoff) + ldsw + _i * 8192), 16, 0, 0); } while (0)
; #define PG8_LDA(dst, b, h) do { _Pragma("unroll") for (int m = 0; m < 4; ++m) _Pragma("unroll") for (int k = 0; k < 2; ++k) dst[m][k] = *(const PG8_LAS bf16x8*)(lds + PG8_SA(b, h) + aoff + m * 2048 + k * 1024); } while (0)
; #define PG8_LDB(dst, b, h) do { _Pragma("unroll") for (int n = 0; n < 2; ++n) _Pragma("unroll") for (int k = 0; k < 2; ++k) dst[n][k] = *(const PG8_LAS bf16x8*)(lds + PG8_SB(b, h) + boff + n * 2048 + k * 1024); } while (0)
; #define PG8_MMA(ai, bj, At, Bt) do { __builtin_amdgcn_s_setprio(1); _Pragma("unroll") for (int m = 0; m < 4; ++m) _Pragma("unroll") for (int n = 0; n < 2; ++n) _Pragma("unroll") for (int k = 0; k < 2; ++k) \
;         acc[ai][bj][m][n] = __builtin_amdgcn_mfma_f32_16x16x32_bf16(Bt[n][k], At[m][k], acc[ai][bj][m][n], 0, 0, 0); __builtin_amdgcn_s_setprio(0); } while (0)
; #define PG8_WAIT_V(n) asm volatile("s_waitcnt vmcnt(" #n ")" ::: "memory")
; #define PG8_WAIT_L(n) asm volatile("s_waitcnt lgkmcnt(" #n ")" ::: "memory")
; #define PG8_BAR __builtin_amdgcn_s_barrier()
; #define PG8_SCHED __builtin_amdgcn_sched_barrier(0)
; template <class Epi, class Sched, bool ALIGN_EPI = false, bool SP2 = false>
; __device__ __forceinline__ void gemm_phase(PG8_LAS unsigned char* lds, const Gemm g, const Sched& S, const Epi& E, const int wave_s) {
;     ...
;             PG8_WAIT_V(8); PG8_WAIT_L(0); PG8_BAR; PG8_MMA(1, 0, At, B0); PG8_MMA(1, 1, At, B1); PG8_BAR; PG8_SCHED;
;             PG8_LDB(B0, 1, 0); PG8_LDB(B1, 1, 1); PG8_SCHED; PG8_LDA(At, 1, 0); PG8_STAGE(PG8_SA(0, 1), a2 + hstep, voffA);
;             PG8_WAIT_V(8); PG8_WAIT_L(0); PG8_BAR; PG8_MMA(0, 0, At, B0); PG8_MMA(0, 1, At, B1); PG8_BAR; PG8_SCHED;
	s_setprio 1
	s_waitcnt lgkmcnt(0)
	v_mfma_f32_16x16x32_bf16 v[60:63], v[100:103], v[176:179], v[60:63]
	v_mfma_f32_16x16x32_bf16 v[56:59], v[112:115], v[176:179], v[56:59]
	v_mfma_f32_16x16x32_bf16 v[48:51], v[100:103], v[184:187], v[48:51]
	v_mfma_f32_16x16x32_bf16 v[40:43], v[112:115], v[184:187], v[40:43]
	v_mfma_f32_16x16x32_bf16 v[28:31], v[100:103], v[192:195], v[28:31]
	v_mfma_f32_16x16x32_bf16 v[24:27], v[112:115], v[192:195], v[24:27]
	v_mfma_f32_16x16x32_bf16 v[16:19], v[100:103], v[200:203], v[16:19]
	v_mfma_f32_16x16x32_bf16 v[8:11], v[112:115], v[200:203], v[8:11]
	v_mfma_f32_16x16x32_bf16 v[60:63], v[108:111], v[180:183], v[60:63]
	v_mfma_f32_16x16x32_bf16 v[56:59], v[116:119], v[180:183], v[56:59]
	v_mfma_f32_16x16x32_bf16 v[48:51], v[108:111], v[188:191], v[48:51]
	v_mfma_f32_16x16x32_bf16 v[40:43], v[116:119], v[188:191], v[40:43]
	v_mfma_f32_16x16x32_bf16 v[28:31], v[108:111], v[196:199], v[28:31]
	v_mfma_f32_16x16x32_bf16 v[24:27], v[116:119], v[196:199], v[24:27]
	v_mfma_f32_16x16x32_bf16 v[16:19], v[108:111], v[204:207], v[16:19]
	v_mfma_f32_16x16x32_bf16 v[8:11], v[116:119], v[204:207], v[8:11]
	s_setprio 0
	s_setprio 1
	v_mfma_f32_16x16x32_bf16 v[52:55], v[144:147], v[176:179], v[52:55]
	v_mfma_f32_16x16x32_bf16 v[44:47], v[152:155], v[176:179], v[44:47]
	v_mfma_f32_16x16x32_bf16 v[36:39], v[144:147], v[184:187], v[36:39]
	v_mfma_f32_16x16x32_bf16 v[32:35], v[152:155], v[184:187], v[32:35]
	v_mfma_f32_16x16x32_bf16 v[20:23], v[144:147], v[192:195], v[20:23]
	v_mfma_f32_16x16x32_bf16 v[12:15], v[152:155], v[192:195], v[12:15]
	v_mfma_f32_16x16x32_bf16 v[4:7], v[144:147], v[200:203], v[4:7]
	v_mfma_f32_16x16x32_bf16 v[0:3], v[152:155], v[200:203], v[0:3]
	v_mfma_f32_16x16x32_bf16 v[52:55], v[148:151], v[180:183], v[52:55]
	v_mfma_f32_16x16x32_bf16 v[44:47], v[156:159], v[180:183], v[44:47]
	v_mfma_f32_16x16x32_bf16 v[36:39], v[148:151], v[188:191], v[36:39]
	v_mfma_f32_16x16x32_bf16 v[32:35], v[156:159], v[188:191], v[32:35]
	v_mfma_f32_16x16x32_bf16 v[20:23], v[148:151], v[196:199], v[20:23]
	v_mfma_f32_16x16x32_bf16 v[12:15], v[156:159], v[196:199], v[12:15]
	v_mfma_f32_16x16x32_bf16 v[4:7], v[148:151], v[204:207], v[4:7]
	v_mfma_f32_16x16x32_bf16 v[0:3], v[156:159], v[204:207], v[0:3]
	s_setprio 0
	s_barrier
	s_add_i32 s63, 0, 0x18000
	s_add_i32 s64, 0, 0x1c000
	v_add_u32_e32 v116, s63, v214
	v_add_u32_e32 v156, s64, v214
	ds_read_b128 v[100:103], v116
	ds_read_b128 v[108:111], v116 offset:1024
	ds_read_b128 v[112:115], v116 offset:2048
	ds_read_b128 v[116:119], v116 offset:3072
	ds_read_b128 v[144:147], v156
	ds_read_b128 v[148:151], v156 offset:1024
	ds_read_b128 v[152:155], v156 offset:2048
	ds_read_b128 v[156:159], v156 offset:3072
	s_add_u32 s26, s30, 0xb0000
	s_addc_u32 s27, s31, 0
	s_mov_b32 m0, s39
	v_lshl_add_u64 v[220:221], s[26:27], 0, v[160:161]
	ds_read_b128 v[176:179], v217 offset:32768
	ds_read_b128 v[180:183], v217 offset:33792
	ds_read_b128 v[184:187], v217 offset:34816
	ds_read_b128 v[188:191], v217 offset:35840
	ds_read_b128 v[192:195], v217 offset:36864
	ds_read_b128 v[196:199], v217 offset:37888
	ds_read_b128 v[200:203], v217 offset:38912
	ds_read_b128 v[204:207], v217 offset:39936
	global_load_lds_dwordx4 v[220:221], off
	v_lshl_add_u64 v[220:221], s[26:27], 0, v[164:165]
	s_mov_b32 m0, s40
	s_nop 0
	global_load_lds_dwordx4 v[220:221], off
	v_lshl_add_u64 v[236:237], v[230:231], 0, s[2:3]
	v_lshl_add_u64 v[238:239], v[232:233], 0, s[2:3]
	s_waitcnt vmcnt(8)
	s_waitcnt lgkmcnt(0)
	s_barrier
	s_setprio 1
	s_waitcnt lgkmcnt(0)
	v_mfma_f32_16x16x32_bf16 v[140:143], v[100:103], v[176:179], v[140:143]
	v_mfma_f32_16x16x32_bf16 v[136:139], v[112:115], v[176:179], v[136:139]
	v_mfma_f32_16x16x32_bf16 v[124:127], v[100:103], v[184:187], v[124:127]
	v_mfma_f32_16x16x32_bf16 v[120:123], v[112:115], v[184:187], v[120:123]
	v_mfma_f32_16x16x32_bf16 v[92:95], v[100:103], v[192:195], v[92:95]
	v_mfma_f32_16x16x32_bf16 v[88:91], v[112:115], v[192:195], v[88:91]
	v_mfma_f32_16x16x32_bf16 v[76:79], v[100:103], v[200:203], v[76:79]
	v_mfma_f32_16x16x32_bf16 v[72:75], v[112:115], v[200:203], v[72:75]
	v_mfma_f32_16x16x32_bf16 v[140:143], v[108:111], v[180:183], v[140:143]
	v_mfma_f32_16x16x32_bf16 v[136:139], v[116:119], v[180:183], v[136:139]
	v_mfma_f32_16x16x32_bf16 v[124:127], v[108:111], v[188:191], v[124:127]
	v_mfma_f32_16x16x32_bf16 v[120:123], v[116:119], v[188:191], v[120:123]
	v_mfma_f32_16x16x32_bf16 v[92:95], v[108:111], v[196:199], v[92:95]
	v_mfma_f32_16x16x32_bf16 v[88:91], v[116:119], v[196:199], v[88:91]
	v_mfma_f32_16x16x32_bf16 v[76:79], v[108:111], v[204:207], v[76:79]
	v_mfma_f32_16x16x32_bf16 v[72:75], v[116:119], v[204:207], v[72:75]
	s_setprio 0
	s_setprio 1
	v_mfma_f32_16x16x32_bf16 v[132:135], v[144:147], v[176:179], v[132:135]
	v_mfma_f32_16x16x32_bf16 v[128:131], v[152:155], v[176:179], v[128:131]
	v_mfma_f32_16x16x32_bf16 v[104:107], v[144:147], v[184:187], v[104:107]
	v_mfma_f32_16x16x32_bf16 v[96:99], v[152:155], v[184:187], v[96:99]
	v_mfma_f32_16x16x32_bf16 v[84:87], v[144:147], v[192:195], v[84:87]
	v_mfma_f32_16x16x32_bf16 v[80:83], v[152:155], v[192:195], v[80:83]
	v_mfma_f32_16x16x32_bf16 v[68:71], v[144:147], v[200:203], v[68:71]
	v_mfma_f32_16x16x32_bf16 v[64:67], v[152:155], v[200:203], v[64:67]
	v_mfma_f32_16x16x32_bf16 v[132:135], v[148:151], v[180:183], v[132:135]
	v_mfma_f32_16x16x32_bf16 v[128:131], v[156:159], v[180:183], v[128:131]
	v_mfma_f32_16x16x32_bf16 v[104:107], v[148:151], v[188:191], v[104:107]
	v_mfma_f32_16x16x32_bf16 v[96:99], v[156:159], v[188:191], v[96:99]
	v_mfma_f32_16x16x32_bf16 v[84:87], v[148:151], v[196:199], v[84:87]
	v_mfma_f32_16x16x32_bf16 v[80:83], v[156:159], v[196:199], v[80:83]
	v_mfma_f32_16x16x32_bf16 v[68:71], v[148:151], v[204:207], v[68:71]
	v_mfma_f32_16x16x32_bf16 v[64:67], v[156:159], v[204:207], v[64:67]
	s_setprio 0
	s_barrier
; #define PG8_STAGE(bufoff, gbase, voff) do { _Pragma("unroll") for (int _i = 0; _i < 2; ++_i) \
;         __builtin_amdgcn_global_load_lds((const unsigned*)((const char*)(gbase) + (voff)[_i]), (PG8_LAS unsigned*)(lds + (bufoff) + ldsw + _i * 8192), 16, 0, 0); } while (0)
; #define PG8_LDA(dst, b, h) do { _Pragma("unroll") for (int m = 0; m < 4; ++m) _Pragma("unroll") for (int k = 0; k < 2; ++k) dst[m][k] = *(const PG8_LAS bf16x8*)(lds + PG8_SA(b, h) + aoff + m * 2048 + k * 1024); } while (0)
; #define PG8_MMA(ai, bj, At, Bt) do { __builtin_amdgcn_s_setprio(1); _Pragma("unroll") for (int m = 0; m < 4; ++m) _Pragma("unroll") for (int n = 0; n < 2; ++n) _Pragma("unroll") for (int k = 0; k < 2; ++k) \
;         acc[ai][bj][m][n] = __builtin_amdgcn_mfma_f32_16x16x32_bf16(Bt[n][k], At[m][k], acc[ai][bj][m][n], 0, 0, 0); __builtin_amdgcn_s_setprio(0); } while (0)
; #define PG8_WAIT_V(n) asm volatile("s_waitcnt vmcnt(" #n ")" ::: "memory")
; #define PG8_WAIT_L(n) asm volatile("s_waitcnt lgkmcnt(" #n ")" ::: "memory")
; #define PG8_BAR __builtin_amdgcn_s_barrier()
; #define PG8_SCHED __builtin_amdgcn_sched_barrier(0)
; template <class Epi, class Sched, bool ALIGN_EPI = false, bool SP2 = false>
; __device__ __forceinline__ void gemm_phase(PG8_LAS unsigned char* lds, const Gemm g, const Sched& S, const Epi& E, const int wave_s) {
;     ...
;             PG8_LDA(At, 1, 1); PG8_STAGE(PG8_SB(1, 0), b3, voffB); PG8_STAGE(PG8_SB(1, 1), b3 + hstep, voffB); PG8_STAGE(PG8_SA(1, 0), a3, voffA);
;             PG8_WAIT_V(8); PG8_WAIT_L(0); PG8_BAR; PG8_MMA(1, 0, At, B0); PG8_MMA(1, 1, At, B1); PG8_BAR; PG8_SCHED;
;     __device__ __forceinline__ void operator()(const af4 (&acc)[2][2][4][2], const pg8::Unit& u, int wr, int wc, int fr_, int fq_) const {
;     ...
;         const int grow = rowbase + u.pm * 256; const int bi = grow < TL ? grow / LSEQ : NB;
;         float* xb = grow < TL ? xl + (size_t)grow * DM : xc + (size_t)(grow - TL) * DM;
;         const float* stb = stats + 2 * (size_t)grow;
;         const int col0 = u.pn * 256 + wc * 32 + 8 * fq; const float* gp = gate + (size_t)bi * 6144 + col0;
	s_add_i32 s26, s63, s33
	s_mov_b32 m0, s26
	ds_read_b128 v[176:179], v217 offset:49152
	ds_read_b128 v[180:183], v217 offset:50176
	ds_read_b128 v[184:187], v217 offset:51200
	ds_read_b128 v[188:191], v217 offset:52224
	ds_read_b128 v[192:195], v217 offset:53248
	ds_read_b128 v[196:199], v217 offset:54272
	ds_read_b128 v[200:203], v217 offset:55296
	ds_read_b128 v[204:207], v217 offset:56320
	global_load_lds_dwordx4 v[236:237], off
	s_add_i32 m0, s26, 0x2000
	s_add_u32 s26, s28, 0xb0080
	s_addc_u32 s27, s29, 0
	s_add_i32 s28, s64, s33
	global_load_lds_dwordx4 v[238:239], off
	v_lshl_add_u64 v[208:209], s[26:27], 0, v[162:163]
	s_mov_b32 m0, s28
	s_nop 0
	global_load_lds_dwordx4 v[208:209], off
	v_lshl_add_u64 v[208:209], s[26:27], 0, v[166:167]
	s_add_i32 m0, s28, 0x2000
	s_nop 0
	global_load_lds_dwordx4 v[208:209], off
	v_lshl_add_u64 v[208:209], v[212:213], 0, s[2:3]
	s_mov_b32 m0, s48
	s_nop 0
	global_load_lds_dwordx4 v[208:209], off
	v_lshl_add_u64 v[208:209], v[234:235], 0, s[2:3]
	s_mov_b32 m0, s49
	s_nop 0
	global_load_lds_dwordx4 v[208:209], off
	s_waitcnt vmcnt(8)
	s_waitcnt lgkmcnt(0)
	s_barrier
	s_setprio 1
	s_waitcnt lgkmcnt(0)
	v_mfma_f32_16x16x32_bf16 v[60:63], v[100:103], v[176:179], v[60:63]
	v_mfma_f32_16x16x32_bf16 v[56:59], v[112:115], v[176:179], v[56:59]
	v_mfma_f32_16x16x32_bf16 v[48:51], v[100:103], v[184:187], v[48:51]
	v_mfma_f32_16x16x32_bf16 v[40:43], v[112:115], v[184:187], v[40:43]
	v_mfma_f32_16x16x32_bf16 v[28:31], v[100:103], v[192:195], v[28:31]
	v_mfma_f32_16x16x32_bf16 v[24:27], v[112:115], v[192:195], v[24:27]
	v_mfma_f32_16x16x32_bf16 v[16:19], v[100:103], v[200:203], v[16:19]
	v_mfma_f32_16x16x32_bf16 v[8:11], v[112:115], v[200:203], v[8:11]
	v_mfma_f32_16x16x32_bf16 v[60:63], v[108:111], v[180:183], v[60:63]
	v_mfma_f32_16x16x32_bf16 v[56:59], v[116:119], v[180:183], v[56:59]
	v_mfma_f32_16x16x32_bf16 v[48:51], v[108:111], v[188:191], v[48:51]
	v_mfma_f32_16x16x32_bf16 v[40:43], v[116:119], v[188:191], v[40:43]
	v_mfma_f32_16x16x32_bf16 v[28:31], v[108:111], v[196:199], v[28:31]
	v_mfma_f32_16x16x32_bf16 v[24:27], v[116:119], v[196:199], v[24:27]
	v_mfma_f32_16x16x32_bf16 v[16:19], v[108:111], v[204:207], v[16:19]
	v_mfma_f32_16x16x32_bf16 v[8:11], v[116:119], v[204:207], v[8:11]
	s_setprio 0
	s_setprio 1
	v_mfma_f32_16x16x32_bf16 v[52:55], v[144:147], v[176:179], v[52:55]
	v_mfma_f32_16x16x32_bf16 v[44:47], v[152:155], v[176:179], v[44:47]
	v_mfma_f32_16x16x32_bf16 v[36:39], v[144:147], v[184:187], v[36:39]
	v_mfma_f32_16x16x32_bf16 v[32:35], v[152:155], v[184:187], v[32:35]
	v_mfma_f32_16x16x32_bf16 v[20:23], v[144:147], v[192:195], v[20:23]
	v_mfma_f32_16x16x32_bf16 v[12:15], v[152:155], v[192:195], v[12:15]
	v_mfma_f32_16x16x32_bf16 v[4:7], v[144:147], v[200:203], v[4:7]
	v_mfma_f32_16x16x32_bf16 v[0:3], v[152:155], v[200:203], v[0:3]
	v_mfma_f32_16x16x32_bf16 v[52:55], v[148:151], v[180:183], v[52:55]
	v_mfma_f32_16x16x32_bf16 v[44:47], v[156:159], v[180:183], v[44:47]
	v_mfma_f32_16x16x32_bf16 v[36:39], v[148:151], v[188:191], v[36:39]
	v_mfma_f32_16x16x32_bf16 v[32:35], v[156:159], v[188:191], v[32:35]
	v_mfma_f32_16x16x32_bf16 v[20:23], v[148:151], v[196:199], v[20:23]
	v_mfma_f32_16x16x32_bf16 v[12:15], v[156:159], v[196:199], v[12:15]
	v_mfma_f32_16x16x32_bf16 v[4:7], v[148:151], v[204:207], v[4:7]
	v_mfma_f32_16x16x32_bf16 v[0:3], v[156:159], v[204:207], v[0:3]
	s_setprio 0
	s_barrier
	s_add_i32 s62, s62, 2
	s_add_u32 s8, s8, 0x100
	s_addc_u32 s61, s61, 0
	s_cmp_gt_u32 s62, 41
	s_mov_b64 s[26:27], s[12:13]
	s_cbranch_scc0 .LBB0_810
	s_cmpk_gt_i32 s60, 0xff
	s_cselect_b64 s[28:29], -1, 0
	s_mov_b64 s[12:13], 0x18000
	s_and_b64 vcc, exec, s[28:29]
	v_mbcnt_lo_u32_b32 v150, -1, 0
	v_mbcnt_hi_u32_b32 v150, -1, v150
	s_cbranch_vccnz .LBB0_813
	s_ashr_i32 s8, s60, 31
	s_lshr_b32 s8, s8, 28
	s_add_i32 s8, s60, s8
	s_ashr_i32 s8, s8, 4
	s_mul_hi_i32 s13, s8, 0x1800
	s_mul_i32 s12, s8, 0x1800

; #define PG8_STAGE(bufoff, gbase, voff) do { _Pragma("unroll") for (int _i = 0; _i < 2; ++_i) \
;         __builtin_amdgcn_global_load_lds((const unsigned*)((const char*)(gbase) + (voff)[_i]), (PG8_LAS unsigned*)(lds + (bufoff) + ldsw + _i * 8192), 16, 0, 0); } while (0)
; #define PG8_LDA(dst, b, h) do { _Pragma("unroll") for (int m = 0; m < 4; ++m) _Pragma("unroll") for (int k = 0; k < 2; ++k) dst[m][k] = *(const PG8_LAS bf16x8*)(lds + PG8_SA(b, h) + aoff + m * 2048 + k * 1024); } while (0)
; #define PG8_LDB(dst, b, h) do { _Pragma("unroll") for (int n = 0; n < 2; ++n) _Pragma("unroll") for (int k = 0; k < 2; ++k) dst[n][k] = *(const PG8_LAS bf16x8*)(lds + PG8_SB(b, h) + boff + n * 2048 + k * 1024); } while (0)
; #define PG8_MMA(ai, bj, At, Bt) do { __builtin_amdgcn_s_setprio(1); _Pragma("unroll") for (int m = 0; m < 4; ++m) _Pragma("unroll") for (int n = 0; n < 2; ++n) _Pragma("unroll") for (int k = 0; k < 2; ++k) \
;         acc[ai][bj][m][n] = __builtin_amdgcn_mfma_f32_16x16x32_bf16(Bt[n][k], At[m][k], acc[ai][bj][m][n], 0, 0, 0); __builtin_amdgcn_s_setprio(0); } while (0)
; #define PG8_WAIT_V(n) asm volatile("s_waitcnt vmcnt(" #n ")" ::: "memory")
; #define PG8_WAIT_L(n) asm volatile("s_waitcnt lgkmcnt(" #n ")" ::: "memory")
; #define PG8_BAR __builtin_amdgcn_s_barrier()
; #define PG8_SCHED __builtin_amdgcn_sched_barrier(0)
; template <class Epi, class Sched, bool ALIGN_EPI = false, bool SP2 = false>
; __device__ __forceinline__ void gemm_phase(PG8_LAS unsigned char* lds, const Gemm g, const Sched& S, const Epi& E, const int wave_s) {
;     ...
;             const bool last = (t == nt - 2);
;             const char* a1 = cA + (size_t)(t + 1) * kstep;
;             const char* a2 = last ? nA : cA + (size_t)(t + 2) * kstep; const char* b2 = last ? nB : cB + (size_t)(t + 2) * kstep;
;             const char* a3 = a2 + kstep; const char* b3 = b2 + kstep;
;             if (last && has_next) S.a_ready(nxt);
;             if constexpr (SP2) {
;             PG8_LDB(B0, 0, 0); PG8_LDB(B1, 0, 1); PG8_SCHED; PG8_LDA(At, 0, 0); PG8_STAGE(PG8_SA(1, 1), a1 + hstep, voffA);
;             PG8_WAIT_V(8); PG8_WAIT_L(0); PG8_BAR; PG8_MMA(0, 0, At, B0); PG8_MMA(0, 1, At, B1); PG8_BAR; PG8_SCHED;
;             PG8_LDA(At, 0, 1); PG8_STAGE(PG8_SB(0, 0), b2, voffB); PG8_STAGE(PG8_SB(0, 1), b2 + hstep, voffB); PG8_STAGE(PG8_SA(0, 0), a2, voffA);
.LBB0_1126:
	ds_read_b128 v[128:131], v203
	ds_read_b128 v[132:135], v203 offset:1024
	ds_read_b128 v[136:139], v203 offset:2048
	ds_read_b128 v[140:143], v203 offset:3072
	ds_read_b128 v[144:147], v205
	ds_read_b128 v[148:151], v205 offset:1024
	ds_read_b128 v[152:155], v205 offset:2048
	ds_read_b128 v[156:159], v205 offset:3072
	s_add_u32 s12, s8, 0xfffc0080
	s_addc_u32 s13, s9, -1
	s_cmp_eq_u32 s69, 12
	s_cselect_b32 s15, s18, s13
	s_cselect_b32 s14, s19, s12
	s_cselect_b32 s13, s20, s35
	s_cselect_b32 s12, s21, s31
	v_lshl_add_u64 v[218:219], s[8:9], 0, v[186:187]
	s_add_i32 m0, s46, 0xc000
	ds_read_b128 v[160:163], v207
	ds_read_b128 v[164:167], v207 offset:1024
	ds_read_b128 v[168:171], v207 offset:2048
	ds_read_b128 v[172:175], v207 offset:3072
	ds_read_b128 v[192:195], v207 offset:4096
	ds_read_b128 v[196:199], v207 offset:5120
	ds_read_b128 v[208:211], v207 offset:6144
	ds_read_b128 v[214:217], v207 offset:7168
	global_load_lds_dwordx4 v[218:219], off
	v_lshl_add_u64 v[218:219], s[8:9], 0, v[184:185]
	s_add_i32 m0, s46, 0xe000
	s_nop 0
	global_load_lds_dwordx4 v[218:219], off
	v_lshl_add_u64 v[230:231], s[12:13], 0, v[180:181]
	v_lshl_add_u64 v[232:233], s[12:13], 0, v[176:177]
	v_lshl_add_u64 v[234:235], s[14:15], 0, v[178:179]
	s_waitcnt vmcnt(8)
	s_waitcnt lgkmcnt(0)
	s_barrier
	s_setprio 1
	s_waitcnt lgkmcnt(0)
	v_mfma_f32_16x16x32_bf16 v[124:127], v[128:131], v[160:163], v[124:127]
	v_mfma_f32_16x16x32_bf16 v[120:123], v[136:139], v[160:163], v[120:123]
	v_mfma_f32_16x16x32_bf16 v[116:119], v[128:131], v[168:171], v[116:119]
	v_mfma_f32_16x16x32_bf16 v[108:111], v[136:139], v[168:171], v[108:111]
	v_mfma_f32_16x16x32_bf16 v[100:103], v[128:131], v[192:195], v[100:103]
	v_mfma_f32_16x16x32_bf16 v[92:95], v[136:139], v[192:195], v[92:95]
	v_mfma_f32_16x16x32_bf16 v[84:87], v[128:131], v[208:211], v[84:87]
	v_mfma_f32_16x16x32_bf16 v[76:79], v[136:139], v[208:211], v[76:79]
	v_mfma_f32_16x16x32_bf16 v[124:127], v[132:135], v[164:167], v[124:127]
	v_mfma_f32_16x16x32_bf16 v[120:123], v[140:143], v[164:167], v[120:123]
	v_mfma_f32_16x16x32_bf16 v[116:119], v[132:135], v[172:175], v[116:119]
	v_mfma_f32_16x16x32_bf16 v[108:111], v[140:143], v[172:175], v[108:111]
	v_mfma_f32_16x16x32_bf16 v[100:103], v[132:135], v[196:199], v[100:103]
	v_mfma_f32_16x16x32_bf16 v[92:95], v[140:143], v[196:199], v[92:95]
	v_mfma_f32_16x16x32_bf16 v[84:87], v[132:135], v[214:217], v[84:87]
	v_mfma_f32_16x16x32_bf16 v[76:79], v[140:143], v[214:217], v[76:79]
	s_setprio 0
	s_setprio 1
	v_mfma_f32_16x16x32_bf16 v[112:115], v[144:147], v[160:163], v[112:115]
	v_mfma_f32_16x16x32_bf16 v[104:107], v[152:155], v[160:163], v[104:107]
	v_mfma_f32_16x16x32_bf16 v[96:99], v[144:147], v[168:171], v[96:99]
	v_mfma_f32_16x16x32_bf16 v[88:91], v[152:155], v[168:171], v[88:91]
	v_mfma_f32_16x16x32_bf16 v[80:83], v[144:147], v[192:195], v[80:83]
	v_mfma_f32_16x16x32_bf16 v[72:75], v[152:155], v[192:195], v[72:75]
	v_mfma_f32_16x16x32_bf16 v[68:71], v[144:147], v[208:211], v[68:71]
	v_mfma_f32_16x16x32_bf16 v[64:67], v[152:155], v[208:211], v[64:67]
	v_mfma_f32_16x16x32_bf16 v[112:115], v[148:151], v[164:167], v[112:115]
	v_mfma_f32_16x16x32_bf16 v[104:107], v[156:159], v[164:167], v[104:107]
	v_mfma_f32_16x16x32_bf16 v[96:99], v[148:151], v[172:175], v[96:99]
	v_mfma_f32_16x16x32_bf16 v[88:91], v[156:159], v[172:175], v[88:91]
	v_mfma_f32_16x16x32_bf16 v[80:83], v[148:151], v[196:199], v[80:83]
	v_mfma_f32_16x16x32_bf16 v[72:75], v[156:159], v[196:199], v[72:75]
	v_mfma_f32_16x16x32_bf16 v[68:71], v[148:151], v[214:217], v[68:71]
	v_mfma_f32_16x16x32_bf16 v[64:67], v[156:159], v[214:217], v[64:67]
	s_setprio 0
	s_barrier
	s_add_i32 s70, s64, s33
	s_mov_b32 m0, s70
	ds_read_b128 v[160:163], v207 offset:16384
	ds_read_b128 v[164:167], v207 offset:17408
	ds_read_b128 v[168:171], v207 offset:18432
	ds_read_b128 v[172:175], v207 offset:19456
	ds_read_b128 v[192:195], v207 offset:20480
	ds_read_b128 v[196:199], v207 offset:21504
	ds_read_b128 v[208:211], v207 offset:22528
	ds_read_b128 v[214:217], v207 offset:23552
	global_load_lds_dwordx4 v[230:231], off
	s_add_i32 m0, s70, 0x2000
	s_add_u32 s70, s12, 0x40000
	s_addc_u32 s71, s13, 0
	s_add_i32 s72, s65, s33
	global_load_lds_dwordx4 v[232:233], off
	v_lshl_add_u64 v[222:223], s[70:71], 0, v[180:181]
	s_mov_b32 m0, s72
	s_nop 0
	global_load_lds_dwordx4 v[222:223], off
	v_lshl_add_u64 v[222:223], s[70:71], 0, v[176:177]
	s_add_i32 m0, s72, 0x2000
	s_nop 0
	global_load_lds_dwordx4 v[222:223], off
	v_lshl_add_u64 v[222:223], s[14:15], 0, v[182:183]
	s_mov_b32 m0, s46
	s_nop 0
	global_load_lds_dwordx4 v[222:223], off
	s_mov_b32 m0, s47
	s_nop 0
	global_load_lds_dwordx4 v[234:235], off
	s_waitcnt vmcnt(8)
	s_waitcnt lgkmcnt(0)
	s_barrier
; #define PG8_STAGE(bufoff, gbase, voff) do { _Pragma("unroll") for (int _i = 0; _i < 2; ++_i) \
;         __builtin_amdgcn_global_load_lds((const unsigned*)((const char*)(gbase) + (voff)[_i]), (PG8_LAS unsigned*)(lds + (bufoff) + ldsw + _i * 8192), 16, 0, 0); } while (0)
; #define PG8_LDA(dst, b, h) do { _Pragma("unroll") for (int m = 0; m < 4; ++m) _Pragma("unroll") for (int k = 0; k < 2; ++k) dst[m][k] = *(const PG8_LAS bf16x8*)(lds + PG8_SA(b, h) + aoff + m * 2048 + k * 1024); } while (0)
; #define PG8_LDB(dst, b, h) do { _Pragma("unroll") for (int n = 0; n < 2; ++n) _Pragma("unroll") for (int k = 0; k < 2; ++k) dst[n][k] = *(const PG8_LAS bf16x8*)(lds + PG8_SB(b, h) + boff + n * 2048 + k * 1024); } while (0)
; #define PG8_MMA(ai, bj, At, Bt) do { __builtin_amdgcn_s_setprio(1); _Pragma("unroll") for (int m = 0; m < 4; ++m) _Pragma("unroll") for (int n = 0; n < 2; ++n) _Pragma("unroll") for (int k = 0; k < 2; ++k) \
;         acc[ai][bj][m][n] = __builtin_amdgcn_mfma_f32_16x16x32_bf16(Bt[n][k], At[m][k], acc[ai][bj][m][n], 0, 0, 0); __builtin_amdgcn_s_setprio(0); } while (0)
; #define PG8_WAIT_V(n) asm volatile("s_waitcnt vmcnt(" #n ")" ::: "memory")
; #define PG8_WAIT_L(n) asm volatile("s_waitcnt lgkmcnt(" #n ")" ::: "memory")
; #define PG8_BAR __builtin_amdgcn_s_barrier()
; #define PG8_SCHED __builtin_amdgcn_sched_barrier(0)
; template <class Epi, class Sched, bool ALIGN_EPI = false, bool SP2 = false>
; __device__ __forceinline__ void gemm_phase(PG8_LAS unsigned char* lds, const Gemm g, const Sched& S, const Epi& E, const int wave_s) {
;     ...
;             PG8_WAIT_V(8); PG8_WAIT_L(0); PG8_BAR; PG8_MMA(1, 0, At, B0); PG8_MMA(1, 1, At, B1); PG8_BAR; PG8_SCHED;
;             PG8_LDB(B0, 1, 0); PG8_LDB(B1, 1, 1); PG8_SCHED; PG8_LDA(At, 1, 0); PG8_STAGE(PG8_SA(0, 1), a2 + hstep, voffA);
;             PG8_WAIT_V(8); PG8_WAIT_L(0); PG8_BAR; PG8_MMA(0, 0, At, B0); PG8_MMA(0, 1, At, B1); PG8_BAR; PG8_SCHED;
	s_setprio 1
	s_waitcnt lgkmcnt(0)
	v_mfma_f32_16x16x32_bf16 v[60:63], v[128:131], v[160:163], v[60:63]
	v_mfma_f32_16x16x32_bf16 v[56:59], v[136:139], v[160:163], v[56:59]
	v_mfma_f32_16x16x32_bf16 v[52:55], v[128:131], v[168:171], v[52:55]
	v_mfma_f32_16x16x32_bf16 v[44:47], v[136:139], v[168:171], v[44:47]
	v_mfma_f32_16x16x32_bf16 v[36:39], v[128:131], v[192:195], v[36:39]
	v_mfma_f32_16x16x32_bf16 v[28:31], v[136:139], v[192:195], v[28:31]
	v_mfma_f32_16x16x32_bf16 v[20:23], v[128:131], v[208:211], v[20:23]
	v_mfma_f32_16x16x32_bf16 v[12:15], v[136:139], v[208:211], v[12:15]
	v_mfma_f32_16x16x32_bf16 v[60:63], v[132:135], v[164:167], v[60:63]
	v_mfma_f32_16x16x32_bf16 v[56:59], v[140:143], v[164:167], v[56:59]
	v_mfma_f32_16x16x32_bf16 v[52:55], v[132:135], v[172:175], v[52:55]
	v_mfma_f32_16x16x32_bf16 v[44:47], v[140:143], v[172:175], v[44:47]
	v_mfma_f32_16x16x32_bf16 v[36:39], v[132:135], v[196:199], v[36:39]
	v_mfma_f32_16x16x32_bf16 v[28:31], v[140:143], v[196:199], v[28:31]
	v_mfma_f32_16x16x32_bf16 v[20:23], v[132:135], v[214:217], v[20:23]
	v_mfma_f32_16x16x32_bf16 v[12:15], v[140:143], v[214:217], v[12:15]
	s_setprio 0
	s_setprio 1
	v_mfma_f32_16x16x32_bf16 v[48:51], v[144:147], v[160:163], v[48:51]
	v_mfma_f32_16x16x32_bf16 v[40:43], v[152:155], v[160:163], v[40:43]
	v_mfma_f32_16x16x32_bf16 v[32:35], v[144:147], v[168:171], v[32:35]
	v_mfma_f32_16x16x32_bf16 v[24:27], v[152:155], v[168:171], v[24:27]
	v_mfma_f32_16x16x32_bf16 v[16:19], v[144:147], v[192:195], v[16:19]
	v_mfma_f32_16x16x32_bf16 v[8:11], v[152:155], v[192:195], v[8:11]
	v_mfma_f32_16x16x32_bf16 v[4:7], v[144:147], v[208:211], v[4:7]
	v_mfma_f32_16x16x32_bf16 v[0:3], v[152:155], v[208:211], v[0:3]
	v_mfma_f32_16x16x32_bf16 v[48:51], v[148:151], v[164:167], v[48:51]
	v_mfma_f32_16x16x32_bf16 v[40:43], v[156:159], v[164:167], v[40:43]
	v_mfma_f32_16x16x32_bf16 v[32:35], v[148:151], v[172:175], v[32:35]
	v_mfma_f32_16x16x32_bf16 v[24:27], v[156:159], v[172:175], v[24:27]
	v_mfma_f32_16x16x32_bf16 v[16:19], v[148:151], v[196:199], v[16:19]
	v_mfma_f32_16x16x32_bf16 v[8:11], v[156:159], v[196:199], v[8:11]
	v_mfma_f32_16x16x32_bf16 v[4:7], v[148:151], v[214:217], v[4:7]
	v_mfma_f32_16x16x32_bf16 v[0:3], v[156:159], v[214:217], v[0:3]
	s_setprio 0
	s_barrier
	s_add_i32 s70, 0, 0x18000
	s_add_i32 s71, 0, 0x1c000
	v_add_u32_e32 v140, s70, v201
	v_add_u32_e32 v156, s71, v201
	ds_read_b128 v[128:131], v140
	ds_read_b128 v[132:135], v140 offset:1024
	ds_read_b128 v[136:139], v140 offset:2048
	ds_read_b128 v[140:143], v140 offset:3072
	ds_read_b128 v[144:147], v156
	ds_read_b128 v[148:151], v156 offset:1024
	ds_read_b128 v[152:155], v156 offset:2048
	ds_read_b128 v[156:159], v156 offset:3072
	s_add_u32 s14, s14, 0x40000
	s_addc_u32 s15, s15, 0
	s_mov_b32 m0, s48
	v_lshl_add_u64 v[226:227], s[14:15], 0, v[182:183]
	ds_read_b128 v[160:163], v207 offset:32768
	ds_read_b128 v[164:167], v207 offset:33792
	ds_read_b128 v[168:171], v207 offset:34816
	ds_read_b128 v[172:175], v207 offset:35840
	ds_read_b128 v[192:195], v207 offset:36864
	ds_read_b128 v[196:199], v207 offset:37888
	ds_read_b128 v[208:211], v207 offset:38912
	ds_read_b128 v[214:217], v207 offset:39936
	global_load_lds_dwordx4 v[226:227], off
	v_lshl_add_u64 v[226:227], s[14:15], 0, v[178:179]
	s_mov_b32 m0, s49
	s_nop 0
	global_load_lds_dwordx4 v[226:227], off
	v_lshl_add_u64 v[236:237], v[230:231], 0, s[26:27]
	s_add_u32 s12, s12, 0x40080
	v_lshl_add_u64 v[238:239], v[232:233], 0, s[26:27]
	s_addc_u32 s13, s13, 0
	v_lshl_add_u64 v[240:241], s[12:13], 0, v[180:181]
	v_lshl_add_u64 v[242:243], s[12:13], 0, v[176:177]
	v_lshl_add_u64 v[244:245], v[222:223], 0, s[26:27]
	v_lshl_add_u64 v[246:247], v[234:235], 0, s[26:27]
	s_waitcnt vmcnt(8)
	s_waitcnt lgkmcnt(0)
	s_barrier
; #define PG8_STAGE(bufoff, gbase, voff) do { _Pragma("unroll") for (int _i = 0; _i < 2; ++_i) \
;         __builtin_amdgcn_global_load_lds((const unsigned*)((const char*)(gbase) + (voff)[_i]), (PG8_LAS unsigned*)(lds + (bufoff) + ldsw + _i * 8192), 16, 0, 0); } while (0)
; #define PG8_LDA(dst, b, h) do { _Pragma("unroll") for (int m = 0; m < 4; ++m) _Pragma("unroll") for (int k = 0; k < 2; ++k) dst[m][k] = *(const PG8_LAS bf16x8*)(lds + PG8_SA(b, h) + aoff + m * 2048 + k * 1024); } while (0)
; #define PG8_MMA(ai, bj, At, Bt) do { __builtin_amdgcn_s_setprio(1); _Pragma("unroll") for (int m = 0; m < 4; ++m) _Pragma("unroll") for (int n = 0; n < 2; ++n) _Pragma("unroll") for (int k = 0; k < 2; ++k) \
;         acc[ai][bj][m][n] = __builtin_amdgcn_mfma_f32_16x16x32_bf16(Bt[n][k], At[m][k], acc[ai][bj][m][n], 0, 0, 0); __builtin_amdgcn_s_setprio(0); } while (0)
; #define PG8_WAIT_V(n) asm volatile("s_waitcnt vmcnt(" #n ")" ::: "memory")
; #define PG8_WAIT_L(n) asm volatile("s_waitcnt lgkmcnt(" #n ")" ::: "memory")
; #define PG8_BAR __builtin_amdgcn_s_barrier()
; #define PG8_SCHED __builtin_amdgcn_sched_barrier(0)
; template <class Epi, class Sched, bool ALIGN_EPI = false, bool SP2 = false>
; __device__ __forceinline__ void gemm_phase(PG8_LAS unsigned char* lds, const Gemm g, const Sched& S, const Epi& E, const int wave_s) {
;     ...
;             PG8_WAIT_V(8); PG8_WAIT_L(0); PG8_BAR; PG8_MMA(0, 0, At, B0); PG8_MMA(0, 1, At, B1); PG8_BAR; PG8_SCHED;
;             PG8_LDA(At, 1, 1); PG8_STAGE(PG8_SB(1, 0), b3, voffB); PG8_STAGE(PG8_SB(1, 1), b3 + hstep, voffB); PG8_STAGE(PG8_SA(1, 0), a3, voffA);
;             PG8_WAIT_V(8); PG8_WAIT_L(0); PG8_BAR; PG8_MMA(1, 0, At, B0); PG8_MMA(1, 1, At, B1); PG8_BAR; PG8_SCHED;
	s_setprio 1
	s_waitcnt lgkmcnt(0)
	v_mfma_f32_16x16x32_bf16 v[124:127], v[128:131], v[160:163], v[124:127]
	v_mfma_f32_16x16x32_bf16 v[120:123], v[136:139], v[160:163], v[120:123]
	v_mfma_f32_16x16x32_bf16 v[116:119], v[128:131], v[168:171], v[116:119]
	v_mfma_f32_16x16x32_bf16 v[108:111], v[136:139], v[168:171], v[108:111]
	v_mfma_f32_16x16x32_bf16 v[100:103], v[128:131], v[192:195], v[100:103]
	v_mfma_f32_16x16x32_bf16 v[92:95], v[136:139], v[192:195], v[92:95]
	v_mfma_f32_16x16x32_bf16 v[84:87], v[128:131], v[208:211], v[84:87]
	v_mfma_f32_16x16x32_bf16 v[76:79], v[136:139], v[208:211], v[76:79]
	v_mfma_f32_16x16x32_bf16 v[124:127], v[132:135], v[164:167], v[124:127]
	v_mfma_f32_16x16x32_bf16 v[120:123], v[140:143], v[164:167], v[120:123]
	v_mfma_f32_16x16x32_bf16 v[116:119], v[132:135], v[172:175], v[116:119]
	v_mfma_f32_16x16x32_bf16 v[108:111], v[140:143], v[172:175], v[108:111]
	v_mfma_f32_16x16x32_bf16 v[100:103], v[132:135], v[196:199], v[100:103]
	v_mfma_f32_16x16x32_bf16 v[92:95], v[140:143], v[196:199], v[92:95]
	v_mfma_f32_16x16x32_bf16 v[84:87], v[132:135], v[214:217], v[84:87]
	v_mfma_f32_16x16x32_bf16 v[76:79], v[140:143], v[214:217], v[76:79]
	s_setprio 0
	s_setprio 1
	v_mfma_f32_16x16x32_bf16 v[112:115], v[144:147], v[160:163], v[112:115]
	v_mfma_f32_16x16x32_bf16 v[104:107], v[152:155], v[160:163], v[104:107]
	v_mfma_f32_16x16x32_bf16 v[96:99], v[144:147], v[168:171], v[96:99]
	v_mfma_f32_16x16x32_bf16 v[88:91], v[152:155], v[168:171], v[88:91]
	v_mfma_f32_16x16x32_bf16 v[80:83], v[144:147], v[192:195], v[80:83]
	v_mfma_f32_16x16x32_bf16 v[72:75], v[152:155], v[192:195], v[72:75]
	v_mfma_f32_16x16x32_bf16 v[68:71], v[144:147], v[208:211], v[68:71]
	v_mfma_f32_16x16x32_bf16 v[64:67], v[152:155], v[208:211], v[64:67]
	v_mfma_f32_16x16x32_bf16 v[112:115], v[148:151], v[164:167], v[112:115]
	v_mfma_f32_16x16x32_bf16 v[104:107], v[156:159], v[164:167], v[104:107]
	v_mfma_f32_16x16x32_bf16 v[96:99], v[148:151], v[172:175], v[96:99]
	v_mfma_f32_16x16x32_bf16 v[88:91], v[156:159], v[172:175], v[88:91]
	v_mfma_f32_16x16x32_bf16 v[80:83], v[148:151], v[196:199], v[80:83]
	v_mfma_f32_16x16x32_bf16 v[72:75], v[156:159], v[196:199], v[72:75]
	v_mfma_f32_16x16x32_bf16 v[68:71], v[148:151], v[214:217], v[68:71]
	v_mfma_f32_16x16x32_bf16 v[64:67], v[156:159], v[214:217], v[64:67]
	s_setprio 0
	s_barrier
	s_add_i32 s14, s70, s33
	s_mov_b32 m0, s14
	ds_read_b128 v[160:163], v207 offset:49152
	ds_read_b128 v[164:167], v207 offset:50176
	ds_read_b128 v[168:171], v207 offset:51200
	ds_read_b128 v[172:175], v207 offset:52224
	ds_read_b128 v[192:195], v207 offset:53248
	ds_read_b128 v[196:199], v207 offset:54272
	ds_read_b128 v[208:211], v207 offset:55296
	ds_read_b128 v[214:217], v207 offset:56320
	global_load_lds_dwordx4 v[236:237], off
	s_add_i32 m0, s14, 0x2000
	s_add_i32 s14, s71, s33
	global_load_lds_dwordx4 v[238:239], off
	s_mov_b32 m0, s14
	s_nop 0
	global_load_lds_dwordx4 v[240:241], off
	s_add_i32 m0, s14, 0x2000
	s_nop 0
	global_load_lds_dwordx4 v[242:243], off
	s_mov_b32 m0, s50
	s_nop 0
	global_load_lds_dwordx4 v[244:245], off
	s_mov_b32 m0, s51
	s_nop 0
	global_load_lds_dwordx4 v[246:247], off
	s_waitcnt vmcnt(8)
	s_waitcnt lgkmcnt(0)
	s_barrier
	s_setprio 1
	s_waitcnt lgkmcnt(0)
	v_mfma_f32_16x16x32_bf16 v[60:63], v[128:131], v[160:163], v[60:63]
	v_mfma_f32_16x16x32_bf16 v[56:59], v[136:139], v[160:163], v[56:59]
	v_mfma_f32_16x16x32_bf16 v[52:55], v[128:131], v[168:171], v[52:55]
	v_mfma_f32_16x16x32_bf16 v[44:47], v[136:139], v[168:171], v[44:47]
	v_mfma_f32_16x16x32_bf16 v[36:39], v[128:131], v[192:195], v[36:39]
	v_mfma_f32_16x16x32_bf16 v[28:31], v[136:139], v[192:195], v[28:31]
	v_mfma_f32_16x16x32_bf16 v[20:23], v[128:131], v[208:211], v[20:23]
	v_mfma_f32_16x16x32_bf16 v[12:15], v[136:139], v[208:211], v[12:15]
	v_mfma_f32_16x16x32_bf16 v[60:63], v[132:135], v[164:167], v[60:63]
	v_mfma_f32_16x16x32_bf16 v[56:59], v[140:143], v[164:167], v[56:59]
	v_mfma_f32_16x16x32_bf16 v[52:55], v[132:135], v[172:175], v[52:55]
	v_mfma_f32_16x16x32_bf16 v[44:47], v[140:143], v[172:175], v[44:47]
	v_mfma_f32_16x16x32_bf16 v[36:39], v[132:135], v[196:199], v[36:39]
	v_mfma_f32_16x16x32_bf16 v[28:31], v[140:143], v[196:199], v[28:31]
	v_mfma_f32_16x16x32_bf16 v[20:23], v[132:135], v[214:217], v[20:23]
	v_mfma_f32_16x16x32_bf16 v[12:15], v[140:143], v[214:217], v[12:15]
	s_setprio 0
	s_setprio 1
	v_mfma_f32_16x16x32_bf16 v[48:51], v[144:147], v[160:163], v[48:51]
	v_mfma_f32_16x16x32_bf16 v[40:43], v[152:155], v[160:163], v[40:43]
	v_mfma_f32_16x16x32_bf16 v[32:35], v[144:147], v[168:171], v[32:35]
	v_mfma_f32_16x16x32_bf16 v[24:27], v[152:155], v[168:171], v[24:27]
	v_mfma_f32_16x16x32_bf16 v[16:19], v[144:147], v[192:195], v[16:19]
	v_mfma_f32_16x16x32_bf16 v[8:11], v[152:155], v[192:195], v[8:11]
	v_mfma_f32_16x16x32_bf16 v[4:7], v[144:147], v[208:211], v[4:7]
	v_mfma_f32_16x16x32_bf16 v[0:3], v[152:155], v[208:211], v[0:3]
	v_mfma_f32_16x16x32_bf16 v[48:51], v[148:151], v[164:167], v[48:51]
	v_mfma_f32_16x16x32_bf16 v[40:43], v[156:159], v[164:167], v[40:43]
	v_mfma_f32_16x16x32_bf16 v[32:35], v[148:151], v[172:175], v[32:35]
	v_mfma_f32_16x16x32_bf16 v[24:27], v[156:159], v[172:175], v[24:27]
	v_mfma_f32_16x16x32_bf16 v[16:19], v[148:151], v[196:199], v[16:19]
	v_mfma_f32_16x16x32_bf16 v[8:11], v[156:159], v[196:199], v[8:11]
	v_mfma_f32_16x16x32_bf16 v[4:7], v[148:151], v[214:217], v[4:7]
	v_mfma_f32_16x16x32_bf16 v[0:3], v[156:159], v[214:217], v[0:3]
	s_setprio 0
	s_barrier
	s_add_i32 s69, s69, 2
	s_add_u32 s31, s31, 0x100
	s_addc_u32 s35, s35, 0
	s_add_u32 s8, s8, 0x100
	s_addc_u32 s9, s9, 0
	s_cmp_gt_u32 s69, 13
	s_cbranch_scc0 .LBB0_1126
	s_and_b64 vcc, exec, s[28:29]
	s_cbranch_vccz .LBB0_1129
	s_barrier

; #define PG8_STAGE(bufoff, gbase, voff) do { _Pragma("unroll") for (int _i = 0; _i < 2; ++_i) \
;         __builtin_amdgcn_global_load_lds((const unsigned*)((const char*)(gbase) + (voff)[_i]), (PG8_LAS unsigned*)(lds + (bufoff) + ldsw + _i * 8192), 16, 0, 0); } while (0)
; #define PG8_LDA(dst, b, h) do { _Pragma("unroll") for (int m = 0; m < 4; ++m) _Pragma("unroll") for (int k = 0; k < 2; ++k) dst[m][k] = *(const PG8_LAS bf16x8*)(lds + PG8_SA(b, h) + aoff + m * 2048 + k * 1024); } while (0)
; #define PG8_LDB(dst, b, h) do { _Pragma("unroll") for (int n = 0; n < 2; ++n) _Pragma("unroll") for (int k = 0; k < 2; ++k) dst[n][k] = *(const PG8_LAS bf16x8*)(lds + PG8_SB(b, h) + boff + n * 2048 + k * 1024); } while (0)
; #define PG8_MMA(ai, bj, At, Bt) do { __builtin_amdgcn_s_setprio(1); _Pragma("unroll") for (int m = 0; m < 4; ++m) _Pragma("unroll") for (int n = 0; n < 2; ++n) _Pragma("unroll") for (int k = 0; k < 2; ++k) \
;         acc[ai][bj][m][n] = __builtin_amdgcn_mfma_f32_16x16x32_bf16(Bt[n][k], At[m][k], acc[ai][bj][m][n], 0, 0, 0); __builtin_amdgcn_s_setprio(0); } while (0)
; #define PG8_WAIT_V(n) asm volatile("s_waitcnt vmcnt(" #n ")" ::: "memory")
; #define PG8_WAIT_L(n) asm volatile("s_waitcnt lgkmcnt(" #n ")" ::: "memory")
; #define PG8_BAR __builtin_amdgcn_s_barrier()
; #define PG8_SCHED __builtin_amdgcn_sched_barrier(0)
; template <class Epi, class Sched, bool ALIGN_EPI = false, bool SP2 = false>
; __device__ __forceinline__ void gemm_phase(PG8_LAS unsigned char* lds, const Gemm g, const Sched& S, const Epi& E, const int wave_s) {
;     ...
;             const bool last = (t == nt - 2);
;             const char* a1 = cA + (size_t)(t + 1) * kstep;
;             const char* a2 = last ? nA : cA + (size_t)(t + 2) * kstep; const char* b2 = last ? nB : cB + (size_t)(t + 2) * kstep;
;             const char* a3 = a2 + kstep; const char* b3 = b2 + kstep;
;             if (last && has_next) S.a_ready(nxt);
;             if constexpr (SP2) {
;             PG8_LDB(B0, 0, 0); PG8_LDB(B1, 0, 1); PG8_SCHED; PG8_LDA(At, 0, 0); PG8_STAGE(PG8_SA(1, 1), a1 + hstep, voffA);
;             PG8_WAIT_V(8); PG8_WAIT_L(0); PG8_BAR; PG8_MMA(0, 0, At, B0); PG8_MMA(0, 1, At, B1); PG8_BAR; PG8_SCHED;
;             PG8_LDA(At, 0, 1); PG8_STAGE(PG8_SB(0, 0), b2, voffB); PG8_STAGE(PG8_SB(0, 1), b2 + hstep, voffB); PG8_STAGE(PG8_SA(0, 0), a2, voffA);
.LBB0_1586:
	ds_read_b128 v[128:131], v195
	ds_read_b128 v[132:135], v195 offset:1024
	ds_read_b128 v[136:139], v195 offset:2048
	ds_read_b128 v[140:143], v195 offset:3072
	ds_read_b128 v[160:163], v196
	ds_read_b128 v[164:167], v196 offset:1024
	ds_read_b128 v[168:171], v196 offset:2048
	ds_read_b128 v[172:175], v196 offset:3072
	s_add_u32 s22, s24, 0x100
	s_addc_u32 s23, s25, 0
	s_cmp_eq_u32 s60, 40
	s_cselect_b32 s29, s17, s23
	s_cselect_b32 s28, s16, s22
	s_cselect_b32 s27, s21, s59
	s_cselect_b32 s26, s20, s58
	v_lshl_add_u64 v[156:157], s[24:25], 0, v[154:155]
	s_add_i32 m0, s37, 0xc000
	ds_read_b128 v[176:179], v197
	ds_read_b128 v[180:183], v197 offset:1024
	ds_read_b128 v[184:187], v197 offset:2048
	ds_read_b128 v[188:191], v197 offset:3072
	ds_read_b128 v[198:201], v197 offset:4096
	ds_read_b128 v[202:205], v197 offset:5120
	ds_read_b128 v[206:209], v197 offset:6144
	ds_read_b128 v[210:213], v197 offset:7168
	global_load_lds_dwordx4 v[156:157], off
	v_lshl_add_u64 v[156:157], s[24:25], 0, v[152:153]
	s_add_i32 m0, s37, 0xe000
	s_nop 0
	global_load_lds_dwordx4 v[156:157], off
	v_lshl_add_u64 v[230:231], s[26:27], 0, v[148:149]
	v_lshl_add_u64 v[232:233], s[26:27], 0, v[144:145]
	v_lshl_add_u64 v[234:235], s[28:29], 0, v[146:147]
	s_waitcnt vmcnt(8)
	s_waitcnt lgkmcnt(0)
	s_barrier
	s_setprio 1
	s_waitcnt lgkmcnt(0)
	v_mfma_f32_16x16x32_bf16 v[124:127], v[128:131], v[176:179], v[124:127]
	v_mfma_f32_16x16x32_bf16 v[120:123], v[136:139], v[176:179], v[120:123]
	v_mfma_f32_16x16x32_bf16 v[112:115], v[128:131], v[184:187], v[112:115]
	v_mfma_f32_16x16x32_bf16 v[104:107], v[136:139], v[184:187], v[104:107]
	v_mfma_f32_16x16x32_bf16 v[92:95], v[128:131], v[198:201], v[92:95]
	v_mfma_f32_16x16x32_bf16 v[88:91], v[136:139], v[198:201], v[88:91]
	v_mfma_f32_16x16x32_bf16 v[80:83], v[128:131], v[206:209], v[80:83]
	v_mfma_f32_16x16x32_bf16 v[72:75], v[136:139], v[206:209], v[72:75]
	v_mfma_f32_16x16x32_bf16 v[124:127], v[132:135], v[180:183], v[124:127]
	v_mfma_f32_16x16x32_bf16 v[120:123], v[140:143], v[180:183], v[120:123]
	v_mfma_f32_16x16x32_bf16 v[112:115], v[132:135], v[188:191], v[112:115]
	v_mfma_f32_16x16x32_bf16 v[104:107], v[140:143], v[188:191], v[104:107]
	v_mfma_f32_16x16x32_bf16 v[92:95], v[132:135], v[202:205], v[92:95]
	v_mfma_f32_16x16x32_bf16 v[88:91], v[140:143], v[202:205], v[88:91]
	v_mfma_f32_16x16x32_bf16 v[80:83], v[132:135], v[210:213], v[80:83]
	v_mfma_f32_16x16x32_bf16 v[72:75], v[140:143], v[210:213], v[72:75]
	s_setprio 0
	s_setprio 1
	v_mfma_f32_16x16x32_bf16 v[116:119], v[160:163], v[176:179], v[116:119]
	v_mfma_f32_16x16x32_bf16 v[108:111], v[168:171], v[176:179], v[108:111]
	v_mfma_f32_16x16x32_bf16 v[100:103], v[160:163], v[184:187], v[100:103]
	v_mfma_f32_16x16x32_bf16 v[96:99], v[168:171], v[184:187], v[96:99]
	v_mfma_f32_16x16x32_bf16 v[84:87], v[160:163], v[198:201], v[84:87]
	v_mfma_f32_16x16x32_bf16 v[76:79], v[168:171], v[198:201], v[76:79]
	v_mfma_f32_16x16x32_bf16 v[68:71], v[160:163], v[206:209], v[68:71]
	v_mfma_f32_16x16x32_bf16 v[64:67], v[168:171], v[206:209], v[64:67]
	v_mfma_f32_16x16x32_bf16 v[116:119], v[164:167], v[180:183], v[116:119]
	v_mfma_f32_16x16x32_bf16 v[108:111], v[172:175], v[180:183], v[108:111]
	v_mfma_f32_16x16x32_bf16 v[100:103], v[164:167], v[188:191], v[100:103]
	v_mfma_f32_16x16x32_bf16 v[96:99], v[172:175], v[188:191], v[96:99]
	v_mfma_f32_16x16x32_bf16 v[84:87], v[164:167], v[202:205], v[84:87]
	v_mfma_f32_16x16x32_bf16 v[76:79], v[172:175], v[202:205], v[76:79]
	v_mfma_f32_16x16x32_bf16 v[68:71], v[164:167], v[210:213], v[68:71]
	v_mfma_f32_16x16x32_bf16 v[64:67], v[172:175], v[210:213], v[64:67]
	s_setprio 0
	s_barrier
	s_add_i32 s24, s52, s33
	s_mov_b32 m0, s24
	ds_read_b128 v[176:179], v197 offset:16384
	ds_read_b128 v[180:183], v197 offset:17408
	ds_read_b128 v[184:187], v197 offset:18432
	ds_read_b128 v[188:191], v197 offset:19456
	ds_read_b128 v[198:201], v197 offset:20480
	ds_read_b128 v[202:205], v197 offset:21504
	ds_read_b128 v[206:209], v197 offset:22528
	ds_read_b128 v[210:213], v197 offset:23552
	global_load_lds_dwordx4 v[230:231], off
	s_add_i32 m0, s24, 0x2000
	s_add_u32 s24, s26, 0xb0000
	s_addc_u32 s25, s27, 0
	s_add_i32 s61, s53, s33
	global_load_lds_dwordx4 v[232:233], off
	v_lshl_add_u64 v[214:215], s[24:25], 0, v[148:149]
	s_mov_b32 m0, s61
	s_nop 0
	global_load_lds_dwordx4 v[214:215], off
	v_lshl_add_u64 v[214:215], s[24:25], 0, v[144:145]
	s_add_i32 m0, s61, 0x2000
	s_nop 0
	global_load_lds_dwordx4 v[214:215], off
	v_lshl_add_u64 v[214:215], s[28:29], 0, v[150:151]
	s_mov_b32 m0, s37
	s_nop 0
	global_load_lds_dwordx4 v[214:215], off
	s_mov_b32 m0, s38
	s_nop 0
	global_load_lds_dwordx4 v[234:235], off
	s_waitcnt vmcnt(8)
	s_waitcnt lgkmcnt(0)
	s_barrier
; #define PG8_STAGE(bufoff, gbase, voff) do { _Pragma("unroll") for (int _i = 0; _i < 2; ++_i) \
;         __builtin_amdgcn_global_load_lds((const unsigned*)((const char*)(gbase) + (voff)[_i]), (PG8_LAS unsigned*)(lds + (bufoff) + ldsw + _i * 8192), 16, 0, 0); } while (0)
; #define PG8_LDA(dst, b, h) do { _Pragma("unroll") for (int m = 0; m < 4; ++m) _Pragma("unroll") for (int k = 0; k < 2; ++k) dst[m][k] = *(const PG8_LAS bf16x8*)(lds + PG8_SA(b, h) + aoff + m * 2048 + k * 1024); } while (0)
; #define PG8_LDB(dst, b, h) do { _Pragma("unroll") for (int n = 0; n < 2; ++n) _Pragma("unroll") for (int k = 0; k < 2; ++k) dst[n][k] = *(const PG8_LAS bf16x8*)(lds + PG8_SB(b, h) + boff + n * 2048 + k * 1024); } while (0)
; #define PG8_MMA(ai, bj, At, Bt) do { __builtin_amdgcn_s_setprio(1); _Pragma("unroll") for (int m = 0; m < 4; ++m) _Pragma("unroll") for (int n = 0; n < 2; ++n) _Pragma("unroll") for (int k = 0; k < 2; ++k) \
;         acc[ai][bj][m][n] = __builtin_amdgcn_mfma_f32_16x16x32_bf16(Bt[n][k], At[m][k], acc[ai][bj][m][n], 0, 0, 0); __builtin_amdgcn_s_setprio(0); } while (0)
; #define PG8_WAIT_V(n) asm volatile("s_waitcnt vmcnt(" #n ")" ::: "memory")
; #define PG8_WAIT_L(n) asm volatile("s_waitcnt lgkmcnt(" #n ")" ::: "memory")
; #define PG8_BAR __builtin_amdgcn_s_barrier()
; #define PG8_SCHED __builtin_amdgcn_sched_barrier(0)
; template <class Epi, class Sched, bool ALIGN_EPI = false, bool SP2 = false>
; __device__ __forceinline__ void gemm_phase(PG8_LAS unsigned char* lds, const Gemm g, const Sched& S, const Epi& E, const int wave_s) {
;     ...
;             PG8_WAIT_V(8); PG8_WAIT_L(0); PG8_BAR; PG8_MMA(1, 0, At, B0); PG8_MMA(1, 1, At, B1); PG8_BAR; PG8_SCHED;
;             PG8_LDB(B0, 1, 0); PG8_LDB(B1, 1, 1); PG8_SCHED; PG8_LDA(At, 1, 0); PG8_STAGE(PG8_SA(0, 1), a2 + hstep, voffA);
;             PG8_WAIT_V(8); PG8_WAIT_L(0); PG8_BAR; PG8_MMA(0, 0, At, B0); PG8_MMA(0, 1, At, B1); PG8_BAR; PG8_SCHED;
	s_setprio 1
	s_waitcnt lgkmcnt(0)
	v_mfma_f32_16x16x32_bf16 v[60:63], v[128:131], v[176:179], v[60:63]
	v_mfma_f32_16x16x32_bf16 v[56:59], v[136:139], v[176:179], v[56:59]
	v_mfma_f32_16x16x32_bf16 v[48:51], v[128:131], v[184:187], v[48:51]
	v_mfma_f32_16x16x32_bf16 v[40:43], v[136:139], v[184:187], v[40:43]
	v_mfma_f32_16x16x32_bf16 v[28:31], v[128:131], v[198:201], v[28:31]
	v_mfma_f32_16x16x32_bf16 v[24:27], v[136:139], v[198:201], v[24:27]
	v_mfma_f32_16x16x32_bf16 v[16:19], v[128:131], v[206:209], v[16:19]
	v_mfma_f32_16x16x32_bf16 v[8:11], v[136:139], v[206:209], v[8:11]
	v_mfma_f32_16x16x32_bf16 v[60:63], v[132:135], v[180:183], v[60:63]
	v_mfma_f32_16x16x32_bf16 v[56:59], v[140:143], v[180:183], v[56:59]
	v_mfma_f32_16x16x32_bf16 v[48:51], v[132:135], v[188:191], v[48:51]
	v_mfma_f32_16x16x32_bf16 v[40:43], v[140:143], v[188:191], v[40:43]
	v_mfma_f32_16x16x32_bf16 v[28:31], v[132:135], v[202:205], v[28:31]
	v_mfma_f32_16x16x32_bf16 v[24:27], v[140:143], v[202:205], v[24:27]
	v_mfma_f32_16x16x32_bf16 v[16:19], v[132:135], v[210:213], v[16:19]
	v_mfma_f32_16x16x32_bf16 v[8:11], v[140:143], v[210:213], v[8:11]
	s_setprio 0
	s_setprio 1
	v_mfma_f32_16x16x32_bf16 v[52:55], v[160:163], v[176:179], v[52:55]
	v_mfma_f32_16x16x32_bf16 v[44:47], v[168:171], v[176:179], v[44:47]
	v_mfma_f32_16x16x32_bf16 v[36:39], v[160:163], v[184:187], v[36:39]
	v_mfma_f32_16x16x32_bf16 v[32:35], v[168:171], v[184:187], v[32:35]
	v_mfma_f32_16x16x32_bf16 v[20:23], v[160:163], v[198:201], v[20:23]
	v_mfma_f32_16x16x32_bf16 v[12:15], v[168:171], v[198:201], v[12:15]
	v_mfma_f32_16x16x32_bf16 v[4:7], v[160:163], v[206:209], v[4:7]
	v_mfma_f32_16x16x32_bf16 v[0:3], v[168:171], v[206:209], v[0:3]
	v_mfma_f32_16x16x32_bf16 v[52:55], v[164:167], v[180:183], v[52:55]
	v_mfma_f32_16x16x32_bf16 v[44:47], v[172:175], v[180:183], v[44:47]
	v_mfma_f32_16x16x32_bf16 v[36:39], v[164:167], v[188:191], v[36:39]
	v_mfma_f32_16x16x32_bf16 v[32:35], v[172:175], v[188:191], v[32:35]
	v_mfma_f32_16x16x32_bf16 v[20:23], v[164:167], v[202:205], v[20:23]
	v_mfma_f32_16x16x32_bf16 v[12:15], v[172:175], v[202:205], v[12:15]
	v_mfma_f32_16x16x32_bf16 v[4:7], v[164:167], v[210:213], v[4:7]
	v_mfma_f32_16x16x32_bf16 v[0:3], v[172:175], v[210:213], v[0:3]
	s_setprio 0
	s_barrier
	s_add_i32 s61, 0, 0x18000
	s_add_i32 s62, 0, 0x1c000
	v_add_u32_e32 v140, s61, v194
	v_add_u32_e32 v172, s62, v194
	ds_read_b128 v[128:131], v140
	ds_read_b128 v[132:135], v140 offset:1024
	ds_read_b128 v[136:139], v140 offset:2048
	ds_read_b128 v[140:143], v140 offset:3072
	ds_read_b128 v[160:163], v172
	ds_read_b128 v[164:167], v172 offset:1024
	ds_read_b128 v[168:171], v172 offset:2048
	ds_read_b128 v[172:175], v172 offset:3072
	s_add_u32 s24, s28, 0xb0000
	s_addc_u32 s25, s29, 0
	s_mov_b32 m0, s39
	v_lshl_add_u64 v[218:219], s[24:25], 0, v[150:151]
	ds_read_b128 v[176:179], v197 offset:32768
	ds_read_b128 v[180:183], v197 offset:33792
	ds_read_b128 v[184:187], v197 offset:34816
	ds_read_b128 v[188:191], v197 offset:35840
	ds_read_b128 v[198:201], v197 offset:36864
	ds_read_b128 v[202:205], v197 offset:37888
	ds_read_b128 v[206:209], v197 offset:38912
	ds_read_b128 v[210:213], v197 offset:39936
	global_load_lds_dwordx4 v[218:219], off
	v_lshl_add_u64 v[218:219], s[24:25], 0, v[146:147]
	s_mov_b32 m0, s40
	s_nop 0
	global_load_lds_dwordx4 v[218:219], off
	v_lshl_add_u64 v[236:237], v[230:231], 0, s[6:7]
	v_lshl_add_u64 v[238:239], v[232:233], 0, s[6:7]
	s_waitcnt vmcnt(8)
	s_waitcnt lgkmcnt(0)
	s_barrier
	s_setprio 1
	s_waitcnt lgkmcnt(0)
	v_mfma_f32_16x16x32_bf16 v[124:127], v[128:131], v[176:179], v[124:127]
	v_mfma_f32_16x16x32_bf16 v[120:123], v[136:139], v[176:179], v[120:123]
	v_mfma_f32_16x16x32_bf16 v[112:115], v[128:131], v[184:187], v[112:115]
	v_mfma_f32_16x16x32_bf16 v[104:107], v[136:139], v[184:187], v[104:107]
	v_mfma_f32_16x16x32_bf16 v[92:95], v[128:131], v[198:201], v[92:95]
	v_mfma_f32_16x16x32_bf16 v[88:91], v[136:139], v[198:201], v[88:91]
	v_mfma_f32_16x16x32_bf16 v[80:83], v[128:131], v[206:209], v[80:83]
	v_mfma_f32_16x16x32_bf16 v[72:75], v[136:139], v[206:209], v[72:75]
	v_mfma_f32_16x16x32_bf16 v[124:127], v[132:135], v[180:183], v[124:127]
	v_mfma_f32_16x16x32_bf16 v[120:123], v[140:143], v[180:183], v[120:123]
	v_mfma_f32_16x16x32_bf16 v[112:115], v[132:135], v[188:191], v[112:115]
	v_mfma_f32_16x16x32_bf16 v[104:107], v[140:143], v[188:191], v[104:107]
	v_mfma_f32_16x16x32_bf16 v[92:95], v[132:135], v[202:205], v[92:95]
	v_mfma_f32_16x16x32_bf16 v[88:91], v[140:143], v[202:205], v[88:91]
	v_mfma_f32_16x16x32_bf16 v[80:83], v[132:135], v[210:213], v[80:83]
	v_mfma_f32_16x16x32_bf16 v[72:75], v[140:143], v[210:213], v[72:75]
	s_setprio 0
	s_setprio 1
	v_mfma_f32_16x16x32_bf16 v[116:119], v[160:163], v[176:179], v[116:119]
	v_mfma_f32_16x16x32_bf16 v[108:111], v[168:171], v[176:179], v[108:111]
	v_mfma_f32_16x16x32_bf16 v[100:103], v[160:163], v[184:187], v[100:103]
	v_mfma_f32_16x16x32_bf16 v[96:99], v[168:171], v[184:187], v[96:99]
	v_mfma_f32_16x16x32_bf16 v[84:87], v[160:163], v[198:201], v[84:87]
	v_mfma_f32_16x16x32_bf16 v[76:79], v[168:171], v[198:201], v[76:79]
	v_mfma_f32_16x16x32_bf16 v[68:71], v[160:163], v[206:209], v[68:71]
	v_mfma_f32_16x16x32_bf16 v[64:67], v[168:171], v[206:209], v[64:67]
	v_mfma_f32_16x16x32_bf16 v[116:119], v[164:167], v[180:183], v[116:119]
	v_mfma_f32_16x16x32_bf16 v[108:111], v[172:175], v[180:183], v[108:111]
	v_mfma_f32_16x16x32_bf16 v[100:103], v[164:167], v[188:191], v[100:103]
	v_mfma_f32_16x16x32_bf16 v[96:99], v[172:175], v[188:191], v[96:99]
	v_mfma_f32_16x16x32_bf16 v[84:87], v[164:167], v[202:205], v[84:87]
	v_mfma_f32_16x16x32_bf16 v[76:79], v[172:175], v[202:205], v[76:79]
	v_mfma_f32_16x16x32_bf16 v[68:71], v[164:167], v[210:213], v[68:71]
	v_mfma_f32_16x16x32_bf16 v[64:67], v[172:175], v[210:213], v[64:67]
	s_setprio 0
	s_barrier
; #define PG8_STAGE(bufoff, gbase, voff) do { _Pragma("unroll") for (int _i = 0; _i < 2; ++_i) \
;         __builtin_amdgcn_global_load_lds((const unsigned*)((const char*)(gbase) + (voff)[_i]), (PG8_LAS unsigned*)(lds + (bufoff) + ldsw + _i * 8192), 16, 0, 0); } while (0)
; #define PG8_LDA(dst, b, h) do { _Pragma("unroll") for (int m = 0; m < 4; ++m) _Pragma("unroll") for (int k = 0; k < 2; ++k) dst[m][k] = *(const PG8_LAS bf16x8*)(lds + PG8_SA(b, h) + aoff + m * 2048 + k * 1024); } while (0)
; #define PG8_MMA(ai, bj, At, Bt) do { __builtin_amdgcn_s_setprio(1); _Pragma("unroll") for (int m = 0; m < 4; ++m) _Pragma("unroll") for (int n = 0; n < 2; ++n) _Pragma("unroll") for (int k = 0; k < 2; ++k) \
;         acc[ai][bj][m][n] = __builtin_amdgcn_mfma_f32_16x16x32_bf16(Bt[n][k], At[m][k], acc[ai][bj][m][n], 0, 0, 0); __builtin_amdgcn_s_setprio(0); } while (0)
; #define PG8_WAIT_V(n) asm volatile("s_waitcnt vmcnt(" #n ")" ::: "memory")
; #define PG8_WAIT_L(n) asm volatile("s_waitcnt lgkmcnt(" #n ")" ::: "memory")
; #define PG8_BAR __builtin_amdgcn_s_barrier()
; #define PG8_SCHED __builtin_amdgcn_sched_barrier(0)
; template <class Epi, class Sched, bool ALIGN_EPI = false, bool SP2 = false>
; __device__ __forceinline__ void gemm_phase(PG8_LAS unsigned char* lds, const Gemm g, const Sched& S, const Epi& E, const int wave_s) {
;     ...
;             PG8_LDA(At, 1, 1); PG8_STAGE(PG8_SB(1, 0), b3, voffB); PG8_STAGE(PG8_SB(1, 1), b3 + hstep, voffB); PG8_STAGE(PG8_SA(1, 0), a3, voffA);
;             PG8_WAIT_V(8); PG8_WAIT_L(0); PG8_BAR; PG8_MMA(1, 0, At, B0); PG8_MMA(1, 1, At, B1); PG8_BAR; PG8_SCHED;
;     __device__ __forceinline__ void operator()(const af4 (&acc)[2][2][4][2], const pg8::Unit& u, int wr, int wc, int fr_, int fq_) const {
;     ...
;         const int grow = rowbase + u.pm * 256; const int bi = grow < TL ? grow / LSEQ : NB;
;         float* xb = grow < TL ? xl + (size_t)grow * DM : xc + (size_t)(grow - TL) * DM;
;         const float* stb = stats + 2 * (size_t)grow;
;         const int col0 = u.pn * 256 + wc * 32 + 8 * fq; const float* gp = gate + (size_t)bi * 6144 + col0;
	s_add_i32 s24, s61, s33
	s_mov_b32 m0, s24
	ds_read_b128 v[176:179], v197 offset:49152
	ds_read_b128 v[180:183], v197 offset:50176
	ds_read_b128 v[184:187], v197 offset:51200
	ds_read_b128 v[188:191], v197 offset:52224
	ds_read_b128 v[198:201], v197 offset:53248
	ds_read_b128 v[202:205], v197 offset:54272
	ds_read_b128 v[206:209], v197 offset:55296
	ds_read_b128 v[210:213], v197 offset:56320
	global_load_lds_dwordx4 v[236:237], off
	s_add_i32 m0, s24, 0x2000
	s_add_u32 s24, s26, 0xb0080
	s_addc_u32 s25, s27, 0
	s_add_i32 s26, s62, s33
	global_load_lds_dwordx4 v[238:239], off
	v_lshl_add_u64 v[156:157], s[24:25], 0, v[148:149]
	s_mov_b32 m0, s26
	s_nop 0
	global_load_lds_dwordx4 v[156:157], off
	v_lshl_add_u64 v[156:157], s[24:25], 0, v[144:145]
	s_add_i32 m0, s26, 0x2000
	s_nop 0
	global_load_lds_dwordx4 v[156:157], off
	v_lshl_add_u64 v[156:157], v[214:215], 0, s[6:7]
	s_mov_b32 m0, s48
	s_nop 0
	global_load_lds_dwordx4 v[156:157], off
	v_lshl_add_u64 v[156:157], v[234:235], 0, s[6:7]
	s_mov_b32 m0, s49
	s_nop 0
	global_load_lds_dwordx4 v[156:157], off
	s_waitcnt vmcnt(8)
	s_waitcnt lgkmcnt(0)
	s_barrier
	s_setprio 1
	s_waitcnt lgkmcnt(0)
	v_mfma_f32_16x16x32_bf16 v[60:63], v[128:131], v[176:179], v[60:63]
	v_mfma_f32_16x16x32_bf16 v[56:59], v[136:139], v[176:179], v[56:59]
	v_mfma_f32_16x16x32_bf16 v[48:51], v[128:131], v[184:187], v[48:51]
	v_mfma_f32_16x16x32_bf16 v[40:43], v[136:139], v[184:187], v[40:43]
	v_mfma_f32_16x16x32_bf16 v[28:31], v[128:131], v[198:201], v[28:31]
	v_mfma_f32_16x16x32_bf16 v[24:27], v[136:139], v[198:201], v[24:27]
	v_mfma_f32_16x16x32_bf16 v[16:19], v[128:131], v[206:209], v[16:19]
	v_mfma_f32_16x16x32_bf16 v[8:11], v[136:139], v[206:209], v[8:11]
	v_mfma_f32_16x16x32_bf16 v[60:63], v[132:135], v[180:183], v[60:63]
	v_mfma_f32_16x16x32_bf16 v[56:59], v[140:143], v[180:183], v[56:59]
	v_mfma_f32_16x16x32_bf16 v[48:51], v[132:135], v[188:191], v[48:51]
	v_mfma_f32_16x16x32_bf16 v[40:43], v[140:143], v[188:191], v[40:43]
	v_mfma_f32_16x16x32_bf16 v[28:31], v[132:135], v[202:205], v[28:31]
	v_mfma_f32_16x16x32_bf16 v[24:27], v[140:143], v[202:205], v[24:27]
	v_mfma_f32_16x16x32_bf16 v[16:19], v[132:135], v[210:213], v[16:19]
	v_mfma_f32_16x16x32_bf16 v[8:11], v[140:143], v[210:213], v[8:11]
	s_setprio 0
	s_setprio 1
	v_mfma_f32_16x16x32_bf16 v[52:55], v[160:163], v[176:179], v[52:55]
	v_mfma_f32_16x16x32_bf16 v[44:47], v[168:171], v[176:179], v[44:47]
	v_mfma_f32_16x16x32_bf16 v[36:39], v[160:163], v[184:187], v[36:39]
	v_mfma_f32_16x16x32_bf16 v[32:35], v[168:171], v[184:187], v[32:35]
	v_mfma_f32_16x16x32_bf16 v[20:23], v[160:163], v[198:201], v[20:23]
	v_mfma_f32_16x16x32_bf16 v[12:15], v[168:171], v[198:201], v[12:15]
	v_mfma_f32_16x16x32_bf16 v[4:7], v[160:163], v[206:209], v[4:7]
	v_mfma_f32_16x16x32_bf16 v[0:3], v[168:171], v[206:209], v[0:3]
	v_mfma_f32_16x16x32_bf16 v[52:55], v[164:167], v[180:183], v[52:55]
	v_mfma_f32_16x16x32_bf16 v[44:47], v[172:175], v[180:183], v[44:47]
	v_mfma_f32_16x16x32_bf16 v[36:39], v[164:167], v[188:191], v[36:39]
	v_mfma_f32_16x16x32_bf16 v[32:35], v[172:175], v[188:191], v[32:35]
	v_mfma_f32_16x16x32_bf16 v[20:23], v[164:167], v[202:205], v[20:23]
	v_mfma_f32_16x16x32_bf16 v[12:15], v[172:175], v[202:205], v[12:15]
	v_mfma_f32_16x16x32_bf16 v[4:7], v[164:167], v[210:213], v[4:7]
	v_mfma_f32_16x16x32_bf16 v[0:3], v[172:175], v[210:213], v[0:3]
	s_setprio 0
	s_barrier
	s_add_i32 s60, s60, 2
	s_add_u32 s58, s58, 0x100
	s_addc_u32 s59, s59, 0
	s_cmp_gt_u32 s60, 41
	s_mov_b64 s[24:25], s[22:23]
	s_cbranch_scc0 .LBB0_1586
	s_cmpk_gt_i32 s8, 0xff
	s_cselect_b64 s[24:25], -1, 0
	s_mov_b64 s[26:27], 0x18000
	s_and_b64 vcc, exec, s[24:25]
	v_mbcnt_lo_u32_b32 v160, -1, 0
	v_mbcnt_hi_u32_b32 v160, -1, v160
	s_cbranch_vccnz .LBB0_1589
	s_ashr_i32 s22, s8, 31
	s_lshr_b32 s22, s22, 28
	s_add_i32 s22, s8, s22
	s_ashr_i32 s22, s22, 4
	s_mul_hi_i32 s27, s22, 0x1800
	s_mul_i32 s26, s22, 0x1800

; #define PG8_STAGE(bufoff, gbase, voff) do { _Pragma("unroll") for (int _i = 0; _i < 2; ++_i) \
;         __builtin_amdgcn_global_load_lds((const unsigned*)((const char*)(gbase) + (voff)[_i]), (PG8_LAS unsigned*)(lds + (bufoff) + ldsw + _i * 8192), 16, 0, 0); } while (0)
; #define PG8_LDA(dst, b, h) do { _Pragma("unroll") for (int m = 0; m < 4; ++m) _Pragma("unroll") for (int k = 0; k < 2; ++k) dst[m][k] = *(const PG8_LAS bf16x8*)(lds + PG8_SA(b, h) + aoff + m * 2048 + k * 1024); } while (0)
; #define PG8_LDB(dst, b, h) do { _Pragma("unroll") for (int n = 0; n < 2; ++n) _Pragma("unroll") for (int k = 0; k < 2; ++k) dst[n][k] = *(const PG8_LAS bf16x8*)(lds + PG8_SB(b, h) + boff + n * 2048 + k * 1024); } while (0)
; #define PG8_MMA(ai, bj, At, Bt) do { __builtin_amdgcn_s_setprio(1); _Pragma("unroll") for (int m = 0; m < 4; ++m) _Pragma("unroll") for (int n = 0; n < 2; ++n) _Pragma("unroll") for (int k = 0; k < 2; ++k) \
;         acc[ai][bj][m][n] = __builtin_amdgcn_mfma_f32_16x16x32_bf16(Bt[n][k], At[m][k], acc[ai][bj][m][n], 0, 0, 0); __builtin_amdgcn_s_setprio(0); } while (0)
; #define PG8_WAIT_V(n) asm volatile("s_waitcnt vmcnt(" #n ")" ::: "memory")
; #define PG8_WAIT_L(n) asm volatile("s_waitcnt lgkmcnt(" #n ")" ::: "memory")
; #define PG8_BAR __builtin_amdgcn_s_barrier()
; #define PG8_SCHED __builtin_amdgcn_sched_barrier(0)
; template <class Epi, class Sched, bool ALIGN_EPI = false, bool SP2 = false>
; __device__ __forceinline__ void gemm_phase(PG8_LAS unsigned char* lds, const Gemm g, const Sched& S, const Epi& E, const int wave_s) {
;     ...
;             const bool last = (t == nt - 2);
;             const char* a1 = cA + (size_t)(t + 1) * kstep;
;             const char* a2 = last ? nA : cA + (size_t)(t + 2) * kstep; const char* b2 = last ? nB : cB + (size_t)(t + 2) * kstep;
;             const char* a3 = a2 + kstep; const char* b3 = b2 + kstep;
;             if (last && has_next) S.a_ready(nxt);
;             if constexpr (SP2) {
;             PG8_LDB(B0, 0, 0); PG8_LDB(B1, 0, 1); PG8_SCHED; PG8_LDA(At, 0, 0); PG8_STAGE(PG8_SA(1, 1), a1 + hstep, voffA);
;             PG8_WAIT_V(8); PG8_WAIT_L(0); PG8_BAR; PG8_MMA(0, 0, At, B0); PG8_MMA(0, 1, At, B1); PG8_BAR; PG8_SCHED;
;             PG8_LDA(At, 0, 1); PG8_STAGE(PG8_SB(0, 0), b2, voffB); PG8_STAGE(PG8_SB(0, 1), b2 + hstep, voffB); PG8_STAGE(PG8_SA(0, 0), a2, voffA);
.LBB0_2338:
	ds_read_b128 v[128:131], v195
	ds_read_b128 v[132:135], v195 offset:1024
	ds_read_b128 v[136:139], v195 offset:2048
	ds_read_b128 v[140:143], v195 offset:3072
	ds_read_b128 v[160:163], v196
	ds_read_b128 v[164:167], v196 offset:1024
	ds_read_b128 v[168:171], v196 offset:2048
	ds_read_b128 v[172:175], v196 offset:3072
	s_add_u32 s24, s22, 0x100
	s_addc_u32 s25, s23, 0
	s_cmp_eq_u32 s60, 40
	s_cselect_b32 s29, s9, s25
	s_cselect_b32 s28, s8, s24
	s_cselect_b32 s27, s15, s59
	s_cselect_b32 s26, s14, s58
	v_lshl_add_u64 v[156:157], s[22:23], 0, v[154:155]
	s_add_i32 m0, s37, 0xc000
	ds_read_b128 v[176:179], v197
	ds_read_b128 v[180:183], v197 offset:1024
	ds_read_b128 v[184:187], v197 offset:2048
	ds_read_b128 v[188:191], v197 offset:3072
	ds_read_b128 v[198:201], v197 offset:4096
	ds_read_b128 v[202:205], v197 offset:5120
	ds_read_b128 v[206:209], v197 offset:6144
	ds_read_b128 v[210:213], v197 offset:7168
	global_load_lds_dwordx4 v[156:157], off
	v_lshl_add_u64 v[156:157], s[22:23], 0, v[152:153]
	s_add_i32 m0, s37, 0xe000
	s_nop 0
	global_load_lds_dwordx4 v[156:157], off
	v_lshl_add_u64 v[230:231], s[26:27], 0, v[148:149]
	v_lshl_add_u64 v[232:233], s[26:27], 0, v[144:145]
	v_lshl_add_u64 v[234:235], s[28:29], 0, v[146:147]
	s_waitcnt vmcnt(8)
	s_waitcnt lgkmcnt(0)
	s_barrier
	s_setprio 1
	s_waitcnt lgkmcnt(0)
	v_mfma_f32_16x16x32_bf16 v[124:127], v[128:131], v[176:179], v[124:127]
	v_mfma_f32_16x16x32_bf16 v[120:123], v[136:139], v[176:179], v[120:123]
	v_mfma_f32_16x16x32_bf16 v[112:115], v[128:131], v[184:187], v[112:115]
	v_mfma_f32_16x16x32_bf16 v[104:107], v[136:139], v[184:187], v[104:107]
	v_mfma_f32_16x16x32_bf16 v[92:95], v[128:131], v[198:201], v[92:95]
	v_mfma_f32_16x16x32_bf16 v[88:91], v[136:139], v[198:201], v[88:91]
	v_mfma_f32_16x16x32_bf16 v[80:83], v[128:131], v[206:209], v[80:83]
	v_mfma_f32_16x16x32_bf16 v[72:75], v[136:139], v[206:209], v[72:75]
	v_mfma_f32_16x16x32_bf16 v[124:127], v[132:135], v[180:183], v[124:127]
	v_mfma_f32_16x16x32_bf16 v[120:123], v[140:143], v[180:183], v[120:123]
	v_mfma_f32_16x16x32_bf16 v[112:115], v[132:135], v[188:191], v[112:115]
	v_mfma_f32_16x16x32_bf16 v[104:107], v[140:143], v[188:191], v[104:107]
	v_mfma_f32_16x16x32_bf16 v[92:95], v[132:135], v[202:205], v[92:95]
	v_mfma_f32_16x16x32_bf16 v[88:91], v[140:143], v[202:205], v[88:91]
	v_mfma_f32_16x16x32_bf16 v[80:83], v[132:135], v[210:213], v[80:83]
	v_mfma_f32_16x16x32_bf16 v[72:75], v[140:143], v[210:213], v[72:75]
	s_setprio 0
	s_setprio 1
	v_mfma_f32_16x16x32_bf16 v[116:119], v[160:163], v[176:179], v[116:119]
	v_mfma_f32_16x16x32_bf16 v[108:111], v[168:171], v[176:179], v[108:111]
	v_mfma_f32_16x16x32_bf16 v[100:103], v[160:163], v[184:187], v[100:103]
	v_mfma_f32_16x16x32_bf16 v[96:99], v[168:171], v[184:187], v[96:99]
	v_mfma_f32_16x16x32_bf16 v[84:87], v[160:163], v[198:201], v[84:87]
	v_mfma_f32_16x16x32_bf16 v[76:79], v[168:171], v[198:201], v[76:79]
	v_mfma_f32_16x16x32_bf16 v[68:71], v[160:163], v[206:209], v[68:71]
	v_mfma_f32_16x16x32_bf16 v[64:67], v[168:171], v[206:209], v[64:67]
	v_mfma_f32_16x16x32_bf16 v[116:119], v[164:167], v[180:183], v[116:119]
	v_mfma_f32_16x16x32_bf16 v[108:111], v[172:175], v[180:183], v[108:111]
	v_mfma_f32_16x16x32_bf16 v[100:103], v[164:167], v[188:191], v[100:103]
	v_mfma_f32_16x16x32_bf16 v[96:99], v[172:175], v[188:191], v[96:99]
	v_mfma_f32_16x16x32_bf16 v[84:87], v[164:167], v[202:205], v[84:87]
	v_mfma_f32_16x16x32_bf16 v[76:79], v[172:175], v[202:205], v[76:79]
	v_mfma_f32_16x16x32_bf16 v[68:71], v[164:167], v[210:213], v[68:71]
	v_mfma_f32_16x16x32_bf16 v[64:67], v[172:175], v[210:213], v[64:67]
	s_setprio 0
	s_barrier
	s_add_i32 s22, s52, s33
	s_mov_b32 m0, s22
	ds_read_b128 v[176:179], v197 offset:16384
	ds_read_b128 v[180:183], v197 offset:17408
	ds_read_b128 v[184:187], v197 offset:18432
	ds_read_b128 v[188:191], v197 offset:19456
	ds_read_b128 v[198:201], v197 offset:20480
	ds_read_b128 v[202:205], v197 offset:21504
	ds_read_b128 v[206:209], v197 offset:22528
	ds_read_b128 v[210:213], v197 offset:23552
	global_load_lds_dwordx4 v[230:231], off
	s_add_i32 m0, s22, 0x2000
	s_add_u32 s22, s26, 0xb0000
	s_addc_u32 s23, s27, 0
	s_add_i32 s61, s53, s33
	global_load_lds_dwordx4 v[232:233], off
	v_lshl_add_u64 v[214:215], s[22:23], 0, v[148:149]
	s_mov_b32 m0, s61
	s_nop 0
	global_load_lds_dwordx4 v[214:215], off
	v_lshl_add_u64 v[214:215], s[22:23], 0, v[144:145]
	s_add_i32 m0, s61, 0x2000
	s_nop 0
	global_load_lds_dwordx4 v[214:215], off
	v_lshl_add_u64 v[214:215], s[28:29], 0, v[150:151]
	s_mov_b32 m0, s37
	s_nop 0
	global_load_lds_dwordx4 v[214:215], off
	s_mov_b32 m0, s38
	s_nop 0
	global_load_lds_dwordx4 v[234:235], off
	s_waitcnt vmcnt(8)
	s_waitcnt lgkmcnt(0)
	s_barrier
; #define PG8_STAGE(bufoff, gbase, voff) do { _Pragma("unroll") for (int _i = 0; _i < 2; ++_i) \
;         __builtin_amdgcn_global_load_lds((const unsigned*)((const char*)(gbase) + (voff)[_i]), (PG8_LAS unsigned*)(lds + (bufoff) + ldsw + _i * 8192), 16, 0, 0); } while (0)
; #define PG8_LDA(dst, b, h) do { _Pragma("unroll") for (int m = 0; m < 4; ++m) _Pragma("unroll") for (int k = 0; k < 2; ++k) dst[m][k] = *(const PG8_LAS bf16x8*)(lds + PG8_SA(b, h) + aoff + m * 2048 + k * 1024); } while (0)
; #define PG8_LDB(dst, b, h) do { _Pragma("unroll") for (int n = 0; n < 2; ++n) _Pragma("unroll") for (int k = 0; k < 2; ++k) dst[n][k] = *(const PG8_LAS bf16x8*)(lds + PG8_SB(b, h) + boff + n * 2048 + k * 1024); } while (0)
; #define PG8_MMA(ai, bj, At, Bt) do { __builtin_amdgcn_s_setprio(1); _Pragma("unroll") for (int m = 0; m < 4; ++m) _Pragma("unroll") for (int n = 0; n < 2; ++n) _Pragma("unroll") for (int k = 0; k < 2; ++k) \
;         acc[ai][bj][m][n] = __builtin_amdgcn_mfma_f32_16x16x32_bf16(Bt[n][k], At[m][k], acc[ai][bj][m][n], 0, 0, 0); __builtin_amdgcn_s_setprio(0); } while (0)
; #define PG8_WAIT_V(n) asm volatile("s_waitcnt vmcnt(" #n ")" ::: "memory")
; #define PG8_WAIT_L(n) asm volatile("s_waitcnt lgkmcnt(" #n ")" ::: "memory")
; #define PG8_BAR __builtin_amdgcn_s_barrier()
; #define PG8_SCHED __builtin_amdgcn_sched_barrier(0)
; template <class Epi, class Sched, bool ALIGN_EPI = false, bool SP2 = false>
; __device__ __forceinline__ void gemm_phase(PG8_LAS unsigned char* lds, const Gemm g, const Sched& S, const Epi& E, const int wave_s) {
;     ...
;             PG8_WAIT_V(8); PG8_WAIT_L(0); PG8_BAR; PG8_MMA(1, 0, At, B0); PG8_MMA(1, 1, At, B1); PG8_BAR; PG8_SCHED;
;             PG8_LDB(B0, 1, 0); PG8_LDB(B1, 1, 1); PG8_SCHED; PG8_LDA(At, 1, 0); PG8_STAGE(PG8_SA(0, 1), a2 + hstep, voffA);
;             PG8_WAIT_V(8); PG8_WAIT_L(0); PG8_BAR; PG8_MMA(0, 0, At, B0); PG8_MMA(0, 1, At, B1); PG8_BAR; PG8_SCHED;
	s_setprio 1
	s_waitcnt lgkmcnt(0)
	v_mfma_f32_16x16x32_bf16 v[60:63], v[128:131], v[176:179], v[60:63]
	v_mfma_f32_16x16x32_bf16 v[56:59], v[136:139], v[176:179], v[56:59]
	v_mfma_f32_16x16x32_bf16 v[48:51], v[128:131], v[184:187], v[48:51]
	v_mfma_f32_16x16x32_bf16 v[40:43], v[136:139], v[184:187], v[40:43]
	v_mfma_f32_16x16x32_bf16 v[28:31], v[128:131], v[198:201], v[28:31]
	v_mfma_f32_16x16x32_bf16 v[24:27], v[136:139], v[198:201], v[24:27]
	v_mfma_f32_16x16x32_bf16 v[16:19], v[128:131], v[206:209], v[16:19]
	v_mfma_f32_16x16x32_bf16 v[8:11], v[136:139], v[206:209], v[8:11]
	v_mfma_f32_16x16x32_bf16 v[60:63], v[132:135], v[180:183], v[60:63]
	v_mfma_f32_16x16x32_bf16 v[56:59], v[140:143], v[180:183], v[56:59]
	v_mfma_f32_16x16x32_bf16 v[48:51], v[132:135], v[188:191], v[48:51]
	v_mfma_f32_16x16x32_bf16 v[40:43], v[140:143], v[188:191], v[40:43]
	v_mfma_f32_16x16x32_bf16 v[28:31], v[132:135], v[202:205], v[28:31]
	v_mfma_f32_16x16x32_bf16 v[24:27], v[140:143], v[202:205], v[24:27]
	v_mfma_f32_16x16x32_bf16 v[16:19], v[132:135], v[210:213], v[16:19]
	v_mfma_f32_16x16x32_bf16 v[8:11], v[140:143], v[210:213], v[8:11]
	s_setprio 0
	s_setprio 1
	v_mfma_f32_16x16x32_bf16 v[52:55], v[160:163], v[176:179], v[52:55]
	v_mfma_f32_16x16x32_bf16 v[44:47], v[168:171], v[176:179], v[44:47]
	v_mfma_f32_16x16x32_bf16 v[36:39], v[160:163], v[184:187], v[36:39]
	v_mfma_f32_16x16x32_bf16 v[32:35], v[168:171], v[184:187], v[32:35]
	v_mfma_f32_16x16x32_bf16 v[20:23], v[160:163], v[198:201], v[20:23]
	v_mfma_f32_16x16x32_bf16 v[12:15], v[168:171], v[198:201], v[12:15]
	v_mfma_f32_16x16x32_bf16 v[4:7], v[160:163], v[206:209], v[4:7]
	v_mfma_f32_16x16x32_bf16 v[0:3], v[168:171], v[206:209], v[0:3]
	v_mfma_f32_16x16x32_bf16 v[52:55], v[164:167], v[180:183], v[52:55]
	v_mfma_f32_16x16x32_bf16 v[44:47], v[172:175], v[180:183], v[44:47]
	v_mfma_f32_16x16x32_bf16 v[36:39], v[164:167], v[188:191], v[36:39]
	v_mfma_f32_16x16x32_bf16 v[32:35], v[172:175], v[188:191], v[32:35]
	v_mfma_f32_16x16x32_bf16 v[20:23], v[164:167], v[202:205], v[20:23]
	v_mfma_f32_16x16x32_bf16 v[12:15], v[172:175], v[202:205], v[12:15]
	v_mfma_f32_16x16x32_bf16 v[4:7], v[164:167], v[210:213], v[4:7]
	v_mfma_f32_16x16x32_bf16 v[0:3], v[172:175], v[210:213], v[0:3]
	s_setprio 0
	s_barrier
	s_add_i32 s61, 0, 0x18000
	s_add_i32 s62, 0, 0x1c000
	v_add_u32_e32 v140, s61, v194
	v_add_u32_e32 v172, s62, v194
	ds_read_b128 v[128:131], v140
	ds_read_b128 v[132:135], v140 offset:1024
	ds_read_b128 v[136:139], v140 offset:2048
	ds_read_b128 v[140:143], v140 offset:3072
	ds_read_b128 v[160:163], v172
	ds_read_b128 v[164:167], v172 offset:1024
	ds_read_b128 v[168:171], v172 offset:2048
	ds_read_b128 v[172:175], v172 offset:3072
	s_add_u32 s22, s28, 0xb0000
	s_addc_u32 s23, s29, 0
	s_mov_b32 m0, s39
	v_lshl_add_u64 v[218:219], s[22:23], 0, v[150:151]
	ds_read_b128 v[176:179], v197 offset:32768
	ds_read_b128 v[180:183], v197 offset:33792
	ds_read_b128 v[184:187], v197 offset:34816
	ds_read_b128 v[188:191], v197 offset:35840
	ds_read_b128 v[198:201], v197 offset:36864
	ds_read_b128 v[202:205], v197 offset:37888
	ds_read_b128 v[206:209], v197 offset:38912
	ds_read_b128 v[210:213], v197 offset:39936
	global_load_lds_dwordx4 v[218:219], off
	v_lshl_add_u64 v[218:219], s[22:23], 0, v[146:147]
	s_mov_b32 m0, s40
	s_nop 0
	global_load_lds_dwordx4 v[218:219], off
	v_lshl_add_u64 v[236:237], v[230:231], 0, s[12:13]
	v_lshl_add_u64 v[238:239], v[232:233], 0, s[12:13]
	s_waitcnt vmcnt(8)
	s_waitcnt lgkmcnt(0)
	s_barrier
	s_setprio 1
	s_waitcnt lgkmcnt(0)
	v_mfma_f32_16x16x32_bf16 v[124:127], v[128:131], v[176:179], v[124:127]
	v_mfma_f32_16x16x32_bf16 v[120:123], v[136:139], v[176:179], v[120:123]
	v_mfma_f32_16x16x32_bf16 v[112:115], v[128:131], v[184:187], v[112:115]
	v_mfma_f32_16x16x32_bf16 v[104:107], v[136:139], v[184:187], v[104:107]
	v_mfma_f32_16x16x32_bf16 v[92:95], v[128:131], v[198:201], v[92:95]
	v_mfma_f32_16x16x32_bf16 v[88:91], v[136:139], v[198:201], v[88:91]
	v_mfma_f32_16x16x32_bf16 v[80:83], v[128:131], v[206:209], v[80:83]
	v_mfma_f32_16x16x32_bf16 v[72:75], v[136:139], v[206:209], v[72:75]
	v_mfma_f32_16x16x32_bf16 v[124:127], v[132:135], v[180:183], v[124:127]
	v_mfma_f32_16x16x32_bf16 v[120:123], v[140:143], v[180:183], v[120:123]
	v_mfma_f32_16x16x32_bf16 v[112:115], v[132:135], v[188:191], v[112:115]
	v_mfma_f32_16x16x32_bf16 v[104:107], v[140:143], v[188:191], v[104:107]
	v_mfma_f32_16x16x32_bf16 v[92:95], v[132:135], v[202:205], v[92:95]
	v_mfma_f32_16x16x32_bf16 v[88:91], v[140:143], v[202:205], v[88:91]
	v_mfma_f32_16x16x32_bf16 v[80:83], v[132:135], v[210:213], v[80:83]
	v_mfma_f32_16x16x32_bf16 v[72:75], v[140:143], v[210:213], v[72:75]
	s_setprio 0
	s_setprio 1
	v_mfma_f32_16x16x32_bf16 v[116:119], v[160:163], v[176:179], v[116:119]
	v_mfma_f32_16x16x32_bf16 v[108:111], v[168:171], v[176:179], v[108:111]
	v_mfma_f32_16x16x32_bf16 v[100:103], v[160:163], v[184:187], v[100:103]
	v_mfma_f32_16x16x32_bf16 v[96:99], v[168:171], v[184:187], v[96:99]
	v_mfma_f32_16x16x32_bf16 v[84:87], v[160:163], v[198:201], v[84:87]
	v_mfma_f32_16x16x32_bf16 v[76:79], v[168:171], v[198:201], v[76:79]
	v_mfma_f32_16x16x32_bf16 v[68:71], v[160:163], v[206:209], v[68:71]
	v_mfma_f32_16x16x32_bf16 v[64:67], v[168:171], v[206:209], v[64:67]
	v_mfma_f32_16x16x32_bf16 v[116:119], v[164:167], v[180:183], v[116:119]
	v_mfma_f32_16x16x32_bf16 v[108:111], v[172:175], v[180:183], v[108:111]
	v_mfma_f32_16x16x32_bf16 v[100:103], v[164:167], v[188:191], v[100:103]
	v_mfma_f32_16x16x32_bf16 v[96:99], v[172:175], v[188:191], v[96:99]
	v_mfma_f32_16x16x32_bf16 v[84:87], v[164:167], v[202:205], v[84:87]
	v_mfma_f32_16x16x32_bf16 v[76:79], v[172:175], v[202:205], v[76:79]
	v_mfma_f32_16x16x32_bf16 v[68:71], v[164:167], v[210:213], v[68:71]
	v_mfma_f32_16x16x32_bf16 v[64:67], v[172:175], v[210:213], v[64:67]
	s_setprio 0
	s_barrier
; #define PG8_STAGE(bufoff, gbase, voff) do { _Pragma("unroll") for (int _i = 0; _i < 2; ++_i) \
;         __builtin_amdgcn_global_load_lds((const unsigned*)((const char*)(gbase) + (voff)[_i]), (PG8_LAS unsigned*)(lds + (bufoff) + ldsw + _i * 8192), 16, 0, 0); } while (0)
; #define PG8_LDA(dst, b, h) do { _Pragma("unroll") for (int m = 0; m < 4; ++m) _Pragma("unroll") for (int k = 0; k < 2; ++k) dst[m][k] = *(const PG8_LAS bf16x8*)(lds + PG8_SA(b, h) + aoff + m * 2048 + k * 1024); } while (0)
; #define PG8_MMA(ai, bj, At, Bt) do { __builtin_amdgcn_s_setprio(1); _Pragma("unroll") for (int m = 0; m < 4; ++m) _Pragma("unroll") for (int n = 0; n < 2; ++n) _Pragma("unroll") for (int k = 0; k < 2; ++k) \
;         acc[ai][bj][m][n] = __builtin_amdgcn_mfma_f32_16x16x32_bf16(Bt[n][k], At[m][k], acc[ai][bj][m][n], 0, 0, 0); __builtin_amdgcn_s_setprio(0); } while (0)
; #define PG8_WAIT_V(n) asm volatile("s_waitcnt vmcnt(" #n ")" ::: "memory")
; #define PG8_WAIT_L(n) asm volatile("s_waitcnt lgkmcnt(" #n ")" ::: "memory")
; #define PG8_BAR __builtin_amdgcn_s_barrier()
; #define PG8_SCHED __builtin_amdgcn_sched_barrier(0)
; template <class Epi, class Sched, bool ALIGN_EPI = false, bool SP2 = false>
; __device__ __forceinline__ void gemm_phase(PG8_LAS unsigned char* lds, const Gemm g, const Sched& S, const Epi& E, const int wave_s) {
;     ...
;             PG8_LDA(At, 1, 1); PG8_STAGE(PG8_SB(1, 0), b3, voffB); PG8_STAGE(PG8_SB(1, 1), b3 + hstep, voffB); PG8_STAGE(PG8_SA(1, 0), a3, voffA);
;             PG8_WAIT_V(8); PG8_WAIT_L(0); PG8_BAR; PG8_MMA(1, 0, At, B0); PG8_MMA(1, 1, At, B1); PG8_BAR; PG8_SCHED;
;     __device__ __forceinline__ void operator()(const af4 (&acc)[2][2][4][2], const pg8::Unit& u, int wr, int wc, int fr_, int fq_) const {
;     ...
;         const int grow = rowbase + u.pm * 256; const int bi = grow < TL ? grow / LSEQ : NB;
;         float* xb = grow < TL ? xl + (size_t)grow * DM : xc + (size_t)(grow - TL) * DM;
;         const float* stb = stats + 2 * (size_t)grow;
;         const int col0 = u.pn * 256 + wc * 32 + 8 * fq; const float* gp = gate + (size_t)bi * 6144 + col0;
	s_add_i32 s22, s61, s33
	s_mov_b32 m0, s22
	ds_read_b128 v[176:179], v197 offset:49152
	ds_read_b128 v[180:183], v197 offset:50176
	ds_read_b128 v[184:187], v197 offset:51200
	ds_read_b128 v[188:191], v197 offset:52224
	ds_read_b128 v[198:201], v197 offset:53248
	ds_read_b128 v[202:205], v197 offset:54272
	ds_read_b128 v[206:209], v197 offset:55296
	ds_read_b128 v[210:213], v197 offset:56320
	global_load_lds_dwordx4 v[236:237], off
	s_add_i32 m0, s22, 0x2000
	s_add_u32 s22, s26, 0xb0080
	s_addc_u32 s23, s27, 0
	s_add_i32 s26, s62, s33
	global_load_lds_dwordx4 v[238:239], off
	v_lshl_add_u64 v[156:157], s[22:23], 0, v[148:149]
	s_mov_b32 m0, s26
	s_nop 0
	global_load_lds_dwordx4 v[156:157], off
	v_lshl_add_u64 v[156:157], s[22:23], 0, v[144:145]
	s_add_i32 m0, s26, 0x2000
	s_nop 0
	global_load_lds_dwordx4 v[156:157], off
	v_lshl_add_u64 v[156:157], v[214:215], 0, s[12:13]
	s_mov_b32 m0, s48
	s_nop 0
	global_load_lds_dwordx4 v[156:157], off
	v_lshl_add_u64 v[156:157], v[234:235], 0, s[12:13]
	s_mov_b32 m0, s49
	s_nop 0
	global_load_lds_dwordx4 v[156:157], off
	s_waitcnt vmcnt(8)
	s_waitcnt lgkmcnt(0)
	s_barrier
	s_setprio 1
	s_waitcnt lgkmcnt(0)
	v_mfma_f32_16x16x32_bf16 v[60:63], v[128:131], v[176:179], v[60:63]
	v_mfma_f32_16x16x32_bf16 v[56:59], v[136:139], v[176:179], v[56:59]
	v_mfma_f32_16x16x32_bf16 v[48:51], v[128:131], v[184:187], v[48:51]
	v_mfma_f32_16x16x32_bf16 v[40:43], v[136:139], v[184:187], v[40:43]
	v_mfma_f32_16x16x32_bf16 v[28:31], v[128:131], v[198:201], v[28:31]
	v_mfma_f32_16x16x32_bf16 v[24:27], v[136:139], v[198:201], v[24:27]
	v_mfma_f32_16x16x32_bf16 v[16:19], v[128:131], v[206:209], v[16:19]
	v_mfma_f32_16x16x32_bf16 v[8:11], v[136:139], v[206:209], v[8:11]
	v_mfma_f32_16x16x32_bf16 v[60:63], v[132:135], v[180:183], v[60:63]
	v_mfma_f32_16x16x32_bf16 v[56:59], v[140:143], v[180:183], v[56:59]
	v_mfma_f32_16x16x32_bf16 v[48:51], v[132:135], v[188:191], v[48:51]
	v_mfma_f32_16x16x32_bf16 v[40:43], v[140:143], v[188:191], v[40:43]
	v_mfma_f32_16x16x32_bf16 v[28:31], v[132:135], v[202:205], v[28:31]
	v_mfma_f32_16x16x32_bf16 v[24:27], v[140:143], v[202:205], v[24:27]
	v_mfma_f32_16x16x32_bf16 v[16:19], v[132:135], v[210:213], v[16:19]
	v_mfma_f32_16x16x32_bf16 v[8:11], v[140:143], v[210:213], v[8:11]
	s_setprio 0
	s_setprio 1
	v_mfma_f32_16x16x32_bf16 v[52:55], v[160:163], v[176:179], v[52:55]
	v_mfma_f32_16x16x32_bf16 v[44:47], v[168:171], v[176:179], v[44:47]
	v_mfma_f32_16x16x32_bf16 v[36:39], v[160:163], v[184:187], v[36:39]
	v_mfma_f32_16x16x32_bf16 v[32:35], v[168:171], v[184:187], v[32:35]
	v_mfma_f32_16x16x32_bf16 v[20:23], v[160:163], v[198:201], v[20:23]
	v_mfma_f32_16x16x32_bf16 v[12:15], v[168:171], v[198:201], v[12:15]
	v_mfma_f32_16x16x32_bf16 v[4:7], v[160:163], v[206:209], v[4:7]
	v_mfma_f32_16x16x32_bf16 v[0:3], v[168:171], v[206:209], v[0:3]
	v_mfma_f32_16x16x32_bf16 v[52:55], v[164:167], v[180:183], v[52:55]
	v_mfma_f32_16x16x32_bf16 v[44:47], v[172:175], v[180:183], v[44:47]
	v_mfma_f32_16x16x32_bf16 v[36:39], v[164:167], v[188:191], v[36:39]
	v_mfma_f32_16x16x32_bf16 v[32:35], v[172:175], v[188:191], v[32:35]
	v_mfma_f32_16x16x32_bf16 v[20:23], v[164:167], v[202:205], v[20:23]
	v_mfma_f32_16x16x32_bf16 v[12:15], v[172:175], v[202:205], v[12:15]
	v_mfma_f32_16x16x32_bf16 v[4:7], v[164:167], v[210:213], v[4:7]
	v_mfma_f32_16x16x32_bf16 v[0:3], v[172:175], v[210:213], v[0:3]
	s_setprio 0
	s_barrier
	s_add_i32 s60, s60, 2
	s_add_u32 s58, s58, 0x100
	s_addc_u32 s59, s59, 0
	s_cmp_gt_u32 s60, 41
	s_mov_b64 s[22:23], s[24:25]
	s_cbranch_scc0 .LBB0_2338
	s_cmpk_gt_i32 s10, 0xff
	s_cselect_b64 s[24:25], -1, 0
	s_mov_b64 s[26:27], 0x18000
	s_and_b64 vcc, exec, s[24:25]
	v_mbcnt_lo_u32_b32 v160, -1, 0
	v_mbcnt_hi_u32_b32 v160, -1, v160
	s_cbranch_vccnz .LBB0_2341
	s_ashr_i32 s22, s10, 31
	s_lshr_b32 s22, s22, 28
	s_add_i32 s22, s10, s22
	s_ashr_i32 s22, s22, 4
	s_mul_hi_i32 s27, s22, 0x1800
	s_mul_i32 s26, s22, 0x1800

; #define PG8_STAGE(bufoff, gbase, voff) do { _Pragma("unroll") for (int _i = 0; _i < 2; ++_i) \
;         __builtin_amdgcn_global_load_lds((const unsigned*)((const char*)(gbase) + (voff)[_i]), (PG8_LAS unsigned*)(lds + (bufoff) + ldsw + _i * 8192), 16, 0, 0); } while (0)
; #define PG8_LDA(dst, b, h) do { _Pragma("unroll") for (int m = 0; m < 4; ++m) _Pragma("unroll") for (int k = 0; k < 2; ++k) dst[m][k] = *(const PG8_LAS bf16x8*)(lds + PG8_SA(b, h) + aoff + m * 2048 + k * 1024); } while (0)
; #define PG8_LDB(dst, b, h) do { _Pragma("unroll") for (int n = 0; n < 2; ++n) _Pragma("unroll") for (int k = 0; k < 2; ++k) dst[n][k] = *(const PG8_LAS bf16x8*)(lds + PG8_SB(b, h) + boff + n * 2048 + k * 1024); } while (0)
; #define PG8_MMA(ai, bj, At, Bt) do { __builtin_amdgcn_s_setprio(1); _Pragma("unroll") for (int m = 0; m < 4; ++m) _Pragma("unroll") for (int n = 0; n < 2; ++n) _Pragma("unroll") for (int k = 0; k < 2; ++k) \
;         acc[ai][bj][m][n] = __builtin_amdgcn_mfma_f32_16x16x32_bf16(Bt[n][k], At[m][k], acc[ai][bj][m][n], 0, 0, 0); __builtin_amdgcn_s_setprio(0); } while (0)
; #define PG8_WAIT_V(n) asm volatile("s_waitcnt vmcnt(" #n ")" ::: "memory")
; #define PG8_WAIT_L(n) asm volatile("s_waitcnt lgkmcnt(" #n ")" ::: "memory")
; #define PG8_BAR __builtin_amdgcn_s_barrier()
; #define PG8_SCHED __builtin_amdgcn_sched_barrier(0)
; template <class Epi, class Sched, bool ALIGN_EPI = false, bool SP2 = false>
; __device__ __forceinline__ void gemm_phase(PG8_LAS unsigned char* lds, const Gemm g, const Sched& S, const Epi& E, const int wave_s) {
;     ...
;             const bool last = (t == nt - 2);
;             const char* a1 = cA + (size_t)(t + 1) * kstep;
;             const char* a2 = last ? nA : cA + (size_t)(t + 2) * kstep; const char* b2 = last ? nB : cB + (size_t)(t + 2) * kstep;
;             const char* a3 = a2 + kstep; const char* b3 = b2 + kstep;
;             if (last && has_next) S.a_ready(nxt);
;             if constexpr (SP2) {
;             PG8_LDB(B0, 0, 0); PG8_LDB(B1, 0, 1); PG8_SCHED; PG8_LDA(At, 0, 0); PG8_STAGE(PG8_SA(1, 1), a1 + hstep, voffA);
;             PG8_WAIT_V(8); PG8_WAIT_L(0); PG8_BAR; PG8_MMA(0, 0, At, B0); PG8_MMA(0, 1, At, B1); PG8_BAR; PG8_SCHED;
;             PG8_LDA(At, 0, 1); PG8_STAGE(PG8_SB(0, 0), b2, voffB); PG8_STAGE(PG8_SB(0, 1), b2 + hstep, voffB); PG8_STAGE(PG8_SA(0, 0), a2, voffA);
.LBB0_2638:
	ds_read_b128 v[128:131], v203
	ds_read_b128 v[132:135], v203 offset:1024
	ds_read_b128 v[136:139], v203 offset:2048
	ds_read_b128 v[140:143], v203 offset:3072
	ds_read_b128 v[144:147], v205
	ds_read_b128 v[148:151], v205 offset:1024
	ds_read_b128 v[152:155], v205 offset:2048
	ds_read_b128 v[156:159], v205 offset:3072
	s_add_u32 s30, s8, 0xfffc0080
	s_addc_u32 s31, s9, -1
	s_cmp_eq_u32 s69, 12
	s_cselect_b32 s35, s7, s31
	s_cselect_b32 s34, s25, s30
	s_cselect_b32 s31, s23, s68
	s_cselect_b32 s30, s66, s67
	v_lshl_add_u64 v[218:219], s[8:9], 0, v[186:187]
	s_add_i32 m0, s42, 0xc000
	ds_read_b128 v[160:163], v207
	ds_read_b128 v[164:167], v207 offset:1024
	ds_read_b128 v[168:171], v207 offset:2048
	ds_read_b128 v[172:175], v207 offset:3072
	ds_read_b128 v[192:195], v207 offset:4096
	ds_read_b128 v[196:199], v207 offset:5120
	ds_read_b128 v[208:211], v207 offset:6144
	ds_read_b128 v[214:217], v207 offset:7168
	global_load_lds_dwordx4 v[218:219], off
	v_lshl_add_u64 v[218:219], s[8:9], 0, v[184:185]
	s_add_i32 m0, s42, 0xe000
	s_nop 0
	global_load_lds_dwordx4 v[218:219], off
	v_lshl_add_u64 v[230:231], s[30:31], 0, v[180:181]
	v_lshl_add_u64 v[232:233], s[30:31], 0, v[176:177]
	v_lshl_add_u64 v[234:235], s[34:35], 0, v[178:179]
	s_waitcnt vmcnt(8)
	s_waitcnt lgkmcnt(0)
	s_barrier
	s_setprio 1
	s_waitcnt lgkmcnt(0)
	v_mfma_f32_16x16x32_bf16 v[124:127], v[128:131], v[160:163], v[124:127]
	v_mfma_f32_16x16x32_bf16 v[120:123], v[136:139], v[160:163], v[120:123]
	v_mfma_f32_16x16x32_bf16 v[116:119], v[128:131], v[168:171], v[116:119]
	v_mfma_f32_16x16x32_bf16 v[108:111], v[136:139], v[168:171], v[108:111]
	v_mfma_f32_16x16x32_bf16 v[100:103], v[128:131], v[192:195], v[100:103]
	v_mfma_f32_16x16x32_bf16 v[92:95], v[136:139], v[192:195], v[92:95]
	v_mfma_f32_16x16x32_bf16 v[84:87], v[128:131], v[208:211], v[84:87]
	v_mfma_f32_16x16x32_bf16 v[76:79], v[136:139], v[208:211], v[76:79]
	v_mfma_f32_16x16x32_bf16 v[124:127], v[132:135], v[164:167], v[124:127]
	v_mfma_f32_16x16x32_bf16 v[120:123], v[140:143], v[164:167], v[120:123]
	v_mfma_f32_16x16x32_bf16 v[116:119], v[132:135], v[172:175], v[116:119]
	v_mfma_f32_16x16x32_bf16 v[108:111], v[140:143], v[172:175], v[108:111]
	v_mfma_f32_16x16x32_bf16 v[100:103], v[132:135], v[196:199], v[100:103]
	v_mfma_f32_16x16x32_bf16 v[92:95], v[140:143], v[196:199], v[92:95]
	v_mfma_f32_16x16x32_bf16 v[84:87], v[132:135], v[214:217], v[84:87]
	v_mfma_f32_16x16x32_bf16 v[76:79], v[140:143], v[214:217], v[76:79]
	s_setprio 0
	s_setprio 1
	v_mfma_f32_16x16x32_bf16 v[112:115], v[144:147], v[160:163], v[112:115]
	v_mfma_f32_16x16x32_bf16 v[104:107], v[152:155], v[160:163], v[104:107]
	v_mfma_f32_16x16x32_bf16 v[96:99], v[144:147], v[168:171], v[96:99]
	v_mfma_f32_16x16x32_bf16 v[88:91], v[152:155], v[168:171], v[88:91]
	v_mfma_f32_16x16x32_bf16 v[80:83], v[144:147], v[192:195], v[80:83]
	v_mfma_f32_16x16x32_bf16 v[72:75], v[152:155], v[192:195], v[72:75]
	v_mfma_f32_16x16x32_bf16 v[68:71], v[144:147], v[208:211], v[68:71]
	v_mfma_f32_16x16x32_bf16 v[64:67], v[152:155], v[208:211], v[64:67]
	v_mfma_f32_16x16x32_bf16 v[112:115], v[148:151], v[164:167], v[112:115]
	v_mfma_f32_16x16x32_bf16 v[104:107], v[156:159], v[164:167], v[104:107]
	v_mfma_f32_16x16x32_bf16 v[96:99], v[148:151], v[172:175], v[96:99]
	v_mfma_f32_16x16x32_bf16 v[88:91], v[156:159], v[172:175], v[88:91]
	v_mfma_f32_16x16x32_bf16 v[80:83], v[148:151], v[196:199], v[80:83]
	v_mfma_f32_16x16x32_bf16 v[72:75], v[156:159], v[196:199], v[72:75]
	v_mfma_f32_16x16x32_bf16 v[68:71], v[148:151], v[214:217], v[68:71]
	v_mfma_f32_16x16x32_bf16 v[64:67], v[156:159], v[214:217], v[64:67]
	s_setprio 0
	s_barrier
	s_add_i32 s70, s61, s33
	s_mov_b32 m0, s70
	ds_read_b128 v[160:163], v207 offset:16384
	ds_read_b128 v[164:167], v207 offset:17408
	ds_read_b128 v[168:171], v207 offset:18432
	ds_read_b128 v[172:175], v207 offset:19456
	ds_read_b128 v[192:195], v207 offset:20480
	ds_read_b128 v[196:199], v207 offset:21504
	ds_read_b128 v[208:211], v207 offset:22528
	ds_read_b128 v[214:217], v207 offset:23552
	global_load_lds_dwordx4 v[230:231], off
	s_add_i32 m0, s70, 0x2000
	s_add_u32 s70, s30, 0x40000
	s_addc_u32 s71, s31, 0
	s_add_i32 s72, s62, s33
	global_load_lds_dwordx4 v[232:233], off
	v_lshl_add_u64 v[222:223], s[70:71], 0, v[180:181]
	s_mov_b32 m0, s72
	s_nop 0
	global_load_lds_dwordx4 v[222:223], off
	v_lshl_add_u64 v[222:223], s[70:71], 0, v[176:177]
	s_add_i32 m0, s72, 0x2000
	s_nop 0
	global_load_lds_dwordx4 v[222:223], off
	v_lshl_add_u64 v[222:223], s[34:35], 0, v[182:183]
	s_mov_b32 m0, s42
	s_nop 0
	global_load_lds_dwordx4 v[222:223], off
	s_mov_b32 m0, s43
	s_nop 0
	global_load_lds_dwordx4 v[234:235], off
	s_waitcnt vmcnt(8)
	s_waitcnt lgkmcnt(0)
	s_barrier
; #define PG8_STAGE(bufoff, gbase, voff) do { _Pragma("unroll") for (int _i = 0; _i < 2; ++_i) \
;         __builtin_amdgcn_global_load_lds((const unsigned*)((const char*)(gbase) + (voff)[_i]), (PG8_LAS unsigned*)(lds + (bufoff) + ldsw + _i * 8192), 16, 0, 0); } while (0)
; #define PG8_LDA(dst, b, h) do { _Pragma("unroll") for (int m = 0; m < 4; ++m) _Pragma("unroll") for (int k = 0; k < 2; ++k) dst[m][k] = *(const PG8_LAS bf16x8*)(lds + PG8_SA(b, h) + aoff + m * 2048 + k * 1024); } while (0)
; #define PG8_LDB(dst, b, h) do { _Pragma("unroll") for (int n = 0; n < 2; ++n) _Pragma("unroll") for (int k = 0; k < 2; ++k) dst[n][k] = *(const PG8_LAS bf16x8*)(lds + PG8_SB(b, h) + boff + n * 2048 + k * 1024); } while (0)
; #define PG8_MMA(ai, bj, At, Bt) do { __builtin_amdgcn_s_setprio(1); _Pragma("unroll") for (int m = 0; m < 4; ++m) _Pragma("unroll") for (int n = 0; n < 2; ++n) _Pragma("unroll") for (int k = 0; k < 2; ++k) \
;         acc[ai][bj][m][n] = __builtin_amdgcn_mfma_f32_16x16x32_bf16(Bt[n][k], At[m][k], acc[ai][bj][m][n], 0, 0, 0); __builtin_amdgcn_s_setprio(0); } while (0)
; #define PG8_WAIT_V(n) asm volatile("s_waitcnt vmcnt(" #n ")" ::: "memory")
; #define PG8_WAIT_L(n) asm volatile("s_waitcnt lgkmcnt(" #n ")" ::: "memory")
; #define PG8_BAR __builtin_amdgcn_s_barrier()
; #define PG8_SCHED __builtin_amdgcn_sched_barrier(0)
; template <class Epi, class Sched, bool ALIGN_EPI = false, bool SP2 = false>
; __device__ __forceinline__ void gemm_phase(PG8_LAS unsigned char* lds, const Gemm g, const Sched& S, const Epi& E, const int wave_s) {
;     ...
;             PG8_WAIT_V(8); PG8_WAIT_L(0); PG8_BAR; PG8_MMA(1, 0, At, B0); PG8_MMA(1, 1, At, B1); PG8_BAR; PG8_SCHED;
;             PG8_LDB(B0, 1, 0); PG8_LDB(B1, 1, 1); PG8_SCHED; PG8_LDA(At, 1, 0); PG8_STAGE(PG8_SA(0, 1), a2 + hstep, voffA);
;             PG8_WAIT_V(8); PG8_WAIT_L(0); PG8_BAR; PG8_MMA(0, 0, At, B0); PG8_MMA(0, 1, At, B1); PG8_BAR; PG8_SCHED;
	s_setprio 1
	s_waitcnt lgkmcnt(0)
	v_mfma_f32_16x16x32_bf16 v[60:63], v[128:131], v[160:163], v[60:63]
	v_mfma_f32_16x16x32_bf16 v[56:59], v[136:139], v[160:163], v[56:59]
	v_mfma_f32_16x16x32_bf16 v[52:55], v[128:131], v[168:171], v[52:55]
	v_mfma_f32_16x16x32_bf16 v[44:47], v[136:139], v[168:171], v[44:47]
	v_mfma_f32_16x16x32_bf16 v[36:39], v[128:131], v[192:195], v[36:39]
	v_mfma_f32_16x16x32_bf16 v[28:31], v[136:139], v[192:195], v[28:31]
	v_mfma_f32_16x16x32_bf16 v[20:23], v[128:131], v[208:211], v[20:23]
	v_mfma_f32_16x16x32_bf16 v[12:15], v[136:139], v[208:211], v[12:15]
	v_mfma_f32_16x16x32_bf16 v[60:63], v[132:135], v[164:167], v[60:63]
	v_mfma_f32_16x16x32_bf16 v[56:59], v[140:143], v[164:167], v[56:59]
	v_mfma_f32_16x16x32_bf16 v[52:55], v[132:135], v[172:175], v[52:55]
	v_mfma_f32_16x16x32_bf16 v[44:47], v[140:143], v[172:175], v[44:47]
	v_mfma_f32_16x16x32_bf16 v[36:39], v[132:135], v[196:199], v[36:39]
	v_mfma_f32_16x16x32_bf16 v[28:31], v[140:143], v[196:199], v[28:31]
	v_mfma_f32_16x16x32_bf16 v[20:23], v[132:135], v[214:217], v[20:23]
	v_mfma_f32_16x16x32_bf16 v[12:15], v[140:143], v[214:217], v[12:15]
	s_setprio 0
	s_setprio 1
	v_mfma_f32_16x16x32_bf16 v[48:51], v[144:147], v[160:163], v[48:51]
	v_mfma_f32_16x16x32_bf16 v[40:43], v[152:155], v[160:163], v[40:43]
	v_mfma_f32_16x16x32_bf16 v[32:35], v[144:147], v[168:171], v[32:35]
	v_mfma_f32_16x16x32_bf16 v[24:27], v[152:155], v[168:171], v[24:27]
	v_mfma_f32_16x16x32_bf16 v[16:19], v[144:147], v[192:195], v[16:19]
	v_mfma_f32_16x16x32_bf16 v[8:11], v[152:155], v[192:195], v[8:11]
	v_mfma_f32_16x16x32_bf16 v[4:7], v[144:147], v[208:211], v[4:7]
	v_mfma_f32_16x16x32_bf16 v[0:3], v[152:155], v[208:211], v[0:3]
	v_mfma_f32_16x16x32_bf16 v[48:51], v[148:151], v[164:167], v[48:51]
	v_mfma_f32_16x16x32_bf16 v[40:43], v[156:159], v[164:167], v[40:43]
	v_mfma_f32_16x16x32_bf16 v[32:35], v[148:151], v[172:175], v[32:35]
	v_mfma_f32_16x16x32_bf16 v[24:27], v[156:159], v[172:175], v[24:27]
	v_mfma_f32_16x16x32_bf16 v[16:19], v[148:151], v[196:199], v[16:19]
	v_mfma_f32_16x16x32_bf16 v[8:11], v[156:159], v[196:199], v[8:11]
	v_mfma_f32_16x16x32_bf16 v[4:7], v[148:151], v[214:217], v[4:7]
	v_mfma_f32_16x16x32_bf16 v[0:3], v[156:159], v[214:217], v[0:3]
	s_setprio 0
	s_barrier
	s_add_i32 s70, 0, 0x18000
	s_add_i32 s71, 0, 0x1c000
	v_add_u32_e32 v140, s70, v201
	v_add_u32_e32 v156, s71, v201
	ds_read_b128 v[128:131], v140
	ds_read_b128 v[132:135], v140 offset:1024
	ds_read_b128 v[136:139], v140 offset:2048
	ds_read_b128 v[140:143], v140 offset:3072
	ds_read_b128 v[144:147], v156
	ds_read_b128 v[148:151], v156 offset:1024
	ds_read_b128 v[152:155], v156 offset:2048
	ds_read_b128 v[156:159], v156 offset:3072
	s_add_u32 s34, s34, 0x40000
	s_addc_u32 s35, s35, 0
	s_mov_b32 m0, s44
	v_lshl_add_u64 v[226:227], s[34:35], 0, v[182:183]
	ds_read_b128 v[160:163], v207 offset:32768
	ds_read_b128 v[164:167], v207 offset:33792
	ds_read_b128 v[168:171], v207 offset:34816
	ds_read_b128 v[172:175], v207 offset:35840
	ds_read_b128 v[192:195], v207 offset:36864
	ds_read_b128 v[196:199], v207 offset:37888
	ds_read_b128 v[208:211], v207 offset:38912
	ds_read_b128 v[214:217], v207 offset:39936
	global_load_lds_dwordx4 v[226:227], off
	v_lshl_add_u64 v[226:227], s[34:35], 0, v[178:179]
	s_mov_b32 m0, s45
	s_nop 0
	global_load_lds_dwordx4 v[226:227], off
	v_lshl_add_u64 v[236:237], v[230:231], 0, s[18:19]
	s_add_u32 s30, s30, 0x40080
	v_lshl_add_u64 v[238:239], v[232:233], 0, s[18:19]
	s_addc_u32 s31, s31, 0
	v_lshl_add_u64 v[240:241], s[30:31], 0, v[180:181]
	v_lshl_add_u64 v[242:243], s[30:31], 0, v[176:177]
	v_lshl_add_u64 v[244:245], v[222:223], 0, s[18:19]
	v_lshl_add_u64 v[246:247], v[234:235], 0, s[18:19]
	s_waitcnt vmcnt(8)
	s_waitcnt lgkmcnt(0)
	s_barrier
; #define PG8_STAGE(bufoff, gbase, voff) do { _Pragma("unroll") for (int _i = 0; _i < 2; ++_i) \
;         __builtin_amdgcn_global_load_lds((const unsigned*)((const char*)(gbase) + (voff)[_i]), (PG8_LAS unsigned*)(lds + (bufoff) + ldsw + _i * 8192), 16, 0, 0); } while (0)
; #define PG8_LDA(dst, b, h) do { _Pragma("unroll") for (int m = 0; m < 4; ++m) _Pragma("unroll") for (int k = 0; k < 2; ++k) dst[m][k] = *(const PG8_LAS bf16x8*)(lds + PG8_SA(b, h) + aoff + m * 2048 + k * 1024); } while (0)
; #define PG8_LDB(dst, b, h) do { _Pragma("unroll") for (int n = 0; n < 2; ++n) _Pragma("unroll") for (int k = 0; k < 2; ++k) dst[n][k] = *(const PG8_LAS bf16x8*)(lds + PG8_SB(b, h) + boff + n * 2048 + k * 1024); } while (0)
; #define PG8_MMA(ai, bj, At, Bt) do { __builtin_amdgcn_s_setprio(1); _Pragma("unroll") for (int m = 0; m < 4; ++m) _Pragma("unroll") for (int n = 0; n < 2; ++n) _Pragma("unroll") for (int k = 0; k < 2; ++k) \
;         acc[ai][bj][m][n] = __builtin_amdgcn_mfma_f32_16x16x32_bf16(Bt[n][k], At[m][k], acc[ai][bj][m][n], 0, 0, 0); __builtin_amdgcn_s_setprio(0); } while (0)
; #define PG8_WAIT_V(n) asm volatile("s_waitcnt vmcnt(" #n ")" ::: "memory")
; #define PG8_WAIT_L(n) asm volatile("s_waitcnt lgkmcnt(" #n ")" ::: "memory")
; #define PG8_BAR __builtin_amdgcn_s_barrier()
; #define PG8_SCHED __builtin_amdgcn_sched_barrier(0)
; template <class Epi, class Sched, bool ALIGN_EPI = false, bool SP2 = false>
; __device__ __forceinline__ void gemm_phase(PG8_LAS unsigned char* lds, const Gemm g, const Sched& S, const Epi& E, const int wave_s) {
;     ...
;             PG8_LDB(B0, 1, 0); PG8_LDB(B1, 1, 1); PG8_SCHED; PG8_LDA(At, 1, 0); PG8_STAGE(PG8_SA(0, 1), a2 + hstep, voffA);
;             PG8_WAIT_V(8); PG8_WAIT_L(0); PG8_BAR; PG8_MMA(0, 0, At, B0); PG8_MMA(0, 1, At, B1); PG8_BAR; PG8_SCHED;
;             PG8_LDA(At, 1, 1); PG8_STAGE(PG8_SB(1, 0), b3, voffB); PG8_STAGE(PG8_SB(1, 1), b3 + hstep, voffB); PG8_STAGE(PG8_SA(1, 0), a3, voffA);
;             PG8_WAIT_V(8); PG8_WAIT_L(0); PG8_BAR; PG8_MMA(1, 0, At, B0); PG8_MMA(1, 1, At, B1); PG8_BAR; PG8_SCHED;
;     ...
;         if constexpr (ALIGN_EPI) { if (wr == 0) PG8_BAR; }
	s_setprio 1
	s_waitcnt lgkmcnt(0)
	v_mfma_f32_16x16x32_bf16 v[124:127], v[128:131], v[160:163], v[124:127]
	v_mfma_f32_16x16x32_bf16 v[120:123], v[136:139], v[160:163], v[120:123]
	v_mfma_f32_16x16x32_bf16 v[116:119], v[128:131], v[168:171], v[116:119]
	v_mfma_f32_16x16x32_bf16 v[108:111], v[136:139], v[168:171], v[108:111]
	v_mfma_f32_16x16x32_bf16 v[100:103], v[128:131], v[192:195], v[100:103]
	v_mfma_f32_16x16x32_bf16 v[92:95], v[136:139], v[192:195], v[92:95]
	v_mfma_f32_16x16x32_bf16 v[84:87], v[128:131], v[208:211], v[84:87]
	v_mfma_f32_16x16x32_bf16 v[76:79], v[136:139], v[208:211], v[76:79]
	v_mfma_f32_16x16x32_bf16 v[124:127], v[132:135], v[164:167], v[124:127]
	v_mfma_f32_16x16x32_bf16 v[120:123], v[140:143], v[164:167], v[120:123]
	v_mfma_f32_16x16x32_bf16 v[116:119], v[132:135], v[172:175], v[116:119]
	v_mfma_f32_16x16x32_bf16 v[108:111], v[140:143], v[172:175], v[108:111]
	v_mfma_f32_16x16x32_bf16 v[100:103], v[132:135], v[196:199], v[100:103]
	v_mfma_f32_16x16x32_bf16 v[92:95], v[140:143], v[196:199], v[92:95]
	v_mfma_f32_16x16x32_bf16 v[84:87], v[132:135], v[214:217], v[84:87]
	v_mfma_f32_16x16x32_bf16 v[76:79], v[140:143], v[214:217], v[76:79]
	s_setprio 0
	s_setprio 1
	v_mfma_f32_16x16x32_bf16 v[112:115], v[144:147], v[160:163], v[112:115]
	v_mfma_f32_16x16x32_bf16 v[104:107], v[152:155], v[160:163], v[104:107]
	v_mfma_f32_16x16x32_bf16 v[96:99], v[144:147], v[168:171], v[96:99]
	v_mfma_f32_16x16x32_bf16 v[88:91], v[152:155], v[168:171], v[88:91]
	v_mfma_f32_16x16x32_bf16 v[80:83], v[144:147], v[192:195], v[80:83]
	v_mfma_f32_16x16x32_bf16 v[72:75], v[152:155], v[192:195], v[72:75]
	v_mfma_f32_16x16x32_bf16 v[68:71], v[144:147], v[208:211], v[68:71]
	v_mfma_f32_16x16x32_bf16 v[64:67], v[152:155], v[208:211], v[64:67]
	v_mfma_f32_16x16x32_bf16 v[112:115], v[148:151], v[164:167], v[112:115]
	v_mfma_f32_16x16x32_bf16 v[104:107], v[156:159], v[164:167], v[104:107]
	v_mfma_f32_16x16x32_bf16 v[96:99], v[148:151], v[172:175], v[96:99]
	v_mfma_f32_16x16x32_bf16 v[88:91], v[156:159], v[172:175], v[88:91]
	v_mfma_f32_16x16x32_bf16 v[80:83], v[148:151], v[196:199], v[80:83]
	v_mfma_f32_16x16x32_bf16 v[72:75], v[156:159], v[196:199], v[72:75]
	v_mfma_f32_16x16x32_bf16 v[68:71], v[148:151], v[214:217], v[68:71]
	v_mfma_f32_16x16x32_bf16 v[64:67], v[156:159], v[214:217], v[64:67]
	s_setprio 0
	s_barrier
	s_add_i32 s34, s70, s33
	s_mov_b32 m0, s34
	ds_read_b128 v[160:163], v207 offset:49152
	ds_read_b128 v[164:167], v207 offset:50176
	ds_read_b128 v[168:171], v207 offset:51200
	ds_read_b128 v[172:175], v207 offset:52224
	ds_read_b128 v[192:195], v207 offset:53248
	ds_read_b128 v[196:199], v207 offset:54272
	ds_read_b128 v[208:211], v207 offset:55296
	ds_read_b128 v[214:217], v207 offset:56320
	global_load_lds_dwordx4 v[236:237], off
	s_add_i32 m0, s34, 0x2000
	s_add_i32 s34, s71, s33
	global_load_lds_dwordx4 v[238:239], off
	s_mov_b32 m0, s34
	s_nop 0
	global_load_lds_dwordx4 v[240:241], off
	s_add_i32 m0, s34, 0x2000
	s_nop 0
	global_load_lds_dwordx4 v[242:243], off
	s_mov_b32 m0, s47
	s_nop 0
	global_load_lds_dwordx4 v[244:245], off
	s_mov_b32 m0, s48
	s_nop 0
	global_load_lds_dwordx4 v[246:247], off
	s_waitcnt vmcnt(8)
	s_waitcnt lgkmcnt(0)
	s_barrier
	s_setprio 1
	s_waitcnt lgkmcnt(0)
	v_mfma_f32_16x16x32_bf16 v[60:63], v[128:131], v[160:163], v[60:63]
	v_mfma_f32_16x16x32_bf16 v[56:59], v[136:139], v[160:163], v[56:59]
	v_mfma_f32_16x16x32_bf16 v[52:55], v[128:131], v[168:171], v[52:55]
	v_mfma_f32_16x16x32_bf16 v[44:47], v[136:139], v[168:171], v[44:47]
	v_mfma_f32_16x16x32_bf16 v[36:39], v[128:131], v[192:195], v[36:39]
	v_mfma_f32_16x16x32_bf16 v[28:31], v[136:139], v[192:195], v[28:31]
	v_mfma_f32_16x16x32_bf16 v[20:23], v[128:131], v[208:211], v[20:23]
	v_mfma_f32_16x16x32_bf16 v[12:15], v[136:139], v[208:211], v[12:15]
	v_mfma_f32_16x16x32_bf16 v[60:63], v[132:135], v[164:167], v[60:63]
	v_mfma_f32_16x16x32_bf16 v[56:59], v[140:143], v[164:167], v[56:59]
	v_mfma_f32_16x16x32_bf16 v[52:55], v[132:135], v[172:175], v[52:55]
	v_mfma_f32_16x16x32_bf16 v[44:47], v[140:143], v[172:175], v[44:47]
	v_mfma_f32_16x16x32_bf16 v[36:39], v[132:135], v[196:199], v[36:39]
	v_mfma_f32_16x16x32_bf16 v[28:31], v[140:143], v[196:199], v[28:31]
	v_mfma_f32_16x16x32_bf16 v[20:23], v[132:135], v[214:217], v[20:23]
	v_mfma_f32_16x16x32_bf16 v[12:15], v[140:143], v[214:217], v[12:15]
	s_setprio 0
	s_setprio 1
	v_mfma_f32_16x16x32_bf16 v[48:51], v[144:147], v[160:163], v[48:51]
	v_mfma_f32_16x16x32_bf16 v[40:43], v[152:155], v[160:163], v[40:43]
	v_mfma_f32_16x16x32_bf16 v[32:35], v[144:147], v[168:171], v[32:35]
	v_mfma_f32_16x16x32_bf16 v[24:27], v[152:155], v[168:171], v[24:27]
	v_mfma_f32_16x16x32_bf16 v[16:19], v[144:147], v[192:195], v[16:19]
	v_mfma_f32_16x16x32_bf16 v[8:11], v[152:155], v[192:195], v[8:11]
	v_mfma_f32_16x16x32_bf16 v[4:7], v[144:147], v[208:211], v[4:7]
	v_mfma_f32_16x16x32_bf16 v[0:3], v[152:155], v[208:211], v[0:3]
	v_mfma_f32_16x16x32_bf16 v[48:51], v[148:151], v[164:167], v[48:51]
	v_mfma_f32_16x16x32_bf16 v[40:43], v[156:159], v[164:167], v[40:43]
	v_mfma_f32_16x16x32_bf16 v[32:35], v[148:151], v[172:175], v[32:35]
	v_mfma_f32_16x16x32_bf16 v[24:27], v[156:159], v[172:175], v[24:27]
	v_mfma_f32_16x16x32_bf16 v[16:19], v[148:151], v[196:199], v[16:19]
	v_mfma_f32_16x16x32_bf16 v[8:11], v[156:159], v[196:199], v[8:11]
	v_mfma_f32_16x16x32_bf16 v[4:7], v[148:151], v[214:217], v[4:7]
	v_mfma_f32_16x16x32_bf16 v[0:3], v[156:159], v[214:217], v[0:3]
	s_setprio 0
	s_barrier
	s_add_i32 s69, s69, 2
	s_add_u32 s67, s67, 0x100
	s_addc_u32 s68, s68, 0
	s_add_u32 s8, s8, 0x100
	s_addc_u32 s9, s9, 0
	s_cmp_gt_u32 s69, 13
	s_cbranch_scc0 .LBB0_2638
	s_and_b64 vcc, exec, s[20:21]
	s_cbranch_vccz .LBB0_2641
	s_barrier

; #define PG8_STAGE(bufoff, gbase, voff) do { _Pragma("unroll") for (int _i = 0; _i < 2; ++_i) \
;         __builtin_amdgcn_global_load_lds((const unsigned*)((const char*)(gbase) + (voff)[_i]), (PG8_LAS unsigned*)(lds + (bufoff) + ldsw + _i * 8192), 16, 0, 0); } while (0)
; #define PG8_LDA(dst, b, h) do { _Pragma("unroll") for (int m = 0; m < 4; ++m) _Pragma("unroll") for (int k = 0; k < 2; ++k) dst[m][k] = *(const PG8_LAS bf16x8*)(lds + PG8_SA(b, h) + aoff + m * 2048 + k * 1024); } while (0)
; #define PG8_LDB(dst, b, h) do { _Pragma("unroll") for (int n = 0; n < 2; ++n) _Pragma("unroll") for (int k = 0; k < 2; ++k) dst[n][k] = *(const PG8_LAS bf16x8*)(lds + PG8_SB(b, h) + boff + n * 2048 + k * 1024); } while (0)
; #define PG8_MMA(ai, bj, At, Bt) do { __builtin_amdgcn_s_setprio(1); _Pragma("unroll") for (int m = 0; m < 4; ++m) _Pragma("unroll") for (int n = 0; n < 2; ++n) _Pragma("unroll") for (int k = 0; k < 2; ++k) \
;         acc[ai][bj][m][n] = __builtin_amdgcn_mfma_f32_16x16x32_bf16(Bt[n][k], At[m][k], acc[ai][bj][m][n], 0, 0, 0); __builtin_amdgcn_s_setprio(0); } while (0)
; #define PG8_WAIT_V(n) asm volatile("s_waitcnt vmcnt(" #n ")" ::: "memory")
; #define PG8_WAIT_L(n) asm volatile("s_waitcnt lgkmcnt(" #n ")" ::: "memory")
; #define PG8_BAR __builtin_amdgcn_s_barrier()
; #define PG8_SCHED __builtin_amdgcn_sched_barrier(0)
; template <class Epi, class Sched, bool ALIGN_EPI = false, bool SP2 = false>
; __device__ __forceinline__ void gemm_phase(PG8_LAS unsigned char* lds, const Gemm g, const Sched& S, const Epi& E, const int wave_s) {
;     ...
;             const bool last = (t == nt - 2);
;             const char* a1 = cA + (size_t)(t + 1) * kstep;
;             const char* a2 = last ? nA : cA + (size_t)(t + 2) * kstep; const char* b2 = last ? nB : cB + (size_t)(t + 2) * kstep;
;             const char* a3 = a2 + kstep; const char* b3 = b2 + kstep;
;             if (last && has_next) S.a_ready(nxt);
;             if constexpr (SP2) {
;             PG8_LDB(B0, 0, 0); PG8_LDB(B1, 0, 1); PG8_SCHED; PG8_LDA(At, 0, 0); PG8_STAGE(PG8_SA(1, 1), a1 + hstep, voffA);
;             PG8_WAIT_V(8); PG8_WAIT_L(0); PG8_BAR; PG8_MMA(0, 0, At, B0); PG8_MMA(0, 1, At, B1); PG8_BAR; PG8_SCHED;
;             PG8_LDA(At, 0, 1); PG8_STAGE(PG8_SB(0, 0), b2, voffB); PG8_STAGE(PG8_SB(0, 1), b2 + hstep, voffB); PG8_STAGE(PG8_SA(0, 0), a2, voffA);
.LBB0_2781:
	ds_read_b128 v[128:131], v155
	ds_read_b128 v[132:135], v155 offset:1024
	ds_read_b128 v[158:161], v155 offset:2048
	ds_read_b128 v[162:165], v155 offset:3072
	ds_read_b128 v[166:169], v156
	ds_read_b128 v[170:173], v156 offset:1024
	ds_read_b128 v[174:177], v156 offset:2048
	ds_read_b128 v[178:181], v156 offset:3072
	s_add_u32 s20, s18, 0xfffe0080
	s_addc_u32 s21, s19, -1
	s_cmp_eq_u32 s47, 4
	s_cselect_b32 s23, s11, s21
	s_cselect_b32 s22, s43, s20
	s_cselect_b32 s21, s9, s46
	s_cselect_b32 s20, s44, s45
	v_lshl_add_u64 v[152:153], s[18:19], 0, v[146:147]
	s_add_i32 m0, s17, 0xc000
	ds_read_b128 v[182:185], v157
	ds_read_b128 v[186:189], v157 offset:1024
	ds_read_b128 v[190:193], v157 offset:2048
	ds_read_b128 v[194:197], v157 offset:3072
	ds_read_b128 v[198:201], v157 offset:4096
	ds_read_b128 v[202:205], v157 offset:5120
	ds_read_b128 v[206:209], v157 offset:6144
	ds_read_b128 v[210:213], v157 offset:7168
	global_load_lds_dwordx4 v[152:153], off
	v_lshl_add_u64 v[152:153], s[18:19], 0, v[144:145]
	s_add_i32 m0, s17, 0xe000
	s_nop 0
	global_load_lds_dwordx4 v[152:153], off
	v_lshl_add_u64 v[230:231], s[20:21], 0, v[138:139]
	v_lshl_add_u64 v[232:233], s[20:21], 0, v[142:143]
	v_lshl_add_u64 v[234:235], s[22:23], 0, v[140:141]
	s_waitcnt vmcnt(8)
	s_waitcnt lgkmcnt(0)
	s_barrier
	s_setprio 1
	s_waitcnt lgkmcnt(0)
	v_mfma_f32_16x16x32_bf16 v[124:127], v[128:131], v[182:185], v[124:127]
	v_mfma_f32_16x16x32_bf16 v[120:123], v[158:161], v[182:185], v[120:123]
	v_mfma_f32_16x16x32_bf16 v[108:111], v[128:131], v[190:193], v[108:111]
	v_mfma_f32_16x16x32_bf16 v[104:107], v[158:161], v[190:193], v[104:107]
	v_mfma_f32_16x16x32_bf16 v[92:95], v[128:131], v[198:201], v[92:95]
	v_mfma_f32_16x16x32_bf16 v[88:91], v[158:161], v[198:201], v[88:91]
	v_mfma_f32_16x16x32_bf16 v[80:83], v[128:131], v[206:209], v[80:83]
	v_mfma_f32_16x16x32_bf16 v[72:75], v[158:161], v[206:209], v[72:75]
	v_mfma_f32_16x16x32_bf16 v[124:127], v[132:135], v[186:189], v[124:127]
	v_mfma_f32_16x16x32_bf16 v[120:123], v[162:165], v[186:189], v[120:123]
	v_mfma_f32_16x16x32_bf16 v[108:111], v[132:135], v[194:197], v[108:111]
	v_mfma_f32_16x16x32_bf16 v[104:107], v[162:165], v[194:197], v[104:107]
	v_mfma_f32_16x16x32_bf16 v[92:95], v[132:135], v[202:205], v[92:95]
	v_mfma_f32_16x16x32_bf16 v[88:91], v[162:165], v[202:205], v[88:91]
	v_mfma_f32_16x16x32_bf16 v[80:83], v[132:135], v[210:213], v[80:83]
	v_mfma_f32_16x16x32_bf16 v[72:75], v[162:165], v[210:213], v[72:75]
	s_setprio 0
	s_setprio 1
	v_mfma_f32_16x16x32_bf16 v[116:119], v[166:169], v[182:185], v[116:119]
	v_mfma_f32_16x16x32_bf16 v[112:115], v[174:177], v[182:185], v[112:115]
	v_mfma_f32_16x16x32_bf16 v[100:103], v[166:169], v[190:193], v[100:103]
	v_mfma_f32_16x16x32_bf16 v[96:99], v[174:177], v[190:193], v[96:99]
	v_mfma_f32_16x16x32_bf16 v[84:87], v[166:169], v[198:201], v[84:87]
	v_mfma_f32_16x16x32_bf16 v[76:79], v[174:177], v[198:201], v[76:79]
	v_mfma_f32_16x16x32_bf16 v[68:71], v[166:169], v[206:209], v[68:71]
	v_mfma_f32_16x16x32_bf16 v[64:67], v[174:177], v[206:209], v[64:67]
	v_mfma_f32_16x16x32_bf16 v[116:119], v[170:173], v[186:189], v[116:119]
	v_mfma_f32_16x16x32_bf16 v[112:115], v[178:181], v[186:189], v[112:115]
	v_mfma_f32_16x16x32_bf16 v[100:103], v[170:173], v[194:197], v[100:103]
	v_mfma_f32_16x16x32_bf16 v[96:99], v[178:181], v[194:197], v[96:99]
	v_mfma_f32_16x16x32_bf16 v[84:87], v[170:173], v[202:205], v[84:87]
	v_mfma_f32_16x16x32_bf16 v[76:79], v[178:181], v[202:205], v[76:79]
	v_mfma_f32_16x16x32_bf16 v[68:71], v[170:173], v[210:213], v[68:71]
	v_mfma_f32_16x16x32_bf16 v[64:67], v[178:181], v[210:213], v[64:67]
	s_setprio 0
	s_barrier
	s_add_i32 s48, s40, s33
	s_mov_b32 m0, s48
	ds_read_b128 v[182:185], v157 offset:16384
	ds_read_b128 v[186:189], v157 offset:17408
	ds_read_b128 v[190:193], v157 offset:18432
	ds_read_b128 v[194:197], v157 offset:19456
	ds_read_b128 v[198:201], v157 offset:20480
	ds_read_b128 v[202:205], v157 offset:21504
	ds_read_b128 v[206:209], v157 offset:22528
	ds_read_b128 v[210:213], v157 offset:23552
	global_load_lds_dwordx4 v[230:231], off
	s_add_i32 m0, s48, 0x2000
	s_add_u32 s48, s20, 0x20000
	s_addc_u32 s49, s21, 0
	s_add_i32 s50, s41, s33
	global_load_lds_dwordx4 v[232:233], off
	v_lshl_add_u64 v[216:217], s[48:49], 0, v[138:139]
	s_mov_b32 m0, s50
	s_nop 0
	global_load_lds_dwordx4 v[216:217], off
	v_lshl_add_u64 v[216:217], s[48:49], 0, v[142:143]
	s_add_i32 m0, s50, 0x2000
	s_nop 0
	global_load_lds_dwordx4 v[216:217], off
	v_lshl_add_u64 v[216:217], s[22:23], 0, v[136:137]
	s_mov_b32 m0, s17
	s_nop 0
	global_load_lds_dwordx4 v[216:217], off
	s_mov_b32 m0, s29
	s_nop 0
	global_load_lds_dwordx4 v[234:235], off
	s_waitcnt vmcnt(8)
	s_waitcnt lgkmcnt(0)
	s_barrier
; #define PG8_STAGE(bufoff, gbase, voff) do { _Pragma("unroll") for (int _i = 0; _i < 2; ++_i) \
;         __builtin_amdgcn_global_load_lds((const unsigned*)((const char*)(gbase) + (voff)[_i]), (PG8_LAS unsigned*)(lds + (bufoff) + ldsw + _i * 8192), 16, 0, 0); } while (0)
; #define PG8_LDA(dst, b, h) do { _Pragma("unroll") for (int m = 0; m < 4; ++m) _Pragma("unroll") for (int k = 0; k < 2; ++k) dst[m][k] = *(const PG8_LAS bf16x8*)(lds + PG8_SA(b, h) + aoff + m * 2048 + k * 1024); } while (0)
; #define PG8_LDB(dst, b, h) do { _Pragma("unroll") for (int n = 0; n < 2; ++n) _Pragma("unroll") for (int k = 0; k < 2; ++k) dst[n][k] = *(const PG8_LAS bf16x8*)(lds + PG8_SB(b, h) + boff + n * 2048 + k * 1024); } while (0)
; #define PG8_MMA(ai, bj, At, Bt) do { __builtin_amdgcn_s_setprio(1); _Pragma("unroll") for (int m = 0; m < 4; ++m) _Pragma("unroll") for (int n = 0; n < 2; ++n) _Pragma("unroll") for (int k = 0; k < 2; ++k) \
;         acc[ai][bj][m][n] = __builtin_amdgcn_mfma_f32_16x16x32_bf16(Bt[n][k], At[m][k], acc[ai][bj][m][n], 0, 0, 0); __builtin_amdgcn_s_setprio(0); } while (0)
; #define PG8_WAIT_V(n) asm volatile("s_waitcnt vmcnt(" #n ")" ::: "memory")
; #define PG8_WAIT_L(n) asm volatile("s_waitcnt lgkmcnt(" #n ")" ::: "memory")
; #define PG8_BAR __builtin_amdgcn_s_barrier()
; #define PG8_SCHED __builtin_amdgcn_sched_barrier(0)
; template <class Epi, class Sched, bool ALIGN_EPI = false, bool SP2 = false>
; __device__ __forceinline__ void gemm_phase(PG8_LAS unsigned char* lds, const Gemm g, const Sched& S, const Epi& E, const int wave_s) {
;     ...
;             PG8_WAIT_V(8); PG8_WAIT_L(0); PG8_BAR; PG8_MMA(1, 0, At, B0); PG8_MMA(1, 1, At, B1); PG8_BAR; PG8_SCHED;
;             PG8_LDB(B0, 1, 0); PG8_LDB(B1, 1, 1); PG8_SCHED; PG8_LDA(At, 1, 0); PG8_STAGE(PG8_SA(0, 1), a2 + hstep, voffA);
;             PG8_WAIT_V(8); PG8_WAIT_L(0); PG8_BAR; PG8_MMA(0, 0, At, B0); PG8_MMA(0, 1, At, B1); PG8_BAR; PG8_SCHED;
;             PG8_LDA(At, 1, 1); PG8_STAGE(PG8_SB(1, 0), b3, voffB); PG8_STAGE(PG8_SB(1, 1), b3 + hstep, voffB); PG8_STAGE(PG8_SA(1, 0), a3, voffA);
	s_setprio 1
	s_waitcnt lgkmcnt(0)
	v_mfma_f32_16x16x32_bf16 v[60:63], v[128:131], v[182:185], v[60:63]
	v_mfma_f32_16x16x32_bf16 v[56:59], v[158:161], v[182:185], v[56:59]
	v_mfma_f32_16x16x32_bf16 v[48:51], v[128:131], v[190:193], v[48:51]
	v_mfma_f32_16x16x32_bf16 v[40:43], v[158:161], v[190:193], v[40:43]
	v_mfma_f32_16x16x32_bf16 v[32:35], v[128:131], v[198:201], v[32:35]
	v_mfma_f32_16x16x32_bf16 v[24:27], v[158:161], v[198:201], v[24:27]
	v_mfma_f32_16x16x32_bf16 v[16:19], v[128:131], v[206:209], v[16:19]
	v_mfma_f32_16x16x32_bf16 v[8:11], v[158:161], v[206:209], v[8:11]
	v_mfma_f32_16x16x32_bf16 v[60:63], v[132:135], v[186:189], v[60:63]
	v_mfma_f32_16x16x32_bf16 v[56:59], v[162:165], v[186:189], v[56:59]
	v_mfma_f32_16x16x32_bf16 v[48:51], v[132:135], v[194:197], v[48:51]
	v_mfma_f32_16x16x32_bf16 v[40:43], v[162:165], v[194:197], v[40:43]
	v_mfma_f32_16x16x32_bf16 v[32:35], v[132:135], v[202:205], v[32:35]
	v_mfma_f32_16x16x32_bf16 v[24:27], v[162:165], v[202:205], v[24:27]
	v_mfma_f32_16x16x32_bf16 v[16:19], v[132:135], v[210:213], v[16:19]
	v_mfma_f32_16x16x32_bf16 v[8:11], v[162:165], v[210:213], v[8:11]
	s_setprio 0
	s_setprio 1
	v_mfma_f32_16x16x32_bf16 v[52:55], v[166:169], v[182:185], v[52:55]
	v_mfma_f32_16x16x32_bf16 v[44:47], v[174:177], v[182:185], v[44:47]
	v_mfma_f32_16x16x32_bf16 v[36:39], v[166:169], v[190:193], v[36:39]
	v_mfma_f32_16x16x32_bf16 v[28:31], v[174:177], v[190:193], v[28:31]
	v_mfma_f32_16x16x32_bf16 v[20:23], v[166:169], v[198:201], v[20:23]
	v_mfma_f32_16x16x32_bf16 v[12:15], v[174:177], v[198:201], v[12:15]
	v_mfma_f32_16x16x32_bf16 v[4:7], v[166:169], v[206:209], v[4:7]
	v_mfma_f32_16x16x32_bf16 v[0:3], v[174:177], v[206:209], v[0:3]
	v_mfma_f32_16x16x32_bf16 v[52:55], v[170:173], v[186:189], v[52:55]
	v_mfma_f32_16x16x32_bf16 v[44:47], v[178:181], v[186:189], v[44:47]
	v_mfma_f32_16x16x32_bf16 v[36:39], v[170:173], v[194:197], v[36:39]
	v_mfma_f32_16x16x32_bf16 v[28:31], v[178:181], v[194:197], v[28:31]
	v_mfma_f32_16x16x32_bf16 v[20:23], v[170:173], v[202:205], v[20:23]
	v_mfma_f32_16x16x32_bf16 v[12:15], v[178:181], v[202:205], v[12:15]
	v_mfma_f32_16x16x32_bf16 v[4:7], v[170:173], v[210:213], v[4:7]
	v_mfma_f32_16x16x32_bf16 v[0:3], v[178:181], v[210:213], v[0:3]
	s_setprio 0
	s_barrier
	s_add_i32 s48, 0, 0x18000
	s_add_i32 s49, 0, 0x1c000
	v_add_u32_e32 v162, s48, v154
	v_add_u32_e32 v178, s49, v154
	ds_read_b128 v[128:131], v162
	ds_read_b128 v[132:135], v162 offset:1024
	ds_read_b128 v[158:161], v162 offset:2048
	ds_read_b128 v[162:165], v162 offset:3072
	ds_read_b128 v[166:169], v178
	ds_read_b128 v[170:173], v178 offset:1024
	ds_read_b128 v[174:177], v178 offset:2048
	ds_read_b128 v[178:181], v178 offset:3072
	s_add_u32 s22, s22, 0x20000
	s_addc_u32 s23, s23, 0
	s_mov_b32 m0, s30
	v_lshl_add_u64 v[220:221], s[22:23], 0, v[136:137]
	ds_read_b128 v[182:185], v157 offset:32768
	ds_read_b128 v[186:189], v157 offset:33792
	ds_read_b128 v[190:193], v157 offset:34816
	ds_read_b128 v[194:197], v157 offset:35840
	ds_read_b128 v[198:201], v157 offset:36864
	ds_read_b128 v[202:205], v157 offset:37888
	ds_read_b128 v[206:209], v157 offset:38912
	ds_read_b128 v[210:213], v157 offset:39936
	global_load_lds_dwordx4 v[220:221], off
	v_lshl_add_u64 v[220:221], s[22:23], 0, v[140:141]
	s_mov_b32 m0, s31
	s_nop 0
	global_load_lds_dwordx4 v[220:221], off
	v_lshl_add_u64 v[236:237], v[230:231], 0, s[6:7]
	s_add_u32 s20, s20, 0x20080
	v_lshl_add_u64 v[238:239], v[232:233], 0, s[6:7]
	s_addc_u32 s21, s21, 0
	v_lshl_add_u64 v[240:241], s[20:21], 0, v[138:139]
	v_lshl_add_u64 v[242:243], s[20:21], 0, v[142:143]
	v_lshl_add_u64 v[244:245], v[216:217], 0, s[6:7]
	v_lshl_add_u64 v[246:247], v[234:235], 0, s[6:7]
	s_waitcnt vmcnt(8)
	s_waitcnt lgkmcnt(0)
	s_barrier
	s_setprio 1
	s_waitcnt lgkmcnt(0)
	v_mfma_f32_16x16x32_bf16 v[124:127], v[128:131], v[182:185], v[124:127]
	v_mfma_f32_16x16x32_bf16 v[120:123], v[158:161], v[182:185], v[120:123]
	v_mfma_f32_16x16x32_bf16 v[108:111], v[128:131], v[190:193], v[108:111]
	v_mfma_f32_16x16x32_bf16 v[104:107], v[158:161], v[190:193], v[104:107]
	v_mfma_f32_16x16x32_bf16 v[92:95], v[128:131], v[198:201], v[92:95]
	v_mfma_f32_16x16x32_bf16 v[88:91], v[158:161], v[198:201], v[88:91]
	v_mfma_f32_16x16x32_bf16 v[80:83], v[128:131], v[206:209], v[80:83]
	v_mfma_f32_16x16x32_bf16 v[72:75], v[158:161], v[206:209], v[72:75]
	v_mfma_f32_16x16x32_bf16 v[124:127], v[132:135], v[186:189], v[124:127]
	v_mfma_f32_16x16x32_bf16 v[120:123], v[162:165], v[186:189], v[120:123]
	v_mfma_f32_16x16x32_bf16 v[108:111], v[132:135], v[194:197], v[108:111]
	v_mfma_f32_16x16x32_bf16 v[104:107], v[162:165], v[194:197], v[104:107]
	v_mfma_f32_16x16x32_bf16 v[92:95], v[132:135], v[202:205], v[92:95]
	v_mfma_f32_16x16x32_bf16 v[88:91], v[162:165], v[202:205], v[88:91]
	v_mfma_f32_16x16x32_bf16 v[80:83], v[132:135], v[210:213], v[80:83]
	v_mfma_f32_16x16x32_bf16 v[72:75], v[162:165], v[210:213], v[72:75]
	s_setprio 0
	s_setprio 1
	v_mfma_f32_16x16x32_bf16 v[116:119], v[166:169], v[182:185], v[116:119]
	v_mfma_f32_16x16x32_bf16 v[112:115], v[174:177], v[182:185], v[112:115]
	v_mfma_f32_16x16x32_bf16 v[100:103], v[166:169], v[190:193], v[100:103]
	v_mfma_f32_16x16x32_bf16 v[96:99], v[174:177], v[190:193], v[96:99]
	v_mfma_f32_16x16x32_bf16 v[84:87], v[166:169], v[198:201], v[84:87]
	v_mfma_f32_16x16x32_bf16 v[76:79], v[174:177], v[198:201], v[76:79]
	v_mfma_f32_16x16x32_bf16 v[68:71], v[166:169], v[206:209], v[68:71]
	v_mfma_f32_16x16x32_bf16 v[64:67], v[174:177], v[206:209], v[64:67]
	v_mfma_f32_16x16x32_bf16 v[116:119], v[170:173], v[186:189], v[116:119]
	v_mfma_f32_16x16x32_bf16 v[112:115], v[178:181], v[186:189], v[112:115]
	v_mfma_f32_16x16x32_bf16 v[100:103], v[170:173], v[194:197], v[100:103]
	v_mfma_f32_16x16x32_bf16 v[96:99], v[178:181], v[194:197], v[96:99]
	v_mfma_f32_16x16x32_bf16 v[84:87], v[170:173], v[202:205], v[84:87]
	v_mfma_f32_16x16x32_bf16 v[76:79], v[178:181], v[202:205], v[76:79]
	v_mfma_f32_16x16x32_bf16 v[68:71], v[170:173], v[210:213], v[68:71]
	v_mfma_f32_16x16x32_bf16 v[64:67], v[178:181], v[210:213], v[64:67]
	s_setprio 0
	s_barrier
; #define PG8_STAGE(bufoff, gbase, voff) do { _Pragma("unroll") for (int _i = 0; _i < 2; ++_i) \
;         __builtin_amdgcn_global_load_lds((const unsigned*)((const char*)(gbase) + (voff)[_i]), (PG8_LAS unsigned*)(lds + (bufoff) + ldsw + _i * 8192), 16, 0, 0); } while (0)
; #define PG8_LDA(dst, b, h) do { _Pragma("unroll") for (int m = 0; m < 4; ++m) _Pragma("unroll") for (int k = 0; k < 2; ++k) dst[m][k] = *(const PG8_LAS bf16x8*)(lds + PG8_SA(b, h) + aoff + m * 2048 + k * 1024); } while (0)
; #define PG8_MMA(ai, bj, At, Bt) do { __builtin_amdgcn_s_setprio(1); _Pragma("unroll") for (int m = 0; m < 4; ++m) _Pragma("unroll") for (int n = 0; n < 2; ++n) _Pragma("unroll") for (int k = 0; k < 2; ++k) \
;         acc[ai][bj][m][n] = __builtin_amdgcn_mfma_f32_16x16x32_bf16(Bt[n][k], At[m][k], acc[ai][bj][m][n], 0, 0, 0); __builtin_amdgcn_s_setprio(0); } while (0)
; #define PG8_WAIT_V(n) asm volatile("s_waitcnt vmcnt(" #n ")" ::: "memory")
; #define PG8_WAIT_L(n) asm volatile("s_waitcnt lgkmcnt(" #n ")" ::: "memory")
; #define PG8_BAR __builtin_amdgcn_s_barrier()
; #define PG8_SCHED __builtin_amdgcn_sched_barrier(0)
; __device__ __forceinline__ int lane_id_v() { int l; asm volatile("v_mbcnt_lo_u32_b32 %0, -1, 0\n\tv_mbcnt_hi_u32_b32 %0, -1, %0" : "=v"(l)); return l; }
; template <class Epi, class Sched, bool ALIGN_EPI = false, bool SP2 = false>
; __device__ __forceinline__ void gemm_phase(PG8_LAS unsigned char* lds, const Gemm g, const Sched& S, const Epi& E, const int wave_s) {
;     ...
;             PG8_LDA(At, 1, 1); PG8_STAGE(PG8_SB(1, 0), b3, voffB); PG8_STAGE(PG8_SB(1, 1), b3 + hstep, voffB); PG8_STAGE(PG8_SA(1, 0), a3, voffA);
;             PG8_WAIT_V(8); PG8_WAIT_L(0); PG8_BAR; PG8_MMA(1, 0, At, B0); PG8_MMA(1, 1, At, B1); PG8_BAR; PG8_SCHED;
;     __device__ __forceinline__ void operator()(const af4 (&acc)[2][2][4][2], const pg8::Unit& u, int wr, int wc, int fr_, int fq_) const {
;         const int ln_ = lane_id_v(); const int fr = ln_ & 15, fq = ln_ >> 4;
;         const int row0 = u.pm * 256 + wr * 64 + fr, col0 = u.pn * 256 + wc * 32 + 8 * fq;
;         v4u o[2][2][2];
;     ...
;         MUL_LOAD(0, 0);
; #pragma unroll
;         for (int b_ = 0; b_ < 4; ++b_) {
;             const int ai = b_ >> 1, mp = b_ & 1, cur = b_ & 1;
;             if (b_ + 1 < 4) { if (cur == 0) MUL_LOAD(1, b_ + 1); else MUL_LOAD(0, b_ + 1); }
	s_add_i32 s22, s48, s33
	s_mov_b32 m0, s22
	ds_read_b128 v[182:185], v157 offset:49152
	ds_read_b128 v[186:189], v157 offset:50176
	ds_read_b128 v[190:193], v157 offset:51200
	ds_read_b128 v[194:197], v157 offset:52224
	ds_read_b128 v[198:201], v157 offset:53248
	ds_read_b128 v[202:205], v157 offset:54272
	ds_read_b128 v[206:209], v157 offset:55296
	ds_read_b128 v[210:213], v157 offset:56320
	global_load_lds_dwordx4 v[236:237], off
	s_add_i32 m0, s22, 0x2000
	s_add_i32 s22, s49, s33
	global_load_lds_dwordx4 v[238:239], off
	s_mov_b32 m0, s22
	s_nop 0
	global_load_lds_dwordx4 v[240:241], off
	s_add_i32 m0, s22, 0x2000
	s_nop 0
	global_load_lds_dwordx4 v[242:243], off
	s_mov_b32 m0, s35
	s_nop 0
	global_load_lds_dwordx4 v[244:245], off
	s_mov_b32 m0, s36
	s_nop 0
	global_load_lds_dwordx4 v[246:247], off
	s_waitcnt vmcnt(8)
	s_waitcnt lgkmcnt(0)
	s_barrier
	s_setprio 1
	s_waitcnt lgkmcnt(0)
	v_mfma_f32_16x16x32_bf16 v[60:63], v[128:131], v[182:185], v[60:63]
	v_mfma_f32_16x16x32_bf16 v[56:59], v[158:161], v[182:185], v[56:59]
	v_mfma_f32_16x16x32_bf16 v[48:51], v[128:131], v[190:193], v[48:51]
	v_mfma_f32_16x16x32_bf16 v[40:43], v[158:161], v[190:193], v[40:43]
	v_mfma_f32_16x16x32_bf16 v[32:35], v[128:131], v[198:201], v[32:35]
	v_mfma_f32_16x16x32_bf16 v[24:27], v[158:161], v[198:201], v[24:27]
	v_mfma_f32_16x16x32_bf16 v[16:19], v[128:131], v[206:209], v[16:19]
	v_mfma_f32_16x16x32_bf16 v[8:11], v[158:161], v[206:209], v[8:11]
	v_mfma_f32_16x16x32_bf16 v[60:63], v[132:135], v[186:189], v[60:63]
	v_mfma_f32_16x16x32_bf16 v[56:59], v[162:165], v[186:189], v[56:59]
	v_mfma_f32_16x16x32_bf16 v[48:51], v[132:135], v[194:197], v[48:51]
	v_mfma_f32_16x16x32_bf16 v[40:43], v[162:165], v[194:197], v[40:43]
	v_mfma_f32_16x16x32_bf16 v[32:35], v[132:135], v[202:205], v[32:35]
	v_mfma_f32_16x16x32_bf16 v[24:27], v[162:165], v[202:205], v[24:27]
	v_mfma_f32_16x16x32_bf16 v[16:19], v[132:135], v[210:213], v[16:19]
	v_mfma_f32_16x16x32_bf16 v[8:11], v[162:165], v[210:213], v[8:11]
	s_setprio 0
	s_setprio 1
	v_mfma_f32_16x16x32_bf16 v[52:55], v[166:169], v[182:185], v[52:55]
	v_mfma_f32_16x16x32_bf16 v[44:47], v[174:177], v[182:185], v[44:47]
	v_mfma_f32_16x16x32_bf16 v[36:39], v[166:169], v[190:193], v[36:39]
	v_mfma_f32_16x16x32_bf16 v[28:31], v[174:177], v[190:193], v[28:31]
	v_mfma_f32_16x16x32_bf16 v[20:23], v[166:169], v[198:201], v[20:23]
	v_mfma_f32_16x16x32_bf16 v[12:15], v[174:177], v[198:201], v[12:15]
	v_mfma_f32_16x16x32_bf16 v[4:7], v[166:169], v[206:209], v[4:7]
	v_mfma_f32_16x16x32_bf16 v[0:3], v[174:177], v[206:209], v[0:3]
	v_mfma_f32_16x16x32_bf16 v[52:55], v[170:173], v[186:189], v[52:55]
	v_mfma_f32_16x16x32_bf16 v[44:47], v[178:181], v[186:189], v[44:47]
	v_mfma_f32_16x16x32_bf16 v[36:39], v[170:173], v[194:197], v[36:39]
	v_mfma_f32_16x16x32_bf16 v[28:31], v[178:181], v[194:197], v[28:31]
	v_mfma_f32_16x16x32_bf16 v[20:23], v[170:173], v[202:205], v[20:23]
	v_mfma_f32_16x16x32_bf16 v[12:15], v[178:181], v[202:205], v[12:15]
	v_mfma_f32_16x16x32_bf16 v[4:7], v[170:173], v[210:213], v[4:7]
	v_mfma_f32_16x16x32_bf16 v[0:3], v[178:181], v[210:213], v[0:3]
	s_setprio 0
	s_barrier
	s_add_i32 s47, s47, 2
	s_add_u32 s45, s45, 0x100
	s_addc_u32 s46, s46, 0
	s_add_u32 s18, s18, 0x100
	s_addc_u32 s19, s19, 0
	s_cmp_gt_u32 s47, 5
	s_cbranch_scc0 .LBB0_2781
	s_lshl_b32 s9, s16, 8
	v_mbcnt_lo_u32_b32 v128, -1, 0
	v_mbcnt_hi_u32_b32 v128, -1, v128
	s_add_i32 s9, s9, s87
	v_and_or_b32 v194, v128, 15, s9
	s_lshl_b32 s9, s42, 8
	v_ashrrev_i32_e32 v128, 1, v128
	s_or_b32 s9, s9, s79
	v_and_b32_e32 v128, -8, v128
	v_mov_b32_e32 v130, v194
	v_add_u32_e32 v128, s9, v128
	v_ashrrev_i32_e32 v129, 31, v128
	v_ashrrev_i32_e32 v131, 31, v130
	v_lshlrev_b64 v[130:131], 11, v[130:131]
	v_lshl_add_u64 v[130:131], s[2:3], 0, v[130:131]
	v_lshlrev_b64 v[152:153], 1, v[128:129]
	v_lshl_add_u64 v[128:129], v[130:131], 0, v[152:153]
	global_load_dwordx4 v[158:161], v[128:129], off
	global_load_dwordx4 v[162:165], v[128:129], off offset:256
	v_add_co_u32_e32 v128, vcc, s37, v128
	v_or_b32_e32 v182, 32, v194
	s_nop 0
	v_addc_co_u32_e32 v129, vcc, 0, v129, vcc
	global_load_dwordx4 v[166:169], v[128:129], off
	global_load_dwordx4 v[170:173], v[128:129], off offset:256
	v_mov_b32_e32 v128, v182
	v_mov_b32_e32 v184, v194
	v_ashrrev_i32_e32 v129, 31, v128
	v_lshlrev_b64 v[128:129], 11, v[128:129]
	v_lshl_add_u64 v[128:129], s[2:3], 0, v[128:129]
	v_lshl_add_u64 v[128:129], v[128:129], 0, v[152:153]
	global_load_dwordx4 v[174:177], v[128:129], off
	global_load_dwordx4 v[178:181], v[128:129], off offset:256
	v_add_co_u32_e32 v128, vcc, s37, v128
	s_mov_b32 s42, s8
	s_nop 0
	v_addc_co_u32_e32 v129, vcc, 0, v129, vcc
	global_load_dwordx4 v[132:135], v[128:129], off
	s_nop 0
	global_load_dwordx4 v[128:131], v[128:129], off offset:256
	s_mov_b32 s16, s10
	v_ashrrev_i32_e32 v185, 31, v184
	v_lshlrev_b64 v[184:185], 11, v[184:185]
	v_lshl_add_u64 v[184:185], s[2:3], 0, v[184:185]
	v_lshl_add_u64 v[184:185], v[184:185], 0, v[152:153]
	s_mov_b64 s[18:19], s[14:15]
	s_mov_b64 s[20:21], s[12:13]
	s_waitcnt vmcnt(0)
; __device__ __forceinline__ unsigned cvtpk(float lo, float hi) { f32x2 v = {lo, hi}; bf16x2_t b = __builtin_convertvector(v, bf16x2_t); return __builtin_bit_cast(unsigned, b); }
; __device__ __forceinline__ float bflo(unsigned u) { return __uint_as_float(u << 16); }
; __device__ __forceinline__ float bfhi(unsigned u) { return __uint_as_float(u & 0xffff0000u); }
; #define MUL_LOAD(buf, b_) do { int RRl = row0 + ((b_) >> 1) * 128 + ((b_) & 1) * 32; asm volatile("" : "+v"(RRl)); const bf16* pl = G + (size_t)RRl * 1024 + col0; \
;             _Pragma("unroll") for (int mi = 0; mi < 2; ++mi) _Pragma("unroll") for (int bj = 0; bj < 2; ++bj) o[buf][mi][bj] = *(const v4u*)(pl + mi * 16 * 1024 + bj * 128); } while (0)
;     __device__ __forceinline__ void operator()(const af4 (&acc)[2][2][4][2], const pg8::Unit& u, int wr, int wc, int fr_, int fq_) const {
;     ...
;         for (int b_ = 0; b_ < 4; ++b_) {
;             const int ai = b_ >> 1, mp = b_ & 1, cur = b_ & 1;
;             if (b_ + 1 < 4) { if (cur == 0) MUL_LOAD(1, b_ + 1); else MUL_LOAD(0, b_ + 1); }
;             int RRb = row0 + ai * 128 + mp * 32; asm volatile("" : "+v"(RRb));
;             bf16* pb = G + (size_t)RRb * 1024 + col0;
; #pragma unroll
;             for (int mi = 0; mi < 2; ++mi)
; #pragma unroll
;                 for (int bj = 0; bj < 2; ++bj) { const af4 v0 = acc[ai][bj][mp * 2 + mi][0], v1 = acc[ai][bj][mp * 2 + mi][1]; const v4u oo = o[cur][mi][bj];
;                     v4u w; w.x = cvtpk(v0[0] * bflo(oo.x), v0[1] * bfhi(oo.x)); w.y = cvtpk(v0[2] * bflo(oo.y), v0[3] * bfhi(oo.y)); w.z = cvtpk(v1[0] * bflo(oo.z), v1[1] * bfhi(oo.z)); w.w = cvtpk(v1[2] * bflo(oo.w), v1[3] * bfhi(oo.w));
;                     *(v4u*)(pb + mi * 16 * 1024 + bj * 128) = w; }
;             asm volatile("" ::: "memory");
;         }
	v_lshlrev_b32_e32 v188, 16, v160
	v_and_b32_e32 v189, 0xffff0000, v160
	v_lshlrev_b32_e32 v160, 16, v161
	v_and_b32_e32 v161, 0xffff0000, v161
	v_lshlrev_b32_e32 v190, 16, v162
	v_and_b32_e32 v191, 0xffff0000, v162
	v_lshlrev_b32_e32 v162, 16, v163
	v_and_b32_e32 v163, 0xffff0000, v163
	v_lshlrev_b32_e32 v192, 16, v164
	v_and_b32_e32 v193, 0xffff0000, v164
	v_lshlrev_b32_e32 v164, 16, v165
	v_and_b32_e32 v165, 0xffff0000, v165
	v_pk_mul_f32 v[122:123], v[122:123], v[160:161]
	v_pk_mul_f32 v[118:119], v[118:119], v[162:163]
	v_pk_mul_f32 v[160:161], v[114:115], v[164:165]
	v_lshlrev_b32_e32 v162, 16, v166
	v_and_b32_e32 v163, 0xffff0000, v166
	v_lshlrev_b32_e32 v164, 16, v167
	v_and_b32_e32 v165, 0xffff0000, v167
	v_lshlrev_b32_e32 v166, 16, v168
	v_and_b32_e32 v167, 0xffff0000, v168
	v_lshlrev_b32_e32 v168, 16, v169
	v_pk_mul_f32 v[108:109], v[108:109], v[162:163]
	v_pk_mul_f32 v[110:111], v[110:111], v[164:165]
	v_pk_mul_f32 v[104:105], v[104:105], v[166:167]
	v_and_b32_e32 v169, 0xffff0000, v169
	v_cvt_pk_bf16_f32 v108, v108, v109
	v_cvt_pk_bf16_f32 v109, v110, v111
	v_cvt_pk_bf16_f32 v110, v104, v105
	v_pk_mul_f32 v[104:105], v[106:107], v[168:169]
	v_lshlrev_b32_e32 v106, 16, v170
	v_and_b32_e32 v107, 0xffff0000, v170
	v_pk_mul_f32 v[100:101], v[100:101], v[106:107]
	v_lshlrev_b32_e32 v106, 16, v171
	v_and_b32_e32 v107, 0xffff0000, v171
	v_pk_mul_f32 v[102:103], v[102:103], v[106:107]
	v_cvt_pk_bf16_f32 v100, v100, v101
	v_cvt_pk_bf16_f32 v101, v102, v103
	v_lshlrev_b32_e32 v102, 16, v172
	v_and_b32_e32 v103, 0xffff0000, v172
	v_lshlrev_b32_e32 v186, 16, v158
	v_and_b32_e32 v187, 0xffff0000, v158
	v_lshlrev_b32_e32 v158, 16, v159
	v_and_b32_e32 v159, 0xffff0000, v159
	v_pk_mul_f32 v[96:97], v[96:97], v[102:103]
	v_pk_mul_f32 v[124:125], v[124:125], v[186:187]
	v_pk_mul_f32 v[126:127], v[126:127], v[158:159]
	v_pk_mul_f32 v[120:121], v[120:121], v[188:189]
	v_cvt_pk_bf16_f32 v102, v96, v97
	v_lshlrev_b32_e32 v96, 16, v173
	v_and_b32_e32 v97, 0xffff0000, v173
	v_pk_mul_f32 v[116:117], v[116:117], v[190:191]
	v_pk_mul_f32 v[158:159], v[112:113], v[192:193]
	v_cvt_pk_bf16_f32 v112, v124, v125
	v_cvt_pk_bf16_f32 v113, v126, v127
	v_cvt_pk_bf16_f32 v114, v120, v121
	v_cvt_pk_bf16_f32 v115, v122, v123
	v_cvt_pk_bf16_f32 v111, v104, v105
	v_add_co_u32_e32 v104, vcc, s37, v184
	v_pk_mul_f32 v[96:97], v[98:99], v[96:97]
	v_cvt_pk_bf16_f32 v116, v116, v117
	v_cvt_pk_bf16_f32 v117, v118, v119
	v_cvt_pk_bf16_f32 v118, v158, v159
	v_cvt_pk_bf16_f32 v119, v160, v161
	global_store_dwordx4 v[184:185], v[112:115], off
	global_store_dwordx4 v[184:185], v[116:119], off offset:256
	v_addc_co_u32_e32 v105, vcc, 0, v185, vcc
	v_cvt_pk_bf16_f32 v103, v96, v97
	v_add_u32_e32 v112, 0x80, v194
	global_store_dwordx4 v[104:105], v[108:111], off
	global_store_dwordx4 v[104:105], v[100:103], off offset:256
	v_mov_b32_e32 v96, v112
	v_lshlrev_b32_e32 v116, 16, v174
	v_ashrrev_i32_e32 v97, 31, v96
	v_lshlrev_b64 v[96:97], 11, v[96:97]
	v_lshl_add_u64 v[96:97], s[2:3], 0, v[96:97]
	v_lshl_add_u64 v[96:97], v[96:97], 0, v[152:153]
	v_and_b32_e32 v117, 0xffff0000, v174
	global_load_dwordx4 v[104:107], v[96:97], off
	global_load_dwordx4 v[108:111], v[96:97], off offset:256
	v_pk_mul_f32 v[92:93], v[92:93], v[116:117]
	v_lshlrev_b32_e32 v116, 16, v175
	v_and_b32_e32 v117, 0xffff0000, v175
	v_pk_mul_f32 v[94:95], v[94:95], v[116:117]
	v_cvt_pk_bf16_f32 v92, v92, v93
	v_cvt_pk_bf16_f32 v93, v94, v95
	v_lshlrev_b32_e32 v94, 16, v176
	v_and_b32_e32 v95, 0xffff0000, v176
	v_pk_mul_f32 v[88:89], v[88:89], v[94:95]
	v_add_co_u32_e32 v96, vcc, s37, v96
	v_cvt_pk_bf16_f32 v94, v88, v89
	v_lshlrev_b32_e32 v88, 16, v177
	v_and_b32_e32 v89, 0xffff0000, v177
	v_pk_mul_f32 v[88:89], v[90:91], v[88:89]
	v_addc_co_u32_e32 v97, vcc, 0, v97, vcc
	v_cvt_pk_bf16_f32 v95, v88, v89
	v_lshlrev_b32_e32 v88, 16, v178
	v_and_b32_e32 v89, 0xffff0000, v178
	v_pk_mul_f32 v[84:85], v[84:85], v[88:89]
	v_lshlrev_b32_e32 v88, 16, v179
	v_and_b32_e32 v89, 0xffff0000, v179
	v_pk_mul_f32 v[86:87], v[86:87], v[88:89]
	v_cvt_pk_bf16_f32 v84, v84, v85
	v_cvt_pk_bf16_f32 v85, v86, v87
	v_lshlrev_b32_e32 v86, 16, v180
	v_and_b32_e32 v87, 0xffff0000, v180
	v_pk_mul_f32 v[76:77], v[76:77], v[86:87]
	global_load_dwordx4 v[100:103], v[96:97], off
	s_nop 0
	global_load_dwordx4 v[96:99], v[96:97], off offset:256
	v_cvt_pk_bf16_f32 v86, v76, v77
	v_lshlrev_b32_e32 v76, 16, v181
	v_and_b32_e32 v77, 0xffff0000, v181
	v_pk_mul_f32 v[76:77], v[78:79], v[76:77]
	v_lshlrev_b32_e32 v78, 16, v133
	v_cvt_pk_bf16_f32 v87, v76, v77
	v_lshlrev_b32_e32 v76, 16, v132
	v_and_b32_e32 v77, 0xffff0000, v132
	v_and_b32_e32 v79, 0xffff0000, v133
	v_pk_mul_f32 v[76:77], v[80:81], v[76:77]
	v_pk_mul_f32 v[78:79], v[82:83], v[78:79]
	v_cvt_pk_bf16_f32 v76, v76, v77
	v_cvt_pk_bf16_f32 v77, v78, v79
	v_lshlrev_b32_e32 v78, 16, v134
	v_and_b32_e32 v79, 0xffff0000, v134
	v_pk_mul_f32 v[72:73], v[72:73], v[78:79]
	v_add_u32_e32 v80, 0xa0, v194
	v_cvt_pk_bf16_f32 v78, v72, v73
	v_lshlrev_b32_e32 v72, 16, v135
	v_and_b32_e32 v73, 0xffff0000, v135
	v_pk_mul_f32 v[72:73], v[74:75], v[72:73]
	v_lshlrev_b32_e32 v74, 16, v128
	v_and_b32_e32 v75, 0xffff0000, v128
	v_pk_mul_f32 v[68:69], v[68:69], v[74:75]
	v_lshlrev_b32_e32 v74, 16, v129
	v_and_b32_e32 v75, 0xffff0000, v129
	v_ashrrev_i32_e32 v183, 31, v182
	v_pk_mul_f32 v[70:71], v[70:71], v[74:75]
	v_lshlrev_b64 v[114:115], 11, v[182:183]
	v_cvt_pk_bf16_f32 v68, v68, v69
	v_cvt_pk_bf16_f32 v69, v70, v71
	v_lshlrev_b32_e32 v70, 16, v130
	v_and_b32_e32 v71, 0xffff0000, v130
	v_lshl_add_u64 v[114:115], s[2:3], 0, v[114:115]
	v_pk_mul_f32 v[64:65], v[64:65], v[70:71]
	v_lshl_add_u64 v[114:115], v[114:115], 0, v[152:153]
	v_cvt_pk_bf16_f32 v70, v64, v65
	v_lshlrev_b32_e32 v64, 16, v131
	v_and_b32_e32 v65, 0xffff0000, v131
	v_cvt_pk_bf16_f32 v79, v72, v73
	v_add_co_u32_e32 v72, vcc, s37, v114
	v_pk_mul_f32 v[64:65], v[66:67], v[64:65]
	s_nop 0
	v_addc_co_u32_e32 v73, vcc, 0, v115, vcc
	v_cvt_pk_bf16_f32 v71, v64, v65
	global_store_dwordx4 v[114:115], v[92:95], off
	global_store_dwordx4 v[114:115], v[84:87], off offset:256
	global_store_dwordx4 v[72:73], v[76:79], off
	global_store_dwordx4 v[72:73], v[68:71], off offset:256
	v_mov_b32_e32 v64, v80
	s_waitcnt vmcnt(7)
; #define PG8_WAIT_V(n) asm volatile("s_waitcnt vmcnt(" #n ")" ::: "memory")
; #define PG8_BAR __builtin_amdgcn_s_barrier()
; __device__ __forceinline__ unsigned cvtpk(float lo, float hi) { f32x2 v = {lo, hi}; bf16x2_t b = __builtin_convertvector(v, bf16x2_t); return __builtin_bit_cast(unsigned, b); }
; __device__ __forceinline__ float bflo(unsigned u) { return __uint_as_float(u << 16); }
; __device__ __forceinline__ float bfhi(unsigned u) { return __uint_as_float(u & 0xffff0000u); }
; #define MUL_LOAD(buf, b_) do { int RRl = row0 + ((b_) >> 1) * 128 + ((b_) & 1) * 32; asm volatile("" : "+v"(RRl)); const bf16* pl = G + (size_t)RRl * 1024 + col0; \
;             _Pragma("unroll") for (int mi = 0; mi < 2; ++mi) _Pragma("unroll") for (int bj = 0; bj < 2; ++bj) o[buf][mi][bj] = *(const v4u*)(pl + mi * 16 * 1024 + bj * 128); } while (0)
; template <class Epi, class Sched, bool ALIGN_EPI = false, bool SP2 = false>
; __device__ __forceinline__ void gemm_phase(PG8_LAS unsigned char* lds, const Gemm g, const Sched& S, const Epi& E, const int wave_s) {
;     ...
;     PG8_WAIT_V(0);
;     if constexpr (!ALIGN_EPI) { if (wr == 0) PG8_BAR; }
;     PG8_BAR;
;     __device__ __forceinline__ void operator()(const af4 (&acc)[2][2][4][2], const pg8::Unit& u, int wr, int wc, int fr_, int fq_) const {
;     ...
;         for (int b_ = 0; b_ < 4; ++b_) {
;             const int ai = b_ >> 1, mp = b_ & 1, cur = b_ & 1;
;             if (b_ + 1 < 4) { if (cur == 0) MUL_LOAD(1, b_ + 1); else MUL_LOAD(0, b_ + 1); }
;             int RRb = row0 + ai * 128 + mp * 32; asm volatile("" : "+v"(RRb));
;             bf16* pb = G + (size_t)RRb * 1024 + col0;
; #pragma unroll
;             for (int mi = 0; mi < 2; ++mi)
; #pragma unroll
;                 for (int bj = 0; bj < 2; ++bj) { const af4 v0 = acc[ai][bj][mp * 2 + mi][0], v1 = acc[ai][bj][mp * 2 + mi][1]; const v4u oo = o[cur][mi][bj];
;                     v4u w; w.x = cvtpk(v0[0] * bflo(oo.x), v0[1] * bfhi(oo.x)); w.y = cvtpk(v0[2] * bflo(oo.y), v0[3] * bfhi(oo.y)); w.z = cvtpk(v1[0] * bflo(oo.z), v1[1] * bfhi(oo.z)); w.w = cvtpk(v1[2] * bflo(oo.w), v1[3] * bfhi(oo.w));
;                     *(v4u*)(pb + mi * 16 * 1024 + bj * 128) = w; }
;             asm volatile("" ::: "memory");
;         }
	v_lshlrev_b32_e32 v84, 16, v104
	v_ashrrev_i32_e32 v65, 31, v64
	v_lshlrev_b64 v[64:65], 11, v[64:65]
	v_lshl_add_u64 v[64:65], s[2:3], 0, v[64:65]
	v_lshl_add_u64 v[64:65], v[64:65], 0, v[152:153]
	global_load_dwordx4 v[68:71], v[64:65], off
	global_load_dwordx4 v[72:75], v[64:65], off offset:256
	v_add_co_u32_e32 v64, vcc, s37, v64
	v_and_b32_e32 v85, 0xffff0000, v104
	s_nop 0
	v_addc_co_u32_e32 v65, vcc, 0, v65, vcc
	global_load_dwordx4 v[76:79], v[64:65], off
	s_nop 0
	global_load_dwordx4 v[64:67], v[64:65], off offset:256
	v_pk_mul_f32 v[60:61], v[60:61], v[84:85]
	v_lshlrev_b32_e32 v84, 16, v105
	v_and_b32_e32 v85, 0xffff0000, v105
	v_pk_mul_f32 v[62:63], v[62:63], v[84:85]
	v_cvt_pk_bf16_f32 v60, v60, v61
	v_cvt_pk_bf16_f32 v61, v62, v63
	v_lshlrev_b32_e32 v62, 16, v106
	v_and_b32_e32 v63, 0xffff0000, v106
	v_pk_mul_f32 v[56:57], v[56:57], v[62:63]
	s_nop 0
	v_cvt_pk_bf16_f32 v62, v56, v57
	v_lshlrev_b32_e32 v56, 16, v107
	v_and_b32_e32 v57, 0xffff0000, v107
	v_pk_mul_f32 v[56:57], v[58:59], v[56:57]
	v_ashrrev_i32_e32 v113, 31, v112
	v_cvt_pk_bf16_f32 v63, v56, v57
	s_waitcnt vmcnt(10)
	v_lshlrev_b32_e32 v56, 16, v108
	v_and_b32_e32 v57, 0xffff0000, v108
	v_pk_mul_f32 v[52:53], v[52:53], v[56:57]
	v_lshlrev_b32_e32 v56, 16, v109
	v_and_b32_e32 v57, 0xffff0000, v109
	v_pk_mul_f32 v[54:55], v[54:55], v[56:57]
	v_cvt_pk_bf16_f32 v52, v52, v53
	v_cvt_pk_bf16_f32 v53, v54, v55
	v_lshlrev_b32_e32 v54, 16, v110
	v_and_b32_e32 v55, 0xffff0000, v110
	v_pk_mul_f32 v[44:45], v[44:45], v[54:55]
	v_lshlrev_b64 v[82:83], 11, v[112:113]
	v_cvt_pk_bf16_f32 v54, v44, v45
	v_lshlrev_b32_e32 v44, 16, v111
	v_and_b32_e32 v45, 0xffff0000, v111
	v_pk_mul_f32 v[44:45], v[46:47], v[44:45]
	s_waitcnt vmcnt(9)
	v_lshlrev_b32_e32 v46, 16, v101
	v_cvt_pk_bf16_f32 v55, v44, v45
	v_lshlrev_b32_e32 v44, 16, v100
	v_and_b32_e32 v45, 0xffff0000, v100
	v_and_b32_e32 v47, 0xffff0000, v101
	v_pk_mul_f32 v[44:45], v[48:49], v[44:45]
	v_pk_mul_f32 v[46:47], v[50:51], v[46:47]
	v_cvt_pk_bf16_f32 v44, v44, v45
	v_cvt_pk_bf16_f32 v45, v46, v47
	v_lshlrev_b32_e32 v46, 16, v102
	v_and_b32_e32 v47, 0xffff0000, v102
	v_pk_mul_f32 v[40:41], v[40:41], v[46:47]
	v_lshl_add_u64 v[82:83], s[2:3], 0, v[82:83]
	v_cvt_pk_bf16_f32 v46, v40, v41
	v_lshlrev_b32_e32 v40, 16, v103
	v_and_b32_e32 v41, 0xffff0000, v103
	v_pk_mul_f32 v[40:41], v[42:43], v[40:41]
	s_waitcnt vmcnt(8)
	v_lshlrev_b32_e32 v42, 16, v96
	v_and_b32_e32 v43, 0xffff0000, v96
	v_pk_mul_f32 v[36:37], v[36:37], v[42:43]
	v_lshlrev_b32_e32 v42, 16, v97
	v_and_b32_e32 v43, 0xffff0000, v97
	v_pk_mul_f32 v[38:39], v[38:39], v[42:43]
	v_cvt_pk_bf16_f32 v36, v36, v37
	v_cvt_pk_bf16_f32 v37, v38, v39
	v_lshlrev_b32_e32 v38, 16, v98
	v_and_b32_e32 v39, 0xffff0000, v98
	v_pk_mul_f32 v[28:29], v[28:29], v[38:39]
	v_lshl_add_u64 v[82:83], v[82:83], 0, v[152:153]
	v_cvt_pk_bf16_f32 v38, v28, v29
	v_lshlrev_b32_e32 v28, 16, v99
	v_and_b32_e32 v29, 0xffff0000, v99
	v_cvt_pk_bf16_f32 v47, v40, v41
	v_add_co_u32_e32 v40, vcc, s37, v82
	v_pk_mul_f32 v[28:29], v[30:31], v[28:29]
	s_nop 0
	v_addc_co_u32_e32 v41, vcc, 0, v83, vcc
	v_cvt_pk_bf16_f32 v39, v28, v29
	global_store_dwordx4 v[82:83], v[60:63], off
	global_store_dwordx4 v[82:83], v[52:55], off offset:256
	global_store_dwordx4 v[40:41], v[44:47], off
	global_store_dwordx4 v[40:41], v[36:39], off offset:256
	s_waitcnt vmcnt(7)
	v_lshlrev_b32_e32 v30, 16, v69
	v_ashrrev_i32_e32 v81, 31, v80
	v_lshlrev_b64 v[28:29], 11, v[80:81]
	v_lshl_add_u64 v[28:29], s[2:3], 0, v[28:29]
	v_lshl_add_u64 v[36:37], v[28:29], 0, v[152:153]
	v_lshlrev_b32_e32 v28, 16, v68
	v_and_b32_e32 v29, 0xffff0000, v68
	v_and_b32_e32 v31, 0xffff0000, v69
	v_pk_mul_f32 v[28:29], v[32:33], v[28:29]
	v_pk_mul_f32 v[30:31], v[34:35], v[30:31]
	v_cvt_pk_bf16_f32 v28, v28, v29
	v_cvt_pk_bf16_f32 v29, v30, v31
	v_lshlrev_b32_e32 v30, 16, v70
	v_and_b32_e32 v31, 0xffff0000, v70
	v_pk_mul_f32 v[24:25], v[24:25], v[30:31]
	s_nop 0
	v_cvt_pk_bf16_f32 v30, v24, v25
	v_lshlrev_b32_e32 v24, 16, v71
	v_and_b32_e32 v25, 0xffff0000, v71
	v_pk_mul_f32 v[24:25], v[26:27], v[24:25]
	s_nop 0
	v_cvt_pk_bf16_f32 v31, v24, v25
	s_waitcnt vmcnt(6)
	v_lshlrev_b32_e32 v24, 16, v72
	v_and_b32_e32 v25, 0xffff0000, v72
	v_pk_mul_f32 v[20:21], v[20:21], v[24:25]
	v_lshlrev_b32_e32 v24, 16, v73
	v_and_b32_e32 v25, 0xffff0000, v73
	v_pk_mul_f32 v[22:23], v[22:23], v[24:25]
	v_cvt_pk_bf16_f32 v20, v20, v21
	v_cvt_pk_bf16_f32 v21, v22, v23
	v_lshlrev_b32_e32 v22, 16, v74
	v_and_b32_e32 v23, 0xffff0000, v74
	v_pk_mul_f32 v[12:13], v[12:13], v[22:23]
	global_store_dwordx4 v[36:37], v[28:31], off
	v_cvt_pk_bf16_f32 v22, v12, v13
	v_lshlrev_b32_e32 v12, 16, v75
	v_and_b32_e32 v13, 0xffff0000, v75
	v_pk_mul_f32 v[12:13], v[14:15], v[12:13]
	s_waitcnt vmcnt(6)
	v_lshlrev_b32_e32 v14, 16, v77
	v_cvt_pk_bf16_f32 v23, v12, v13
	v_lshlrev_b32_e32 v12, 16, v76
	v_and_b32_e32 v13, 0xffff0000, v76
	v_and_b32_e32 v15, 0xffff0000, v77
	v_pk_mul_f32 v[12:13], v[16:17], v[12:13]
	v_pk_mul_f32 v[14:15], v[18:19], v[14:15]
	v_cvt_pk_bf16_f32 v12, v12, v13
	v_cvt_pk_bf16_f32 v13, v14, v15
	v_lshlrev_b32_e32 v14, 16, v78
	v_and_b32_e32 v15, 0xffff0000, v78
	v_pk_mul_f32 v[8:9], v[8:9], v[14:15]
	global_store_dwordx4 v[36:37], v[20:23], off offset:256
	v_cvt_pk_bf16_f32 v14, v8, v9
	v_lshlrev_b32_e32 v8, 16, v79
	v_and_b32_e32 v9, 0xffff0000, v79
	v_pk_mul_f32 v[8:9], v[10:11], v[8:9]
	s_waitcnt vmcnt(6)
	v_lshlrev_b32_e32 v10, 16, v64
	v_and_b32_e32 v11, 0xffff0000, v64
	v_pk_mul_f32 v[4:5], v[4:5], v[10:11]
	v_lshlrev_b32_e32 v10, 16, v65
	v_and_b32_e32 v11, 0xffff0000, v65
	v_pk_mul_f32 v[6:7], v[6:7], v[10:11]
	v_cvt_pk_bf16_f32 v4, v4, v5
	v_cvt_pk_bf16_f32 v5, v6, v7
	v_lshlrev_b32_e32 v6, 16, v66
	v_and_b32_e32 v7, 0xffff0000, v66
	v_pk_mul_f32 v[0:1], v[0:1], v[6:7]
	v_cvt_pk_bf16_f32 v15, v8, v9
	v_cvt_pk_bf16_f32 v6, v0, v1
	v_lshlrev_b32_e32 v0, 16, v67
	v_and_b32_e32 v1, 0xffff0000, v67
	v_add_co_u32_e32 v8, vcc, s37, v36
	v_pk_mul_f32 v[0:1], v[2:3], v[0:1]
	s_nop 0
	v_addc_co_u32_e32 v9, vcc, 0, v37, vcc
	v_cvt_pk_bf16_f32 v7, v0, v1
	global_store_dwordx4 v[8:9], v[12:15], off
	global_store_dwordx4 v[8:9], v[4:7], off offset:256
	s_and_b64 vcc, exec, s[4:5]
	s_cbranch_vccz .LBB0_2774
	s_waitcnt vmcnt(0)
	s_cmpk_gt_u32 s86, 0xff
	s_cbranch_scc1 .LBB0_2785
	s_barrier

; #define PG8_STAGE(bufoff, gbase, voff) do { _Pragma("unroll") for (int _i = 0; _i < 2; ++_i) \
;         __builtin_amdgcn_global_load_lds((const unsigned*)((const char*)(gbase) + (voff)[_i]), (PG8_LAS unsigned*)(lds + (bufoff) + ldsw + _i * 8192), 16, 0, 0); } while (0)
; #define PG8_LDA(dst, b, h) do { _Pragma("unroll") for (int m = 0; m < 4; ++m) _Pragma("unroll") for (int k = 0; k < 2; ++k) dst[m][k] = *(const PG8_LAS bf16x8*)(lds + PG8_SA(b, h) + aoff + m * 2048 + k * 1024); } while (0)
; #define PG8_LDB(dst, b, h) do { _Pragma("unroll") for (int n = 0; n < 2; ++n) _Pragma("unroll") for (int k = 0; k < 2; ++k) dst[n][k] = *(const PG8_LAS bf16x8*)(lds + PG8_SB(b, h) + boff + n * 2048 + k * 1024); } while (0)
; #define PG8_MMA(ai, bj, At, Bt) do { __builtin_amdgcn_s_setprio(1); _Pragma("unroll") for (int m = 0; m < 4; ++m) _Pragma("unroll") for (int n = 0; n < 2; ++n) _Pragma("unroll") for (int k = 0; k < 2; ++k) \
;         acc[ai][bj][m][n] = __builtin_amdgcn_mfma_f32_16x16x32_bf16(Bt[n][k], At[m][k], acc[ai][bj][m][n], 0, 0, 0); __builtin_amdgcn_s_setprio(0); } while (0)
; #define PG8_WAIT_V(n) asm volatile("s_waitcnt vmcnt(" #n ")" ::: "memory")
; #define PG8_WAIT_L(n) asm volatile("s_waitcnt lgkmcnt(" #n ")" ::: "memory")
; template <class Epi, class Sched, bool ALIGN_EPI = false, bool SP2 = false>
; __device__ __forceinline__ void gemm_phase(PG8_LAS unsigned char* lds, const Gemm g, const Sched& S, const Epi& E, const int wave_s) {
;     ...
;             const bool last = (t == nt - 2);
;             const char* a1 = cA + (size_t)(t + 1) * kstep;
;             const char* a2 = last ? nA : cA + (size_t)(t + 2) * kstep; const char* b2 = last ? nB : cB + (size_t)(t + 2) * kstep;
;             const char* a3 = a2 + kstep; const char* b3 = b2 + kstep;
;             if (last && has_next) S.a_ready(nxt);
;             if constexpr (SP2) {
;             PG8_LDB(B0, 0, 0); PG8_LDB(B1, 0, 1); PG8_SCHED; PG8_LDA(At, 0, 0); PG8_STAGE(PG8_SA(1, 1), a1 + hstep, voffA);
;             PG8_WAIT_V(8); PG8_WAIT_L(0); PG8_BAR; PG8_MMA(0, 0, At, B0); PG8_MMA(0, 1, At, B1); PG8_BAR; PG8_SCHED;
;             PG8_LDA(At, 0, 1); PG8_STAGE(PG8_SB(0, 0), b2, voffB); PG8_STAGE(PG8_SB(0, 1), b2 + hstep, voffB); PG8_STAGE(PG8_SA(0, 0), a2, voffA);
;             PG8_WAIT_V(8); PG8_WAIT_L(0); PG8_BAR; PG8_MMA(1, 0, At, B0); PG8_MMA(1, 1, At, B1); PG8_BAR; PG8_SCHED;
.LBB0_2801:
	ds_read_b128 v[128:131], v185
	ds_read_b128 v[132:135], v185 offset:1024
	ds_read_b128 v[136:139], v185 offset:2048
	ds_read_b128 v[140:143], v185 offset:3072
	ds_read_b128 v[144:147], v186
	ds_read_b128 v[148:151], v186 offset:1024
	ds_read_b128 v[152:155], v186 offset:2048
	ds_read_b128 v[156:159], v186 offset:3072
	s_add_u32 s22, s20, 0xfffc0080
	s_addc_u32 s23, s21, -1
	s_cmp_eq_u32 s49, 12
	s_cselect_b32 s25, s13, s23
	s_cselect_b32 s24, s45, s22
	s_cselect_b32 s23, s11, s48
	s_cselect_b32 s22, s46, s47
	v_lshl_add_u64 v[212:213], s[20:21], 0, v[170:171]
	s_add_i32 m0, s19, 0xc000
	ds_read_b128 v[176:179], v187
	ds_read_b128 v[180:183], v187 offset:1024
	ds_read_b128 v[188:191], v187 offset:2048
	ds_read_b128 v[192:195], v187 offset:3072
	ds_read_b128 v[196:199], v187 offset:4096
	ds_read_b128 v[200:203], v187 offset:5120
	ds_read_b128 v[204:207], v187 offset:6144
	ds_read_b128 v[208:211], v187 offset:7168
	global_load_lds_dwordx4 v[212:213], off
	v_lshl_add_u64 v[212:213], s[20:21], 0, v[168:169]
	s_add_i32 m0, s19, 0xe000
	s_nop 0
	global_load_lds_dwordx4 v[212:213], off
	v_lshl_add_u64 v[230:231], s[22:23], 0, v[162:163]
	v_lshl_add_u64 v[232:233], s[22:23], 0, v[166:167]
	v_lshl_add_u64 v[234:235], s[24:25], 0, v[164:165]
	s_waitcnt vmcnt(8)
	s_waitcnt lgkmcnt(0)
	s_barrier
	s_setprio 1
	s_waitcnt lgkmcnt(0)
	v_mfma_f32_16x16x32_bf16 v[124:127], v[128:131], v[176:179], v[124:127]
	v_mfma_f32_16x16x32_bf16 v[120:123], v[136:139], v[176:179], v[120:123]
	v_mfma_f32_16x16x32_bf16 v[112:115], v[128:131], v[188:191], v[112:115]
	v_mfma_f32_16x16x32_bf16 v[104:107], v[136:139], v[188:191], v[104:107]
	v_mfma_f32_16x16x32_bf16 v[92:95], v[128:131], v[196:199], v[92:95]
	v_mfma_f32_16x16x32_bf16 v[88:91], v[136:139], v[196:199], v[88:91]
	v_mfma_f32_16x16x32_bf16 v[80:83], v[128:131], v[204:207], v[80:83]
	v_mfma_f32_16x16x32_bf16 v[72:75], v[136:139], v[204:207], v[72:75]
	v_mfma_f32_16x16x32_bf16 v[124:127], v[132:135], v[180:183], v[124:127]
	v_mfma_f32_16x16x32_bf16 v[120:123], v[140:143], v[180:183], v[120:123]
	v_mfma_f32_16x16x32_bf16 v[112:115], v[132:135], v[192:195], v[112:115]
	v_mfma_f32_16x16x32_bf16 v[104:107], v[140:143], v[192:195], v[104:107]
	v_mfma_f32_16x16x32_bf16 v[92:95], v[132:135], v[200:203], v[92:95]
	v_mfma_f32_16x16x32_bf16 v[88:91], v[140:143], v[200:203], v[88:91]
	v_mfma_f32_16x16x32_bf16 v[80:83], v[132:135], v[208:211], v[80:83]
	v_mfma_f32_16x16x32_bf16 v[72:75], v[140:143], v[208:211], v[72:75]
	s_setprio 0
	s_setprio 1
	v_mfma_f32_16x16x32_bf16 v[116:119], v[144:147], v[176:179], v[116:119]
	v_mfma_f32_16x16x32_bf16 v[108:111], v[152:155], v[176:179], v[108:111]
	v_mfma_f32_16x16x32_bf16 v[100:103], v[144:147], v[188:191], v[100:103]
	v_mfma_f32_16x16x32_bf16 v[96:99], v[152:155], v[188:191], v[96:99]
	v_mfma_f32_16x16x32_bf16 v[84:87], v[144:147], v[196:199], v[84:87]
	v_mfma_f32_16x16x32_bf16 v[76:79], v[152:155], v[196:199], v[76:79]
	v_mfma_f32_16x16x32_bf16 v[68:71], v[144:147], v[204:207], v[68:71]
	v_mfma_f32_16x16x32_bf16 v[64:67], v[152:155], v[204:207], v[64:67]
	v_mfma_f32_16x16x32_bf16 v[116:119], v[148:151], v[180:183], v[116:119]
	v_mfma_f32_16x16x32_bf16 v[108:111], v[156:159], v[180:183], v[108:111]
	v_mfma_f32_16x16x32_bf16 v[100:103], v[148:151], v[192:195], v[100:103]
	v_mfma_f32_16x16x32_bf16 v[96:99], v[156:159], v[192:195], v[96:99]
	v_mfma_f32_16x16x32_bf16 v[84:87], v[148:151], v[200:203], v[84:87]
	v_mfma_f32_16x16x32_bf16 v[76:79], v[156:159], v[200:203], v[76:79]
	v_mfma_f32_16x16x32_bf16 v[68:71], v[148:151], v[208:211], v[68:71]
	v_mfma_f32_16x16x32_bf16 v[64:67], v[156:159], v[208:211], v[64:67]
	s_setprio 0
	s_barrier
	s_add_i32 s50, s42, s33
	s_mov_b32 m0, s50
	ds_read_b128 v[176:179], v187 offset:16384
	ds_read_b128 v[180:183], v187 offset:17408
	ds_read_b128 v[188:191], v187 offset:18432
	ds_read_b128 v[192:195], v187 offset:19456
	ds_read_b128 v[196:199], v187 offset:20480
	ds_read_b128 v[200:203], v187 offset:21504
	ds_read_b128 v[204:207], v187 offset:22528
	ds_read_b128 v[208:211], v187 offset:23552
	global_load_lds_dwordx4 v[230:231], off
	s_add_i32 m0, s50, 0x2000
	s_add_u32 s50, s22, 0x40000
	s_addc_u32 s51, s23, 0
	s_add_i32 s52, s43, s33
	global_load_lds_dwordx4 v[232:233], off
	v_lshl_add_u64 v[216:217], s[50:51], 0, v[162:163]
	s_mov_b32 m0, s52
	s_nop 0
	global_load_lds_dwordx4 v[216:217], off
	v_lshl_add_u64 v[216:217], s[50:51], 0, v[166:167]
	s_add_i32 m0, s52, 0x2000
	s_nop 0
	global_load_lds_dwordx4 v[216:217], off
	v_lshl_add_u64 v[216:217], s[24:25], 0, v[160:161]
	s_mov_b32 m0, s19
	s_nop 0
	global_load_lds_dwordx4 v[216:217], off
	s_mov_b32 m0, s31
	s_nop 0
	global_load_lds_dwordx4 v[234:235], off
	s_waitcnt vmcnt(8)
	s_waitcnt lgkmcnt(0)
	s_barrier
; #define PG8_STAGE(bufoff, gbase, voff) do { _Pragma("unroll") for (int _i = 0; _i < 2; ++_i) \
;         __builtin_amdgcn_global_load_lds((const unsigned*)((const char*)(gbase) + (voff)[_i]), (PG8_LAS unsigned*)(lds + (bufoff) + ldsw + _i * 8192), 16, 0, 0); } while (0)
; #define PG8_LDA(dst, b, h) do { _Pragma("unroll") for (int m = 0; m < 4; ++m) _Pragma("unroll") for (int k = 0; k < 2; ++k) dst[m][k] = *(const PG8_LAS bf16x8*)(lds + PG8_SA(b, h) + aoff + m * 2048 + k * 1024); } while (0)
; #define PG8_LDB(dst, b, h) do { _Pragma("unroll") for (int n = 0; n < 2; ++n) _Pragma("unroll") for (int k = 0; k < 2; ++k) dst[n][k] = *(const PG8_LAS bf16x8*)(lds + PG8_SB(b, h) + boff + n * 2048 + k * 1024); } while (0)
; #define PG8_MMA(ai, bj, At, Bt) do { __builtin_amdgcn_s_setprio(1); _Pragma("unroll") for (int m = 0; m < 4; ++m) _Pragma("unroll") for (int n = 0; n < 2; ++n) _Pragma("unroll") for (int k = 0; k < 2; ++k) \
;         acc[ai][bj][m][n] = __builtin_amdgcn_mfma_f32_16x16x32_bf16(Bt[n][k], At[m][k], acc[ai][bj][m][n], 0, 0, 0); __builtin_amdgcn_s_setprio(0); } while (0)
; #define PG8_WAIT_V(n) asm volatile("s_waitcnt vmcnt(" #n ")" ::: "memory")
; #define PG8_WAIT_L(n) asm volatile("s_waitcnt lgkmcnt(" #n ")" ::: "memory")
; #define PG8_BAR __builtin_amdgcn_s_barrier()
; #define PG8_SCHED __builtin_amdgcn_sched_barrier(0)
; template <class Epi, class Sched, bool ALIGN_EPI = false, bool SP2 = false>
; __device__ __forceinline__ void gemm_phase(PG8_LAS unsigned char* lds, const Gemm g, const Sched& S, const Epi& E, const int wave_s) {
;     ...
;             PG8_WAIT_V(8); PG8_WAIT_L(0); PG8_BAR; PG8_MMA(1, 0, At, B0); PG8_MMA(1, 1, At, B1); PG8_BAR; PG8_SCHED;
;             PG8_LDB(B0, 1, 0); PG8_LDB(B1, 1, 1); PG8_SCHED; PG8_LDA(At, 1, 0); PG8_STAGE(PG8_SA(0, 1), a2 + hstep, voffA);
;             PG8_WAIT_V(8); PG8_WAIT_L(0); PG8_BAR; PG8_MMA(0, 0, At, B0); PG8_MMA(0, 1, At, B1); PG8_BAR; PG8_SCHED;
;             PG8_LDA(At, 1, 1); PG8_STAGE(PG8_SB(1, 0), b3, voffB); PG8_STAGE(PG8_SB(1, 1), b3 + hstep, voffB); PG8_STAGE(PG8_SA(1, 0), a3, voffA);
	s_setprio 1
	s_waitcnt lgkmcnt(0)
	v_mfma_f32_16x16x32_bf16 v[60:63], v[128:131], v[176:179], v[60:63]
	v_mfma_f32_16x16x32_bf16 v[56:59], v[136:139], v[176:179], v[56:59]
	v_mfma_f32_16x16x32_bf16 v[48:51], v[128:131], v[188:191], v[48:51]
	v_mfma_f32_16x16x32_bf16 v[40:43], v[136:139], v[188:191], v[40:43]
	v_mfma_f32_16x16x32_bf16 v[28:31], v[128:131], v[196:199], v[28:31]
	v_mfma_f32_16x16x32_bf16 v[24:27], v[136:139], v[196:199], v[24:27]
	v_mfma_f32_16x16x32_bf16 v[16:19], v[128:131], v[204:207], v[16:19]
	v_mfma_f32_16x16x32_bf16 v[8:11], v[136:139], v[204:207], v[8:11]
	v_mfma_f32_16x16x32_bf16 v[60:63], v[132:135], v[180:183], v[60:63]
	v_mfma_f32_16x16x32_bf16 v[56:59], v[140:143], v[180:183], v[56:59]
	v_mfma_f32_16x16x32_bf16 v[48:51], v[132:135], v[192:195], v[48:51]
	v_mfma_f32_16x16x32_bf16 v[40:43], v[140:143], v[192:195], v[40:43]
	v_mfma_f32_16x16x32_bf16 v[28:31], v[132:135], v[200:203], v[28:31]
	v_mfma_f32_16x16x32_bf16 v[24:27], v[140:143], v[200:203], v[24:27]
	v_mfma_f32_16x16x32_bf16 v[16:19], v[132:135], v[208:211], v[16:19]
	v_mfma_f32_16x16x32_bf16 v[8:11], v[140:143], v[208:211], v[8:11]
	s_setprio 0
	s_setprio 1
	v_mfma_f32_16x16x32_bf16 v[52:55], v[144:147], v[176:179], v[52:55]
	v_mfma_f32_16x16x32_bf16 v[44:47], v[152:155], v[176:179], v[44:47]
	v_mfma_f32_16x16x32_bf16 v[36:39], v[144:147], v[188:191], v[36:39]
	v_mfma_f32_16x16x32_bf16 v[32:35], v[152:155], v[188:191], v[32:35]
	v_mfma_f32_16x16x32_bf16 v[20:23], v[144:147], v[196:199], v[20:23]
	v_mfma_f32_16x16x32_bf16 v[12:15], v[152:155], v[196:199], v[12:15]
	v_mfma_f32_16x16x32_bf16 v[4:7], v[144:147], v[204:207], v[4:7]
	v_mfma_f32_16x16x32_bf16 v[0:3], v[152:155], v[204:207], v[0:3]
	v_mfma_f32_16x16x32_bf16 v[52:55], v[148:151], v[180:183], v[52:55]
	v_mfma_f32_16x16x32_bf16 v[44:47], v[156:159], v[180:183], v[44:47]
	v_mfma_f32_16x16x32_bf16 v[36:39], v[148:151], v[192:195], v[36:39]
	v_mfma_f32_16x16x32_bf16 v[32:35], v[156:159], v[192:195], v[32:35]
	v_mfma_f32_16x16x32_bf16 v[20:23], v[148:151], v[200:203], v[20:23]
	v_mfma_f32_16x16x32_bf16 v[12:15], v[156:159], v[200:203], v[12:15]
	v_mfma_f32_16x16x32_bf16 v[4:7], v[148:151], v[208:211], v[4:7]
	v_mfma_f32_16x16x32_bf16 v[0:3], v[156:159], v[208:211], v[0:3]
	s_setprio 0
	s_barrier
	s_add_i32 s50, 0, 0x18000
	s_add_i32 s51, 0, 0x1c000
	v_add_u32_e32 v140, s50, v184
	v_add_u32_e32 v156, s51, v184
	ds_read_b128 v[128:131], v140
	ds_read_b128 v[132:135], v140 offset:1024
	ds_read_b128 v[136:139], v140 offset:2048
	ds_read_b128 v[140:143], v140 offset:3072
	ds_read_b128 v[144:147], v156
	ds_read_b128 v[148:151], v156 offset:1024
	ds_read_b128 v[152:155], v156 offset:2048
	ds_read_b128 v[156:159], v156 offset:3072
	s_add_u32 s24, s24, 0x40000
	s_addc_u32 s25, s25, 0
	s_mov_b32 m0, s34
	v_lshl_add_u64 v[220:221], s[24:25], 0, v[160:161]
	ds_read_b128 v[176:179], v187 offset:32768
	ds_read_b128 v[180:183], v187 offset:33792
	ds_read_b128 v[188:191], v187 offset:34816
	ds_read_b128 v[192:195], v187 offset:35840
	ds_read_b128 v[196:199], v187 offset:36864
	ds_read_b128 v[200:203], v187 offset:37888
	ds_read_b128 v[204:207], v187 offset:38912
	ds_read_b128 v[208:211], v187 offset:39936
	global_load_lds_dwordx4 v[220:221], off
	v_lshl_add_u64 v[220:221], s[24:25], 0, v[164:165]
	s_mov_b32 m0, s35
	s_nop 0
	global_load_lds_dwordx4 v[220:221], off
	v_lshl_add_u64 v[236:237], v[230:231], 0, s[8:9]
	s_add_u32 s22, s22, 0x40080
	v_lshl_add_u64 v[238:239], v[232:233], 0, s[8:9]
	s_addc_u32 s23, s23, 0
	v_lshl_add_u64 v[240:241], s[22:23], 0, v[162:163]
	v_lshl_add_u64 v[242:243], s[22:23], 0, v[166:167]
	v_lshl_add_u64 v[244:245], v[216:217], 0, s[8:9]
	v_lshl_add_u64 v[246:247], v[234:235], 0, s[8:9]
	s_waitcnt vmcnt(8)
	s_waitcnt lgkmcnt(0)
	s_barrier
	s_setprio 1
	s_waitcnt lgkmcnt(0)
	v_mfma_f32_16x16x32_bf16 v[124:127], v[128:131], v[176:179], v[124:127]
	v_mfma_f32_16x16x32_bf16 v[120:123], v[136:139], v[176:179], v[120:123]
	v_mfma_f32_16x16x32_bf16 v[112:115], v[128:131], v[188:191], v[112:115]
	v_mfma_f32_16x16x32_bf16 v[104:107], v[136:139], v[188:191], v[104:107]
	v_mfma_f32_16x16x32_bf16 v[92:95], v[128:131], v[196:199], v[92:95]
	v_mfma_f32_16x16x32_bf16 v[88:91], v[136:139], v[196:199], v[88:91]
	v_mfma_f32_16x16x32_bf16 v[80:83], v[128:131], v[204:207], v[80:83]
	v_mfma_f32_16x16x32_bf16 v[72:75], v[136:139], v[204:207], v[72:75]
	v_mfma_f32_16x16x32_bf16 v[124:127], v[132:135], v[180:183], v[124:127]
	v_mfma_f32_16x16x32_bf16 v[120:123], v[140:143], v[180:183], v[120:123]
	v_mfma_f32_16x16x32_bf16 v[112:115], v[132:135], v[192:195], v[112:115]
	v_mfma_f32_16x16x32_bf16 v[104:107], v[140:143], v[192:195], v[104:107]
	v_mfma_f32_16x16x32_bf16 v[92:95], v[132:135], v[200:203], v[92:95]
	v_mfma_f32_16x16x32_bf16 v[88:91], v[140:143], v[200:203], v[88:91]
	v_mfma_f32_16x16x32_bf16 v[80:83], v[132:135], v[208:211], v[80:83]
	v_mfma_f32_16x16x32_bf16 v[72:75], v[140:143], v[208:211], v[72:75]
	s_setprio 0
	s_setprio 1
	v_mfma_f32_16x16x32_bf16 v[116:119], v[144:147], v[176:179], v[116:119]
	v_mfma_f32_16x16x32_bf16 v[108:111], v[152:155], v[176:179], v[108:111]
	v_mfma_f32_16x16x32_bf16 v[100:103], v[144:147], v[188:191], v[100:103]
	v_mfma_f32_16x16x32_bf16 v[96:99], v[152:155], v[188:191], v[96:99]
	v_mfma_f32_16x16x32_bf16 v[84:87], v[144:147], v[196:199], v[84:87]
	v_mfma_f32_16x16x32_bf16 v[76:79], v[152:155], v[196:199], v[76:79]
	v_mfma_f32_16x16x32_bf16 v[68:71], v[144:147], v[204:207], v[68:71]
	v_mfma_f32_16x16x32_bf16 v[64:67], v[152:155], v[204:207], v[64:67]
	v_mfma_f32_16x16x32_bf16 v[116:119], v[148:151], v[180:183], v[116:119]
	v_mfma_f32_16x16x32_bf16 v[108:111], v[156:159], v[180:183], v[108:111]
	v_mfma_f32_16x16x32_bf16 v[100:103], v[148:151], v[192:195], v[100:103]
	v_mfma_f32_16x16x32_bf16 v[96:99], v[156:159], v[192:195], v[96:99]
	v_mfma_f32_16x16x32_bf16 v[84:87], v[148:151], v[200:203], v[84:87]
	v_mfma_f32_16x16x32_bf16 v[76:79], v[156:159], v[200:203], v[76:79]
	v_mfma_f32_16x16x32_bf16 v[68:71], v[148:151], v[208:211], v[68:71]
	v_mfma_f32_16x16x32_bf16 v[64:67], v[156:159], v[208:211], v[64:67]
	s_setprio 0
	s_barrier
; #define PG8_STAGE(bufoff, gbase, voff) do { _Pragma("unroll") for (int _i = 0; _i < 2; ++_i) \
;         __builtin_amdgcn_global_load_lds((const unsigned*)((const char*)(gbase) + (voff)[_i]), (PG8_LAS unsigned*)(lds + (bufoff) + ldsw + _i * 8192), 16, 0, 0); } while (0)
; #define PG8_LDA(dst, b, h) do { _Pragma("unroll") for (int m = 0; m < 4; ++m) _Pragma("unroll") for (int k = 0; k < 2; ++k) dst[m][k] = *(const PG8_LAS bf16x8*)(lds + PG8_SA(b, h) + aoff + m * 2048 + k * 1024); } while (0)
; #define PG8_MMA(ai, bj, At, Bt) do { __builtin_amdgcn_s_setprio(1); _Pragma("unroll") for (int m = 0; m < 4; ++m) _Pragma("unroll") for (int n = 0; n < 2; ++n) _Pragma("unroll") for (int k = 0; k < 2; ++k) \
;         acc[ai][bj][m][n] = __builtin_amdgcn_mfma_f32_16x16x32_bf16(Bt[n][k], At[m][k], acc[ai][bj][m][n], 0, 0, 0); __builtin_amdgcn_s_setprio(0); } while (0)
; #define PG8_WAIT_V(n) asm volatile("s_waitcnt vmcnt(" #n ")" ::: "memory")
; #define PG8_WAIT_L(n) asm volatile("s_waitcnt lgkmcnt(" #n ")" ::: "memory")
; #define PG8_BAR __builtin_amdgcn_s_barrier()
; #define PG8_SCHED __builtin_amdgcn_sched_barrier(0)
; __device__ __forceinline__ int lane_id_v() { int l; asm volatile("v_mbcnt_lo_u32_b32 %0, -1, 0\n\tv_mbcnt_hi_u32_b32 %0, -1, %0" : "=v"(l)); return l; }
; template <class Epi, class Sched, bool ALIGN_EPI = false, bool SP2 = false>
; __device__ __forceinline__ void gemm_phase(PG8_LAS unsigned char* lds, const Gemm g, const Sched& S, const Epi& E, const int wave_s) {
;     ...
;             PG8_LDA(At, 1, 1); PG8_STAGE(PG8_SB(1, 0), b3, voffB); PG8_STAGE(PG8_SB(1, 1), b3 + hstep, voffB); PG8_STAGE(PG8_SA(1, 0), a3, voffA);
;             PG8_WAIT_V(8); PG8_WAIT_L(0); PG8_BAR; PG8_MMA(1, 0, At, B0); PG8_MMA(1, 1, At, B1); PG8_BAR; PG8_SCHED;
;     __device__ __forceinline__ void operator()(const af4 (&acc)[2][2][4][2], const pg8::Unit& u, int wr, int wc, int fr_, int fq_) const {
;         const int ln_ = lane_id_v(); const int fr = ln_ & 15, fq = ln_ >> 4;
;         const int row0 = u.pm * 256 + wr * 64 + fr, col0 = u.pn * 256 + wc * 32 + 8 * fq;
;         v4u o[2][2][2], yv[2][2][2];
;     ...
;         MA_LOAD(0, 0);
; #pragma unroll
;         for (int b_ = 0; b_ < 4; ++b_) {
;             const int ai = b_ >> 1, mp = b_ & 1, cur = b_ & 1;
;             if (b_ + 1 < 4) { if (cur == 0) MA_LOAD(1, b_ + 1); else MA_LOAD(0, b_ + 1); }
	s_add_i32 s24, s50, s33
	s_mov_b32 m0, s24
	ds_read_b128 v[176:179], v187 offset:49152
	ds_read_b128 v[180:183], v187 offset:50176
	ds_read_b128 v[188:191], v187 offset:51200
	ds_read_b128 v[192:195], v187 offset:52224
	ds_read_b128 v[196:199], v187 offset:53248
	ds_read_b128 v[200:203], v187 offset:54272
	ds_read_b128 v[204:207], v187 offset:55296
	ds_read_b128 v[208:211], v187 offset:56320
	global_load_lds_dwordx4 v[236:237], off
	s_add_i32 m0, s24, 0x2000
	s_add_i32 s24, s51, s33
	global_load_lds_dwordx4 v[238:239], off
	s_mov_b32 m0, s24
	s_nop 0
	global_load_lds_dwordx4 v[240:241], off
	s_add_i32 m0, s24, 0x2000
	s_nop 0
	global_load_lds_dwordx4 v[242:243], off
	s_mov_b32 m0, s37
	s_nop 0
	global_load_lds_dwordx4 v[244:245], off
	s_mov_b32 m0, s38
	s_nop 0
	global_load_lds_dwordx4 v[246:247], off
	s_waitcnt vmcnt(8)
	s_waitcnt lgkmcnt(0)
	s_barrier
	s_setprio 1
	s_waitcnt lgkmcnt(0)
	v_mfma_f32_16x16x32_bf16 v[60:63], v[128:131], v[176:179], v[60:63]
	v_mfma_f32_16x16x32_bf16 v[56:59], v[136:139], v[176:179], v[56:59]
	v_mfma_f32_16x16x32_bf16 v[48:51], v[128:131], v[188:191], v[48:51]
	v_mfma_f32_16x16x32_bf16 v[40:43], v[136:139], v[188:191], v[40:43]
	v_mfma_f32_16x16x32_bf16 v[28:31], v[128:131], v[196:199], v[28:31]
	v_mfma_f32_16x16x32_bf16 v[24:27], v[136:139], v[196:199], v[24:27]
	v_mfma_f32_16x16x32_bf16 v[16:19], v[128:131], v[204:207], v[16:19]
	v_mfma_f32_16x16x32_bf16 v[8:11], v[136:139], v[204:207], v[8:11]
	v_mfma_f32_16x16x32_bf16 v[60:63], v[132:135], v[180:183], v[60:63]
	v_mfma_f32_16x16x32_bf16 v[56:59], v[140:143], v[180:183], v[56:59]
	v_mfma_f32_16x16x32_bf16 v[48:51], v[132:135], v[192:195], v[48:51]
	v_mfma_f32_16x16x32_bf16 v[40:43], v[140:143], v[192:195], v[40:43]
	v_mfma_f32_16x16x32_bf16 v[28:31], v[132:135], v[200:203], v[28:31]
	v_mfma_f32_16x16x32_bf16 v[24:27], v[140:143], v[200:203], v[24:27]
	v_mfma_f32_16x16x32_bf16 v[16:19], v[132:135], v[208:211], v[16:19]
	v_mfma_f32_16x16x32_bf16 v[8:11], v[140:143], v[208:211], v[8:11]
	s_setprio 0
	s_setprio 1
	v_mfma_f32_16x16x32_bf16 v[52:55], v[144:147], v[176:179], v[52:55]
	v_mfma_f32_16x16x32_bf16 v[44:47], v[152:155], v[176:179], v[44:47]
	v_mfma_f32_16x16x32_bf16 v[36:39], v[144:147], v[188:191], v[36:39]
	v_mfma_f32_16x16x32_bf16 v[32:35], v[152:155], v[188:191], v[32:35]
	v_mfma_f32_16x16x32_bf16 v[20:23], v[144:147], v[196:199], v[20:23]
	v_mfma_f32_16x16x32_bf16 v[12:15], v[152:155], v[196:199], v[12:15]
	v_mfma_f32_16x16x32_bf16 v[4:7], v[144:147], v[204:207], v[4:7]
	v_mfma_f32_16x16x32_bf16 v[0:3], v[152:155], v[204:207], v[0:3]
	v_mfma_f32_16x16x32_bf16 v[52:55], v[148:151], v[180:183], v[52:55]
	v_mfma_f32_16x16x32_bf16 v[44:47], v[156:159], v[180:183], v[44:47]
	v_mfma_f32_16x16x32_bf16 v[36:39], v[148:151], v[192:195], v[36:39]
	v_mfma_f32_16x16x32_bf16 v[32:35], v[156:159], v[192:195], v[32:35]
	v_mfma_f32_16x16x32_bf16 v[20:23], v[148:151], v[200:203], v[20:23]
	v_mfma_f32_16x16x32_bf16 v[12:15], v[156:159], v[200:203], v[12:15]
	v_mfma_f32_16x16x32_bf16 v[4:7], v[148:151], v[208:211], v[4:7]
	v_mfma_f32_16x16x32_bf16 v[0:3], v[156:159], v[208:211], v[0:3]
	s_setprio 0
	s_barrier
	s_add_i32 s49, s49, 2
	s_add_u32 s47, s47, 0x100
	s_addc_u32 s48, s48, 0
	s_add_u32 s20, s20, 0x100
	s_addc_u32 s21, s21, 0
	s_cmp_gt_u32 s49, 13
	s_cbranch_scc0 .LBB0_2801
	s_lshl_b32 s11, s18, 8
	v_mbcnt_lo_u32_b32 v128, -1, 0
	v_mbcnt_hi_u32_b32 v128, -1, v128
	s_add_i32 s11, s11, s87
	v_and_or_b32 v183, v128, 15, s11
	s_lshl_b32 s11, s44, 8
	v_ashrrev_i32_e32 v128, 1, v128
	s_or_b32 s11, s11, s79
	v_and_b32_e32 v128, -8, v128
	v_add_u32_e32 v178, s11, v128
	v_mov_b32_e32 v128, v183
	v_ashrrev_i32_e32 v179, 31, v178
	v_ashrrev_i32_e32 v129, 31, v128
	v_lshlrev_b64 v[128:129], 10, v[128:129]
	v_lshl_add_u64 v[128:129], v[128:129], 0, v[178:179]
	v_lshlrev_b64 v[128:129], 1, v[128:129]
	v_lshl_add_u64 v[130:131], s[2:3], 0, v[128:129]
	global_load_dwordx4 v[188:191], v[130:131], off
	v_lshl_add_u64 v[128:129], s[0:1], 0, v[128:129]
	global_load_dwordx4 v[192:195], v[128:129], off
	global_load_dwordx4 v[196:199], v[130:131], off offset:256
	global_load_dwordx4 v[200:203], v[128:129], off offset:256
	v_add_co_u32_e32 v128, vcc, s39, v128
	v_or_b32_e32 v180, 32, v183
	s_nop 0
	v_addc_co_u32_e32 v129, vcc, 0, v129, vcc
	v_add_co_u32_e32 v130, vcc, s39, v130
	v_mov_b32_e32 v132, v180
	s_nop 0
	v_addc_co_u32_e32 v131, vcc, 0, v131, vcc
	global_load_dwordx4 v[204:207], v[128:129], off
	global_load_dwordx4 v[208:211], v[128:129], off offset:256
	global_load_dwordx4 v[212:215], v[130:131], off
	global_load_dwordx4 v[216:219], v[130:131], off offset:256
	v_mov_b32_e32 v220, v183
	v_ashrrev_i32_e32 v133, 31, v132
	v_lshlrev_b64 v[128:129], 10, v[132:133]
	v_lshl_add_u64 v[128:129], v[128:129], 0, v[178:179]
	v_lshlrev_b64 v[128:129], 1, v[128:129]
	v_lshl_add_u64 v[130:131], s[0:1], 0, v[128:129]
	v_lshl_add_u64 v[128:129], s[2:3], 0, v[128:129]
	global_load_dwordx4 v[152:155], v[130:131], off
	global_load_dwordx4 v[144:147], v[130:131], off offset:256
	global_load_dwordx4 v[156:159], v[128:129], off
	global_load_dwordx4 v[148:151], v[128:129], off offset:256
	v_add_co_u32_e32 v130, vcc, s39, v130
	v_lshlrev_b64 v[176:177], 1, v[178:179]
	s_nop 0
	v_addc_co_u32_e32 v131, vcc, 0, v131, vcc
	v_add_co_u32_e32 v132, vcc, s39, v128
	v_add_u32_e32 v182, 0x80, v183
	s_nop 0
	v_addc_co_u32_e32 v133, vcc, 0, v129, vcc
	global_load_dwordx4 v[136:139], v[130:131], off
	s_nop 0
	global_load_dwordx4 v[128:131], v[130:131], off offset:256
	s_nop 0
	global_load_dwordx4 v[140:143], v[132:133], off
	s_nop 0
	global_load_dwordx4 v[132:135], v[132:133], off offset:256
	s_mov_b32 s44, s10
	v_ashrrev_i32_e32 v221, 31, v220
	v_lshlrev_b64 v[220:221], 11, v[220:221]
	v_lshl_add_u64 v[220:221], s[0:1], 0, v[220:221]
	v_lshl_add_u64 v[220:221], v[220:221], 0, v[176:177]
	s_mov_b32 s18, s12
	s_mov_b64 s[20:21], s[16:17]
	s_mov_b64 s[22:23], s[14:15]
	s_waitcnt vmcnt(0)
; __device__ __forceinline__ unsigned cvtpk(float lo, float hi) { f32x2 v = {lo, hi}; bf16x2_t b = __builtin_convertvector(v, bf16x2_t); return __builtin_bit_cast(unsigned, b); }
; __device__ __forceinline__ float bflo(unsigned u) { return __uint_as_float(u << 16); }
; __device__ __forceinline__ float bfhi(unsigned u) { return __uint_as_float(u & 0xffff0000u); }
;     __device__ __forceinline__ void operator()(const af4 (&acc)[2][2][4][2], const pg8::Unit& u, int wr, int wc, int fr_, int fq_) const {
;     ...
;         for (int b_ = 0; b_ < 4; ++b_) {
;             const int ai = b_ >> 1, mp = b_ & 1, cur = b_ & 1;
;             if (b_ + 1 < 4) { if (cur == 0) MA_LOAD(1, b_ + 1); else MA_LOAD(0, b_ + 1); }
;             int RRb = row0 + ai * 128 + mp * 32; asm volatile("" : "+v"(RRb));
;             const size_t ob = (size_t)RRb * 1024 + col0;
; #pragma unroll
;             for (int mi = 0; mi < 2; ++mi)
; #pragma unroll
;                 for (int bj = 0; bj < 2; ++bj) { const af4 v0 = acc[ai][bj][mp * 2 + mi][0], v1 = acc[ai][bj][mp * 2 + mi][1]; const v4u oo = o[cur][mi][bj], y = yv[cur][mi][bj];
;                     v4u w; w.x = cvtpk(bflo(y.x) + v0[0] * bflo(oo.x), bfhi(y.x) + v0[1] * bfhi(oo.x)); w.y = cvtpk(bflo(y.y) + v0[2] * bflo(oo.y), bfhi(y.y) + v0[3] * bfhi(oo.y));
;                     w.z = cvtpk(bflo(y.z) + v1[0] * bflo(oo.z), bfhi(y.z) + v1[1] * bfhi(oo.z)); w.w = cvtpk(bflo(y.w) + v1[2] * bflo(oo.w), bfhi(y.w) + v1[3] * bfhi(oo.w));
;                     *(v4u*)(G + ob + mi * 16 * 1024 + bj * 128) = w; }
;             asm volatile("" ::: "memory");
;         }
	v_lshlrev_b32_e32 v224, 16, v192
	v_lshlrev_b32_e32 v222, 16, v188
	v_and_b32_e32 v223, 0xffff0000, v188
	v_and_b32_e32 v225, 0xffff0000, v192
	v_lshlrev_b32_e32 v188, 16, v189
	v_and_b32_e32 v189, 0xffff0000, v189
	v_lshlrev_b32_e32 v192, 16, v193
	v_and_b32_e32 v193, 0xffff0000, v193
	v_lshlrev_b32_e32 v226, 16, v190
	v_and_b32_e32 v227, 0xffff0000, v190
	v_lshlrev_b32_e32 v228, 16, v194
	v_and_b32_e32 v229, 0xffff0000, v194
	v_lshlrev_b32_e32 v190, 16, v191
	v_and_b32_e32 v191, 0xffff0000, v191
	v_lshlrev_b32_e32 v194, 16, v195
	v_and_b32_e32 v195, 0xffff0000, v195
	v_pk_fma_f32 v[124:125], v[124:125], v[224:225], v[222:223]
	v_pk_fma_f32 v[126:127], v[126:127], v[192:193], v[188:189]
	v_pk_fma_f32 v[188:189], v[120:121], v[228:229], v[226:227]
	v_pk_fma_f32 v[190:191], v[122:123], v[194:195], v[190:191]
	v_cvt_pk_bf16_f32 v120, v124, v125
	v_cvt_pk_bf16_f32 v121, v126, v127
	v_cvt_pk_bf16_f32 v122, v188, v189
	v_cvt_pk_bf16_f32 v123, v190, v191
	v_lshlrev_b32_e32 v230, 16, v196
	v_and_b32_e32 v231, 0xffff0000, v196
	v_lshlrev_b32_e32 v232, 16, v200
	global_store_dwordx4 v[220:221], v[120:123], off
	v_and_b32_e32 v233, 0xffff0000, v200
	v_pk_fma_f32 v[116:117], v[116:117], v[232:233], v[230:231]
	v_lshlrev_b32_e32 v120, 16, v197
	v_and_b32_e32 v121, 0xffff0000, v197
	v_lshlrev_b32_e32 v122, 16, v201
	v_and_b32_e32 v123, 0xffff0000, v201
	v_pk_fma_f32 v[118:119], v[118:119], v[122:123], v[120:121]
	v_cvt_pk_bf16_f32 v116, v116, v117
	v_cvt_pk_bf16_f32 v117, v118, v119
	v_lshlrev_b32_e32 v118, 16, v198
	v_and_b32_e32 v119, 0xffff0000, v198
	v_lshlrev_b32_e32 v120, 16, v202
	v_and_b32_e32 v121, 0xffff0000, v202
	v_pk_fma_f32 v[108:109], v[108:109], v[120:121], v[118:119]
	v_lshlrev_b32_e32 v120, 16, v203
	v_cvt_pk_bf16_f32 v118, v108, v109
	v_lshlrev_b32_e32 v108, 16, v199
	v_and_b32_e32 v109, 0xffff0000, v199
	v_and_b32_e32 v121, 0xffff0000, v203
	v_pk_fma_f32 v[108:109], v[110:111], v[120:121], v[108:109]
	v_lshlrev_b32_e32 v110, 16, v204
	v_cvt_pk_bf16_f32 v119, v108, v109
	v_lshlrev_b32_e32 v108, 16, v212
	v_and_b32_e32 v109, 0xffff0000, v212
	v_and_b32_e32 v111, 0xffff0000, v204
	v_pk_fma_f32 v[108:109], v[112:113], v[110:111], v[108:109]
	v_lshlrev_b32_e32 v110, 16, v213
	v_and_b32_e32 v111, 0xffff0000, v213
	v_lshlrev_b32_e32 v112, 16, v205
	v_and_b32_e32 v113, 0xffff0000, v205
	v_pk_fma_f32 v[110:111], v[114:115], v[112:113], v[110:111]
	v_cvt_pk_bf16_f32 v108, v108, v109
	v_cvt_pk_bf16_f32 v109, v110, v111
	v_lshlrev_b32_e32 v110, 16, v214
	v_and_b32_e32 v111, 0xffff0000, v214
	v_lshlrev_b32_e32 v112, 16, v206
	v_and_b32_e32 v113, 0xffff0000, v206
	v_pk_fma_f32 v[104:105], v[104:105], v[112:113], v[110:111]
	v_lshlrev_b32_e32 v112, 16, v207
	v_cvt_pk_bf16_f32 v110, v104, v105
	v_lshlrev_b32_e32 v104, 16, v215
	v_and_b32_e32 v105, 0xffff0000, v215
	v_and_b32_e32 v113, 0xffff0000, v207
	v_pk_fma_f32 v[104:105], v[106:107], v[112:113], v[104:105]
	v_lshlrev_b32_e32 v106, 16, v216
	v_cvt_pk_bf16_f32 v111, v104, v105
	v_add_co_u32_e32 v104, vcc, s39, v220
	v_and_b32_e32 v107, 0xffff0000, v216
	s_nop 0
	v_addc_co_u32_e32 v105, vcc, 0, v221, vcc
	global_store_dwordx4 v[104:105], v[108:111], off
	global_store_dwordx4 v[220:221], v[116:119], off offset:256
	v_lshlrev_b32_e32 v188, 16, v156
	v_lshlrev_b32_e32 v108, 16, v208
	v_and_b32_e32 v109, 0xffff0000, v208
	v_pk_fma_f32 v[100:101], v[100:101], v[108:109], v[106:107]
	v_lshlrev_b32_e32 v106, 16, v217
	v_and_b32_e32 v107, 0xffff0000, v217
	v_lshlrev_b32_e32 v108, 16, v209
	v_and_b32_e32 v109, 0xffff0000, v209
	v_pk_fma_f32 v[102:103], v[102:103], v[108:109], v[106:107]
	v_cvt_pk_bf16_f32 v100, v100, v101
	v_cvt_pk_bf16_f32 v101, v102, v103
	v_lshlrev_b32_e32 v102, 16, v218
	v_and_b32_e32 v103, 0xffff0000, v218
	v_lshlrev_b32_e32 v106, 16, v210
	v_and_b32_e32 v107, 0xffff0000, v210
	v_pk_fma_f32 v[96:97], v[96:97], v[106:107], v[102:103]
	v_lshlrev_b32_e32 v106, 16, v211
	v_cvt_pk_bf16_f32 v102, v96, v97
	v_lshlrev_b32_e32 v96, 16, v219
	v_and_b32_e32 v97, 0xffff0000, v219
	v_and_b32_e32 v107, 0xffff0000, v211
	v_pk_fma_f32 v[96:97], v[98:99], v[106:107], v[96:97]
	v_and_b32_e32 v189, 0xffff0000, v156
	v_cvt_pk_bf16_f32 v103, v96, v97
	global_store_dwordx4 v[104:105], v[100:103], off offset:256
	v_mov_b32_e32 v96, v182
	v_lshlrev_b32_e32 v190, 16, v152
	v_ashrrev_i32_e32 v97, 31, v96
	v_lshlrev_b64 v[96:97], 10, v[96:97]
	v_lshl_add_u64 v[96:97], v[96:97], 0, v[178:179]
	v_lshlrev_b64 v[96:97], 1, v[96:97]
	v_lshl_add_u64 v[98:99], s[0:1], 0, v[96:97]
	v_lshl_add_u64 v[96:97], s[2:3], 0, v[96:97]
	global_load_dwordx4 v[120:123], v[98:99], off
	global_load_dwordx4 v[112:115], v[98:99], off offset:256
	global_load_dwordx4 v[124:127], v[96:97], off
	global_load_dwordx4 v[116:119], v[96:97], off offset:256
	v_add_co_u32_e32 v98, vcc, s39, v98
	v_and_b32_e32 v191, 0xffff0000, v152
	v_lshlrev_b32_e32 v156, 16, v157
	v_and_b32_e32 v157, 0xffff0000, v157
	v_lshlrev_b32_e32 v152, 16, v153
	v_and_b32_e32 v153, 0xffff0000, v153
	v_addc_co_u32_e32 v99, vcc, 0, v99, vcc
	v_pk_fma_f32 v[92:93], v[92:93], v[190:191], v[188:189]
	v_pk_fma_f32 v[94:95], v[94:95], v[152:153], v[156:157]
	v_add_co_u32_e32 v100, vcc, s39, v96
	v_cvt_pk_bf16_f32 v92, v92, v93
	v_cvt_pk_bf16_f32 v93, v94, v95
	v_lshlrev_b32_e32 v94, 16, v158
	v_and_b32_e32 v95, 0xffff0000, v158
	v_lshlrev_b32_e32 v152, 16, v154
	v_and_b32_e32 v153, 0xffff0000, v154
	v_addc_co_u32_e32 v101, vcc, 0, v97, vcc
	v_pk_fma_f32 v[88:89], v[88:89], v[152:153], v[94:95]
	global_load_dwordx4 v[104:107], v[98:99], off
	s_nop 0
	global_load_dwordx4 v[96:99], v[98:99], off offset:256
	s_nop 0
	global_load_dwordx4 v[108:111], v[100:101], off
	s_nop 0
; __device__ __forceinline__ unsigned cvtpk(float lo, float hi) { f32x2 v = {lo, hi}; bf16x2_t b = __builtin_convertvector(v, bf16x2_t); return __builtin_bit_cast(unsigned, b); }
; __device__ __forceinline__ float bflo(unsigned u) { return __uint_as_float(u << 16); }
; __device__ __forceinline__ float bfhi(unsigned u) { return __uint_as_float(u & 0xffff0000u); }
;     __device__ __forceinline__ void operator()(const af4 (&acc)[2][2][4][2], const pg8::Unit& u, int wr, int wc, int fr_, int fq_) const {
;     ...
;         for (int b_ = 0; b_ < 4; ++b_) {
;             const int ai = b_ >> 1, mp = b_ & 1, cur = b_ & 1;
;             if (b_ + 1 < 4) { if (cur == 0) MA_LOAD(1, b_ + 1); else MA_LOAD(0, b_ + 1); }
;             int RRb = row0 + ai * 128 + mp * 32; asm volatile("" : "+v"(RRb));
;             const size_t ob = (size_t)RRb * 1024 + col0;
; #pragma unroll
;             for (int mi = 0; mi < 2; ++mi)
; #pragma unroll
;                 for (int bj = 0; bj < 2; ++bj) { const af4 v0 = acc[ai][bj][mp * 2 + mi][0], v1 = acc[ai][bj][mp * 2 + mi][1]; const v4u oo = o[cur][mi][bj], y = yv[cur][mi][bj];
;                     v4u w; w.x = cvtpk(bflo(y.x) + v0[0] * bflo(oo.x), bfhi(y.x) + v0[1] * bfhi(oo.x)); w.y = cvtpk(bflo(y.y) + v0[2] * bflo(oo.y), bfhi(y.y) + v0[3] * bfhi(oo.y));
;                     w.z = cvtpk(bflo(y.z) + v1[0] * bflo(oo.z), bfhi(y.z) + v1[1] * bfhi(oo.z)); w.w = cvtpk(bflo(y.w) + v1[2] * bflo(oo.w), bfhi(y.w) + v1[3] * bfhi(oo.w));
;                     *(v4u*)(G + ob + mi * 16 * 1024 + bj * 128) = w; }
;             asm volatile("" ::: "memory");
;         }
	global_load_dwordx4 v[100:103], v[100:101], off offset:256
	v_cvt_pk_bf16_f32 v94, v88, v89
	v_ashrrev_i32_e32 v181, 31, v180
	v_lshlrev_b32_e32 v88, 16, v159
	v_and_b32_e32 v89, 0xffff0000, v159
	v_lshlrev_b32_e32 v152, 16, v155
	v_and_b32_e32 v153, 0xffff0000, v155
	v_lshlrev_b64 v[180:181], 11, v[180:181]
	v_pk_fma_f32 v[88:89], v[90:91], v[152:153], v[88:89]
	v_lshlrev_b32_e32 v90, 16, v148
	v_cvt_pk_bf16_f32 v95, v88, v89
	v_lshl_add_u64 v[88:89], s[0:1], 0, v[180:181]
	v_lshl_add_u64 v[88:89], v[88:89], 0, v[176:177]
	global_store_dwordx4 v[88:89], v[92:95], off
	v_and_b32_e32 v91, 0xffff0000, v148
	s_nop 0
	v_lshlrev_b32_e32 v92, 16, v144
	v_and_b32_e32 v93, 0xffff0000, v144
	v_pk_fma_f32 v[84:85], v[84:85], v[92:93], v[90:91]
	v_lshlrev_b32_e32 v90, 16, v149
	v_and_b32_e32 v91, 0xffff0000, v149
	v_lshlrev_b32_e32 v92, 16, v145
	v_and_b32_e32 v93, 0xffff0000, v145
	v_pk_fma_f32 v[86:87], v[86:87], v[92:93], v[90:91]
	v_cvt_pk_bf16_f32 v84, v84, v85
	v_cvt_pk_bf16_f32 v85, v86, v87
	v_lshlrev_b32_e32 v86, 16, v150
	v_and_b32_e32 v87, 0xffff0000, v150
	v_lshlrev_b32_e32 v90, 16, v146
	v_and_b32_e32 v91, 0xffff0000, v146
	v_pk_fma_f32 v[76:77], v[76:77], v[90:91], v[86:87]
	v_lshlrev_b32_e32 v90, 16, v147
	v_cvt_pk_bf16_f32 v86, v76, v77
	v_lshlrev_b32_e32 v76, 16, v151
	v_and_b32_e32 v77, 0xffff0000, v151
	v_and_b32_e32 v91, 0xffff0000, v147
	v_pk_fma_f32 v[76:77], v[78:79], v[90:91], v[76:77]
	v_lshlrev_b32_e32 v78, 16, v136
	v_cvt_pk_bf16_f32 v87, v76, v77
	v_lshlrev_b32_e32 v76, 16, v140
	v_and_b32_e32 v77, 0xffff0000, v140
	v_and_b32_e32 v79, 0xffff0000, v136
	v_pk_fma_f32 v[76:77], v[80:81], v[78:79], v[76:77]
	v_lshlrev_b32_e32 v78, 16, v141
	v_and_b32_e32 v79, 0xffff0000, v141
	v_lshlrev_b32_e32 v80, 16, v137
	v_and_b32_e32 v81, 0xffff0000, v137
	v_pk_fma_f32 v[78:79], v[82:83], v[80:81], v[78:79]
	v_cvt_pk_bf16_f32 v76, v76, v77
	v_cvt_pk_bf16_f32 v77, v78, v79
	v_lshlrev_b32_e32 v78, 16, v142
	v_and_b32_e32 v79, 0xffff0000, v142
	v_lshlrev_b32_e32 v80, 16, v138
	v_and_b32_e32 v81, 0xffff0000, v138
	v_pk_fma_f32 v[72:73], v[72:73], v[80:81], v[78:79]
	v_lshlrev_b32_e32 v80, 16, v139
	v_cvt_pk_bf16_f32 v78, v72, v73
	v_lshlrev_b32_e32 v72, 16, v143
	v_and_b32_e32 v73, 0xffff0000, v143
	v_and_b32_e32 v81, 0xffff0000, v139
	v_pk_fma_f32 v[72:73], v[74:75], v[80:81], v[72:73]
	v_lshlrev_b32_e32 v74, 16, v132
	v_cvt_pk_bf16_f32 v79, v72, v73
	v_add_co_u32_e32 v72, vcc, s39, v88
	v_and_b32_e32 v75, 0xffff0000, v132
	s_nop 0
	v_addc_co_u32_e32 v73, vcc, 0, v89, vcc
	global_store_dwordx4 v[72:73], v[76:79], off
	global_store_dwordx4 v[88:89], v[84:87], off offset:256
	s_waitcnt vmcnt(8)
	v_lshlrev_b32_e32 v132, 16, v124
	v_lshlrev_b32_e32 v76, 16, v128
	v_and_b32_e32 v77, 0xffff0000, v128
	v_pk_fma_f32 v[68:69], v[68:69], v[76:77], v[74:75]
	v_lshlrev_b32_e32 v74, 16, v133
	v_and_b32_e32 v75, 0xffff0000, v133
	v_lshlrev_b32_e32 v76, 16, v129
	v_and_b32_e32 v77, 0xffff0000, v129
	v_pk_fma_f32 v[70:71], v[70:71], v[76:77], v[74:75]
	v_cvt_pk_bf16_f32 v68, v68, v69
	v_cvt_pk_bf16_f32 v69, v70, v71
	v_lshlrev_b32_e32 v70, 16, v134
	v_and_b32_e32 v71, 0xffff0000, v134
	v_lshlrev_b32_e32 v74, 16, v130
	v_and_b32_e32 v75, 0xffff0000, v130
	v_pk_fma_f32 v[64:65], v[64:65], v[74:75], v[70:71]
	v_lshlrev_b32_e32 v74, 16, v131
	v_cvt_pk_bf16_f32 v70, v64, v65
	v_lshlrev_b32_e32 v64, 16, v135
	v_and_b32_e32 v65, 0xffff0000, v135
	v_and_b32_e32 v75, 0xffff0000, v131
	v_pk_fma_f32 v[64:65], v[66:67], v[74:75], v[64:65]
	v_add_u32_e32 v128, 0xa0, v183
	v_cvt_pk_bf16_f32 v71, v64, v65
	global_store_dwordx4 v[72:73], v[68:71], off offset:256
	v_mov_b32_e32 v64, v128
	v_and_b32_e32 v133, 0xffff0000, v124
	v_ashrrev_i32_e32 v65, 31, v64
	v_lshlrev_b64 v[64:65], 10, v[64:65]
	v_lshl_add_u64 v[64:65], v[64:65], 0, v[178:179]
	v_lshlrev_b64 v[64:65], 1, v[64:65]
	v_lshl_add_u64 v[66:67], s[0:1], 0, v[64:65]
	v_lshl_add_u64 v[64:65], s[2:3], 0, v[64:65]
	global_load_dwordx4 v[88:91], v[66:67], off
	global_load_dwordx4 v[80:83], v[66:67], off offset:256
	global_load_dwordx4 v[92:95], v[64:65], off
	global_load_dwordx4 v[84:87], v[64:65], off offset:256
	v_add_co_u32_e32 v66, vcc, s39, v66
	v_lshlrev_b32_e32 v134, 16, v120
	s_nop 0
	v_addc_co_u32_e32 v67, vcc, 0, v67, vcc
	v_add_co_u32_e32 v68, vcc, s39, v64
	v_and_b32_e32 v135, 0xffff0000, v120
	s_nop 0
	v_addc_co_u32_e32 v69, vcc, 0, v65, vcc
	global_load_dwordx4 v[72:75], v[66:67], off
	s_nop 0
	global_load_dwordx4 v[64:67], v[66:67], off offset:256
	s_nop 0
	global_load_dwordx4 v[76:79], v[68:69], off
	s_nop 0
	global_load_dwordx4 v[68:71], v[68:69], off offset:256
	v_lshlrev_b32_e32 v124, 16, v125
	v_and_b32_e32 v125, 0xffff0000, v125
	v_lshlrev_b32_e32 v120, 16, v121
	v_and_b32_e32 v121, 0xffff0000, v121
	v_pk_fma_f32 v[60:61], v[60:61], v[134:135], v[132:133]
	v_pk_fma_f32 v[62:63], v[62:63], v[120:121], v[124:125]
	v_cvt_pk_bf16_f32 v60, v60, v61
	v_cvt_pk_bf16_f32 v61, v62, v63
	v_lshlrev_b32_e32 v62, 16, v126
	v_and_b32_e32 v63, 0xffff0000, v126
	v_lshlrev_b32_e32 v120, 16, v122
	v_and_b32_e32 v121, 0xffff0000, v122
	v_pk_fma_f32 v[56:57], v[56:57], v[120:121], v[62:63]
	v_lshlrev_b32_e32 v120, 16, v123
	v_ashrrev_i32_e32 v183, 31, v182
	v_cvt_pk_bf16_f32 v62, v56, v57
	v_lshlrev_b32_e32 v56, 16, v127
	v_and_b32_e32 v57, 0xffff0000, v127
	v_and_b32_e32 v121, 0xffff0000, v123
	v_lshlrev_b64 v[130:131], 11, v[182:183]
	v_pk_fma_f32 v[56:57], v[58:59], v[120:121], v[56:57]
	s_waitcnt vmcnt(16)
; __device__ __forceinline__ unsigned cvtpk(float lo, float hi) { f32x2 v = {lo, hi}; bf16x2_t b = __builtin_convertvector(v, bf16x2_t); return __builtin_bit_cast(unsigned, b); }
; __device__ __forceinline__ float bflo(unsigned u) { return __uint_as_float(u << 16); }
; __device__ __forceinline__ float bfhi(unsigned u) { return __uint_as_float(u & 0xffff0000u); }
;     __device__ __forceinline__ void operator()(const af4 (&acc)[2][2][4][2], const pg8::Unit& u, int wr, int wc, int fr_, int fq_) const {
;     ...
;         for (int b_ = 0; b_ < 4; ++b_) {
;             const int ai = b_ >> 1, mp = b_ & 1, cur = b_ & 1;
;             if (b_ + 1 < 4) { if (cur == 0) MA_LOAD(1, b_ + 1); else MA_LOAD(0, b_ + 1); }
;             int RRb = row0 + ai * 128 + mp * 32; asm volatile("" : "+v"(RRb));
;             const size_t ob = (size_t)RRb * 1024 + col0;
; #pragma unroll
;             for (int mi = 0; mi < 2; ++mi)
; #pragma unroll
;                 for (int bj = 0; bj < 2; ++bj) { const af4 v0 = acc[ai][bj][mp * 2 + mi][0], v1 = acc[ai][bj][mp * 2 + mi][1]; const v4u oo = o[cur][mi][bj], y = yv[cur][mi][bj];
;                     v4u w; w.x = cvtpk(bflo(y.x) + v0[0] * bflo(oo.x), bfhi(y.x) + v0[1] * bfhi(oo.x)); w.y = cvtpk(bflo(y.y) + v0[2] * bflo(oo.y), bfhi(y.y) + v0[3] * bfhi(oo.y));
;                     w.z = cvtpk(bflo(y.z) + v1[0] * bflo(oo.z), bfhi(y.z) + v1[1] * bfhi(oo.z)); w.w = cvtpk(bflo(y.w) + v1[2] * bflo(oo.w), bfhi(y.w) + v1[3] * bfhi(oo.w));
;                     *(v4u*)(G + ob + mi * 16 * 1024 + bj * 128) = w; }
;             asm volatile("" ::: "memory");
;         }
	v_lshlrev_b32_e32 v58, 16, v116
	v_cvt_pk_bf16_f32 v63, v56, v57
	v_lshl_add_u64 v[56:57], s[0:1], 0, v[130:131]
	v_lshl_add_u64 v[56:57], v[56:57], 0, v[176:177]
	global_store_dwordx4 v[56:57], v[60:63], off
	v_and_b32_e32 v59, 0xffff0000, v116
	s_nop 0
	v_lshlrev_b32_e32 v60, 16, v112
	v_and_b32_e32 v61, 0xffff0000, v112
	v_pk_fma_f32 v[52:53], v[52:53], v[60:61], v[58:59]
	v_lshlrev_b32_e32 v58, 16, v117
	v_and_b32_e32 v59, 0xffff0000, v117
	v_lshlrev_b32_e32 v60, 16, v113
	v_and_b32_e32 v61, 0xffff0000, v113
	v_pk_fma_f32 v[54:55], v[54:55], v[60:61], v[58:59]
	v_cvt_pk_bf16_f32 v52, v52, v53
	v_cvt_pk_bf16_f32 v53, v54, v55
	v_lshlrev_b32_e32 v54, 16, v118
	v_and_b32_e32 v55, 0xffff0000, v118
	v_lshlrev_b32_e32 v58, 16, v114
	v_and_b32_e32 v59, 0xffff0000, v114
	v_pk_fma_f32 v[44:45], v[44:45], v[58:59], v[54:55]
	v_lshlrev_b32_e32 v58, 16, v115
	v_cvt_pk_bf16_f32 v54, v44, v45
	v_lshlrev_b32_e32 v44, 16, v119
	v_and_b32_e32 v45, 0xffff0000, v119
	v_and_b32_e32 v59, 0xffff0000, v115
	v_pk_fma_f32 v[44:45], v[46:47], v[58:59], v[44:45]
	s_waitcnt vmcnt(16)
	v_lshlrev_b32_e32 v46, 16, v104
	v_cvt_pk_bf16_f32 v55, v44, v45
	s_waitcnt vmcnt(14)
	v_lshlrev_b32_e32 v44, 16, v108
	v_and_b32_e32 v45, 0xffff0000, v108
	v_and_b32_e32 v47, 0xffff0000, v104
	v_pk_fma_f32 v[44:45], v[48:49], v[46:47], v[44:45]
	v_lshlrev_b32_e32 v46, 16, v109
	v_and_b32_e32 v47, 0xffff0000, v109
	v_lshlrev_b32_e32 v48, 16, v105
	v_and_b32_e32 v49, 0xffff0000, v105
	v_pk_fma_f32 v[46:47], v[50:51], v[48:49], v[46:47]
	v_cvt_pk_bf16_f32 v44, v44, v45
	v_cvt_pk_bf16_f32 v45, v46, v47
	v_lshlrev_b32_e32 v46, 16, v110
	v_and_b32_e32 v47, 0xffff0000, v110
	v_lshlrev_b32_e32 v48, 16, v106
	v_and_b32_e32 v49, 0xffff0000, v106
	v_pk_fma_f32 v[40:41], v[40:41], v[48:49], v[46:47]
	v_lshlrev_b32_e32 v48, 16, v107
	v_cvt_pk_bf16_f32 v46, v40, v41
	v_lshlrev_b32_e32 v40, 16, v111
	v_and_b32_e32 v41, 0xffff0000, v111
	v_and_b32_e32 v49, 0xffff0000, v107
	v_pk_fma_f32 v[40:41], v[42:43], v[48:49], v[40:41]
	s_waitcnt vmcnt(13)
	v_lshlrev_b32_e32 v42, 16, v100
	v_cvt_pk_bf16_f32 v47, v40, v41
	v_add_co_u32_e32 v40, vcc, s39, v56
	v_and_b32_e32 v43, 0xffff0000, v100
	s_nop 0
	v_addc_co_u32_e32 v41, vcc, 0, v57, vcc
	global_store_dwordx4 v[40:41], v[44:47], off
	global_store_dwordx4 v[56:57], v[52:55], off offset:256
	s_nop 0
	v_lshlrev_b32_e32 v44, 16, v96
	v_and_b32_e32 v45, 0xffff0000, v96
	v_pk_fma_f32 v[36:37], v[36:37], v[44:45], v[42:43]
	v_lshlrev_b32_e32 v42, 16, v101
	v_and_b32_e32 v43, 0xffff0000, v101
	v_lshlrev_b32_e32 v44, 16, v97
	v_and_b32_e32 v45, 0xffff0000, v97
	v_pk_fma_f32 v[38:39], v[38:39], v[44:45], v[42:43]
	v_cvt_pk_bf16_f32 v36, v36, v37
	v_cvt_pk_bf16_f32 v37, v38, v39
	v_lshlrev_b32_e32 v38, 16, v102
	v_and_b32_e32 v39, 0xffff0000, v102
	v_lshlrev_b32_e32 v42, 16, v98
	v_and_b32_e32 v43, 0xffff0000, v98
	v_pk_fma_f32 v[32:33], v[32:33], v[42:43], v[38:39]
	v_lshlrev_b32_e32 v42, 16, v99
	v_cvt_pk_bf16_f32 v38, v32, v33
	v_lshlrev_b32_e32 v32, 16, v103
	v_and_b32_e32 v33, 0xffff0000, v103
	v_and_b32_e32 v43, 0xffff0000, v99
	v_pk_fma_f32 v[32:33], v[34:35], v[42:43], v[32:33]
	s_waitcnt vmcnt(8)
	v_lshlrev_b32_e32 v34, 16, v92
	v_cvt_pk_bf16_f32 v39, v32, v33
	global_store_dwordx4 v[40:41], v[36:39], off offset:256
	v_and_b32_e32 v35, 0xffff0000, v92
	s_nop 0
	v_lshlrev_b32_e32 v36, 16, v88
	v_and_b32_e32 v37, 0xffff0000, v88
	v_pk_fma_f32 v[28:29], v[28:29], v[36:37], v[34:35]
	v_lshlrev_b32_e32 v34, 16, v93
	v_and_b32_e32 v35, 0xffff0000, v93
	v_lshlrev_b32_e32 v36, 16, v89
	v_and_b32_e32 v37, 0xffff0000, v89
	v_pk_fma_f32 v[30:31], v[30:31], v[36:37], v[34:35]
	v_cvt_pk_bf16_f32 v28, v28, v29
	v_cvt_pk_bf16_f32 v29, v30, v31
	v_lshlrev_b32_e32 v30, 16, v94
	v_and_b32_e32 v31, 0xffff0000, v94
	v_lshlrev_b32_e32 v34, 16, v90
	v_and_b32_e32 v35, 0xffff0000, v90
	v_pk_fma_f32 v[24:25], v[24:25], v[34:35], v[30:31]
	v_ashrrev_i32_e32 v129, 31, v128
	v_cvt_pk_bf16_f32 v30, v24, v25
	v_lshlrev_b32_e32 v24, 16, v95
	v_and_b32_e32 v25, 0xffff0000, v95
	v_lshlrev_b32_e32 v34, 16, v91
	v_and_b32_e32 v35, 0xffff0000, v91
	v_lshlrev_b64 v[32:33], 11, v[128:129]
	v_pk_fma_f32 v[24:25], v[26:27], v[34:35], v[24:25]
	s_waitcnt vmcnt(8)
; #define PG8_WAIT_V(n) asm volatile("s_waitcnt vmcnt(" #n ")" ::: "memory")
; #define PG8_BAR __builtin_amdgcn_s_barrier()
; __device__ __forceinline__ unsigned cvtpk(float lo, float hi) { f32x2 v = {lo, hi}; bf16x2_t b = __builtin_convertvector(v, bf16x2_t); return __builtin_bit_cast(unsigned, b); }
; __device__ __forceinline__ float bflo(unsigned u) { return __uint_as_float(u << 16); }
; __device__ __forceinline__ float bfhi(unsigned u) { return __uint_as_float(u & 0xffff0000u); }
; template <class Epi, class Sched, bool ALIGN_EPI = false, bool SP2 = false>
; __device__ __forceinline__ void gemm_phase(PG8_LAS unsigned char* lds, const Gemm g, const Sched& S, const Epi& E, const int wave_s) {
;     ...
;     PG8_WAIT_V(0);
;     if constexpr (!ALIGN_EPI) { if (wr == 0) PG8_BAR; }
;     PG8_BAR;
;     __device__ __forceinline__ void operator()(const af4 (&acc)[2][2][4][2], const pg8::Unit& u, int wr, int wc, int fr_, int fq_) const {
;     ...
;         for (int b_ = 0; b_ < 4; ++b_) {
;             const int ai = b_ >> 1, mp = b_ & 1, cur = b_ & 1;
;             if (b_ + 1 < 4) { if (cur == 0) MA_LOAD(1, b_ + 1); else MA_LOAD(0, b_ + 1); }
;             int RRb = row0 + ai * 128 + mp * 32; asm volatile("" : "+v"(RRb));
;             const size_t ob = (size_t)RRb * 1024 + col0;
; #pragma unroll
;             for (int mi = 0; mi < 2; ++mi)
; #pragma unroll
;                 for (int bj = 0; bj < 2; ++bj) { const af4 v0 = acc[ai][bj][mp * 2 + mi][0], v1 = acc[ai][bj][mp * 2 + mi][1]; const v4u oo = o[cur][mi][bj], y = yv[cur][mi][bj];
;                     v4u w; w.x = cvtpk(bflo(y.x) + v0[0] * bflo(oo.x), bfhi(y.x) + v0[1] * bfhi(oo.x)); w.y = cvtpk(bflo(y.y) + v0[2] * bflo(oo.y), bfhi(y.y) + v0[3] * bfhi(oo.y));
;                     w.z = cvtpk(bflo(y.z) + v1[0] * bflo(oo.z), bfhi(y.z) + v1[1] * bfhi(oo.z)); w.w = cvtpk(bflo(y.w) + v1[2] * bflo(oo.w), bfhi(y.w) + v1[3] * bfhi(oo.w));
;                     *(v4u*)(G + ob + mi * 16 * 1024 + bj * 128) = w; }
;             asm volatile("" ::: "memory");
;         }
	v_lshlrev_b32_e32 v26, 16, v84
	v_cvt_pk_bf16_f32 v31, v24, v25
	v_lshl_add_u64 v[24:25], s[0:1], 0, v[32:33]
	v_lshl_add_u64 v[24:25], v[24:25], 0, v[176:177]
	global_store_dwordx4 v[24:25], v[28:31], off
	v_and_b32_e32 v27, 0xffff0000, v84
	s_nop 0
	v_lshlrev_b32_e32 v28, 16, v80
	v_and_b32_e32 v29, 0xffff0000, v80
	v_pk_fma_f32 v[20:21], v[20:21], v[28:29], v[26:27]
	v_lshlrev_b32_e32 v26, 16, v85
	v_and_b32_e32 v27, 0xffff0000, v85
	v_lshlrev_b32_e32 v28, 16, v81
	v_and_b32_e32 v29, 0xffff0000, v81
	v_pk_fma_f32 v[22:23], v[22:23], v[28:29], v[26:27]
	v_cvt_pk_bf16_f32 v20, v20, v21
	v_cvt_pk_bf16_f32 v21, v22, v23
	v_lshlrev_b32_e32 v22, 16, v86
	v_and_b32_e32 v23, 0xffff0000, v86
	v_lshlrev_b32_e32 v26, 16, v82
	v_and_b32_e32 v27, 0xffff0000, v82
	v_pk_fma_f32 v[12:13], v[12:13], v[26:27], v[22:23]
	v_lshlrev_b32_e32 v26, 16, v83
	v_cvt_pk_bf16_f32 v22, v12, v13
	v_lshlrev_b32_e32 v12, 16, v87
	v_and_b32_e32 v13, 0xffff0000, v87
	v_and_b32_e32 v27, 0xffff0000, v83
	v_pk_fma_f32 v[12:13], v[14:15], v[26:27], v[12:13]
	s_waitcnt vmcnt(8)
	v_lshlrev_b32_e32 v14, 16, v72
	v_cvt_pk_bf16_f32 v23, v12, v13
	s_waitcnt vmcnt(6)
	v_lshlrev_b32_e32 v12, 16, v76
	v_and_b32_e32 v13, 0xffff0000, v76
	v_and_b32_e32 v15, 0xffff0000, v72
	v_pk_fma_f32 v[12:13], v[16:17], v[14:15], v[12:13]
	v_lshlrev_b32_e32 v14, 16, v77
	v_and_b32_e32 v15, 0xffff0000, v77
	v_lshlrev_b32_e32 v16, 16, v73
	v_and_b32_e32 v17, 0xffff0000, v73
	v_pk_fma_f32 v[14:15], v[18:19], v[16:17], v[14:15]
	v_cvt_pk_bf16_f32 v12, v12, v13
	v_cvt_pk_bf16_f32 v13, v14, v15
	v_lshlrev_b32_e32 v14, 16, v78
	v_and_b32_e32 v15, 0xffff0000, v78
	v_lshlrev_b32_e32 v16, 16, v74
	v_and_b32_e32 v17, 0xffff0000, v74
	v_pk_fma_f32 v[8:9], v[8:9], v[16:17], v[14:15]
	v_lshlrev_b32_e32 v16, 16, v75
	v_cvt_pk_bf16_f32 v14, v8, v9
	v_lshlrev_b32_e32 v8, 16, v79
	v_and_b32_e32 v9, 0xffff0000, v79
	v_and_b32_e32 v17, 0xffff0000, v75
	v_pk_fma_f32 v[8:9], v[10:11], v[16:17], v[8:9]
	s_waitcnt vmcnt(5)
	v_lshlrev_b32_e32 v10, 16, v68
	v_cvt_pk_bf16_f32 v15, v8, v9
	v_add_co_u32_e32 v8, vcc, s39, v24
	v_and_b32_e32 v11, 0xffff0000, v68
	s_nop 0
	v_addc_co_u32_e32 v9, vcc, 0, v25, vcc
	global_store_dwordx4 v[8:9], v[12:15], off
	global_store_dwordx4 v[24:25], v[20:23], off offset:256
	s_and_b64 vcc, exec, s[6:7]
	v_lshlrev_b32_e32 v12, 16, v64
	v_and_b32_e32 v13, 0xffff0000, v64
	v_pk_fma_f32 v[4:5], v[4:5], v[12:13], v[10:11]
	v_lshlrev_b32_e32 v10, 16, v69
	v_and_b32_e32 v11, 0xffff0000, v69
	v_lshlrev_b32_e32 v12, 16, v65
	v_and_b32_e32 v13, 0xffff0000, v65
	v_pk_fma_f32 v[6:7], v[6:7], v[12:13], v[10:11]
	v_cvt_pk_bf16_f32 v4, v4, v5
	v_cvt_pk_bf16_f32 v5, v6, v7
	v_lshlrev_b32_e32 v6, 16, v70
	v_and_b32_e32 v7, 0xffff0000, v70
	v_lshlrev_b32_e32 v10, 16, v66
	v_and_b32_e32 v11, 0xffff0000, v66
	v_pk_fma_f32 v[0:1], v[0:1], v[10:11], v[6:7]
	v_lshlrev_b32_e32 v10, 16, v67
	v_cvt_pk_bf16_f32 v6, v0, v1
	v_lshlrev_b32_e32 v0, 16, v71
	v_and_b32_e32 v1, 0xffff0000, v71
	v_and_b32_e32 v11, 0xffff0000, v67
	v_pk_fma_f32 v[0:1], v[2:3], v[10:11], v[0:1]
	s_nop 0
	v_cvt_pk_bf16_f32 v7, v0, v1
	global_store_dwordx4 v[8:9], v[4:7], off offset:256
	s_cbranch_vccz .LBB0_2794
	s_waitcnt vmcnt(0)
	s_cmpk_gt_u32 s86, 0xff
	s_cbranch_scc1 .LBB0_2805
	s_barrier

; #define PG8_STAGE(bufoff, gbase, voff) do { _Pragma("unroll") for (int _i = 0; _i < 2; ++_i) \
;         __builtin_amdgcn_global_load_lds((const unsigned*)((const char*)(gbase) + (voff)[_i]), (PG8_LAS unsigned*)(lds + (bufoff) + ldsw + _i * 8192), 16, 0, 0); } while (0)
; #define PG8_LDA(dst, b, h) do { _Pragma("unroll") for (int m = 0; m < 4; ++m) _Pragma("unroll") for (int k = 0; k < 2; ++k) dst[m][k] = *(const PG8_LAS bf16x8*)(lds + PG8_SA(b, h) + aoff + m * 2048 + k * 1024); } while (0)
; #define PG8_LDB(dst, b, h) do { _Pragma("unroll") for (int n = 0; n < 2; ++n) _Pragma("unroll") for (int k = 0; k < 2; ++k) dst[n][k] = *(const PG8_LAS bf16x8*)(lds + PG8_SB(b, h) + boff + n * 2048 + k * 1024); } while (0)
; #define PG8_MMA(ai, bj, At, Bt) do { __builtin_amdgcn_s_setprio(1); _Pragma("unroll") for (int m = 0; m < 4; ++m) _Pragma("unroll") for (int n = 0; n < 2; ++n) _Pragma("unroll") for (int k = 0; k < 2; ++k) \
;         acc[ai][bj][m][n] = __builtin_amdgcn_mfma_f32_16x16x32_bf16(Bt[n][k], At[m][k], acc[ai][bj][m][n], 0, 0, 0); __builtin_amdgcn_s_setprio(0); } while (0)
; #define PG8_WAIT_V(n) asm volatile("s_waitcnt vmcnt(" #n ")" ::: "memory")
; #define PG8_WAIT_L(n) asm volatile("s_waitcnt lgkmcnt(" #n ")" ::: "memory")
; template <class Epi, class Sched, bool ALIGN_EPI = false, bool SP2 = false>
; __device__ __forceinline__ void gemm_phase(PG8_LAS unsigned char* lds, const Gemm g, const Sched& S, const Epi& E, const int wave_s) {
;     ...
;             const bool last = (t == nt - 2);
;             const char* a1 = cA + (size_t)(t + 1) * kstep;
;             const char* a2 = last ? nA : cA + (size_t)(t + 2) * kstep; const char* b2 = last ? nB : cB + (size_t)(t + 2) * kstep;
;             const char* a3 = a2 + kstep; const char* b3 = b2 + kstep;
;             if (last && has_next) S.a_ready(nxt);
;             if constexpr (SP2) {
;             PG8_LDB(B0, 0, 0); PG8_LDB(B1, 0, 1); PG8_SCHED; PG8_LDA(At, 0, 0); PG8_STAGE(PG8_SA(1, 1), a1 + hstep, voffA);
;             PG8_WAIT_V(8); PG8_WAIT_L(0); PG8_BAR; PG8_MMA(0, 0, At, B0); PG8_MMA(0, 1, At, B1); PG8_BAR; PG8_SCHED;
;             PG8_LDA(At, 0, 1); PG8_STAGE(PG8_SB(0, 0), b2, voffB); PG8_STAGE(PG8_SB(0, 1), b2 + hstep, voffB); PG8_STAGE(PG8_SA(0, 0), a2, voffA);
;             PG8_WAIT_V(8); PG8_WAIT_L(0); PG8_BAR; PG8_MMA(1, 0, At, B0); PG8_MMA(1, 1, At, B1); PG8_BAR; PG8_SCHED;
.LBB0_2876:
	ds_read_b128 v[128:131], v195
	ds_read_b128 v[132:135], v195 offset:1024
	ds_read_b128 v[136:139], v195 offset:2048
	ds_read_b128 v[140:143], v195 offset:3072
	ds_read_b128 v[160:163], v196
	ds_read_b128 v[164:167], v196 offset:1024
	ds_read_b128 v[168:171], v196 offset:2048
	ds_read_b128 v[172:175], v196 offset:3072
	s_add_u32 s30, s28, 0xfffc0080
	s_addc_u32 s31, s29, -1
	s_cmp_eq_u32 s63, 12
	s_cselect_b32 s35, s23, s31
	s_cselect_b32 s34, s36, s30
	s_cselect_b32 s31, s21, s62
	s_cselect_b32 s30, s37, s61
	v_lshl_add_u64 v[156:157], s[28:29], 0, v[154:155]
	s_add_i32 m0, s43, 0xc000
	ds_read_b128 v[176:179], v197
	ds_read_b128 v[180:183], v197 offset:1024
	ds_read_b128 v[184:187], v197 offset:2048
	ds_read_b128 v[188:191], v197 offset:3072
	ds_read_b128 v[198:201], v197 offset:4096
	ds_read_b128 v[202:205], v197 offset:5120
	ds_read_b128 v[206:209], v197 offset:6144
	ds_read_b128 v[210:213], v197 offset:7168
	global_load_lds_dwordx4 v[156:157], off
	v_lshl_add_u64 v[156:157], s[28:29], 0, v[152:153]
	s_add_i32 m0, s43, 0xe000
	s_nop 0
	global_load_lds_dwordx4 v[156:157], off
	v_lshl_add_u64 v[230:231], s[30:31], 0, v[146:147]
	v_lshl_add_u64 v[232:233], s[30:31], 0, v[150:151]
	v_lshl_add_u64 v[234:235], s[34:35], 0, v[148:149]
	s_waitcnt vmcnt(8)
	s_waitcnt lgkmcnt(0)
	s_barrier
	s_setprio 1
	s_waitcnt lgkmcnt(0)
	v_mfma_f32_16x16x32_bf16 v[124:127], v[128:131], v[176:179], v[124:127]
	v_mfma_f32_16x16x32_bf16 v[120:123], v[136:139], v[176:179], v[120:123]
	v_mfma_f32_16x16x32_bf16 v[112:115], v[128:131], v[184:187], v[112:115]
	v_mfma_f32_16x16x32_bf16 v[104:107], v[136:139], v[184:187], v[104:107]
	v_mfma_f32_16x16x32_bf16 v[92:95], v[128:131], v[198:201], v[92:95]
	v_mfma_f32_16x16x32_bf16 v[88:91], v[136:139], v[198:201], v[88:91]
	v_mfma_f32_16x16x32_bf16 v[80:83], v[128:131], v[206:209], v[80:83]
	v_mfma_f32_16x16x32_bf16 v[72:75], v[136:139], v[206:209], v[72:75]
	v_mfma_f32_16x16x32_bf16 v[124:127], v[132:135], v[180:183], v[124:127]
	v_mfma_f32_16x16x32_bf16 v[120:123], v[140:143], v[180:183], v[120:123]
	v_mfma_f32_16x16x32_bf16 v[112:115], v[132:135], v[188:191], v[112:115]
	v_mfma_f32_16x16x32_bf16 v[104:107], v[140:143], v[188:191], v[104:107]
	v_mfma_f32_16x16x32_bf16 v[92:95], v[132:135], v[202:205], v[92:95]
	v_mfma_f32_16x16x32_bf16 v[88:91], v[140:143], v[202:205], v[88:91]
	v_mfma_f32_16x16x32_bf16 v[80:83], v[132:135], v[210:213], v[80:83]
	v_mfma_f32_16x16x32_bf16 v[72:75], v[140:143], v[210:213], v[72:75]
	s_setprio 0
	s_setprio 1
	v_mfma_f32_16x16x32_bf16 v[116:119], v[160:163], v[176:179], v[116:119]
	v_mfma_f32_16x16x32_bf16 v[108:111], v[168:171], v[176:179], v[108:111]
	v_mfma_f32_16x16x32_bf16 v[100:103], v[160:163], v[184:187], v[100:103]
	v_mfma_f32_16x16x32_bf16 v[96:99], v[168:171], v[184:187], v[96:99]
	v_mfma_f32_16x16x32_bf16 v[84:87], v[160:163], v[198:201], v[84:87]
	v_mfma_f32_16x16x32_bf16 v[76:79], v[168:171], v[198:201], v[76:79]
	v_mfma_f32_16x16x32_bf16 v[68:71], v[160:163], v[206:209], v[68:71]
	v_mfma_f32_16x16x32_bf16 v[64:67], v[168:171], v[206:209], v[64:67]
	v_mfma_f32_16x16x32_bf16 v[116:119], v[164:167], v[180:183], v[116:119]
	v_mfma_f32_16x16x32_bf16 v[108:111], v[172:175], v[180:183], v[108:111]
	v_mfma_f32_16x16x32_bf16 v[100:103], v[164:167], v[188:191], v[100:103]
	v_mfma_f32_16x16x32_bf16 v[96:99], v[172:175], v[188:191], v[96:99]
	v_mfma_f32_16x16x32_bf16 v[84:87], v[164:167], v[202:205], v[84:87]
	v_mfma_f32_16x16x32_bf16 v[76:79], v[172:175], v[202:205], v[76:79]
	v_mfma_f32_16x16x32_bf16 v[68:71], v[164:167], v[210:213], v[68:71]
	v_mfma_f32_16x16x32_bf16 v[64:67], v[172:175], v[210:213], v[64:67]
	s_setprio 0
	s_barrier
	s_add_i32 s64, s57, s33
	s_mov_b32 m0, s64
	ds_read_b128 v[176:179], v197 offset:16384
	ds_read_b128 v[180:183], v197 offset:17408
	ds_read_b128 v[184:187], v197 offset:18432
	ds_read_b128 v[188:191], v197 offset:19456
	ds_read_b128 v[198:201], v197 offset:20480
	ds_read_b128 v[202:205], v197 offset:21504
	ds_read_b128 v[206:209], v197 offset:22528
	ds_read_b128 v[210:213], v197 offset:23552
	global_load_lds_dwordx4 v[230:231], off
	s_add_i32 m0, s64, 0x2000
	s_add_u32 s64, s30, 0x40000
	s_addc_u32 s65, s31, 0
	s_add_i32 s66, s58, s33
	global_load_lds_dwordx4 v[232:233], off
	v_lshl_add_u64 v[214:215], s[64:65], 0, v[146:147]
	s_mov_b32 m0, s66
	s_nop 0
	global_load_lds_dwordx4 v[214:215], off
	v_lshl_add_u64 v[214:215], s[64:65], 0, v[150:151]
	s_add_i32 m0, s66, 0x2000
	s_nop 0
	global_load_lds_dwordx4 v[214:215], off
	v_lshl_add_u64 v[214:215], s[34:35], 0, v[144:145]
	s_mov_b32 m0, s43
	s_nop 0
	global_load_lds_dwordx4 v[214:215], off
	s_mov_b32 m0, s44
	s_nop 0
	global_load_lds_dwordx4 v[234:235], off
	s_waitcnt vmcnt(8)
	s_waitcnt lgkmcnt(0)
	s_barrier
; #define PG8_STAGE(bufoff, gbase, voff) do { _Pragma("unroll") for (int _i = 0; _i < 2; ++_i) \
;         __builtin_amdgcn_global_load_lds((const unsigned*)((const char*)(gbase) + (voff)[_i]), (PG8_LAS unsigned*)(lds + (bufoff) + ldsw + _i * 8192), 16, 0, 0); } while (0)
; #define PG8_LDA(dst, b, h) do { _Pragma("unroll") for (int m = 0; m < 4; ++m) _Pragma("unroll") for (int k = 0; k < 2; ++k) dst[m][k] = *(const PG8_LAS bf16x8*)(lds + PG8_SA(b, h) + aoff + m * 2048 + k * 1024); } while (0)
; #define PG8_LDB(dst, b, h) do { _Pragma("unroll") for (int n = 0; n < 2; ++n) _Pragma("unroll") for (int k = 0; k < 2; ++k) dst[n][k] = *(const PG8_LAS bf16x8*)(lds + PG8_SB(b, h) + boff + n * 2048 + k * 1024); } while (0)
; #define PG8_MMA(ai, bj, At, Bt) do { __builtin_amdgcn_s_setprio(1); _Pragma("unroll") for (int m = 0; m < 4; ++m) _Pragma("unroll") for (int n = 0; n < 2; ++n) _Pragma("unroll") for (int k = 0; k < 2; ++k) \
;         acc[ai][bj][m][n] = __builtin_amdgcn_mfma_f32_16x16x32_bf16(Bt[n][k], At[m][k], acc[ai][bj][m][n], 0, 0, 0); __builtin_amdgcn_s_setprio(0); } while (0)
; #define PG8_WAIT_V(n) asm volatile("s_waitcnt vmcnt(" #n ")" ::: "memory")
; #define PG8_WAIT_L(n) asm volatile("s_waitcnt lgkmcnt(" #n ")" ::: "memory")
; #define PG8_BAR __builtin_amdgcn_s_barrier()
; #define PG8_SCHED __builtin_amdgcn_sched_barrier(0)
; template <class Epi, class Sched, bool ALIGN_EPI = false, bool SP2 = false>
; __device__ __forceinline__ void gemm_phase(PG8_LAS unsigned char* lds, const Gemm g, const Sched& S, const Epi& E, const int wave_s) {
;     ...
;             PG8_WAIT_V(8); PG8_WAIT_L(0); PG8_BAR; PG8_MMA(1, 0, At, B0); PG8_MMA(1, 1, At, B1); PG8_BAR; PG8_SCHED;
;             PG8_LDB(B0, 1, 0); PG8_LDB(B1, 1, 1); PG8_SCHED; PG8_LDA(At, 1, 0); PG8_STAGE(PG8_SA(0, 1), a2 + hstep, voffA);
;             PG8_WAIT_V(8); PG8_WAIT_L(0); PG8_BAR; PG8_MMA(0, 0, At, B0); PG8_MMA(0, 1, At, B1); PG8_BAR; PG8_SCHED;
;             PG8_LDA(At, 1, 1); PG8_STAGE(PG8_SB(1, 0), b3, voffB); PG8_STAGE(PG8_SB(1, 1), b3 + hstep, voffB); PG8_STAGE(PG8_SA(1, 0), a3, voffA);
	s_setprio 1
	s_waitcnt lgkmcnt(0)
	v_mfma_f32_16x16x32_bf16 v[60:63], v[128:131], v[176:179], v[60:63]
	v_mfma_f32_16x16x32_bf16 v[56:59], v[136:139], v[176:179], v[56:59]
	v_mfma_f32_16x16x32_bf16 v[48:51], v[128:131], v[184:187], v[48:51]
	v_mfma_f32_16x16x32_bf16 v[40:43], v[136:139], v[184:187], v[40:43]
	v_mfma_f32_16x16x32_bf16 v[28:31], v[128:131], v[198:201], v[28:31]
	v_mfma_f32_16x16x32_bf16 v[24:27], v[136:139], v[198:201], v[24:27]
	v_mfma_f32_16x16x32_bf16 v[16:19], v[128:131], v[206:209], v[16:19]
	v_mfma_f32_16x16x32_bf16 v[8:11], v[136:139], v[206:209], v[8:11]
	v_mfma_f32_16x16x32_bf16 v[60:63], v[132:135], v[180:183], v[60:63]
	v_mfma_f32_16x16x32_bf16 v[56:59], v[140:143], v[180:183], v[56:59]
	v_mfma_f32_16x16x32_bf16 v[48:51], v[132:135], v[188:191], v[48:51]
	v_mfma_f32_16x16x32_bf16 v[40:43], v[140:143], v[188:191], v[40:43]
	v_mfma_f32_16x16x32_bf16 v[28:31], v[132:135], v[202:205], v[28:31]
	v_mfma_f32_16x16x32_bf16 v[24:27], v[140:143], v[202:205], v[24:27]
	v_mfma_f32_16x16x32_bf16 v[16:19], v[132:135], v[210:213], v[16:19]
	v_mfma_f32_16x16x32_bf16 v[8:11], v[140:143], v[210:213], v[8:11]
	s_setprio 0
	s_setprio 1
	v_mfma_f32_16x16x32_bf16 v[52:55], v[160:163], v[176:179], v[52:55]
	v_mfma_f32_16x16x32_bf16 v[44:47], v[168:171], v[176:179], v[44:47]
	v_mfma_f32_16x16x32_bf16 v[36:39], v[160:163], v[184:187], v[36:39]
	v_mfma_f32_16x16x32_bf16 v[32:35], v[168:171], v[184:187], v[32:35]
	v_mfma_f32_16x16x32_bf16 v[20:23], v[160:163], v[198:201], v[20:23]
	v_mfma_f32_16x16x32_bf16 v[12:15], v[168:171], v[198:201], v[12:15]
	v_mfma_f32_16x16x32_bf16 v[4:7], v[160:163], v[206:209], v[4:7]
	v_mfma_f32_16x16x32_bf16 v[0:3], v[168:171], v[206:209], v[0:3]
	v_mfma_f32_16x16x32_bf16 v[52:55], v[164:167], v[180:183], v[52:55]
	v_mfma_f32_16x16x32_bf16 v[44:47], v[172:175], v[180:183], v[44:47]
	v_mfma_f32_16x16x32_bf16 v[36:39], v[164:167], v[188:191], v[36:39]
	v_mfma_f32_16x16x32_bf16 v[32:35], v[172:175], v[188:191], v[32:35]
	v_mfma_f32_16x16x32_bf16 v[20:23], v[164:167], v[202:205], v[20:23]
	v_mfma_f32_16x16x32_bf16 v[12:15], v[172:175], v[202:205], v[12:15]
	v_mfma_f32_16x16x32_bf16 v[4:7], v[164:167], v[210:213], v[4:7]
	v_mfma_f32_16x16x32_bf16 v[0:3], v[172:175], v[210:213], v[0:3]
	s_setprio 0
	s_barrier
	s_add_i32 s64, 0, 0x18000
	s_add_i32 s65, 0, 0x1c000
	v_add_u32_e32 v140, s64, v194
	v_add_u32_e32 v172, s65, v194
	ds_read_b128 v[128:131], v140
	ds_read_b128 v[132:135], v140 offset:1024
	ds_read_b128 v[136:139], v140 offset:2048
	ds_read_b128 v[140:143], v140 offset:3072
	ds_read_b128 v[160:163], v172
	ds_read_b128 v[164:167], v172 offset:1024
	ds_read_b128 v[168:171], v172 offset:2048
	ds_read_b128 v[172:175], v172 offset:3072
	s_add_u32 s34, s34, 0x40000
	s_addc_u32 s35, s35, 0
	s_mov_b32 m0, s45
	v_lshl_add_u64 v[218:219], s[34:35], 0, v[144:145]
	ds_read_b128 v[176:179], v197 offset:32768
	ds_read_b128 v[180:183], v197 offset:33792
	ds_read_b128 v[184:187], v197 offset:34816
	ds_read_b128 v[188:191], v197 offset:35840
	ds_read_b128 v[198:201], v197 offset:36864
	ds_read_b128 v[202:205], v197 offset:37888
	ds_read_b128 v[206:209], v197 offset:38912
	ds_read_b128 v[210:213], v197 offset:39936
	global_load_lds_dwordx4 v[218:219], off
	v_lshl_add_u64 v[218:219], s[34:35], 0, v[148:149]
	s_mov_b32 m0, s46
	s_nop 0
	global_load_lds_dwordx4 v[218:219], off
	v_lshl_add_u64 v[236:237], v[230:231], 0, s[10:11]
	s_add_u32 s30, s30, 0x40080
	v_lshl_add_u64 v[238:239], v[232:233], 0, s[10:11]
	s_addc_u32 s31, s31, 0
	v_lshl_add_u64 v[240:241], s[30:31], 0, v[146:147]
	v_lshl_add_u64 v[242:243], s[30:31], 0, v[150:151]
	v_lshl_add_u64 v[244:245], v[214:215], 0, s[10:11]
	v_lshl_add_u64 v[246:247], v[234:235], 0, s[10:11]
	s_waitcnt vmcnt(8)
	s_waitcnt lgkmcnt(0)
	s_barrier
; #define PG8_STAGE(bufoff, gbase, voff) do { _Pragma("unroll") for (int _i = 0; _i < 2; ++_i) \
;         __builtin_amdgcn_global_load_lds((const unsigned*)((const char*)(gbase) + (voff)[_i]), (PG8_LAS unsigned*)(lds + (bufoff) + ldsw + _i * 8192), 16, 0, 0); } while (0)
; #define PG8_LDA(dst, b, h) do { _Pragma("unroll") for (int m = 0; m < 4; ++m) _Pragma("unroll") for (int k = 0; k < 2; ++k) dst[m][k] = *(const PG8_LAS bf16x8*)(lds + PG8_SA(b, h) + aoff + m * 2048 + k * 1024); } while (0)
; #define PG8_MMA(ai, bj, At, Bt) do { __builtin_amdgcn_s_setprio(1); _Pragma("unroll") for (int m = 0; m < 4; ++m) _Pragma("unroll") for (int n = 0; n < 2; ++n) _Pragma("unroll") for (int k = 0; k < 2; ++k) \
;         acc[ai][bj][m][n] = __builtin_amdgcn_mfma_f32_16x16x32_bf16(Bt[n][k], At[m][k], acc[ai][bj][m][n], 0, 0, 0); __builtin_amdgcn_s_setprio(0); } while (0)
; #define PG8_WAIT_V(n) asm volatile("s_waitcnt vmcnt(" #n ")" ::: "memory")
; #define PG8_WAIT_L(n) asm volatile("s_waitcnt lgkmcnt(" #n ")" ::: "memory")
; #define PG8_BAR __builtin_amdgcn_s_barrier()
; #define PG8_SCHED __builtin_amdgcn_sched_barrier(0)
; __device__ __forceinline__ int lane_id_v() { int l; asm volatile("v_mbcnt_lo_u32_b32 %0, -1, 0\n\tv_mbcnt_hi_u32_b32 %0, -1, %0" : "=v"(l)); return l; }
; template <class Epi, class Sched, bool ALIGN_EPI = false, bool SP2 = false>
; __device__ __forceinline__ void gemm_phase(PG8_LAS unsigned char* lds, const Gemm g, const Sched& S, const Epi& E, const int wave_s) {
;     ...
;             PG8_LDA(At, 1, 1); PG8_STAGE(PG8_SB(1, 0), b3, voffB); PG8_STAGE(PG8_SB(1, 1), b3 + hstep, voffB); PG8_STAGE(PG8_SA(1, 0), a3, voffA);
;             PG8_WAIT_V(8); PG8_WAIT_L(0); PG8_BAR; PG8_MMA(1, 0, At, B0); PG8_MMA(1, 1, At, B1); PG8_BAR; PG8_SCHED;
;     __device__ __forceinline__ void operator()(const af4 (&acc)[2][2][4][2], const pg8::Unit& u, int wr, int wc, int fr_, int fq_) const {
;         const int ln_ = lane_id_v(); const int fr = ln_ & 15, fq = ln_ >> 4;
;         const int grow = rowbase + u.pm * 256; const int bi = grow < TL ? grow / LSEQ : NB;
;         float* xb = grow < TL ? xl + (size_t)grow * DM : xc + (size_t)(grow - TL) * DM;
;         const float* stb = stats + 2 * (size_t)grow;
;         const int col0 = u.pn * 256 + wc * 32 + 8 * fq; const float* gp = gate + (size_t)bi * 6144 + col0;
	s_setprio 1
	s_waitcnt lgkmcnt(0)
	v_mfma_f32_16x16x32_bf16 v[124:127], v[128:131], v[176:179], v[124:127]
	v_mfma_f32_16x16x32_bf16 v[120:123], v[136:139], v[176:179], v[120:123]
	v_mfma_f32_16x16x32_bf16 v[112:115], v[128:131], v[184:187], v[112:115]
	v_mfma_f32_16x16x32_bf16 v[104:107], v[136:139], v[184:187], v[104:107]
	v_mfma_f32_16x16x32_bf16 v[92:95], v[128:131], v[198:201], v[92:95]
	v_mfma_f32_16x16x32_bf16 v[88:91], v[136:139], v[198:201], v[88:91]
	v_mfma_f32_16x16x32_bf16 v[80:83], v[128:131], v[206:209], v[80:83]
	v_mfma_f32_16x16x32_bf16 v[72:75], v[136:139], v[206:209], v[72:75]
	v_mfma_f32_16x16x32_bf16 v[124:127], v[132:135], v[180:183], v[124:127]
	v_mfma_f32_16x16x32_bf16 v[120:123], v[140:143], v[180:183], v[120:123]
	v_mfma_f32_16x16x32_bf16 v[112:115], v[132:135], v[188:191], v[112:115]
	v_mfma_f32_16x16x32_bf16 v[104:107], v[140:143], v[188:191], v[104:107]
	v_mfma_f32_16x16x32_bf16 v[92:95], v[132:135], v[202:205], v[92:95]
	v_mfma_f32_16x16x32_bf16 v[88:91], v[140:143], v[202:205], v[88:91]
	v_mfma_f32_16x16x32_bf16 v[80:83], v[132:135], v[210:213], v[80:83]
	v_mfma_f32_16x16x32_bf16 v[72:75], v[140:143], v[210:213], v[72:75]
	s_setprio 0
	s_setprio 1
	v_mfma_f32_16x16x32_bf16 v[116:119], v[160:163], v[176:179], v[116:119]
	v_mfma_f32_16x16x32_bf16 v[108:111], v[168:171], v[176:179], v[108:111]
	v_mfma_f32_16x16x32_bf16 v[100:103], v[160:163], v[184:187], v[100:103]
	v_mfma_f32_16x16x32_bf16 v[96:99], v[168:171], v[184:187], v[96:99]
	v_mfma_f32_16x16x32_bf16 v[84:87], v[160:163], v[198:201], v[84:87]
	v_mfma_f32_16x16x32_bf16 v[76:79], v[168:171], v[198:201], v[76:79]
	v_mfma_f32_16x16x32_bf16 v[68:71], v[160:163], v[206:209], v[68:71]
	v_mfma_f32_16x16x32_bf16 v[64:67], v[168:171], v[206:209], v[64:67]
	v_mfma_f32_16x16x32_bf16 v[116:119], v[164:167], v[180:183], v[116:119]
	v_mfma_f32_16x16x32_bf16 v[108:111], v[172:175], v[180:183], v[108:111]
	v_mfma_f32_16x16x32_bf16 v[100:103], v[164:167], v[188:191], v[100:103]
	v_mfma_f32_16x16x32_bf16 v[96:99], v[172:175], v[188:191], v[96:99]
	v_mfma_f32_16x16x32_bf16 v[84:87], v[164:167], v[202:205], v[84:87]
	v_mfma_f32_16x16x32_bf16 v[76:79], v[172:175], v[202:205], v[76:79]
	v_mfma_f32_16x16x32_bf16 v[68:71], v[164:167], v[210:213], v[68:71]
	v_mfma_f32_16x16x32_bf16 v[64:67], v[172:175], v[210:213], v[64:67]
	s_setprio 0
	s_barrier
	s_add_i32 s34, s64, s33
	s_mov_b32 m0, s34
	ds_read_b128 v[176:179], v197 offset:49152
	ds_read_b128 v[180:183], v197 offset:50176
	ds_read_b128 v[184:187], v197 offset:51200
	ds_read_b128 v[188:191], v197 offset:52224
	ds_read_b128 v[198:201], v197 offset:53248
	ds_read_b128 v[202:205], v197 offset:54272
	ds_read_b128 v[206:209], v197 offset:55296
	ds_read_b128 v[210:213], v197 offset:56320
	global_load_lds_dwordx4 v[236:237], off
	s_add_i32 m0, s34, 0x2000
	s_add_i32 s34, s65, s33
	global_load_lds_dwordx4 v[238:239], off
	s_mov_b32 m0, s34
	s_nop 0
	global_load_lds_dwordx4 v[240:241], off
	s_add_i32 m0, s34, 0x2000
	s_nop 0
	global_load_lds_dwordx4 v[242:243], off
	s_mov_b32 m0, s53
	s_nop 0
	global_load_lds_dwordx4 v[244:245], off
	s_mov_b32 m0, s54
	s_nop 0
	global_load_lds_dwordx4 v[246:247], off
	s_waitcnt vmcnt(8)
	s_waitcnt lgkmcnt(0)
	s_barrier
	s_setprio 1
	s_waitcnt lgkmcnt(0)
	v_mfma_f32_16x16x32_bf16 v[60:63], v[128:131], v[176:179], v[60:63]
	v_mfma_f32_16x16x32_bf16 v[56:59], v[136:139], v[176:179], v[56:59]
	v_mfma_f32_16x16x32_bf16 v[48:51], v[128:131], v[184:187], v[48:51]
	v_mfma_f32_16x16x32_bf16 v[40:43], v[136:139], v[184:187], v[40:43]
	v_mfma_f32_16x16x32_bf16 v[28:31], v[128:131], v[198:201], v[28:31]
	v_mfma_f32_16x16x32_bf16 v[24:27], v[136:139], v[198:201], v[24:27]
	v_mfma_f32_16x16x32_bf16 v[16:19], v[128:131], v[206:209], v[16:19]
	v_mfma_f32_16x16x32_bf16 v[8:11], v[136:139], v[206:209], v[8:11]
	v_mfma_f32_16x16x32_bf16 v[60:63], v[132:135], v[180:183], v[60:63]
	v_mfma_f32_16x16x32_bf16 v[56:59], v[140:143], v[180:183], v[56:59]
	v_mfma_f32_16x16x32_bf16 v[48:51], v[132:135], v[188:191], v[48:51]
	v_mfma_f32_16x16x32_bf16 v[40:43], v[140:143], v[188:191], v[40:43]
	v_mfma_f32_16x16x32_bf16 v[28:31], v[132:135], v[202:205], v[28:31]
	v_mfma_f32_16x16x32_bf16 v[24:27], v[140:143], v[202:205], v[24:27]
	v_mfma_f32_16x16x32_bf16 v[16:19], v[132:135], v[210:213], v[16:19]
	v_mfma_f32_16x16x32_bf16 v[8:11], v[140:143], v[210:213], v[8:11]
	s_setprio 0
	s_setprio 1
	v_mfma_f32_16x16x32_bf16 v[52:55], v[160:163], v[176:179], v[52:55]
	v_mfma_f32_16x16x32_bf16 v[44:47], v[168:171], v[176:179], v[44:47]
	v_mfma_f32_16x16x32_bf16 v[36:39], v[160:163], v[184:187], v[36:39]
	v_mfma_f32_16x16x32_bf16 v[32:35], v[168:171], v[184:187], v[32:35]
	v_mfma_f32_16x16x32_bf16 v[20:23], v[160:163], v[198:201], v[20:23]
	v_mfma_f32_16x16x32_bf16 v[12:15], v[168:171], v[198:201], v[12:15]
	v_mfma_f32_16x16x32_bf16 v[4:7], v[160:163], v[206:209], v[4:7]
	v_mfma_f32_16x16x32_bf16 v[0:3], v[168:171], v[206:209], v[0:3]
	v_mfma_f32_16x16x32_bf16 v[52:55], v[164:167], v[180:183], v[52:55]
	v_mfma_f32_16x16x32_bf16 v[44:47], v[172:175], v[180:183], v[44:47]
	v_mfma_f32_16x16x32_bf16 v[36:39], v[164:167], v[188:191], v[36:39]
	v_mfma_f32_16x16x32_bf16 v[32:35], v[172:175], v[188:191], v[32:35]
	v_mfma_f32_16x16x32_bf16 v[20:23], v[164:167], v[202:205], v[20:23]
	v_mfma_f32_16x16x32_bf16 v[12:15], v[172:175], v[202:205], v[12:15]
	v_mfma_f32_16x16x32_bf16 v[4:7], v[164:167], v[210:213], v[4:7]
	v_mfma_f32_16x16x32_bf16 v[0:3], v[172:175], v[210:213], v[0:3]
	s_setprio 0
	s_barrier
	s_add_i32 s63, s63, 2
	s_add_u32 s61, s61, 0x100
	s_addc_u32 s62, s62, 0
	s_add_u32 s28, s28, 0x100
	s_addc_u32 s29, s29, 0
	s_cmp_gt_u32 s63, 13
	s_cbranch_scc0 .LBB0_2876
	s_cmpk_gt_i32 s0, 0xff
	s_cselect_b64 s[30:31], -1, 0
	s_mov_b64 s[34:35], 0x18000
	s_and_b64 vcc, exec, s[30:31]
	v_mbcnt_lo_u32_b32 v160, -1, 0
	v_mbcnt_hi_u32_b32 v160, -1, v160
	s_cbranch_vccnz .LBB0_2879
	s_ashr_i32 s21, s0, 31
	s_lshr_b32 s21, s21, 28
	s_add_i32 s21, s0, s21
	s_ashr_i32 s21, s21, 4
	s_mul_hi_i32 s35, s21, 0x1800
	s_mul_i32 s34, s21, 0x1800

; #define PG8_STAGE(bufoff, gbase, voff) do { _Pragma("unroll") for (int _i = 0; _i < 2; ++_i) \
;         __builtin_amdgcn_global_load_lds((const unsigned*)((const char*)(gbase) + (voff)[_i]), (PG8_LAS unsigned*)(lds + (bufoff) + ldsw + _i * 8192), 16, 0, 0); } while (0)
; #define PG8_LDA(dst, b, h) do { _Pragma("unroll") for (int m = 0; m < 4; ++m) _Pragma("unroll") for (int k = 0; k < 2; ++k) dst[m][k] = *(const PG8_LAS bf16x8*)(lds + PG8_SA(b, h) + aoff + m * 2048 + k * 1024); } while (0)
; #define PG8_LDB(dst, b, h) do { _Pragma("unroll") for (int n = 0; n < 2; ++n) _Pragma("unroll") for (int k = 0; k < 2; ++k) dst[n][k] = *(const PG8_LAS bf16x8*)(lds + PG8_SB(b, h) + boff + n * 2048 + k * 1024); } while (0)
; #define PG8_MMA(ai, bj, At, Bt) do { __builtin_amdgcn_s_setprio(1); _Pragma("unroll") for (int m = 0; m < 4; ++m) _Pragma("unroll") for (int n = 0; n < 2; ++n) _Pragma("unroll") for (int k = 0; k < 2; ++k) \
;         acc[ai][bj][m][n] = __builtin_amdgcn_mfma_f32_16x16x32_bf16(Bt[n][k], At[m][k], acc[ai][bj][m][n], 0, 0, 0); __builtin_amdgcn_s_setprio(0); } while (0)
; #define PG8_WAIT_V(n) asm volatile("s_waitcnt vmcnt(" #n ")" ::: "memory")
; #define PG8_WAIT_L(n) asm volatile("s_waitcnt lgkmcnt(" #n ")" ::: "memory")
; template <class Epi, class Sched, bool ALIGN_EPI = false, bool SP2 = false>
; __device__ __forceinline__ void gemm_phase(PG8_LAS unsigned char* lds, const Gemm g, const Sched& S, const Epi& E, const int wave_s) {
;     ...
;             const bool last = (t == nt - 2);
;             const char* a1 = cA + (size_t)(t + 1) * kstep;
;             const char* a2 = last ? nA : cA + (size_t)(t + 2) * kstep; const char* b2 = last ? nB : cB + (size_t)(t + 2) * kstep;
;             const char* a3 = a2 + kstep; const char* b3 = b2 + kstep;
;             if (last && has_next) S.a_ready(nxt);
;             if constexpr (SP2) {
;             PG8_LDB(B0, 0, 0); PG8_LDB(B1, 0, 1); PG8_SCHED; PG8_LDA(At, 0, 0); PG8_STAGE(PG8_SA(1, 1), a1 + hstep, voffA);
;             PG8_WAIT_V(8); PG8_WAIT_L(0); PG8_BAR; PG8_MMA(0, 0, At, B0); PG8_MMA(0, 1, At, B1); PG8_BAR; PG8_SCHED;
;             PG8_LDA(At, 0, 1); PG8_STAGE(PG8_SB(0, 0), b2, voffB); PG8_STAGE(PG8_SB(0, 1), b2 + hstep, voffB); PG8_STAGE(PG8_SA(0, 0), a2, voffA);
;             PG8_WAIT_V(8); PG8_WAIT_L(0); PG8_BAR; PG8_MMA(1, 0, At, B0); PG8_MMA(1, 1, At, B1); PG8_BAR; PG8_SCHED;
.LBB0_3010:
	ds_read_b128 v[56:59], v187
	ds_read_b128 v[60:63], v187 offset:1024
	ds_read_b128 v[64:67], v187 offset:2048
	ds_read_b128 v[68:71], v187 offset:3072
	ds_read_b128 v[100:103], v188
	ds_read_b128 v[104:107], v188 offset:1024
	ds_read_b128 v[108:111], v188 offset:2048
	ds_read_b128 v[112:115], v188 offset:3072
	s_add_u32 s14, s12, 0xfffc0080
	s_addc_u32 s15, s13, -1
	s_cmp_eq_u32 s79, 12
	s_cselect_b32 s59, s9, s15
	s_cselect_b32 s58, s11, s14
	s_cselect_b32 s15, s51, s61
	s_cselect_b32 s14, s53, s60
	v_lshl_add_u64 v[184:185], s[12:13], 0, v[178:179]
	s_add_i32 m0, s45, 0xc000
	ds_read_b128 v[160:163], v189
	ds_read_b128 v[164:167], v189 offset:1024
	ds_read_b128 v[190:193], v189 offset:2048
	ds_read_b128 v[194:197], v189 offset:3072
	ds_read_b128 v[198:201], v189 offset:4096
	ds_read_b128 v[202:205], v189 offset:5120
	ds_read_b128 v[206:209], v189 offset:6144
	ds_read_b128 v[210:213], v189 offset:7168
	global_load_lds_dwordx4 v[184:185], off
	v_lshl_add_u64 v[184:185], s[12:13], 0, v[176:177]
	s_add_i32 m0, s45, 0xe000
	s_nop 0
	global_load_lds_dwordx4 v[184:185], off
	v_lshl_add_u64 v[230:231], s[14:15], 0, v[170:171]
	v_lshl_add_u64 v[232:233], s[14:15], 0, v[174:175]
	v_lshl_add_u64 v[234:235], s[58:59], 0, v[172:173]
	s_waitcnt vmcnt(8)
	s_waitcnt lgkmcnt(0)
	s_barrier
	s_setprio 1
	s_waitcnt lgkmcnt(0)
	v_mfma_f32_16x16x32_bf16 v[148:151], v[56:59], v[160:163], v[148:151]
	v_mfma_f32_16x16x32_bf16 v[116:119], v[64:67], v[160:163], v[116:119]
	v_mfma_f32_16x16x32_bf16 v[152:155], v[56:59], v[190:193], v[152:155]
	v_mfma_f32_16x16x32_bf16 v[120:123], v[64:67], v[190:193], v[120:123]
	v_mfma_f32_16x16x32_bf16 v[140:143], v[56:59], v[198:201], v[140:143]
	v_mfma_f32_16x16x32_bf16 v[92:95], v[64:67], v[198:201], v[92:95]
	v_mfma_f32_16x16x32_bf16 v[128:131], v[56:59], v[206:209], v[128:131]
	v_mfma_f32_16x16x32_bf16 v[80:83], v[64:67], v[206:209], v[80:83]
	v_mfma_f32_16x16x32_bf16 v[148:151], v[60:63], v[164:167], v[148:151]
	v_mfma_f32_16x16x32_bf16 v[116:119], v[68:71], v[164:167], v[116:119]
	v_mfma_f32_16x16x32_bf16 v[152:155], v[60:63], v[194:197], v[152:155]
	v_mfma_f32_16x16x32_bf16 v[120:123], v[68:71], v[194:197], v[120:123]
	v_mfma_f32_16x16x32_bf16 v[140:143], v[60:63], v[202:205], v[140:143]
	v_mfma_f32_16x16x32_bf16 v[92:95], v[68:71], v[202:205], v[92:95]
	v_mfma_f32_16x16x32_bf16 v[128:131], v[60:63], v[210:213], v[128:131]
	v_mfma_f32_16x16x32_bf16 v[80:83], v[68:71], v[210:213], v[80:83]
	s_setprio 0
	s_setprio 1
	v_mfma_f32_16x16x32_bf16 v[156:159], v[100:103], v[160:163], v[156:159]
	v_mfma_f32_16x16x32_bf16 v[124:127], v[108:111], v[160:163], v[124:127]
	v_mfma_f32_16x16x32_bf16 v[144:147], v[100:103], v[190:193], v[144:147]
	v_mfma_f32_16x16x32_bf16 v[96:99], v[108:111], v[190:193], v[96:99]
	v_mfma_f32_16x16x32_bf16 v[136:139], v[100:103], v[198:201], v[136:139]
	v_mfma_f32_16x16x32_bf16 v[88:91], v[108:111], v[198:201], v[88:91]
	v_mfma_f32_16x16x32_bf16 v[132:135], v[100:103], v[206:209], v[132:135]
	v_mfma_f32_16x16x32_bf16 v[84:87], v[108:111], v[206:209], v[84:87]
	v_mfma_f32_16x16x32_bf16 v[156:159], v[104:107], v[164:167], v[156:159]
	v_mfma_f32_16x16x32_bf16 v[124:127], v[112:115], v[164:167], v[124:127]
	v_mfma_f32_16x16x32_bf16 v[144:147], v[104:107], v[194:197], v[144:147]
	v_mfma_f32_16x16x32_bf16 v[96:99], v[112:115], v[194:197], v[96:99]
	v_mfma_f32_16x16x32_bf16 v[136:139], v[104:107], v[202:205], v[136:139]
	v_mfma_f32_16x16x32_bf16 v[88:91], v[112:115], v[202:205], v[88:91]
	v_mfma_f32_16x16x32_bf16 v[132:135], v[104:107], v[210:213], v[132:135]
	v_mfma_f32_16x16x32_bf16 v[84:87], v[112:115], v[210:213], v[84:87]
	s_setprio 0
	s_barrier
	s_add_i32 s80, s76, s33
	s_mov_b32 m0, s80
	ds_read_b128 v[160:163], v189 offset:16384
	ds_read_b128 v[164:167], v189 offset:17408
	ds_read_b128 v[190:193], v189 offset:18432
	ds_read_b128 v[194:197], v189 offset:19456
	ds_read_b128 v[198:201], v189 offset:20480
	ds_read_b128 v[202:205], v189 offset:21504
	ds_read_b128 v[206:209], v189 offset:22528
	ds_read_b128 v[210:213], v189 offset:23552
	global_load_lds_dwordx4 v[230:231], off
	s_add_i32 m0, s80, 0x2000
	s_add_u32 s80, s14, 0x40000
	s_addc_u32 s81, s15, 0
	s_add_i32 s82, s77, s33
	global_load_lds_dwordx4 v[232:233], off
	v_lshl_add_u64 v[216:217], s[80:81], 0, v[170:171]
	s_mov_b32 m0, s82
	s_nop 0
	global_load_lds_dwordx4 v[216:217], off
	v_lshl_add_u64 v[216:217], s[80:81], 0, v[174:175]
	s_add_i32 m0, s82, 0x2000
	s_nop 0
	global_load_lds_dwordx4 v[216:217], off
	v_lshl_add_u64 v[216:217], s[58:59], 0, v[168:169]
	s_mov_b32 m0, s45
	s_nop 0
	global_load_lds_dwordx4 v[216:217], off
	s_mov_b32 m0, s47
	s_nop 0
	global_load_lds_dwordx4 v[234:235], off
	s_waitcnt vmcnt(8)
	s_waitcnt lgkmcnt(0)
	s_barrier
; #define PG8_STAGE(bufoff, gbase, voff) do { _Pragma("unroll") for (int _i = 0; _i < 2; ++_i) \
;         __builtin_amdgcn_global_load_lds((const unsigned*)((const char*)(gbase) + (voff)[_i]), (PG8_LAS unsigned*)(lds + (bufoff) + ldsw + _i * 8192), 16, 0, 0); } while (0)
; #define PG8_LDA(dst, b, h) do { _Pragma("unroll") for (int m = 0; m < 4; ++m) _Pragma("unroll") for (int k = 0; k < 2; ++k) dst[m][k] = *(const PG8_LAS bf16x8*)(lds + PG8_SA(b, h) + aoff + m * 2048 + k * 1024); } while (0)
; #define PG8_LDB(dst, b, h) do { _Pragma("unroll") for (int n = 0; n < 2; ++n) _Pragma("unroll") for (int k = 0; k < 2; ++k) dst[n][k] = *(const PG8_LAS bf16x8*)(lds + PG8_SB(b, h) + boff + n * 2048 + k * 1024); } while (0)
; #define PG8_MMA(ai, bj, At, Bt) do { __builtin_amdgcn_s_setprio(1); _Pragma("unroll") for (int m = 0; m < 4; ++m) _Pragma("unroll") for (int n = 0; n < 2; ++n) _Pragma("unroll") for (int k = 0; k < 2; ++k) \
;         acc[ai][bj][m][n] = __builtin_amdgcn_mfma_f32_16x16x32_bf16(Bt[n][k], At[m][k], acc[ai][bj][m][n], 0, 0, 0); __builtin_amdgcn_s_setprio(0); } while (0)
; #define PG8_WAIT_V(n) asm volatile("s_waitcnt vmcnt(" #n ")" ::: "memory")
; #define PG8_WAIT_L(n) asm volatile("s_waitcnt lgkmcnt(" #n ")" ::: "memory")
; #define PG8_BAR __builtin_amdgcn_s_barrier()
; #define PG8_SCHED __builtin_amdgcn_sched_barrier(0)
; template <class Epi, class Sched, bool ALIGN_EPI = false, bool SP2 = false>
; __device__ __forceinline__ void gemm_phase(PG8_LAS unsigned char* lds, const Gemm g, const Sched& S, const Epi& E, const int wave_s) {
;     ...
;             PG8_WAIT_V(8); PG8_WAIT_L(0); PG8_BAR; PG8_MMA(1, 0, At, B0); PG8_MMA(1, 1, At, B1); PG8_BAR; PG8_SCHED;
;             PG8_LDB(B0, 1, 0); PG8_LDB(B1, 1, 1); PG8_SCHED; PG8_LDA(At, 1, 0); PG8_STAGE(PG8_SA(0, 1), a2 + hstep, voffA);
;             PG8_WAIT_V(8); PG8_WAIT_L(0); PG8_BAR; PG8_MMA(0, 0, At, B0); PG8_MMA(0, 1, At, B1); PG8_BAR; PG8_SCHED;
;             PG8_LDA(At, 1, 1); PG8_STAGE(PG8_SB(1, 0), b3, voffB); PG8_STAGE(PG8_SB(1, 1), b3 + hstep, voffB); PG8_STAGE(PG8_SA(1, 0), a3, voffA);
	s_setprio 1
	s_waitcnt lgkmcnt(0)
	v_mfma_f32_16x16x32_bf16 v[76:79], v[56:59], v[160:163], v[76:79]
	v_mfma_f32_16x16x32_bf16 v[24:27], v[64:67], v[160:163], v[24:27]
	v_mfma_f32_16x16x32_bf16 v[52:55], v[56:59], v[190:193], v[52:55]
	v_mfma_f32_16x16x32_bf16 v[20:23], v[64:67], v[190:193], v[20:23]
	v_mfma_f32_16x16x32_bf16 v[44:47], v[56:59], v[198:201], v[44:47]
	v_mfma_f32_16x16x32_bf16 v[12:15], v[64:67], v[198:201], v[12:15]
	v_mfma_f32_16x16x32_bf16 v[36:39], v[56:59], v[206:209], v[36:39]
	v_mfma_f32_16x16x32_bf16 v[0:3], v[64:67], v[206:209], v[0:3]
	v_mfma_f32_16x16x32_bf16 v[76:79], v[60:63], v[164:167], v[76:79]
	v_mfma_f32_16x16x32_bf16 v[24:27], v[68:71], v[164:167], v[24:27]
	v_mfma_f32_16x16x32_bf16 v[52:55], v[60:63], v[194:197], v[52:55]
	v_mfma_f32_16x16x32_bf16 v[20:23], v[68:71], v[194:197], v[20:23]
	v_mfma_f32_16x16x32_bf16 v[44:47], v[60:63], v[202:205], v[44:47]
	v_mfma_f32_16x16x32_bf16 v[12:15], v[68:71], v[202:205], v[12:15]
	v_mfma_f32_16x16x32_bf16 v[36:39], v[60:63], v[210:213], v[36:39]
	v_mfma_f32_16x16x32_bf16 v[0:3], v[68:71], v[210:213], v[0:3]
	s_setprio 0
	s_setprio 1
	v_mfma_f32_16x16x32_bf16 v[28:31], v[108:111], v[160:163], v[28:31]
	v_mfma_f32_16x16x32_bf16 v[48:51], v[100:103], v[190:193], v[48:51]
	v_mfma_f32_16x16x32_bf16 v[16:19], v[108:111], v[190:193], v[16:19]
	v_mfma_f32_16x16x32_bf16 v[40:43], v[100:103], v[198:201], v[40:43]
	v_mfma_f32_16x16x32_bf16 v[8:11], v[108:111], v[198:201], v[8:11]
	v_mfma_f32_16x16x32_bf16 v[32:35], v[100:103], v[206:209], v[32:35]
	v_mfma_f32_16x16x32_bf16 v[4:7], v[108:111], v[206:209], v[4:7]
	v_mfma_f32_16x16x32_bf16 v[56:59], v[100:103], v[160:163], v[72:75]
	v_mfma_f32_16x16x32_bf16 v[28:31], v[112:115], v[164:167], v[28:31]
	v_mfma_f32_16x16x32_bf16 v[48:51], v[104:107], v[194:197], v[48:51]
	v_mfma_f32_16x16x32_bf16 v[16:19], v[112:115], v[194:197], v[16:19]
	v_mfma_f32_16x16x32_bf16 v[40:43], v[104:107], v[202:205], v[40:43]
	v_mfma_f32_16x16x32_bf16 v[8:11], v[112:115], v[202:205], v[8:11]
	v_mfma_f32_16x16x32_bf16 v[32:35], v[104:107], v[210:213], v[32:35]
	v_mfma_f32_16x16x32_bf16 v[4:7], v[112:115], v[210:213], v[4:7]
	v_mfma_f32_16x16x32_bf16 v[56:59], v[104:107], v[164:167], v[56:59]
	s_setprio 0
	s_barrier
	s_add_i32 s80, 0, 0x18000
	s_add_i32 s81, 0, 0x1c000
	v_add_u32_e32 v72, s80, v186
	v_add_u32_e32 v112, s81, v186
	ds_read_b128 v[60:63], v72
	ds_read_b128 v[64:67], v72 offset:1024
	ds_read_b128 v[68:71], v72 offset:2048
	ds_read_b128 v[72:75], v72 offset:3072
	ds_read_b128 v[100:103], v112
	ds_read_b128 v[104:107], v112 offset:1024
	ds_read_b128 v[108:111], v112 offset:2048
	ds_read_b128 v[112:115], v112 offset:3072
	s_add_u32 s58, s58, 0x40000
	s_addc_u32 s59, s59, 0
	s_mov_b32 m0, s49
	v_lshl_add_u64 v[220:221], s[58:59], 0, v[168:169]
	ds_read_b128 v[160:163], v189 offset:32768
	ds_read_b128 v[164:167], v189 offset:33792
	ds_read_b128 v[190:193], v189 offset:34816
	ds_read_b128 v[194:197], v189 offset:35840
	ds_read_b128 v[198:201], v189 offset:36864
	ds_read_b128 v[202:205], v189 offset:37888
	ds_read_b128 v[206:209], v189 offset:38912
	ds_read_b128 v[210:213], v189 offset:39936
	global_load_lds_dwordx4 v[220:221], off
	v_lshl_add_u64 v[220:221], s[58:59], 0, v[172:173]
	s_mov_b32 m0, s62
	s_nop 0
	global_load_lds_dwordx4 v[220:221], off
	v_lshl_add_u64 v[236:237], v[230:231], 0, s[24:25]
	s_add_u32 s14, s14, 0x40080
	v_lshl_add_u64 v[238:239], v[232:233], 0, s[24:25]
	s_addc_u32 s15, s15, 0
	v_lshl_add_u64 v[240:241], s[14:15], 0, v[170:171]
	v_lshl_add_u64 v[242:243], s[14:15], 0, v[174:175]
	v_lshl_add_u64 v[244:245], v[216:217], 0, s[24:25]
	v_lshl_add_u64 v[246:247], v[234:235], 0, s[24:25]
	s_waitcnt vmcnt(8)
	s_waitcnt lgkmcnt(0)
	s_barrier
; #define PG8_STAGE(bufoff, gbase, voff) do { _Pragma("unroll") for (int _i = 0; _i < 2; ++_i) \
;         __builtin_amdgcn_global_load_lds((const unsigned*)((const char*)(gbase) + (voff)[_i]), (PG8_LAS unsigned*)(lds + (bufoff) + ldsw + _i * 8192), 16, 0, 0); } while (0)
; #define PG8_LDA(dst, b, h) do { _Pragma("unroll") for (int m = 0; m < 4; ++m) _Pragma("unroll") for (int k = 0; k < 2; ++k) dst[m][k] = *(const PG8_LAS bf16x8*)(lds + PG8_SA(b, h) + aoff + m * 2048 + k * 1024); } while (0)
; #define PG8_MMA(ai, bj, At, Bt) do { __builtin_amdgcn_s_setprio(1); _Pragma("unroll") for (int m = 0; m < 4; ++m) _Pragma("unroll") for (int n = 0; n < 2; ++n) _Pragma("unroll") for (int k = 0; k < 2; ++k) \
;         acc[ai][bj][m][n] = __builtin_amdgcn_mfma_f32_16x16x32_bf16(Bt[n][k], At[m][k], acc[ai][bj][m][n], 0, 0, 0); __builtin_amdgcn_s_setprio(0); } while (0)
; #define PG8_WAIT_V(n) asm volatile("s_waitcnt vmcnt(" #n ")" ::: "memory")
; #define PG8_WAIT_L(n) asm volatile("s_waitcnt lgkmcnt(" #n ")" ::: "memory")
; #define PG8_BAR __builtin_amdgcn_s_barrier()
; #define PG8_SCHED __builtin_amdgcn_sched_barrier(0)
; template <class Epi, class Sched, bool ALIGN_EPI = false, bool SP2 = false>
; __device__ __forceinline__ void gemm_phase(PG8_LAS unsigned char* lds, const Gemm g, const Sched& S, const Epi& E, const int wave_s) {
;     ...
;             PG8_LDA(At, 1, 1); PG8_STAGE(PG8_SB(1, 0), b3, voffB); PG8_STAGE(PG8_SB(1, 1), b3 + hstep, voffB); PG8_STAGE(PG8_SA(1, 0), a3, voffA);
;             PG8_WAIT_V(8); PG8_WAIT_L(0); PG8_BAR; PG8_MMA(1, 0, At, B0); PG8_MMA(1, 1, At, B1); PG8_BAR; PG8_SCHED;
;     ...
;         if constexpr (ALIGN_EPI) { if (wr == 0) PG8_BAR; }
	s_setprio 1
	s_waitcnt lgkmcnt(0)
	v_mfma_f32_16x16x32_bf16 v[148:151], v[60:63], v[160:163], v[148:151]
	v_mfma_f32_16x16x32_bf16 v[116:119], v[68:71], v[160:163], v[116:119]
	v_mfma_f32_16x16x32_bf16 v[152:155], v[60:63], v[190:193], v[152:155]
	v_mfma_f32_16x16x32_bf16 v[120:123], v[68:71], v[190:193], v[120:123]
	v_mfma_f32_16x16x32_bf16 v[140:143], v[60:63], v[198:201], v[140:143]
	v_mfma_f32_16x16x32_bf16 v[92:95], v[68:71], v[198:201], v[92:95]
	v_mfma_f32_16x16x32_bf16 v[128:131], v[60:63], v[206:209], v[128:131]
	v_mfma_f32_16x16x32_bf16 v[80:83], v[68:71], v[206:209], v[80:83]
	v_mfma_f32_16x16x32_bf16 v[148:151], v[64:67], v[164:167], v[148:151]
	v_mfma_f32_16x16x32_bf16 v[116:119], v[72:75], v[164:167], v[116:119]
	v_mfma_f32_16x16x32_bf16 v[152:155], v[64:67], v[194:197], v[152:155]
	v_mfma_f32_16x16x32_bf16 v[120:123], v[72:75], v[194:197], v[120:123]
	v_mfma_f32_16x16x32_bf16 v[140:143], v[64:67], v[202:205], v[140:143]
	v_mfma_f32_16x16x32_bf16 v[92:95], v[72:75], v[202:205], v[92:95]
	v_mfma_f32_16x16x32_bf16 v[128:131], v[64:67], v[210:213], v[128:131]
	v_mfma_f32_16x16x32_bf16 v[80:83], v[72:75], v[210:213], v[80:83]
	s_setprio 0
	s_setprio 1
	v_mfma_f32_16x16x32_bf16 v[156:159], v[100:103], v[160:163], v[156:159]
	v_mfma_f32_16x16x32_bf16 v[124:127], v[108:111], v[160:163], v[124:127]
	v_mfma_f32_16x16x32_bf16 v[144:147], v[100:103], v[190:193], v[144:147]
	v_mfma_f32_16x16x32_bf16 v[96:99], v[108:111], v[190:193], v[96:99]
	v_mfma_f32_16x16x32_bf16 v[136:139], v[100:103], v[198:201], v[136:139]
	v_mfma_f32_16x16x32_bf16 v[88:91], v[108:111], v[198:201], v[88:91]
	v_mfma_f32_16x16x32_bf16 v[132:135], v[100:103], v[206:209], v[132:135]
	v_mfma_f32_16x16x32_bf16 v[84:87], v[108:111], v[206:209], v[84:87]
	v_mfma_f32_16x16x32_bf16 v[156:159], v[104:107], v[164:167], v[156:159]
	v_mfma_f32_16x16x32_bf16 v[124:127], v[112:115], v[164:167], v[124:127]
	v_mfma_f32_16x16x32_bf16 v[144:147], v[104:107], v[194:197], v[144:147]
	v_mfma_f32_16x16x32_bf16 v[96:99], v[112:115], v[194:197], v[96:99]
	v_mfma_f32_16x16x32_bf16 v[136:139], v[104:107], v[202:205], v[136:139]
	v_mfma_f32_16x16x32_bf16 v[88:91], v[112:115], v[202:205], v[88:91]
	v_mfma_f32_16x16x32_bf16 v[132:135], v[104:107], v[210:213], v[132:135]
	v_mfma_f32_16x16x32_bf16 v[84:87], v[112:115], v[210:213], v[84:87]
	s_setprio 0
	s_barrier
	s_add_i32 s58, s80, s33
	s_mov_b32 m0, s58
	ds_read_b128 v[160:163], v189 offset:49152
	ds_read_b128 v[164:167], v189 offset:50176
	ds_read_b128 v[190:193], v189 offset:51200
	ds_read_b128 v[194:197], v189 offset:52224
	ds_read_b128 v[198:201], v189 offset:53248
	ds_read_b128 v[202:205], v189 offset:54272
	ds_read_b128 v[206:209], v189 offset:55296
	ds_read_b128 v[210:213], v189 offset:56320
	global_load_lds_dwordx4 v[236:237], off
	s_add_i32 m0, s58, 0x2000
	s_add_i32 s58, s81, s33
	global_load_lds_dwordx4 v[238:239], off
	s_mov_b32 m0, s58
	s_nop 0
	global_load_lds_dwordx4 v[240:241], off
	s_add_i32 m0, s58, 0x2000
	s_nop 0
	global_load_lds_dwordx4 v[242:243], off
	s_mov_b32 m0, s64
	s_nop 0
	global_load_lds_dwordx4 v[244:245], off
	s_mov_b32 m0, s65
	s_nop 0
	global_load_lds_dwordx4 v[246:247], off
	s_waitcnt vmcnt(8)
	s_waitcnt lgkmcnt(0)
	s_barrier
	s_setprio 1
	s_waitcnt lgkmcnt(0)
	v_mfma_f32_16x16x32_bf16 v[76:79], v[60:63], v[160:163], v[76:79]
	v_mfma_f32_16x16x32_bf16 v[24:27], v[68:71], v[160:163], v[24:27]
	v_mfma_f32_16x16x32_bf16 v[52:55], v[60:63], v[190:193], v[52:55]
	v_mfma_f32_16x16x32_bf16 v[20:23], v[68:71], v[190:193], v[20:23]
	v_mfma_f32_16x16x32_bf16 v[44:47], v[60:63], v[198:201], v[44:47]
	v_mfma_f32_16x16x32_bf16 v[12:15], v[68:71], v[198:201], v[12:15]
	v_mfma_f32_16x16x32_bf16 v[36:39], v[60:63], v[206:209], v[36:39]
	v_mfma_f32_16x16x32_bf16 v[0:3], v[68:71], v[206:209], v[0:3]
	v_mfma_f32_16x16x32_bf16 v[76:79], v[64:67], v[164:167], v[76:79]
	v_mfma_f32_16x16x32_bf16 v[24:27], v[72:75], v[164:167], v[24:27]
	v_mfma_f32_16x16x32_bf16 v[52:55], v[64:67], v[194:197], v[52:55]
	v_mfma_f32_16x16x32_bf16 v[20:23], v[72:75], v[194:197], v[20:23]
	v_mfma_f32_16x16x32_bf16 v[44:47], v[64:67], v[202:205], v[44:47]
	v_mfma_f32_16x16x32_bf16 v[12:15], v[72:75], v[202:205], v[12:15]
	v_mfma_f32_16x16x32_bf16 v[36:39], v[64:67], v[210:213], v[36:39]
	v_mfma_f32_16x16x32_bf16 v[0:3], v[72:75], v[210:213], v[0:3]
	s_setprio 0
	s_setprio 1
	v_mfma_f32_16x16x32_bf16 v[56:59], v[100:103], v[160:163], v[56:59]
	v_mfma_f32_16x16x32_bf16 v[28:31], v[108:111], v[160:163], v[28:31]
	v_mfma_f32_16x16x32_bf16 v[48:51], v[100:103], v[190:193], v[48:51]
	v_mfma_f32_16x16x32_bf16 v[16:19], v[108:111], v[190:193], v[16:19]
	v_mfma_f32_16x16x32_bf16 v[40:43], v[100:103], v[198:201], v[40:43]
	v_mfma_f32_16x16x32_bf16 v[8:11], v[108:111], v[198:201], v[8:11]
	v_mfma_f32_16x16x32_bf16 v[32:35], v[100:103], v[206:209], v[32:35]
	v_mfma_f32_16x16x32_bf16 v[4:7], v[108:111], v[206:209], v[4:7]
	v_mfma_f32_16x16x32_bf16 v[72:75], v[104:107], v[164:167], v[56:59]
	v_mfma_f32_16x16x32_bf16 v[28:31], v[112:115], v[164:167], v[28:31]
	v_mfma_f32_16x16x32_bf16 v[48:51], v[104:107], v[194:197], v[48:51]
	v_mfma_f32_16x16x32_bf16 v[16:19], v[112:115], v[194:197], v[16:19]
	v_mfma_f32_16x16x32_bf16 v[40:43], v[104:107], v[202:205], v[40:43]
	v_mfma_f32_16x16x32_bf16 v[8:11], v[112:115], v[202:205], v[8:11]
	v_mfma_f32_16x16x32_bf16 v[32:35], v[104:107], v[210:213], v[32:35]
	v_mfma_f32_16x16x32_bf16 v[4:7], v[112:115], v[210:213], v[4:7]
	s_setprio 0
	s_barrier
	s_add_i32 s79, s79, 2
	s_add_u32 s60, s60, 0x100
	s_addc_u32 s61, s61, 0
	s_add_u32 s12, s12, 0x100
	s_addc_u32 s13, s13, 0
	s_cmp_gt_u32 s79, 13
	s_cbranch_scc0 .LBB0_3010
	s_and_b64 vcc, exec, s[26:27]
	s_cbranch_vccz .LBB0_3013
	s_barrier

; #define PG8_STAGE(bufoff, gbase, voff) do { _Pragma("unroll") for (int _i = 0; _i < 2; ++_i) \
;         __builtin_amdgcn_global_load_lds((const unsigned*)((const char*)(gbase) + (voff)[_i]), (PG8_LAS unsigned*)(lds + (bufoff) + ldsw + _i * 8192), 16, 0, 0); } while (0)
; #define PG8_LDA(dst, b, h) do { _Pragma("unroll") for (int m = 0; m < 4; ++m) _Pragma("unroll") for (int k = 0; k < 2; ++k) dst[m][k] = *(const PG8_LAS bf16x8*)(lds + PG8_SA(b, h) + aoff + m * 2048 + k * 1024); } while (0)
; #define PG8_LDB(dst, b, h) do { _Pragma("unroll") for (int n = 0; n < 2; ++n) _Pragma("unroll") for (int k = 0; k < 2; ++k) dst[n][k] = *(const PG8_LAS bf16x8*)(lds + PG8_SB(b, h) + boff + n * 2048 + k * 1024); } while (0)
; #define PG8_MMA(ai, bj, At, Bt) do { __builtin_amdgcn_s_setprio(1); _Pragma("unroll") for (int m = 0; m < 4; ++m) _Pragma("unroll") for (int n = 0; n < 2; ++n) _Pragma("unroll") for (int k = 0; k < 2; ++k) \
;         acc[ai][bj][m][n] = __builtin_amdgcn_mfma_f32_16x16x32_bf16(Bt[n][k], At[m][k], acc[ai][bj][m][n], 0, 0, 0); __builtin_amdgcn_s_setprio(0); } while (0)
; #define PG8_WAIT_V(n) asm volatile("s_waitcnt vmcnt(" #n ")" ::: "memory")
; #define PG8_WAIT_L(n) asm volatile("s_waitcnt lgkmcnt(" #n ")" ::: "memory")
; template <class Epi, class Sched, bool ALIGN_EPI = false, bool SP2 = false>
; __device__ __forceinline__ void gemm_phase(PG8_LAS unsigned char* lds, const Gemm g, const Sched& S, const Epi& E, const int wave_s) {
;     ...
;             const bool last = (t == nt - 2);
;             const char* a1 = cA + (size_t)(t + 1) * kstep;
;             const char* a2 = last ? nA : cA + (size_t)(t + 2) * kstep; const char* b2 = last ? nB : cB + (size_t)(t + 2) * kstep;
;             const char* a3 = a2 + kstep; const char* b3 = b2 + kstep;
;             if (last && has_next) S.a_ready(nxt);
;             if constexpr (SP2) {
;             PG8_LDB(B0, 0, 0); PG8_LDB(B1, 0, 1); PG8_SCHED; PG8_LDA(At, 0, 0); PG8_STAGE(PG8_SA(1, 1), a1 + hstep, voffA);
;             PG8_WAIT_V(8); PG8_WAIT_L(0); PG8_BAR; PG8_MMA(0, 0, At, B0); PG8_MMA(0, 1, At, B1); PG8_BAR; PG8_SCHED;
;             PG8_LDA(At, 0, 1); PG8_STAGE(PG8_SB(0, 0), b2, voffB); PG8_STAGE(PG8_SB(0, 1), b2 + hstep, voffB); PG8_STAGE(PG8_SA(0, 0), a2, voffA);
;             PG8_WAIT_V(8); PG8_WAIT_L(0); PG8_BAR; PG8_MMA(1, 0, At, B0); PG8_MMA(1, 1, At, B1); PG8_BAR; PG8_SCHED;
.LBB0_3120:
	ds_read_b128 v[128:131], v195
	ds_read_b128 v[132:135], v195 offset:1024
	ds_read_b128 v[136:139], v195 offset:2048
	ds_read_b128 v[140:143], v195 offset:3072
	ds_read_b128 v[160:163], v196
	ds_read_b128 v[164:167], v196 offset:1024
	ds_read_b128 v[168:171], v196 offset:2048
	ds_read_b128 v[172:175], v196 offset:3072
	s_add_u32 s26, s24, 0x100
	s_addc_u32 s27, s25, 0
	s_cmp_eq_u32 s61, 40
	s_cselect_b32 s31, s7, s27
	s_cselect_b32 s30, s6, s26
	s_cselect_b32 s29, s9, s60
	s_cselect_b32 s28, s8, s59
	v_lshl_add_u64 v[156:157], s[24:25], 0, v[154:155]
	s_add_i32 m0, s38, 0xc000
	ds_read_b128 v[176:179], v197
	ds_read_b128 v[180:183], v197 offset:1024
	ds_read_b128 v[184:187], v197 offset:2048
	ds_read_b128 v[188:191], v197 offset:3072
	ds_read_b128 v[198:201], v197 offset:4096
	ds_read_b128 v[202:205], v197 offset:5120
	ds_read_b128 v[206:209], v197 offset:6144
	ds_read_b128 v[210:213], v197 offset:7168
	global_load_lds_dwordx4 v[156:157], off
	v_lshl_add_u64 v[156:157], s[24:25], 0, v[152:153]
	s_add_i32 m0, s38, 0xe000
	s_nop 0
	global_load_lds_dwordx4 v[156:157], off
	v_lshl_add_u64 v[230:231], s[28:29], 0, v[146:147]
	v_lshl_add_u64 v[232:233], s[28:29], 0, v[150:151]
	v_lshl_add_u64 v[234:235], s[30:31], 0, v[148:149]
	s_waitcnt vmcnt(8)
	s_waitcnt lgkmcnt(0)
	s_barrier
	s_setprio 1
	s_waitcnt lgkmcnt(0)
	v_mfma_f32_16x16x32_bf16 v[124:127], v[128:131], v[176:179], v[124:127]
	v_mfma_f32_16x16x32_bf16 v[120:123], v[136:139], v[176:179], v[120:123]
	v_mfma_f32_16x16x32_bf16 v[112:115], v[128:131], v[184:187], v[112:115]
	v_mfma_f32_16x16x32_bf16 v[104:107], v[136:139], v[184:187], v[104:107]
	v_mfma_f32_16x16x32_bf16 v[92:95], v[128:131], v[198:201], v[92:95]
	v_mfma_f32_16x16x32_bf16 v[88:91], v[136:139], v[198:201], v[88:91]
	v_mfma_f32_16x16x32_bf16 v[80:83], v[128:131], v[206:209], v[80:83]
	v_mfma_f32_16x16x32_bf16 v[72:75], v[136:139], v[206:209], v[72:75]
	v_mfma_f32_16x16x32_bf16 v[124:127], v[132:135], v[180:183], v[124:127]
	v_mfma_f32_16x16x32_bf16 v[120:123], v[140:143], v[180:183], v[120:123]
	v_mfma_f32_16x16x32_bf16 v[112:115], v[132:135], v[188:191], v[112:115]
	v_mfma_f32_16x16x32_bf16 v[104:107], v[140:143], v[188:191], v[104:107]
	v_mfma_f32_16x16x32_bf16 v[92:95], v[132:135], v[202:205], v[92:95]
	v_mfma_f32_16x16x32_bf16 v[88:91], v[140:143], v[202:205], v[88:91]
	v_mfma_f32_16x16x32_bf16 v[80:83], v[132:135], v[210:213], v[80:83]
	v_mfma_f32_16x16x32_bf16 v[72:75], v[140:143], v[210:213], v[72:75]
	s_setprio 0
	s_setprio 1
	v_mfma_f32_16x16x32_bf16 v[116:119], v[160:163], v[176:179], v[116:119]
	v_mfma_f32_16x16x32_bf16 v[108:111], v[168:171], v[176:179], v[108:111]
	v_mfma_f32_16x16x32_bf16 v[100:103], v[160:163], v[184:187], v[100:103]
	v_mfma_f32_16x16x32_bf16 v[96:99], v[168:171], v[184:187], v[96:99]
	v_mfma_f32_16x16x32_bf16 v[84:87], v[160:163], v[198:201], v[84:87]
	v_mfma_f32_16x16x32_bf16 v[76:79], v[168:171], v[198:201], v[76:79]
	v_mfma_f32_16x16x32_bf16 v[68:71], v[160:163], v[206:209], v[68:71]
	v_mfma_f32_16x16x32_bf16 v[64:67], v[168:171], v[206:209], v[64:67]
	v_mfma_f32_16x16x32_bf16 v[116:119], v[164:167], v[180:183], v[116:119]
	v_mfma_f32_16x16x32_bf16 v[108:111], v[172:175], v[180:183], v[108:111]
	v_mfma_f32_16x16x32_bf16 v[100:103], v[164:167], v[188:191], v[100:103]
	v_mfma_f32_16x16x32_bf16 v[96:99], v[172:175], v[188:191], v[96:99]
	v_mfma_f32_16x16x32_bf16 v[84:87], v[164:167], v[202:205], v[84:87]
	v_mfma_f32_16x16x32_bf16 v[76:79], v[172:175], v[202:205], v[76:79]
	v_mfma_f32_16x16x32_bf16 v[68:71], v[164:167], v[210:213], v[68:71]
	v_mfma_f32_16x16x32_bf16 v[64:67], v[172:175], v[210:213], v[64:67]
	s_setprio 0
	s_barrier
	s_add_i32 s24, s53, s33
	s_mov_b32 m0, s24
	ds_read_b128 v[176:179], v197 offset:16384
	ds_read_b128 v[180:183], v197 offset:17408
	ds_read_b128 v[184:187], v197 offset:18432
	ds_read_b128 v[188:191], v197 offset:19456
	ds_read_b128 v[198:201], v197 offset:20480
	ds_read_b128 v[202:205], v197 offset:21504
	ds_read_b128 v[206:209], v197 offset:22528
	ds_read_b128 v[210:213], v197 offset:23552
	global_load_lds_dwordx4 v[230:231], off
	s_add_i32 m0, s24, 0x2000
	s_add_u32 s24, s28, 0xb0000
	s_addc_u32 s25, s29, 0
	s_add_i32 s62, s54, s33
	global_load_lds_dwordx4 v[232:233], off
	v_lshl_add_u64 v[214:215], s[24:25], 0, v[146:147]
	s_mov_b32 m0, s62
	s_nop 0
	global_load_lds_dwordx4 v[214:215], off
	v_lshl_add_u64 v[214:215], s[24:25], 0, v[150:151]
	s_add_i32 m0, s62, 0x2000
	s_nop 0
	global_load_lds_dwordx4 v[214:215], off
	v_lshl_add_u64 v[214:215], s[30:31], 0, v[144:145]
	s_mov_b32 m0, s38
	s_nop 0
	global_load_lds_dwordx4 v[214:215], off
	s_mov_b32 m0, s39
	s_nop 0
	global_load_lds_dwordx4 v[234:235], off
	s_waitcnt vmcnt(8)
	s_waitcnt lgkmcnt(0)
	s_barrier
; #define PG8_STAGE(bufoff, gbase, voff) do { _Pragma("unroll") for (int _i = 0; _i < 2; ++_i) \
;         __builtin_amdgcn_global_load_lds((const unsigned*)((const char*)(gbase) + (voff)[_i]), (PG8_LAS unsigned*)(lds + (bufoff) + ldsw + _i * 8192), 16, 0, 0); } while (0)
; #define PG8_LDA(dst, b, h) do { _Pragma("unroll") for (int m = 0; m < 4; ++m) _Pragma("unroll") for (int k = 0; k < 2; ++k) dst[m][k] = *(const PG8_LAS bf16x8*)(lds + PG8_SA(b, h) + aoff + m * 2048 + k * 1024); } while (0)
; #define PG8_LDB(dst, b, h) do { _Pragma("unroll") for (int n = 0; n < 2; ++n) _Pragma("unroll") for (int k = 0; k < 2; ++k) dst[n][k] = *(const PG8_LAS bf16x8*)(lds + PG8_SB(b, h) + boff + n * 2048 + k * 1024); } while (0)
; #define PG8_MMA(ai, bj, At, Bt) do { __builtin_amdgcn_s_setprio(1); _Pragma("unroll") for (int m = 0; m < 4; ++m) _Pragma("unroll") for (int n = 0; n < 2; ++n) _Pragma("unroll") for (int k = 0; k < 2; ++k) \
;         acc[ai][bj][m][n] = __builtin_amdgcn_mfma_f32_16x16x32_bf16(Bt[n][k], At[m][k], acc[ai][bj][m][n], 0, 0, 0); __builtin_amdgcn_s_setprio(0); } while (0)
; #define PG8_WAIT_V(n) asm volatile("s_waitcnt vmcnt(" #n ")" ::: "memory")
; #define PG8_WAIT_L(n) asm volatile("s_waitcnt lgkmcnt(" #n ")" ::: "memory")
; #define PG8_BAR __builtin_amdgcn_s_barrier()
; #define PG8_SCHED __builtin_amdgcn_sched_barrier(0)
; template <class Epi, class Sched, bool ALIGN_EPI = false, bool SP2 = false>
; __device__ __forceinline__ void gemm_phase(PG8_LAS unsigned char* lds, const Gemm g, const Sched& S, const Epi& E, const int wave_s) {
;     ...
;             PG8_WAIT_V(8); PG8_WAIT_L(0); PG8_BAR; PG8_MMA(1, 0, At, B0); PG8_MMA(1, 1, At, B1); PG8_BAR; PG8_SCHED;
;             PG8_LDB(B0, 1, 0); PG8_LDB(B1, 1, 1); PG8_SCHED; PG8_LDA(At, 1, 0); PG8_STAGE(PG8_SA(0, 1), a2 + hstep, voffA);
;             PG8_WAIT_V(8); PG8_WAIT_L(0); PG8_BAR; PG8_MMA(0, 0, At, B0); PG8_MMA(0, 1, At, B1); PG8_BAR; PG8_SCHED;
;             PG8_LDA(At, 1, 1); PG8_STAGE(PG8_SB(1, 0), b3, voffB); PG8_STAGE(PG8_SB(1, 1), b3 + hstep, voffB); PG8_STAGE(PG8_SA(1, 0), a3, voffA);
	s_setprio 1
	s_waitcnt lgkmcnt(0)
	v_mfma_f32_16x16x32_bf16 v[60:63], v[128:131], v[176:179], v[60:63]
	v_mfma_f32_16x16x32_bf16 v[56:59], v[136:139], v[176:179], v[56:59]
	v_mfma_f32_16x16x32_bf16 v[48:51], v[128:131], v[184:187], v[48:51]
	v_mfma_f32_16x16x32_bf16 v[40:43], v[136:139], v[184:187], v[40:43]
	v_mfma_f32_16x16x32_bf16 v[28:31], v[128:131], v[198:201], v[28:31]
	v_mfma_f32_16x16x32_bf16 v[24:27], v[136:139], v[198:201], v[24:27]
	v_mfma_f32_16x16x32_bf16 v[16:19], v[128:131], v[206:209], v[16:19]
	v_mfma_f32_16x16x32_bf16 v[8:11], v[136:139], v[206:209], v[8:11]
	v_mfma_f32_16x16x32_bf16 v[60:63], v[132:135], v[180:183], v[60:63]
	v_mfma_f32_16x16x32_bf16 v[56:59], v[140:143], v[180:183], v[56:59]
	v_mfma_f32_16x16x32_bf16 v[48:51], v[132:135], v[188:191], v[48:51]
	v_mfma_f32_16x16x32_bf16 v[40:43], v[140:143], v[188:191], v[40:43]
	v_mfma_f32_16x16x32_bf16 v[28:31], v[132:135], v[202:205], v[28:31]
	v_mfma_f32_16x16x32_bf16 v[24:27], v[140:143], v[202:205], v[24:27]
	v_mfma_f32_16x16x32_bf16 v[16:19], v[132:135], v[210:213], v[16:19]
	v_mfma_f32_16x16x32_bf16 v[8:11], v[140:143], v[210:213], v[8:11]
	s_setprio 0
	s_setprio 1
	v_mfma_f32_16x16x32_bf16 v[52:55], v[160:163], v[176:179], v[52:55]
	v_mfma_f32_16x16x32_bf16 v[44:47], v[168:171], v[176:179], v[44:47]
	v_mfma_f32_16x16x32_bf16 v[36:39], v[160:163], v[184:187], v[36:39]
	v_mfma_f32_16x16x32_bf16 v[32:35], v[168:171], v[184:187], v[32:35]
	v_mfma_f32_16x16x32_bf16 v[20:23], v[160:163], v[198:201], v[20:23]
	v_mfma_f32_16x16x32_bf16 v[12:15], v[168:171], v[198:201], v[12:15]
	v_mfma_f32_16x16x32_bf16 v[4:7], v[160:163], v[206:209], v[4:7]
	v_mfma_f32_16x16x32_bf16 v[0:3], v[168:171], v[206:209], v[0:3]
	v_mfma_f32_16x16x32_bf16 v[52:55], v[164:167], v[180:183], v[52:55]
	v_mfma_f32_16x16x32_bf16 v[44:47], v[172:175], v[180:183], v[44:47]
	v_mfma_f32_16x16x32_bf16 v[36:39], v[164:167], v[188:191], v[36:39]
	v_mfma_f32_16x16x32_bf16 v[32:35], v[172:175], v[188:191], v[32:35]
	v_mfma_f32_16x16x32_bf16 v[20:23], v[164:167], v[202:205], v[20:23]
	v_mfma_f32_16x16x32_bf16 v[12:15], v[172:175], v[202:205], v[12:15]
	v_mfma_f32_16x16x32_bf16 v[4:7], v[164:167], v[210:213], v[4:7]
	v_mfma_f32_16x16x32_bf16 v[0:3], v[172:175], v[210:213], v[0:3]
	s_setprio 0
	s_barrier
	s_add_i32 s62, 0, 0x18000
	s_add_i32 s63, 0, 0x1c000
	v_add_u32_e32 v140, s62, v194
	v_add_u32_e32 v172, s63, v194
	ds_read_b128 v[128:131], v140
	ds_read_b128 v[132:135], v140 offset:1024
	ds_read_b128 v[136:139], v140 offset:2048
	ds_read_b128 v[140:143], v140 offset:3072
	ds_read_b128 v[160:163], v172
	ds_read_b128 v[164:167], v172 offset:1024
	ds_read_b128 v[168:171], v172 offset:2048
	ds_read_b128 v[172:175], v172 offset:3072
	s_add_u32 s24, s30, 0xb0000
	s_addc_u32 s25, s31, 0
	s_mov_b32 m0, s40
	v_lshl_add_u64 v[218:219], s[24:25], 0, v[144:145]
	ds_read_b128 v[176:179], v197 offset:32768
	ds_read_b128 v[180:183], v197 offset:33792
	ds_read_b128 v[184:187], v197 offset:34816
	ds_read_b128 v[188:191], v197 offset:35840
	ds_read_b128 v[198:201], v197 offset:36864
	ds_read_b128 v[202:205], v197 offset:37888
	ds_read_b128 v[206:209], v197 offset:38912
	ds_read_b128 v[210:213], v197 offset:39936
	global_load_lds_dwordx4 v[218:219], off
	v_lshl_add_u64 v[218:219], s[24:25], 0, v[148:149]
	s_mov_b32 m0, s41
	s_nop 0
	global_load_lds_dwordx4 v[218:219], off
	v_lshl_add_u64 v[236:237], v[230:231], 0, s[14:15]
	v_lshl_add_u64 v[238:239], v[232:233], 0, s[14:15]
	s_waitcnt vmcnt(8)
	s_waitcnt lgkmcnt(0)
	s_barrier
	s_setprio 1
	s_waitcnt lgkmcnt(0)
	v_mfma_f32_16x16x32_bf16 v[124:127], v[128:131], v[176:179], v[124:127]
	v_mfma_f32_16x16x32_bf16 v[120:123], v[136:139], v[176:179], v[120:123]
	v_mfma_f32_16x16x32_bf16 v[112:115], v[128:131], v[184:187], v[112:115]
	v_mfma_f32_16x16x32_bf16 v[104:107], v[136:139], v[184:187], v[104:107]
	v_mfma_f32_16x16x32_bf16 v[92:95], v[128:131], v[198:201], v[92:95]
	v_mfma_f32_16x16x32_bf16 v[88:91], v[136:139], v[198:201], v[88:91]
	v_mfma_f32_16x16x32_bf16 v[80:83], v[128:131], v[206:209], v[80:83]
	v_mfma_f32_16x16x32_bf16 v[72:75], v[136:139], v[206:209], v[72:75]
	v_mfma_f32_16x16x32_bf16 v[124:127], v[132:135], v[180:183], v[124:127]
	v_mfma_f32_16x16x32_bf16 v[120:123], v[140:143], v[180:183], v[120:123]
	v_mfma_f32_16x16x32_bf16 v[112:115], v[132:135], v[188:191], v[112:115]
	v_mfma_f32_16x16x32_bf16 v[104:107], v[140:143], v[188:191], v[104:107]
	v_mfma_f32_16x16x32_bf16 v[92:95], v[132:135], v[202:205], v[92:95]
	v_mfma_f32_16x16x32_bf16 v[88:91], v[140:143], v[202:205], v[88:91]
	v_mfma_f32_16x16x32_bf16 v[80:83], v[132:135], v[210:213], v[80:83]
	v_mfma_f32_16x16x32_bf16 v[72:75], v[140:143], v[210:213], v[72:75]
	s_setprio 0
	s_setprio 1
	v_mfma_f32_16x16x32_bf16 v[116:119], v[160:163], v[176:179], v[116:119]
	v_mfma_f32_16x16x32_bf16 v[108:111], v[168:171], v[176:179], v[108:111]
	v_mfma_f32_16x16x32_bf16 v[100:103], v[160:163], v[184:187], v[100:103]
	v_mfma_f32_16x16x32_bf16 v[96:99], v[168:171], v[184:187], v[96:99]
	v_mfma_f32_16x16x32_bf16 v[84:87], v[160:163], v[198:201], v[84:87]
	v_mfma_f32_16x16x32_bf16 v[76:79], v[168:171], v[198:201], v[76:79]
	v_mfma_f32_16x16x32_bf16 v[68:71], v[160:163], v[206:209], v[68:71]
	v_mfma_f32_16x16x32_bf16 v[64:67], v[168:171], v[206:209], v[64:67]
	v_mfma_f32_16x16x32_bf16 v[116:119], v[164:167], v[180:183], v[116:119]
	v_mfma_f32_16x16x32_bf16 v[108:111], v[172:175], v[180:183], v[108:111]
	v_mfma_f32_16x16x32_bf16 v[100:103], v[164:167], v[188:191], v[100:103]
	v_mfma_f32_16x16x32_bf16 v[96:99], v[172:175], v[188:191], v[96:99]
	v_mfma_f32_16x16x32_bf16 v[84:87], v[164:167], v[202:205], v[84:87]
	v_mfma_f32_16x16x32_bf16 v[76:79], v[172:175], v[202:205], v[76:79]
	v_mfma_f32_16x16x32_bf16 v[68:71], v[164:167], v[210:213], v[68:71]
	v_mfma_f32_16x16x32_bf16 v[64:67], v[172:175], v[210:213], v[64:67]
	s_setprio 0
	s_barrier
; #define PG8_STAGE(bufoff, gbase, voff) do { _Pragma("unroll") for (int _i = 0; _i < 2; ++_i) \
;         __builtin_amdgcn_global_load_lds((const unsigned*)((const char*)(gbase) + (voff)[_i]), (PG8_LAS unsigned*)(lds + (bufoff) + ldsw + _i * 8192), 16, 0, 0); } while (0)
; #define PG8_LDA(dst, b, h) do { _Pragma("unroll") for (int m = 0; m < 4; ++m) _Pragma("unroll") for (int k = 0; k < 2; ++k) dst[m][k] = *(const PG8_LAS bf16x8*)(lds + PG8_SA(b, h) + aoff + m * 2048 + k * 1024); } while (0)
; #define PG8_MMA(ai, bj, At, Bt) do { __builtin_amdgcn_s_setprio(1); _Pragma("unroll") for (int m = 0; m < 4; ++m) _Pragma("unroll") for (int n = 0; n < 2; ++n) _Pragma("unroll") for (int k = 0; k < 2; ++k) \
;         acc[ai][bj][m][n] = __builtin_amdgcn_mfma_f32_16x16x32_bf16(Bt[n][k], At[m][k], acc[ai][bj][m][n], 0, 0, 0); __builtin_amdgcn_s_setprio(0); } while (0)
; #define PG8_WAIT_V(n) asm volatile("s_waitcnt vmcnt(" #n ")" ::: "memory")
; #define PG8_WAIT_L(n) asm volatile("s_waitcnt lgkmcnt(" #n ")" ::: "memory")
; #define PG8_BAR __builtin_amdgcn_s_barrier()
; #define PG8_SCHED __builtin_amdgcn_sched_barrier(0)
; __device__ __forceinline__ int lane_id_v() { int l; asm volatile("v_mbcnt_lo_u32_b32 %0, -1, 0\n\tv_mbcnt_hi_u32_b32 %0, -1, %0" : "=v"(l)); return l; }
; template <class Epi, class Sched, bool ALIGN_EPI = false, bool SP2 = false>
; __device__ __forceinline__ void gemm_phase(PG8_LAS unsigned char* lds, const Gemm g, const Sched& S, const Epi& E, const int wave_s) {
;     ...
;             PG8_LDA(At, 1, 1); PG8_STAGE(PG8_SB(1, 0), b3, voffB); PG8_STAGE(PG8_SB(1, 1), b3 + hstep, voffB); PG8_STAGE(PG8_SA(1, 0), a3, voffA);
;             PG8_WAIT_V(8); PG8_WAIT_L(0); PG8_BAR; PG8_MMA(1, 0, At, B0); PG8_MMA(1, 1, At, B1); PG8_BAR; PG8_SCHED;
;     __device__ __forceinline__ void operator()(const af4 (&acc)[2][2][4][2], const pg8::Unit& u, int wr, int wc, int fr_, int fq_) const {
;         const int ln_ = lane_id_v(); const int fr = ln_ & 15, fq = ln_ >> 4;
;         const int grow = rowbase + u.pm * 256; const int bi = grow < TL ? grow / LSEQ : NB;
;         float* xb = grow < TL ? xl + (size_t)grow * DM : xc + (size_t)(grow - TL) * DM;
;         const float* stb = stats + 2 * (size_t)grow;
;         const int col0 = u.pn * 256 + wc * 32 + 8 * fq; const float* gp = gate + (size_t)bi * 6144 + col0;
	s_add_i32 s24, s62, s33
	s_mov_b32 m0, s24
	ds_read_b128 v[176:179], v197 offset:49152
	ds_read_b128 v[180:183], v197 offset:50176
	ds_read_b128 v[184:187], v197 offset:51200
	ds_read_b128 v[188:191], v197 offset:52224
	ds_read_b128 v[198:201], v197 offset:53248
	ds_read_b128 v[202:205], v197 offset:54272
	ds_read_b128 v[206:209], v197 offset:55296
	ds_read_b128 v[210:213], v197 offset:56320
	global_load_lds_dwordx4 v[236:237], off
	s_add_i32 m0, s24, 0x2000
	s_add_u32 s24, s28, 0xb0080
	s_addc_u32 s25, s29, 0
	s_add_i32 s28, s63, s33
	global_load_lds_dwordx4 v[238:239], off
	v_lshl_add_u64 v[156:157], s[24:25], 0, v[146:147]
	s_mov_b32 m0, s28
	s_nop 0
	global_load_lds_dwordx4 v[156:157], off
	v_lshl_add_u64 v[156:157], s[24:25], 0, v[150:151]
	s_add_i32 m0, s28, 0x2000
	s_nop 0
	global_load_lds_dwordx4 v[156:157], off
	v_lshl_add_u64 v[156:157], v[214:215], 0, s[14:15]
	s_mov_b32 m0, s49
	s_nop 0
	global_load_lds_dwordx4 v[156:157], off
	v_lshl_add_u64 v[156:157], v[234:235], 0, s[14:15]
	s_mov_b32 m0, s50
	s_nop 0
	global_load_lds_dwordx4 v[156:157], off
	s_waitcnt vmcnt(8)
	s_waitcnt lgkmcnt(0)
	s_barrier
	s_setprio 1
	s_waitcnt lgkmcnt(0)
	v_mfma_f32_16x16x32_bf16 v[60:63], v[128:131], v[176:179], v[60:63]
	v_mfma_f32_16x16x32_bf16 v[56:59], v[136:139], v[176:179], v[56:59]
	v_mfma_f32_16x16x32_bf16 v[48:51], v[128:131], v[184:187], v[48:51]
	v_mfma_f32_16x16x32_bf16 v[40:43], v[136:139], v[184:187], v[40:43]
	v_mfma_f32_16x16x32_bf16 v[28:31], v[128:131], v[198:201], v[28:31]
	v_mfma_f32_16x16x32_bf16 v[24:27], v[136:139], v[198:201], v[24:27]
	v_mfma_f32_16x16x32_bf16 v[16:19], v[128:131], v[206:209], v[16:19]
	v_mfma_f32_16x16x32_bf16 v[8:11], v[136:139], v[206:209], v[8:11]
	v_mfma_f32_16x16x32_bf16 v[60:63], v[132:135], v[180:183], v[60:63]
	v_mfma_f32_16x16x32_bf16 v[56:59], v[140:143], v[180:183], v[56:59]
	v_mfma_f32_16x16x32_bf16 v[48:51], v[132:135], v[188:191], v[48:51]
	v_mfma_f32_16x16x32_bf16 v[40:43], v[140:143], v[188:191], v[40:43]
	v_mfma_f32_16x16x32_bf16 v[28:31], v[132:135], v[202:205], v[28:31]
	v_mfma_f32_16x16x32_bf16 v[24:27], v[140:143], v[202:205], v[24:27]
	v_mfma_f32_16x16x32_bf16 v[16:19], v[132:135], v[210:213], v[16:19]
	v_mfma_f32_16x16x32_bf16 v[8:11], v[140:143], v[210:213], v[8:11]
	s_setprio 0
	s_setprio 1
	v_mfma_f32_16x16x32_bf16 v[52:55], v[160:163], v[176:179], v[52:55]
	v_mfma_f32_16x16x32_bf16 v[44:47], v[168:171], v[176:179], v[44:47]
	v_mfma_f32_16x16x32_bf16 v[36:39], v[160:163], v[184:187], v[36:39]
	v_mfma_f32_16x16x32_bf16 v[32:35], v[168:171], v[184:187], v[32:35]
	v_mfma_f32_16x16x32_bf16 v[20:23], v[160:163], v[198:201], v[20:23]
	v_mfma_f32_16x16x32_bf16 v[12:15], v[168:171], v[198:201], v[12:15]
	v_mfma_f32_16x16x32_bf16 v[4:7], v[160:163], v[206:209], v[4:7]
	v_mfma_f32_16x16x32_bf16 v[0:3], v[168:171], v[206:209], v[0:3]
	v_mfma_f32_16x16x32_bf16 v[52:55], v[164:167], v[180:183], v[52:55]
	v_mfma_f32_16x16x32_bf16 v[44:47], v[172:175], v[180:183], v[44:47]
	v_mfma_f32_16x16x32_bf16 v[36:39], v[164:167], v[188:191], v[36:39]
	v_mfma_f32_16x16x32_bf16 v[32:35], v[172:175], v[188:191], v[32:35]
	v_mfma_f32_16x16x32_bf16 v[20:23], v[164:167], v[202:205], v[20:23]
	v_mfma_f32_16x16x32_bf16 v[12:15], v[172:175], v[202:205], v[12:15]
	v_mfma_f32_16x16x32_bf16 v[4:7], v[164:167], v[210:213], v[4:7]
	v_mfma_f32_16x16x32_bf16 v[0:3], v[172:175], v[210:213], v[0:3]
	s_setprio 0
	s_barrier
	s_add_i32 s61, s61, 2
	s_add_u32 s59, s59, 0x100
	s_addc_u32 s60, s60, 0
	s_cmp_gt_u32 s61, 41
	s_mov_b64 s[24:25], s[26:27]
	s_cbranch_scc0 .LBB0_3120
	s_cmpk_gt_i32 s10, 0xff
	s_cselect_b64 s[26:27], -1, 0
	s_mov_b64 s[28:29], 0x18000
	s_and_b64 vcc, exec, s[26:27]
	v_mbcnt_lo_u32_b32 v160, -1, 0
	v_mbcnt_hi_u32_b32 v160, -1, v160
	s_cbranch_vccnz .LBB0_3123
	s_ashr_i32 s24, s10, 31
	s_lshr_b32 s24, s24, 28
	s_add_i32 s24, s10, s24
	s_ashr_i32 s24, s24, 4
	s_mul_hi_i32 s29, s24, 0x1800
	s_mul_i32 s28, s24, 0x1800
